# removed 1447 SGPR-reload v_readlane whose destination is dead (whole-kernel liveness), each run replaced by s_nop of equal wait states
# speedup vs baseline: 1.0136x; 1.0026x over previous
.LBB0_160:
	s_or_b64 exec, exec, s[2:3]
	s_load_dwordx16 s[4:19], s[0:1], 0x100
	s_cmpk_lg_i32 s92, 0x100
	s_cselect_b64 s[60:61], -1, 0
	s_cmpk_lt_i32 s62, 0x800
	s_cselect_b64 s[0:1], -1, 0
	s_waitcnt lgkmcnt(0)
	v_writelane_b32 v252, s4, 7
	s_ashr_i32 s2, s62, 31
	s_bfe_u32 s3, s62, 0x20003
	v_writelane_b32 v252, s5, 8
	v_writelane_b32 v252, s6, 9
	v_writelane_b32 v252, s7, 10
	v_writelane_b32 v252, s8, 11
	v_writelane_b32 v252, s9, 12
	v_writelane_b32 v252, s10, 13
	v_writelane_b32 v252, s11, 14
	v_writelane_b32 v252, s12, 15
	v_writelane_b32 v252, s13, 16
	v_writelane_b32 v252, s14, 17
	v_writelane_b32 v252, s15, 18
	v_writelane_b32 v252, s16, 19
	v_writelane_b32 v252, s17, 20
	v_writelane_b32 v252, s18, 21
	v_writelane_b32 v252, s19, 22
	v_writelane_b32 v252, s2, 23
	s_lshr_b32 s2, s2, 28
	s_add_i32 s2, s62, s2
	s_ashr_i32 s4, s2, 4
	s_and_b32 s2, s2, -16
	s_sub_i32 s5, s62, s2
	s_lshl_b32 s2, s62, 2
	s_and_b32 s2, s2, 12
	v_writelane_b32 v252, s3, 24
	s_or_b32 s8, s2, s3
	s_lshl_b32 s2, s62, 4
	v_writelane_b32 v252, s2, 25
	s_and_b32 s2, s2, 64
	s_ashr_i32 s3, s62, 5
	s_add_i32 s9, s2, s3
	s_cmpk_eq_i32 s92, 0x100
	s_cselect_b64 s[6:7], -1, 0
	v_writelane_b32 v252, s3, 26
	s_and_b64 s[2:3], s[6:7], exec
	v_writelane_b32 v252, s8, 27
	s_cselect_b32 s2, s8, s5
	v_writelane_b32 v252, s2, 28
	s_barrier
	s_nop 0
	v_writelane_b32 v252, s3, 29
	v_writelane_b32 v252, s9, 30
	s_cselect_b32 s2, s9, s4
	v_writelane_b32 v252, s2, 31
	v_mov_b32 v10, v178
	s_nop 1
	v_writelane_b32 v252, s3, 32
	v_writelane_b32 v252, s6, 33
	s_or_b64 s[0:1], s[6:7], s[0:1]
	v_readfirstlane_b32 s10, v10
	v_writelane_b32 v252, s7, 34
	v_writelane_b32 v252, s0, 35
	s_and_b64 vcc, exec, s[0:1]
	s_nop 0
	v_writelane_b32 v252, s1, 36
	v_writelane_b32 v252, s62, 37
	v_writelane_b32 v252, s92, 38
	s_nop 1
	v_writelane_b32 v252, s93, 39
	v_writelane_b32 v252, s60, 40
	s_nop 1
	v_writelane_b32 v252, s61, 41
	v_writelane_b32 v252, s94, 42
	s_nop 1
	v_writelane_b32 v252, s95, 43
	s_cbranch_vccz .LBB0_545
	v_lshlrev_b32_e32 v0, 4, v10
	v_add_u32_e32 v1, 0x2000, v0
	v_ashrrev_i32_e32 v2, 31, v1
	v_lshrrev_b32_e32 v2, 22, v2
	v_add_u32_e32 v2, v1, v2
	v_ashrrev_i32_e32 v8, 10, v2
	v_mul_i32_i24_e32 v2, 0x400, v8
	v_sub_u32_e32 v1, v1, v2
	v_lshrrev_b32_e32 v2, 4, v1
	v_bitop3_b32 v1, v2, v1, 32 bitop3:0x6c
	v_ashrrev_i32_e32 v2, 31, v1
	v_lshrrev_b32_e32 v2, 26, v2
	v_add_u32_e32 v2, v1, v2
	v_lshlrev_b32_e32 v3, 3, v8
	v_ashrrev_i32_e32 v9, 6, v2
	v_and_b32_e32 v3, -16, v3
	v_add_u32_e32 v3, v9, v3
	v_and_b32_e32 v4, 3, v9
	s_mov_b32 s1, 0x1fffe0
	v_lshrrev_b32_e32 v5, 2, v3
	v_lshlrev_b32_e32 v6, 1, v3
	v_and_b32_e32 v2, 0xc0, v2
	v_and_or_b32 v4, v3, s1, v4
	v_and_b32_e32 v5, 4, v5
	v_and_b32_e32 v6, 24, v6
	v_sub_u32_e32 v1, v1, v2
	v_mov_b32_e32 v2, 1
	v_or3_b32 v4, v4, v5, v6
	v_lshlrev_b32_e32 v5, 5, v8
	v_ashrrev_i16_sdwa v1, v2, sext(v1) dst_sel:DWORD dst_unused:UNUSED_PAD src0_sel:DWORD src1_sel:BYTE_0
	v_and_b32_e32 v5, 32, v5
	v_bfe_i32 v11, v1, 0, 16
	v_add_lshl_u32 v1, v5, v11, 1
	v_lshl_add_u32 v162, v4, 11, v1
	v_lshl_add_u32 v164, v3, 11, v1
	v_bfe_i32 v1, v10, 27, 1
	v_lshrrev_b32_e32 v1, 22, v1
	v_add_u32_e32 v1, v0, v1
	v_and_b32_e32 v1, 0xfffffc00, v1
	v_sub_u32_e32 v0, v0, v1
	v_lshrrev_b32_e32 v1, 4, v0
	v_bitop3_b32 v1, v1, v0, 32 bitop3:0x6c
	v_ashrrev_i32_e32 v0, 31, v0
	v_lshrrev_b32_e32 v0, 26, v0
	v_add_u32_e32 v0, v1, v0
	v_ashrrev_i32_e32 v12, 6, v0
	v_ashrrev_i32_e32 v0, 31, v10
	v_lshrrev_b32_e32 v0, 26, v0
	v_add_u32_e32 v0, v10, v0
	v_ashrrev_i32_e32 v13, 6, v0
	v_readlane_b32 s2, v252, 31
	v_lshlrev_b32_e32 v0, 3, v13
	v_readlane_b32 s3, v252, 32
	s_ashr_i32 s8, s10, 6
	v_and_b32_e32 v0, -16, v0
	s_mov_b32 s4, s2
	s_ashr_i32 s5, s2, 31
	v_writelane_b32 v252, s2, 31
	s_nop 0
	s_ashr_i32 s0, s10, 8
	s_lshl_b32 s33, s8, 10
	v_add_u32_e32 v0, v12, v0
	v_writelane_b32 v252, s3, 32
	s_lshl_b64 s[2:3], s[4:5], 19
	v_readlane_b32 s18, v253, 40
	v_and_b32_e32 v3, 3, v12
	v_lshrrev_b32_e32 v4, 2, v0
	v_lshlrev_b32_e32 v5, 1, v0
	v_readlane_b32 s19, v253, 41
	s_add_u32 s4, s18, s2
	v_and_or_b32 v3, v0, s1, v3
	v_and_b32_e32 v4, 4, v4
	v_and_b32_e32 v5, 24, v5
	s_addc_u32 s5, s19, s3
	v_readlane_b32 s2, v252, 28
	v_or3_b32 v3, v3, v4, v5
	v_mul_i32_i24_e32 v5, 64, v12
	v_readlane_b32 s3, v252, 29
	v_sub_u32_e32 v1, v1, v5
	s_mov_b32 s6, s2
	s_ashr_i32 s7, s2, 31
	v_writelane_b32 v252, s2, 28
	v_lshlrev_b32_e32 v4, 5, v13
	v_ashrrev_i16_sdwa v1, v2, sext(v1) dst_sel:DWORD dst_unused:UNUSED_PAD src0_sel:DWORD src1_sel:BYTE_0
	v_readlane_b32 s20, v253, 42
	v_writelane_b32 v252, s3, 29
	s_lshl_b64 s[2:3], s[6:7], 19
	v_and_b32_e32 v4, 32, v4
	v_bfe_i32 v14, v1, 0, 16
	v_readlane_b32 s21, v253, 43
	s_add_u32 s6, s20, s2
	v_add_lshl_u32 v1, v4, v14, 1
	s_addc_u32 s7, s21, s3
	s_add_i32 s92, s33, 0
	v_lshl_add_u32 v166, v3, 11, v1
	s_add_i32 m0, s92, 0x10000
	v_lshl_add_u32 v168, v0, 11, v1
	global_load_lds_dwordx4 v166, s[6:7]
	s_add_i32 m0, s92, 0x12000
	s_add_i32 s93, s92, 0x2000
	global_load_lds_dwordx4 v162, s[6:7]
	s_mov_b32 m0, s92
	s_add_u32 s2, s6, 0x40000
	global_load_lds_dwordx4 v168, s[4:5]
	s_mov_b32 m0, s93
	s_addc_u32 s3, s7, 0
	global_load_lds_dwordx4 v164, s[4:5]
	s_add_i32 m0, s92, 0x14000
	v_mov_b32_e32 v171, 0
	global_load_lds_dwordx4 v166, s[2:3]
	s_add_i32 m0, s92, 0x16000
	s_nop 0
	global_load_lds_dwordx4 v162, s[2:3]
	s_add_u32 s2, s4, 0x40000
	s_addc_u32 s3, s5, 0
	s_add_i32 s96, s92, 0x4000
	s_mov_b32 m0, s96
	s_add_i32 s97, s92, 0x6000
	global_load_lds_dwordx4 v168, s[2:3]
	s_mov_b32 m0, s97
	v_mov_b32_e32 v167, v171
	global_load_lds_dwordx4 v164, s[2:3]
	v_mov_b32_e32 v163, v171
	v_mov_b32_e32 v169, v171
	v_mov_b32_e32 v165, v171
	s_mov_b32 s13, 0
	v_lshl_add_u64 v[6:7], s[6:7], 0, v[166:167]
	v_lshl_add_u64 v[4:5], s[6:7], 0, v[162:163]
	v_lshl_add_u64 v[2:3], s[4:5], 0, v[168:169]
	s_cmp_lg_u32 s0, 1
	v_lshl_add_u64 v[0:1], s[4:5], 0, v[164:165]
	s_nop 1
	v_readlane_b32 s16, v253, 38
	s_nop 2
	v_readlane_b32 s24, v253, 46
	s_nop 2
	s_cbranch_scc1 .LBB0_163
	s_barrier
.LBB0_163:
	s_mov_b64 s[14:15], 0x80
	s_and_b32 s9, s8, 3
	s_add_i32 m0, s92, 0x18000
	v_lshl_add_u64 v[6:7], v[6:7], 0, s[14:15]
	s_lshl_b32 s52, s0, 6
	s_lshl_b32 s2, s0, 13
	s_lshl_b32 s3, s9, 12
	s_waitcnt vmcnt(4)
	s_barrier
	global_load_lds_dwordx4 v[6:7], off
	v_lshl_add_u64 v[4:5], v[4:5], 0, s[14:15]
	s_add_i32 m0, s92, 0x1a000
	s_add_i32 s53, s92, 0x8000
	s_add_i32 s23, s92, 0xa000
	global_load_lds_dwordx4 v[4:5], off
	v_lshl_add_u64 v[2:3], v[2:3], 0, s[14:15]
	s_mov_b32 m0, s53
	s_add_u32 s0, s6, 0x40080
	global_load_lds_dwordx4 v[2:3], off
	v_lshl_add_u64 v[0:1], v[0:1], 0, s[14:15]
	s_mov_b32 m0, s23
	s_addc_u32 s1, s7, 0
	global_load_lds_dwordx4 v[0:1], off
	s_add_i32 m0, s92, 0x1c000
	v_lshl_add_u64 v[0:1], s[0:1], 0, v[166:167]
	global_load_lds_dwordx4 v[0:1], off
	v_lshl_add_u64 v[0:1], s[0:1], 0, v[162:163]
	s_add_i32 m0, s92, 0x1e000
	v_writelane_b32 v252, s10, 44
	global_load_lds_dwordx4 v[0:1], off
	s_bfe_u32 s10, s10, 0x10006
	s_cmp_eq_u32 s10, 0
	s_cselect_b64 s[0:1], -1, 0
	v_bfe_u32 v0, v10, 4, 2
	v_writelane_b32 v252, s0, 45
	v_and_b32_e32 v179, 15, v10
	v_lshlrev_b32_e32 v2, 4, v0
	v_lshlrev_b32_e32 v4, 2, v10
	v_writelane_b32 v252, s1, 46
	v_cmp_eq_u32_e64 s[0:1], 0, v0
	v_lshl_or_b32 v3, v179, 6, v2
	v_and_b32_e32 v4, 32, v4
	v_cndmask_b32_e64 v172, 1.0, -1.0, s[0:1]
	s_bfe_u32 s0, s8, 0x10001
	v_lshlrev_b32_e32 v1, 3, v0
	v_bitop3_b32 v5, v3, s2, v4 bitop3:0xde
	v_bitop3_b32 v232, v3, s3, v4 bitop3:0xde
	v_cmp_ne_u32_e32 vcc, 3, v0
	v_cmp_gt_u32_e64 s[2:3], 2, v0
	s_cmp_eq_u32 s9, 0
	v_lshlrev_b32_e32 v170, 5, v0
	v_lshlrev_b32_e32 v0, 14, v13
	v_lshl_or_b32 v174, s9, 5, v1
	s_cselect_b64 s[8:9], -1, 0
	v_and_b32_e32 v0, 0xffff8000, v0
	s_and_b64 s[8:9], vcc, s[8:9]
	v_lshl_add_u32 v0, v12, 11, v0
	v_and_b32_e32 v1, 1, v13
	v_writelane_b32 v252, s8, 47
	v_lshl_or_b32 v0, v1, 6, v0
	v_lshl_add_u32 v182, v14, 1, v0
	v_writelane_b32 v252, s9, 48
	v_lshlrev_b32_e32 v0, 14, v8
	v_readlane_b32 s56, v252, 7
	v_and_b32_e32 v0, 0xffff8000, v0
	v_readlane_b32 s8, v252, 28
	s_waitcnt vmcnt(6)
	v_readlane_b32 s58, v252, 9
	v_readlane_b32 s59, v252, 10
	v_lshl_add_u32 v0, v9, 11, v0
	v_and_b32_e32 v1, 1, v8
	s_nop 0
	v_readlane_b32 s57, v252, 8
	v_lshl_add_u64 v[176:177], s[58:59], 0, v[170:171]
	v_lshl_or_b32 v170, s10, 6, v2
	v_lshl_or_b32 v0, v1, 6, v0
	s_add_i32 s1, 0, 0x10000
	s_add_i32 s18, 0, 0x14000
	s_mov_b32 s28, s8
	v_readlane_b32 s8, v252, 31
	v_lshl_add_u64 v[180:181], s[56:57], 0, v[170:171]
	v_mov_b32_e32 v173, v172
	v_mov_b32_e32 v183, v171
	v_lshl_add_u32 v184, v11, 1, v0
	v_mov_b32_e32 v185, v171
	v_add_u32_e32 v233, s1, v232
	v_add_u32_e32 v234, 0, v5
	v_add_u32_e32 v235, s18, v232
	s_mov_b32 s22, 0x3e38aa3b
	s_movk_i32 s19, 0xfdf
	s_movk_i32 s26, 0xfff
	v_mbcnt_hi_u32_b32 v236, -1, v220
	v_mov_b32_e32 v237, 0xfcf
	s_mov_b32 s12, s8
	s_mov_b32 s25, 0
	s_barrier
	s_nop 7
	s_nop 4
	s_branch .LBB0_167

.LBB0_167:
	v_readlane_b32 s8, v252, 40
	v_readlane_b32 s9, v252, 41
	s_add_i32 s27, s25, 1
	s_and_b64 vcc, exec, s[8:9]
	s_mov_b64 s[10:11], -1
	s_cbranch_vccz .LBB0_170
	v_readlane_b32 s8, v252, 38
	s_mul_i32 s31, s27, s8
	v_readlane_b32 s8, v252, 37
	s_nop 0
	s_add_i32 s31, s31, s8
	s_mov_b64 s[10:11], 0
	s_cmpk_gt_i32 s31, 0x7ff
	s_mov_b64 s[8:9], 0
	s_mov_b32 s29, s24
	s_mov_b32 s30, s16
	s_cbranch_scc1 .LBB0_170
	s_ashr_i32 s8, s31, 31
	s_lshr_b32 s8, s8, 28
	s_add_i32 s8, s31, s8
	s_ashr_i32 s29, s8, 4
	s_and_b32 s8, s8, -16
	s_sub_i32 s30, s31, s8
	s_mov_b64 s[8:9], -1

.LBB0_174:
	s_xor_b64 s[10:11], s[8:9], -1
	s_mov_b32 s24, s29
	v_writelane_b32 v252, s10, 49
	s_ashr_i32 s25, s29, 31
	s_nop 0
	v_writelane_b32 v252, s11, 50
	s_lshl_b64 s[10:11], s[24:25], 19
	v_readlane_b32 s62, v253, 40
	v_readlane_b32 s63, v253, 41
	s_add_u32 s20, s62, s10
	s_addc_u32 s21, s63, s11
	s_and_b64 s[10:11], s[8:9], exec
	s_mov_b32 s16, s30
	s_cselect_b32 s10, s21, s5
	s_cselect_b32 s11, s20, s4
	s_ashr_i32 s17, s30, 31
	v_readlane_b32 s64, v253, 42
	s_lshl_b64 s[30:31], s[16:17], 19
	v_readlane_b32 s65, v253, 43
	s_add_u32 s54, s64, s30
	s_addc_u32 s55, s65, s31
	s_and_b64 s[8:9], s[8:9], exec
	s_cselect_b32 s25, s55, s7
	s_cselect_b32 s29, s54, s6
	s_add_u32 s4, s4, 0x40080
	s_addc_u32 s5, s5, 0
	s_add_u32 s30, s6, 0x100
	v_mov_b32_e32 v0, 0
	s_addc_u32 s31, s7, 0
	s_mov_b32 s34, -2
	v_mov_b32_e32 v1, v0
	v_mov_b32_e32 v2, v0
	v_mov_b32_e32 v3, v0
	v_mov_b32_e32 v4, v0
	v_mov_b32_e32 v5, v0
	v_mov_b32_e32 v6, v0
	v_mov_b32_e32 v7, v0
	v_mov_b32_e32 v32, v0
	v_mov_b32_e32 v33, v0
	v_mov_b32_e32 v34, v0
	v_mov_b32_e32 v35, v0
	v_mov_b32_e32 v36, v0
	v_mov_b32_e32 v37, v0
	v_mov_b32_e32 v38, v0
	v_mov_b32_e32 v39, v0
	v_mov_b32_e32 v64, v0
	v_mov_b32_e32 v65, v0
	v_mov_b32_e32 v66, v0
	v_mov_b32_e32 v67, v0
	v_mov_b32_e32 v68, v0
	v_mov_b32_e32 v69, v0
	v_mov_b32_e32 v70, v0
	v_mov_b32_e32 v71, v0
	v_mov_b32_e32 v80, v0
	s_waitcnt lgkmcnt(0)
	v_mov_b32_e32 v81, v0
	v_mov_b32_e32 v82, v0
	v_mov_b32_e32 v83, v0
	v_mov_b32_e32 v84, v0
	v_mov_b32_e32 v85, v0
	v_mov_b32_e32 v86, v0
	v_mov_b32_e32 v87, v0
	v_mov_b32_e32 v8, v0
	v_mov_b32_e32 v9, v0
	v_mov_b32_e32 v10, v0
	v_mov_b32_e32 v11, v0
	v_mov_b32_e32 v12, v0
	v_mov_b32_e32 v13, v0
	v_mov_b32_e32 v14, v0
	v_mov_b32_e32 v15, v0
	v_mov_b32_e32 v56, v0
	v_mov_b32_e32 v57, v0
	v_mov_b32_e32 v58, v0
	v_mov_b32_e32 v59, v0
	v_mov_b32_e32 v60, v0
	v_mov_b32_e32 v61, v0
	v_mov_b32_e32 v62, v0
	v_mov_b32_e32 v63, v0
	v_mov_b32_e32 v72, v0
	v_mov_b32_e32 v73, v0
	v_mov_b32_e32 v74, v0
	v_mov_b32_e32 v75, v0
	v_mov_b32_e32 v76, v0
	v_mov_b32_e32 v77, v0
	v_mov_b32_e32 v78, v0
	v_mov_b32_e32 v79, v0
	v_mov_b32_e32 v88, v0
	v_mov_b32_e32 v89, v0
	v_mov_b32_e32 v90, v0
	v_mov_b32_e32 v91, v0
	v_mov_b32_e32 v92, v0
	v_mov_b32_e32 v93, v0
	v_mov_b32_e32 v94, v0
	v_mov_b32_e32 v95, v0
	v_mov_b32_e32 v96, v0
	v_mov_b32_e32 v97, v0
	v_mov_b32_e32 v98, v0
	v_mov_b32_e32 v99, v0
	v_mov_b32_e32 v100, v0
	v_mov_b32_e32 v101, v0
	v_mov_b32_e32 v102, v0
	v_mov_b32_e32 v103, v0
	v_mov_b32_e32 v112, v0
	v_mov_b32_e32 v113, v0
	v_mov_b32_e32 v114, v0
	v_mov_b32_e32 v115, v0
	v_mov_b32_e32 v116, v0
	v_mov_b32_e32 v117, v0
	v_mov_b32_e32 v118, v0
	v_mov_b32_e32 v119, v0
	v_mov_b32_e32 v128, v0
	v_mov_b32_e32 v129, v0
	v_mov_b32_e32 v130, v0
	v_mov_b32_e32 v131, v0
	v_mov_b32_e32 v132, v0
	v_mov_b32_e32 v133, v0
	v_mov_b32_e32 v134, v0
	v_mov_b32_e32 v135, v0
	v_mov_b32_e32 v144, v0
	v_mov_b32_e32 v145, v0
	v_mov_b32_e32 v146, v0
	v_mov_b32_e32 v147, v0
	v_mov_b32_e32 v148, v0
	v_mov_b32_e32 v149, v0
	v_mov_b32_e32 v150, v0
	v_mov_b32_e32 v151, v0
	v_mov_b32_e32 v104, v0
	v_mov_b32_e32 v105, v0
	v_mov_b32_e32 v106, v0
	v_mov_b32_e32 v107, v0
	v_mov_b32_e32 v108, v0
	v_mov_b32_e32 v109, v0
	v_mov_b32_e32 v110, v0
	v_mov_b32_e32 v111, v0
	v_mov_b32_e32 v120, v0
	v_mov_b32_e32 v121, v0
	v_mov_b32_e32 v122, v0
	v_mov_b32_e32 v123, v0
	v_mov_b32_e32 v124, v0
	v_mov_b32_e32 v125, v0
	v_mov_b32_e32 v126, v0
	v_mov_b32_e32 v127, v0
	v_mov_b32_e32 v136, v0
	v_mov_b32_e32 v137, v0
	v_mov_b32_e32 v138, v0
	v_mov_b32_e32 v139, v0
	v_mov_b32_e32 v140, v0
	v_mov_b32_e32 v141, v0
	v_mov_b32_e32 v142, v0
	v_mov_b32_e32 v143, v0
	v_mov_b32_e32 v152, v0
	v_mov_b32_e32 v153, v0
	v_mov_b32_e32 v154, v0
	v_mov_b32_e32 v155, v0
	v_mov_b32_e32 v156, v0
	v_mov_b32_e32 v157, v0
	v_mov_b32_e32 v158, v0
	v_mov_b32_e32 v159, v0
	s_nop 2
	v_readlane_b32 s60, v253, 38
	v_readlane_b32 s61, v253, 39
	s_nop 5
	s_waitcnt vmcnt(0)
.LBB0_175:
	ds_read_b128 v[16:19], v233
	ds_read_b128 v[20:23], v233 offset:1024
	ds_read_b128 v[24:27], v233 offset:2048
	ds_read_b128 v[28:31], v233 offset:3072
	s_add_u32 s6, s4, 0xfffc0080
	s_addc_u32 s7, s5, -1
	s_cmp_eq_u32 s34, 12
	s_cselect_b32 s9, s10, s7
	s_cselect_b32 s8, s11, s6
	s_cselect_b32 s7, s25, s31
	s_cselect_b32 s6, s29, s30
	v_lshl_add_u64 v[202:203], s[4:5], 0, v[182:183]
	s_add_i32 m0, s92, 0xc000
	ds_read_b128 v[40:43], v234
	ds_read_b128 v[44:47], v234 offset:1024
	ds_read_b128 v[48:51], v234 offset:2048
	ds_read_b128 v[52:55], v234 offset:3072
	ds_read_b128 v[186:189], v234 offset:4096
	ds_read_b128 v[190:193], v234 offset:5120
	ds_read_b128 v[194:197], v234 offset:6144
	ds_read_b128 v[198:201], v234 offset:7168
	global_load_lds_dwordx4 v[202:203], off
	v_lshl_add_u64 v[202:203], s[4:5], 0, v[184:185]
	s_add_i32 m0, s92, 0xe000
	s_nop 0
	global_load_lds_dwordx4 v[202:203], off
	s_waitcnt lgkmcnt(8)
	s_barrier
	s_waitcnt lgkmcnt(0)
	s_setprio 1
	s_waitcnt lgkmcnt(0)
	v_mfma_f32_16x16x32_bf16 v[156:159], v[16:19], v[40:43], v[156:159]
	v_mfma_f32_16x16x32_bf16 v[152:155], v[24:27], v[40:43], v[152:155]
	v_mfma_f32_16x16x32_bf16 v[140:143], v[16:19], v[48:51], v[140:143]
	v_mfma_f32_16x16x32_bf16 v[136:139], v[24:27], v[48:51], v[136:139]
	v_mfma_f32_16x16x32_bf16 v[124:127], v[16:19], v[186:189], v[124:127]
	v_mfma_f32_16x16x32_bf16 v[120:123], v[24:27], v[186:189], v[120:123]
	v_mfma_f32_16x16x32_bf16 v[108:111], v[16:19], v[194:197], v[108:111]
	v_mfma_f32_16x16x32_bf16 v[104:107], v[24:27], v[194:197], v[104:107]
	v_mfma_f32_16x16x32_bf16 v[156:159], v[20:23], v[44:47], v[156:159]
	v_mfma_f32_16x16x32_bf16 v[152:155], v[28:31], v[44:47], v[152:155]
	v_mfma_f32_16x16x32_bf16 v[140:143], v[20:23], v[52:55], v[140:143]
	v_mfma_f32_16x16x32_bf16 v[136:139], v[28:31], v[52:55], v[136:139]
	v_mfma_f32_16x16x32_bf16 v[124:127], v[20:23], v[190:193], v[124:127]
	v_mfma_f32_16x16x32_bf16 v[120:123], v[28:31], v[190:193], v[120:123]
	v_mfma_f32_16x16x32_bf16 v[108:111], v[20:23], v[198:201], v[108:111]
	v_mfma_f32_16x16x32_bf16 v[104:107], v[28:31], v[198:201], v[104:107]
	s_setprio 0
	s_barrier
	s_add_i32 s35, s1, s33
	v_lshl_add_u64 v[218:219], s[6:7], 0, v[166:167]
	s_mov_b32 m0, s35
	ds_read_b128 v[202:205], v235
	ds_read_b128 v[206:209], v235 offset:1024
	ds_read_b128 v[210:213], v235 offset:2048
	ds_read_b128 v[214:217], v235 offset:3072
	global_load_lds_dwordx4 v[218:219], off
	v_lshl_add_u64 v[246:247], s[6:7], 0, v[162:163]
	s_add_i32 m0, s35, 0x2000
	s_nop 0
	global_load_lds_dwordx4 v[246:247], off
	s_barrier
	s_waitcnt lgkmcnt(0)
	s_setprio 1
	s_waitcnt lgkmcnt(0)
	v_mfma_f32_16x16x32_bf16 v[148:151], v[202:205], v[40:43], v[148:151]
	v_mfma_f32_16x16x32_bf16 v[40:43], v[210:213], v[40:43], v[144:147]
	v_mfma_f32_16x16x32_bf16 v[148:151], v[206:209], v[44:47], v[148:151]
	v_mfma_f32_16x16x32_bf16 v[40:43], v[214:217], v[44:47], v[40:43]
	v_mfma_f32_16x16x32_bf16 v[44:47], v[202:205], v[48:51], v[132:135]
	v_mfma_f32_16x16x32_bf16 v[48:51], v[210:213], v[48:51], v[128:131]
	v_mfma_f32_16x16x32_bf16 v[112:115], v[210:213], v[186:189], v[112:115]
	v_mfma_f32_16x16x32_bf16 v[100:103], v[202:205], v[194:197], v[100:103]
	v_mfma_f32_16x16x32_bf16 v[96:99], v[210:213], v[194:197], v[96:99]
	v_mfma_f32_16x16x32_bf16 v[44:47], v[206:209], v[52:55], v[44:47]
	v_mfma_f32_16x16x32_bf16 v[48:51], v[214:217], v[52:55], v[48:51]
	v_mfma_f32_16x16x32_bf16 v[52:55], v[202:205], v[186:189], v[116:119]
	v_mfma_f32_16x16x32_bf16 v[112:115], v[214:217], v[190:193], v[112:115]
	v_mfma_f32_16x16x32_bf16 v[100:103], v[206:209], v[198:201], v[100:103]
	v_mfma_f32_16x16x32_bf16 v[96:99], v[214:217], v[198:201], v[96:99]
	v_mfma_f32_16x16x32_bf16 v[52:55], v[206:209], v[190:193], v[52:55]
	s_setprio 0
	s_mov_b32 m0, s92
	v_lshl_add_u64 v[248:249], s[8:9], 0, v[168:169]
	s_barrier
	ds_read_b128 v[116:119], v234 offset:16384
	ds_read_b128 v[128:131], v234 offset:17408
	ds_read_b128 v[132:135], v234 offset:18432
	ds_read_b128 v[144:147], v234 offset:19456
	ds_read_b128 v[186:189], v234 offset:20480
	ds_read_b128 v[190:193], v234 offset:21504
	ds_read_b128 v[194:197], v234 offset:22528
	ds_read_b128 v[198:201], v234 offset:23552
	global_load_lds_dwordx4 v[248:249], off
	v_lshl_add_u64 v[250:251], s[8:9], 0, v[164:165]
	s_mov_b32 m0, s93
	s_nop 0
	global_load_lds_dwordx4 v[250:251], off
	s_barrier
	s_waitcnt lgkmcnt(0)
	s_setprio 1
	s_waitcnt lgkmcnt(0)
	v_mfma_f32_16x16x32_bf16 v[92:95], v[16:19], v[116:119], v[92:95]
	v_mfma_f32_16x16x32_bf16 v[88:91], v[24:27], v[116:119], v[88:91]
	v_mfma_f32_16x16x32_bf16 v[76:79], v[16:19], v[132:135], v[76:79]
	v_mfma_f32_16x16x32_bf16 v[72:75], v[24:27], v[132:135], v[72:75]
	v_mfma_f32_16x16x32_bf16 v[60:63], v[16:19], v[186:189], v[60:63]
	v_mfma_f32_16x16x32_bf16 v[56:59], v[24:27], v[186:189], v[56:59]
	v_mfma_f32_16x16x32_bf16 v[12:15], v[16:19], v[194:197], v[12:15]
	v_mfma_f32_16x16x32_bf16 v[8:11], v[24:27], v[194:197], v[8:11]
	v_mfma_f32_16x16x32_bf16 v[92:95], v[20:23], v[128:131], v[92:95]
	v_mfma_f32_16x16x32_bf16 v[88:91], v[28:31], v[128:131], v[88:91]
	v_mfma_f32_16x16x32_bf16 v[76:79], v[20:23], v[144:147], v[76:79]
	v_mfma_f32_16x16x32_bf16 v[72:75], v[28:31], v[144:147], v[72:75]
	v_mfma_f32_16x16x32_bf16 v[60:63], v[20:23], v[190:193], v[60:63]
	v_mfma_f32_16x16x32_bf16 v[56:59], v[28:31], v[190:193], v[56:59]
	v_mfma_f32_16x16x32_bf16 v[12:15], v[20:23], v[198:201], v[12:15]
	v_mfma_f32_16x16x32_bf16 v[8:11], v[28:31], v[198:201], v[8:11]
	s_setprio 0
	s_barrier
	s_add_u32 s56, s6, 0x40000
	s_addc_u32 s57, s7, 0
	s_add_i32 s35, s18, s33
	v_lshl_add_u64 v[16:17], s[56:57], 0, v[166:167]
	s_mov_b32 m0, s35
	s_nop 0
	global_load_lds_dwordx4 v[16:17], off
	v_lshl_add_u64 v[16:17], s[56:57], 0, v[162:163]
	s_add_i32 m0, s35, 0x2000
	s_nop 0
	global_load_lds_dwordx4 v[16:17], off
	s_waitcnt vmcnt(6)
	s_barrier
	s_setprio 1
	v_mfma_f32_16x16x32_bf16 v[36:39], v[202:205], v[186:189], v[36:39]
	v_mfma_f32_16x16x32_bf16 v[32:35], v[210:213], v[186:189], v[32:35]
	v_mfma_f32_16x16x32_bf16 v[4:7], v[202:205], v[194:197], v[4:7]
	v_mfma_f32_16x16x32_bf16 v[0:3], v[210:213], v[194:197], v[0:3]
	v_mfma_f32_16x16x32_bf16 v[16:19], v[202:205], v[116:119], v[84:87]
	v_mfma_f32_16x16x32_bf16 v[20:23], v[210:213], v[116:119], v[80:83]
	v_mfma_f32_16x16x32_bf16 v[24:27], v[202:205], v[132:135], v[68:71]
	v_mfma_f32_16x16x32_bf16 v[28:31], v[210:213], v[132:135], v[64:67]
	v_mfma_f32_16x16x32_bf16 v[36:39], v[206:209], v[190:193], v[36:39]
	v_mfma_f32_16x16x32_bf16 v[32:35], v[214:217], v[190:193], v[32:35]
	v_mfma_f32_16x16x32_bf16 v[4:7], v[206:209], v[198:201], v[4:7]
	v_mfma_f32_16x16x32_bf16 v[0:3], v[214:217], v[198:201], v[0:3]
	v_mfma_f32_16x16x32_bf16 v[16:19], v[206:209], v[128:131], v[16:19]
	v_mfma_f32_16x16x32_bf16 v[20:23], v[214:217], v[128:131], v[20:23]
	v_mfma_f32_16x16x32_bf16 v[24:27], v[206:209], v[144:147], v[24:27]
	v_mfma_f32_16x16x32_bf16 v[28:31], v[214:217], v[144:147], v[28:31]
	s_setprio 0
	s_add_i32 s35, 0, 0x18000
	v_add_u32_e32 v84, s35, v232
	s_barrier
	ds_read_b128 v[64:67], v84
	ds_read_b128 v[68:71], v84 offset:1024
	ds_read_b128 v[80:83], v84 offset:2048
	ds_read_b128 v[84:87], v84 offset:3072
	s_add_u32 s8, s8, 0x40000
	s_addc_u32 s9, s9, 0
	s_mov_b32 m0, s96
	v_lshl_add_u64 v[132:133], s[8:9], 0, v[168:169]
	ds_read_b128 v[116:119], v234 offset:32768
	ds_read_b128 v[128:131], v234 offset:33792
	ds_read_b128 v[186:189], v234 offset:34816
	ds_read_b128 v[190:193], v234 offset:35840
	ds_read_b128 v[194:197], v234 offset:36864
	ds_read_b128 v[198:201], v234 offset:37888
	ds_read_b128 v[202:205], v234 offset:38912
	ds_read_b128 v[206:209], v234 offset:39936
	global_load_lds_dwordx4 v[132:133], off
	v_lshl_add_u64 v[132:133], s[8:9], 0, v[164:165]
	s_mov_b32 m0, s97
	s_nop 0
	global_load_lds_dwordx4 v[132:133], off
	s_waitcnt lgkmcnt(8)
	s_barrier
	s_waitcnt lgkmcnt(0)
	s_setprio 1
	s_waitcnt lgkmcnt(0)
	v_mfma_f32_16x16x32_bf16 v[132:135], v[64:67], v[116:119], v[156:159]
	v_mfma_f32_16x16x32_bf16 v[156:159], v[68:71], v[128:131], v[132:135]
	v_mfma_f32_16x16x32_bf16 v[132:135], v[80:83], v[116:119], v[152:155]
	v_mfma_f32_16x16x32_bf16 v[152:155], v[84:87], v[128:131], v[132:135]
	v_mfma_f32_16x16x32_bf16 v[132:135], v[64:67], v[186:189], v[140:143]
	v_mfma_f32_16x16x32_bf16 v[140:143], v[68:71], v[190:193], v[132:135]
	v_mfma_f32_16x16x32_bf16 v[132:135], v[80:83], v[186:189], v[136:139]
	v_mfma_f32_16x16x32_bf16 v[124:127], v[64:67], v[194:197], v[124:127]
	v_mfma_f32_16x16x32_bf16 v[120:123], v[80:83], v[194:197], v[120:123]
	v_mfma_f32_16x16x32_bf16 v[108:111], v[64:67], v[202:205], v[108:111]
	v_mfma_f32_16x16x32_bf16 v[104:107], v[80:83], v[202:205], v[104:107]
	v_mfma_f32_16x16x32_bf16 v[136:139], v[84:87], v[190:193], v[132:135]
	v_mfma_f32_16x16x32_bf16 v[124:127], v[68:71], v[198:201], v[124:127]
	v_mfma_f32_16x16x32_bf16 v[120:123], v[84:87], v[198:201], v[120:123]
	v_mfma_f32_16x16x32_bf16 v[108:111], v[68:71], v[206:209], v[108:111]
	v_mfma_f32_16x16x32_bf16 v[104:107], v[84:87], v[206:209], v[104:107]
	s_setprio 0
	s_barrier
	s_add_i32 s8, 0, 0x1c000
	v_add_u32_e32 v132, s8, v232
	s_add_i32 s9, s35, s33
	ds_read_b128 v[210:213], v132
	ds_read_b128 v[214:217], v132 offset:1024
	ds_read_b128 v[238:241], v132 offset:2048
	ds_read_b128 v[242:245], v132 offset:3072
	v_lshl_add_u64 v[132:133], v[218:219], 0, s[14:15]
	s_mov_b32 m0, s9
	s_nop 0
	global_load_lds_dwordx4 v[132:133], off
	v_lshl_add_u64 v[132:133], v[246:247], 0, s[14:15]
	s_add_i32 m0, s9, 0x2000
	s_nop 0
	global_load_lds_dwordx4 v[132:133], off
	s_barrier
	s_waitcnt lgkmcnt(0)
	s_setprio 1
	s_waitcnt lgkmcnt(0)
	v_mfma_f32_16x16x32_bf16 v[40:43], v[238:241], v[116:119], v[40:43]
	v_mfma_f32_16x16x32_bf16 v[132:135], v[210:213], v[116:119], v[148:151]
	v_mfma_f32_16x16x32_bf16 v[144:147], v[242:245], v[128:131], v[40:43]
	v_mfma_f32_16x16x32_bf16 v[40:43], v[210:213], v[186:189], v[44:47]
	v_mfma_f32_16x16x32_bf16 v[148:151], v[214:217], v[128:131], v[132:135]
	v_mfma_f32_16x16x32_bf16 v[132:135], v[214:217], v[190:193], v[40:43]
	v_mfma_f32_16x16x32_bf16 v[40:43], v[238:241], v[186:189], v[48:51]
	v_mfma_f32_16x16x32_bf16 v[128:131], v[242:245], v[190:193], v[40:43]
	v_mfma_f32_16x16x32_bf16 v[40:43], v[210:213], v[194:197], v[52:55]
	v_mfma_f32_16x16x32_bf16 v[116:119], v[214:217], v[198:201], v[40:43]
	v_mfma_f32_16x16x32_bf16 v[40:43], v[238:241], v[194:197], v[112:115]
	v_mfma_f32_16x16x32_bf16 v[112:115], v[242:245], v[198:201], v[40:43]
	v_mfma_f32_16x16x32_bf16 v[40:43], v[210:213], v[202:205], v[100:103]
	v_mfma_f32_16x16x32_bf16 v[100:103], v[214:217], v[206:209], v[40:43]
	v_mfma_f32_16x16x32_bf16 v[40:43], v[238:241], v[202:205], v[96:99]
	v_mfma_f32_16x16x32_bf16 v[96:99], v[242:245], v[206:209], v[40:43]
	s_setprio 0
	s_mov_b32 m0, s53
	v_lshl_add_u64 v[202:203], v[248:249], 0, s[14:15]
	s_barrier
	s_nop 2
	ds_read_b128 v[40:43], v234 offset:49152
	ds_read_b128 v[44:47], v234 offset:50176
	ds_read_b128 v[48:51], v234 offset:51200
	ds_read_b128 v[52:55], v234 offset:52224
	ds_read_b128 v[186:189], v234 offset:53248
	ds_read_b128 v[190:193], v234 offset:54272
	ds_read_b128 v[194:197], v234 offset:55296
	ds_read_b128 v[198:201], v234 offset:56320
	global_load_lds_dwordx4 v[202:203], off
	v_lshl_add_u64 v[202:203], v[250:251], 0, s[14:15]
	s_mov_b32 m0, s23
	s_nop 0
	global_load_lds_dwordx4 v[202:203], off
	s_barrier
	s_waitcnt lgkmcnt(0)
	s_setprio 1
	s_waitcnt lgkmcnt(0)
	v_mfma_f32_16x16x32_bf16 v[92:95], v[64:67], v[40:43], v[92:95]
	v_mfma_f32_16x16x32_bf16 v[88:91], v[80:83], v[40:43], v[88:91]
	v_mfma_f32_16x16x32_bf16 v[76:79], v[64:67], v[48:51], v[76:79]
	v_mfma_f32_16x16x32_bf16 v[72:75], v[80:83], v[48:51], v[72:75]
	v_mfma_f32_16x16x32_bf16 v[60:63], v[64:67], v[186:189], v[60:63]
	v_mfma_f32_16x16x32_bf16 v[56:59], v[80:83], v[186:189], v[56:59]
	v_mfma_f32_16x16x32_bf16 v[12:15], v[64:67], v[194:197], v[12:15]
	v_mfma_f32_16x16x32_bf16 v[8:11], v[80:83], v[194:197], v[8:11]
	v_mfma_f32_16x16x32_bf16 v[92:95], v[68:71], v[44:47], v[92:95]
	v_mfma_f32_16x16x32_bf16 v[88:91], v[84:87], v[44:47], v[88:91]
	v_mfma_f32_16x16x32_bf16 v[76:79], v[68:71], v[52:55], v[76:79]
	v_mfma_f32_16x16x32_bf16 v[72:75], v[84:87], v[52:55], v[72:75]
	v_mfma_f32_16x16x32_bf16 v[60:63], v[68:71], v[190:193], v[60:63]
	v_mfma_f32_16x16x32_bf16 v[56:59], v[84:87], v[190:193], v[56:59]
	v_mfma_f32_16x16x32_bf16 v[12:15], v[68:71], v[198:201], v[12:15]
	v_mfma_f32_16x16x32_bf16 v[8:11], v[84:87], v[198:201], v[8:11]
	s_setprio 0
	s_barrier
	s_add_u32 s6, s6, 0x40080
	s_addc_u32 s7, s7, 0
	s_add_i32 s8, s8, s33
	v_lshl_add_u64 v[64:65], s[6:7], 0, v[166:167]
	s_mov_b32 m0, s8
	s_nop 0
	global_load_lds_dwordx4 v[64:65], off
	v_lshl_add_u64 v[64:65], s[6:7], 0, v[162:163]
	s_add_i32 m0, s8, 0x2000
	s_nop 0
	global_load_lds_dwordx4 v[64:65], off
	s_waitcnt vmcnt(6)
	s_barrier
	s_setprio 1
	v_mfma_f32_16x16x32_bf16 v[16:19], v[210:213], v[40:43], v[16:19]
	v_mfma_f32_16x16x32_bf16 v[84:87], v[214:217], v[44:47], v[16:19]
	v_mfma_f32_16x16x32_bf16 v[16:19], v[238:241], v[40:43], v[20:23]
	v_mfma_f32_16x16x32_bf16 v[80:83], v[242:245], v[44:47], v[16:19]
	v_mfma_f32_16x16x32_bf16 v[16:19], v[210:213], v[48:51], v[24:27]
	v_mfma_f32_16x16x32_bf16 v[68:71], v[214:217], v[52:55], v[16:19]
	v_mfma_f32_16x16x32_bf16 v[16:19], v[238:241], v[48:51], v[28:31]
	v_mfma_f32_16x16x32_bf16 v[64:67], v[242:245], v[52:55], v[16:19]
	v_mfma_f32_16x16x32_bf16 v[16:19], v[210:213], v[186:189], v[36:39]
	v_mfma_f32_16x16x32_bf16 v[36:39], v[214:217], v[190:193], v[16:19]
	v_mfma_f32_16x16x32_bf16 v[16:19], v[238:241], v[186:189], v[32:35]
	v_mfma_f32_16x16x32_bf16 v[4:7], v[210:213], v[194:197], v[4:7]
	v_mfma_f32_16x16x32_bf16 v[0:3], v[238:241], v[194:197], v[0:3]
	v_mfma_f32_16x16x32_bf16 v[32:35], v[242:245], v[190:193], v[16:19]
	v_mfma_f32_16x16x32_bf16 v[4:7], v[214:217], v[198:201], v[4:7]
	v_mfma_f32_16x16x32_bf16 v[0:3], v[242:245], v[198:201], v[0:3]
	s_setprio 0
	s_add_i32 s34, s34, 2
	s_add_u32 s4, s4, 0x100
	s_addc_u32 s5, s5, 0
	s_add_u32 s30, s30, 0x100
	s_addc_u32 s31, s31, 0
	s_cmp_gt_u32 s34, 13
	s_barrier
	s_cbranch_scc0 .LBB0_175
	s_cmp_gt_i32 s28, 1
	s_cselect_b64 s[6:7], -1, 0
	s_cmp_lt_i32 s28, 2
	s_cselect_b64 s[4:5], -1, 0
	s_add_i32 s8, s28, -3
	s_cmp_lt_u32 s8, 2
	s_cselect_b64 s[8:9], -1, 0
	s_lshl_b32 s29, s12, 8
	s_add_i32 s29, s29, s52
	v_or_b32_e32 v196, s29, v179
	s_nop 0
	v_ashrrev_i32_e32 v197, 31, v196
	v_readlane_b32 s72, v253, 63
	v_readlane_b32 s73, v252, 0
	s_or_b64 s[4:5], s[4:5], s[8:9]
	s_and_b32 s8, s29, 0xfc0
	v_lshl_add_u64 v[16:17], v[196:197], 2, s[72:73]
	global_load_dword v204, v[16:17], off
	global_load_dword v200, v[16:17], off offset:64
	global_load_dword v198, v[16:17], off offset:128
	global_load_dword v194, v[16:17], off offset:192
	global_load_dword v192, v[16:17], off offset:512
	global_load_dword v190, v[16:17], off offset:576
	global_load_dword v188, v[16:17], off offset:640
	global_load_dword v186, v[16:17], off offset:704
	v_or_b32_e32 v16, s8, v179
	v_readlane_b32 s8, v252, 45
	v_readlane_b32 s9, v252, 46
	s_and_b64 s[62:63], s[8:9], s[4:5]
	v_cndmask_b32_e64 v17, 0, 1, s[62:63]
	v_readlane_b32 s68, v253, 59
	v_readlane_b32 s69, v253, 60
	v_readlane_b32 s76, v252, 3
	v_readlane_b32 s77, v252, 4
	v_readlane_b32 s78, v252, 5
	v_readlane_b32 s79, v252, 6
	v_cmp_ne_u32_e64 s[4:5], 1, v17
	s_andn2_b64 vcc, exec, s[62:63]
	v_lshlrev_b32_e32 v187, 6, v16
	s_nop 6
	s_cbranch_vccnz .LBB0_178
	global_load_dwordx4 v[40:43], v187, s[76:77] offset:48
	global_load_dwordx4 v[44:47], v187, s[76:77] offset:32
	global_load_dwordx4 v[48:51], v187, s[76:77] offset:16
	global_load_dwordx4 v[52:55], v187, s[76:77]
	global_load_dwordx4 v[16:19], v187, s[76:77] offset:1072
	global_load_dwordx4 v[20:23], v187, s[76:77] offset:1056
	global_load_dwordx4 v[24:27], v187, s[76:77] offset:1040
	global_load_dwordx4 v[28:31], v187, s[76:77] offset:1024

.LBB0_185:
	s_andn2_b64 vcc, exec, s[8:9]
	s_cbranch_vccnz .LBB0_187
	v_mul_f32_e32 v170, 0xbfb8aa3b, v156
	v_mul_f32_e32 v193, 0xbfb8aa3b, v157
	v_exp_f32_e32 v170, v170
	v_mul_f32_e32 v191, 0xbfb8aa3b, v152
	v_exp_f32_e32 v193, v193
	v_mul_f32_e32 v195, 0xbfb8aa3b, v153
	v_mul_f32_e32 v197, 0xbfb8aa3b, v158
	v_mul_f32_e32 v199, 0xbfb8aa3b, v154
	v_mul_f32_e32 v201, 0xbfb8aa3b, v159
	v_mul_f32_e32 v205, 0xbfb8aa3b, v155
	v_exp_f32_e32 v191, v191
	v_exp_f32_e32 v195, v195
	v_exp_f32_e32 v197, v197
	v_exp_f32_e32 v199, v199
	v_exp_f32_e32 v201, v201
	v_exp_f32_e32 v205, v205
	v_add_f32_e32 v170, 1.0, v170
	v_add_f32_e32 v193, 1.0, v193
	v_add_f32_e32 v191, 1.0, v191
	v_rcp_f32_e32 v170, v170
	v_rcp_f32_e32 v193, v193
	v_add_f32_e32 v195, 1.0, v195
	v_add_f32_e32 v197, 1.0, v197
	v_add_f32_e32 v199, 1.0, v199
	v_add_f32_e32 v201, 1.0, v201
	v_add_f32_e32 v205, 1.0, v205
	v_rcp_f32_e32 v191, v191
	v_rcp_f32_e32 v195, v195
	v_rcp_f32_e32 v197, v197
	v_rcp_f32_e32 v199, v199
	v_rcp_f32_e32 v201, v201
	v_rcp_f32_e32 v205, v205
	s_nop 0
	v_readlane_b32 s42, v252, 13
	v_readlane_b32 s43, v252, 14
	v_cvt_pk_bf16_f32 v208, v170, v193
	v_lshlrev_b32_e32 v170, 1, v174
	v_lshl_add_u64 v[212:213], s[42:43], 0, v[206:207]
	v_lshl_add_u64 v[212:213], s[12:13], 1, v[212:213]
	v_cvt_pk_bf16_f32 v209, v197, v201
	v_cvt_pk_bf16_f32 v210, v191, v195
	v_cvt_pk_bf16_f32 v211, v199, v205
	v_lshl_add_u64 v[212:213], v[212:213], 0, v[170:171]
	s_nop 7
	s_nop 4
	global_store_dwordx4 v[212:213], v[208:211], off offset:-3584 nt

.LBB0_188:
	s_andn2_b64 vcc, exec, s[8:9]
	s_cbranch_vccnz .LBB0_190
	s_nop 0
	v_readlane_b32 s40, v252, 11
	v_readlane_b32 s41, v252, 12
	v_lshlrev_b32_e32 v170, 1, v174
	v_cvt_pk_bf16_f32 v208, v156, v157
	v_lshl_add_u64 v[212:213], s[40:41], 0, v[202:203]
	v_lshl_add_u64 v[212:213], s[12:13], 1, v[212:213]
	v_cvt_pk_bf16_f32 v209, v158, v159
	v_cvt_pk_bf16_f32 v210, v152, v153
	v_cvt_pk_bf16_f32 v211, v154, v155
	v_lshl_add_u64 v[212:213], v[212:213], 0, v[170:171]
	s_nop 7
	s_nop 4
	global_store_dwordx4 v[212:213], v[208:211], off offset:-2560

.LBB0_205:
	s_nop 1
	v_mov_b32_e32 v152, v204
	v_mov_b32_e32 v153, v204
	v_pk_mul_f32 v[150:151], v[150:151], v[152:153]
	v_pk_mul_f32 v[146:147], v[146:147], v[152:153]
	v_cndmask_b32_e64 v152, 0, 1, s[6:7]
	v_mov_b32_e32 v205, v204
	v_cmp_ne_u32_e64 s[8:9], 1, v152
	v_cndmask_b32_e64 v152, 0, 1, s[10:11]
	v_pk_mul_f32 v[148:149], v[148:149], v[204:205]
	v_pk_mul_f32 v[144:145], v[144:145], v[204:205]
	s_mov_b64 s[94:95], -1
	s_andn2_b64 vcc, exec, s[6:7]
	v_cmp_ne_u32_e64 s[6:7], 1, v152
	s_cbranch_vccnz .LBB0_217
	s_and_b64 vcc, exec, s[6:7]
	s_mov_b64 s[10:11], -1
	s_cbranch_vccnz .LBB0_214
	s_andn2_b64 vcc, exec, s[58:59]
	s_cbranch_vccnz .LBB0_211
	s_andn2_b64 vcc, exec, s[56:57]
	s_cbranch_vccnz .LBB0_210
	v_mul_f32_e32 v153, 0xbfb8aa3b, v144
	v_exp_f32_e32 v153, v153
	v_mul_f32_e32 v154, 0xbfb8aa3b, v149
	v_mul_f32_e32 v155, 0xbfb8aa3b, v145
	v_exp_f32_e32 v154, v154
	v_exp_f32_e32 v155, v155
	v_add_f32_e32 v153, 1.0, v153
	v_mul_f32_e32 v152, 0xbfb8aa3b, v148
	v_rcp_f32_e32 v156, v153
	v_add_f32_e32 v153, 1.0, v154
	v_add_f32_e32 v154, 1.0, v155
	v_mul_f32_e32 v155, 0xbfb8aa3b, v150
	v_mul_f32_e32 v157, 0xbfb8aa3b, v146
	v_mul_f32_e32 v158, 0xbfb8aa3b, v151
	v_mul_f32_e32 v159, 0xbfb8aa3b, v147
	v_exp_f32_e32 v152, v152
	v_exp_f32_e32 v155, v155
	v_exp_f32_e32 v157, v157
	v_exp_f32_e32 v158, v158
	v_exp_f32_e32 v159, v159
	v_add_f32_e32 v152, 1.0, v152
	v_add_f32_e32 v155, 1.0, v155
	v_add_f32_e32 v157, 1.0, v157
	v_add_f32_e32 v158, 1.0, v158
	v_add_f32_e32 v159, 1.0, v159
	v_rcp_f32_e32 v152, v152
	v_rcp_f32_e32 v153, v153
	v_rcp_f32_e32 v154, v154
	v_rcp_f32_e32 v155, v155
	v_rcp_f32_e32 v157, v157
	v_rcp_f32_e32 v158, v158
	v_rcp_f32_e32 v159, v159
	s_nop 0
	v_readlane_b32 s42, v252, 13
	v_readlane_b32 s43, v252, 14
	v_cvt_pk_bf16_f32 v152, v152, v153
	v_cvt_pk_bf16_f32 v153, v155, v158
	v_cvt_pk_bf16_f32 v154, v156, v154
	v_cvt_pk_bf16_f32 v155, v157, v159
	v_lshl_add_u64 v[156:157], s[42:43], 0, v[206:207]
	v_lshl_add_u64 v[156:157], s[12:13], 1, v[156:157]
	s_waitcnt lgkmcnt(0)
	v_lshlrev_b32_e32 v170, 1, v174
	v_lshl_add_u64 v[156:157], v[156:157], 0, v[170:171]
	s_nop 7
	s_nop 4
	global_store_dwordx4 v[156:157], v[152:155], off offset:-3328 nt

.LBB0_211:
	s_andn2_b64 vcc, exec, s[10:11]
	s_cbranch_vccnz .LBB0_213
	s_nop 0
	v_readlane_b32 s40, v252, 11
	v_readlane_b32 s41, v252, 12
	s_waitcnt lgkmcnt(0)
	v_lshlrev_b32_e32 v170, 1, v174
	v_cvt_pk_bf16_f32 v152, v148, v149
	v_lshl_add_u64 v[156:157], s[40:41], 0, v[202:203]
	v_lshl_add_u64 v[156:157], s[12:13], 1, v[156:157]
	v_cvt_pk_bf16_f32 v153, v150, v151
	v_cvt_pk_bf16_f32 v154, v144, v145
	v_cvt_pk_bf16_f32 v155, v146, v147
	v_lshl_add_u64 v[156:157], v[156:157], 0, v[170:171]
	s_nop 7
	s_nop 4
	global_store_dwordx4 v[156:157], v[152:155], off offset:-2304

.LBB0_230:
	s_andn2_b64 vcc, exec, s[10:11]
	s_cbranch_vccnz .LBB0_232
	v_mul_f32_e32 v149, 0xbfb8aa3b, v136
	v_exp_f32_e32 v149, v149
	v_mul_f32_e32 v150, 0xbfb8aa3b, v141
	v_mul_f32_e32 v151, 0xbfb8aa3b, v137
	v_exp_f32_e32 v150, v150
	v_exp_f32_e32 v151, v151
	v_add_f32_e32 v149, 1.0, v149
	v_mul_f32_e32 v148, 0xbfb8aa3b, v140
	v_rcp_f32_e32 v152, v149
	v_add_f32_e32 v149, 1.0, v150
	v_add_f32_e32 v150, 1.0, v151
	v_mul_f32_e32 v151, 0xbfb8aa3b, v142
	v_mul_f32_e32 v153, 0xbfb8aa3b, v138
	v_mul_f32_e32 v154, 0xbfb8aa3b, v143
	v_mul_f32_e32 v155, 0xbfb8aa3b, v139
	v_exp_f32_e32 v148, v148
	v_exp_f32_e32 v151, v151
	v_exp_f32_e32 v153, v153
	v_exp_f32_e32 v154, v154
	v_exp_f32_e32 v155, v155
	v_add_f32_e32 v148, 1.0, v148
	v_add_f32_e32 v151, 1.0, v151
	v_add_f32_e32 v153, 1.0, v153
	v_add_f32_e32 v154, 1.0, v154
	v_add_f32_e32 v155, 1.0, v155
	v_rcp_f32_e32 v148, v148
	v_rcp_f32_e32 v149, v149
	v_rcp_f32_e32 v150, v150
	v_rcp_f32_e32 v151, v151
	v_rcp_f32_e32 v153, v153
	v_rcp_f32_e32 v154, v154
	v_rcp_f32_e32 v155, v155
	s_nop 0
	v_readlane_b32 s42, v252, 13
	v_readlane_b32 s43, v252, 14
	v_cvt_pk_bf16_f32 v148, v148, v149
	v_cvt_pk_bf16_f32 v149, v151, v154
	v_cvt_pk_bf16_f32 v150, v152, v150
	v_cvt_pk_bf16_f32 v151, v153, v155
	v_lshl_add_u64 v[152:153], s[42:43], 0, v[146:147]
	v_lshl_add_u64 v[152:153], s[12:13], 1, v[152:153]
	s_waitcnt lgkmcnt(0)
	v_lshlrev_b32_e32 v170, 1, v174
	v_lshl_add_u64 v[152:153], v[152:153], 0, v[170:171]
	s_nop 7
	s_nop 4
	global_store_dwordx4 v[152:153], v[148:151], off offset:-3584 nt

.LBB0_233:
	s_andn2_b64 vcc, exec, s[10:11]
	s_cbranch_vccnz .LBB0_235
	s_nop 0
	v_readlane_b32 s40, v252, 11
	v_readlane_b32 s41, v252, 12
	s_waitcnt lgkmcnt(0)
	v_lshlrev_b32_e32 v170, 1, v174
	v_cvt_pk_bf16_f32 v148, v140, v141
	v_lshl_add_u64 v[152:153], s[40:41], 0, v[144:145]
	v_lshl_add_u64 v[152:153], s[12:13], 1, v[152:153]
	v_cvt_pk_bf16_f32 v149, v142, v143
	v_cvt_pk_bf16_f32 v150, v136, v137
	v_cvt_pk_bf16_f32 v151, v138, v139
	v_lshl_add_u64 v[152:153], v[152:153], 0, v[170:171]
	s_nop 7
	s_nop 4
	global_store_dwordx4 v[152:153], v[148:151], off offset:-2560

.LBB0_250:
	v_mov_b32_e32 v201, v200
	s_nop 0
	v_mov_b32_e32 v136, v200
	v_mov_b32_e32 v137, v200
	v_pk_mul_f32 v[134:135], v[134:135], v[136:137]
	v_pk_mul_f32 v[132:133], v[132:133], v[200:201]
	v_pk_mul_f32 v[130:131], v[130:131], v[136:137]
	v_pk_mul_f32 v[128:129], v[128:129], v[200:201]
	s_and_b64 vcc, exec, s[8:9]
	s_mov_b64 s[10:11], -1
	s_cbranch_vccnz .LBB0_282
	s_and_b64 vcc, exec, s[6:7]
	s_cbranch_vccnz .LBB0_259
	s_andn2_b64 vcc, exec, s[58:59]
	s_cbranch_vccnz .LBB0_256
	s_andn2_b64 vcc, exec, s[56:57]
	s_cbranch_vccnz .LBB0_255
	v_mul_f32_e32 v137, 0xbfb8aa3b, v128
	v_exp_f32_e32 v137, v137
	v_mul_f32_e32 v138, 0xbfb8aa3b, v133
	v_mul_f32_e32 v139, 0xbfb8aa3b, v129
	v_exp_f32_e32 v138, v138
	v_exp_f32_e32 v139, v139
	v_add_f32_e32 v137, 1.0, v137
	v_mul_f32_e32 v136, 0xbfb8aa3b, v132
	v_rcp_f32_e32 v140, v137
	v_add_f32_e32 v137, 1.0, v138
	v_add_f32_e32 v138, 1.0, v139
	v_mul_f32_e32 v139, 0xbfb8aa3b, v134
	v_mul_f32_e32 v141, 0xbfb8aa3b, v130
	v_mul_f32_e32 v142, 0xbfb8aa3b, v135
	v_mul_f32_e32 v143, 0xbfb8aa3b, v131
	v_exp_f32_e32 v136, v136
	v_exp_f32_e32 v139, v139
	v_exp_f32_e32 v141, v141
	v_exp_f32_e32 v142, v142
	v_exp_f32_e32 v143, v143
	v_add_f32_e32 v136, 1.0, v136
	v_add_f32_e32 v139, 1.0, v139
	v_add_f32_e32 v141, 1.0, v141
	v_add_f32_e32 v142, 1.0, v142
	v_add_f32_e32 v143, 1.0, v143
	v_rcp_f32_e32 v136, v136
	v_rcp_f32_e32 v137, v137
	v_rcp_f32_e32 v138, v138
	v_rcp_f32_e32 v139, v139
	v_rcp_f32_e32 v141, v141
	v_rcp_f32_e32 v142, v142
	v_rcp_f32_e32 v143, v143
	s_nop 0
	v_readlane_b32 s42, v252, 13
	v_readlane_b32 s43, v252, 14
	v_cvt_pk_bf16_f32 v136, v136, v137
	v_cvt_pk_bf16_f32 v137, v139, v142
	v_cvt_pk_bf16_f32 v138, v140, v138
	v_cvt_pk_bf16_f32 v139, v141, v143
	v_lshl_add_u64 v[140:141], s[42:43], 0, v[146:147]
	v_lshl_add_u64 v[140:141], s[12:13], 1, v[140:141]
	s_waitcnt lgkmcnt(0)
	v_lshlrev_b32_e32 v170, 1, v174
	v_lshl_add_u64 v[140:141], v[140:141], 0, v[170:171]
	s_nop 7
	s_nop 4
	global_store_dwordx4 v[140:141], v[136:139], off offset:-3328 nt

.LBB0_256:
	s_andn2_b64 vcc, exec, s[10:11]
	s_cbranch_vccnz .LBB0_258
	s_nop 0
	v_readlane_b32 s40, v252, 11
	v_readlane_b32 s41, v252, 12
	s_waitcnt lgkmcnt(0)
	v_lshlrev_b32_e32 v170, 1, v174
	v_cvt_pk_bf16_f32 v136, v132, v133
	v_lshl_add_u64 v[140:141], s[40:41], 0, v[144:145]
	v_lshl_add_u64 v[140:141], s[12:13], 1, v[140:141]
	v_cvt_pk_bf16_f32 v137, v134, v135
	v_cvt_pk_bf16_f32 v138, v128, v129
	v_cvt_pk_bf16_f32 v139, v130, v131
	v_lshl_add_u64 v[140:141], v[140:141], 0, v[170:171]
	s_nop 7
	s_nop 4
	global_store_dwordx4 v[140:141], v[136:139], off offset:-2304

.LBB0_271:
	s_andn2_b64 vcc, exec, s[10:11]
	s_cbranch_vccnz .LBB0_273
	v_mul_f32_e32 v133, 0xbfb8aa3b, v120
	v_exp_f32_e32 v133, v133
	v_mul_f32_e32 v134, 0xbfb8aa3b, v125
	v_mul_f32_e32 v135, 0xbfb8aa3b, v121
	v_exp_f32_e32 v134, v134
	v_exp_f32_e32 v135, v135
	v_add_f32_e32 v133, 1.0, v133
	v_mul_f32_e32 v132, 0xbfb8aa3b, v124
	v_rcp_f32_e32 v136, v133
	v_add_f32_e32 v133, 1.0, v134
	v_add_f32_e32 v134, 1.0, v135
	v_mul_f32_e32 v135, 0xbfb8aa3b, v126
	v_mul_f32_e32 v137, 0xbfb8aa3b, v122
	v_mul_f32_e32 v138, 0xbfb8aa3b, v127
	v_mul_f32_e32 v139, 0xbfb8aa3b, v123
	v_exp_f32_e32 v132, v132
	v_exp_f32_e32 v135, v135
	v_exp_f32_e32 v137, v137
	v_exp_f32_e32 v138, v138
	v_exp_f32_e32 v139, v139
	v_add_f32_e32 v132, 1.0, v132
	v_add_f32_e32 v135, 1.0, v135
	v_add_f32_e32 v137, 1.0, v137
	v_add_f32_e32 v138, 1.0, v138
	v_add_f32_e32 v139, 1.0, v139
	v_rcp_f32_e32 v132, v132
	v_rcp_f32_e32 v133, v133
	v_rcp_f32_e32 v134, v134
	v_rcp_f32_e32 v135, v135
	v_rcp_f32_e32 v137, v137
	v_rcp_f32_e32 v138, v138
	v_rcp_f32_e32 v139, v139
	s_nop 0
	v_readlane_b32 s42, v252, 13
	v_readlane_b32 s43, v252, 14
	v_cvt_pk_bf16_f32 v132, v132, v133
	v_cvt_pk_bf16_f32 v133, v135, v138
	v_cvt_pk_bf16_f32 v134, v136, v134
	v_cvt_pk_bf16_f32 v135, v137, v139
	v_lshl_add_u64 v[136:137], s[42:43], 0, v[130:131]
	v_lshl_add_u64 v[136:137], s[12:13], 1, v[136:137]
	s_waitcnt lgkmcnt(0)
	v_lshlrev_b32_e32 v170, 1, v174
	v_lshl_add_u64 v[136:137], v[136:137], 0, v[170:171]
	s_nop 7
	s_nop 4
	global_store_dwordx4 v[136:137], v[132:135], off offset:-3584 nt

.LBB0_274:
	s_andn2_b64 vcc, exec, s[10:11]
	s_cbranch_vccnz .LBB0_276
	s_nop 0
	v_readlane_b32 s40, v252, 11
	v_readlane_b32 s41, v252, 12
	s_waitcnt lgkmcnt(0)
	v_lshlrev_b32_e32 v170, 1, v174
	v_cvt_pk_bf16_f32 v132, v124, v125
	v_lshl_add_u64 v[136:137], s[40:41], 0, v[128:129]
	v_lshl_add_u64 v[136:137], s[12:13], 1, v[136:137]
	v_cvt_pk_bf16_f32 v133, v126, v127
	v_cvt_pk_bf16_f32 v134, v120, v121
	v_cvt_pk_bf16_f32 v135, v122, v123
	v_lshl_add_u64 v[136:137], v[136:137], 0, v[170:171]
	s_nop 7
	s_nop 4
	global_store_dwordx4 v[136:137], v[132:135], off offset:-2560

.LBB0_297:
	v_mov_b32_e32 v199, v198
	s_nop 0
	v_mov_b32_e32 v120, v198
	v_mov_b32_e32 v121, v198
	v_pk_mul_f32 v[118:119], v[118:119], v[120:121]
	v_pk_mul_f32 v[116:117], v[116:117], v[198:199]
	v_pk_mul_f32 v[114:115], v[114:115], v[120:121]
	v_pk_mul_f32 v[112:113], v[112:113], v[198:199]
	s_and_b64 vcc, exec, s[8:9]
	s_mov_b64 s[10:11], -1
	s_cbranch_vccnz .LBB0_309
	s_and_b64 vcc, exec, s[6:7]
	s_cbranch_vccnz .LBB0_306
	s_andn2_b64 vcc, exec, s[58:59]
	s_cbranch_vccnz .LBB0_303
	s_andn2_b64 vcc, exec, s[56:57]
	s_cbranch_vccnz .LBB0_302
	v_mul_f32_e32 v121, 0xbfb8aa3b, v112
	v_exp_f32_e32 v121, v121
	v_mul_f32_e32 v122, 0xbfb8aa3b, v117
	v_mul_f32_e32 v123, 0xbfb8aa3b, v113
	v_exp_f32_e32 v122, v122
	v_exp_f32_e32 v123, v123
	v_add_f32_e32 v121, 1.0, v121
	v_mul_f32_e32 v120, 0xbfb8aa3b, v116
	v_rcp_f32_e32 v124, v121
	v_add_f32_e32 v121, 1.0, v122
	v_add_f32_e32 v122, 1.0, v123
	v_mul_f32_e32 v123, 0xbfb8aa3b, v118
	v_mul_f32_e32 v125, 0xbfb8aa3b, v114
	v_mul_f32_e32 v126, 0xbfb8aa3b, v119
	v_mul_f32_e32 v127, 0xbfb8aa3b, v115
	v_exp_f32_e32 v120, v120
	v_exp_f32_e32 v123, v123
	v_exp_f32_e32 v125, v125
	v_exp_f32_e32 v126, v126
	v_exp_f32_e32 v127, v127
	v_add_f32_e32 v120, 1.0, v120
	v_add_f32_e32 v123, 1.0, v123
	v_add_f32_e32 v125, 1.0, v125
	v_add_f32_e32 v126, 1.0, v126
	v_add_f32_e32 v127, 1.0, v127
	v_rcp_f32_e32 v120, v120
	v_rcp_f32_e32 v121, v121
	v_rcp_f32_e32 v122, v122
	v_rcp_f32_e32 v123, v123
	v_rcp_f32_e32 v125, v125
	v_rcp_f32_e32 v126, v126
	v_rcp_f32_e32 v127, v127
	s_nop 0
	v_readlane_b32 s42, v252, 13
	v_readlane_b32 s43, v252, 14
	v_cvt_pk_bf16_f32 v120, v120, v121
	v_cvt_pk_bf16_f32 v121, v123, v126
	v_cvt_pk_bf16_f32 v122, v124, v122
	v_cvt_pk_bf16_f32 v123, v125, v127
	v_lshl_add_u64 v[124:125], s[42:43], 0, v[130:131]
	v_lshl_add_u64 v[124:125], s[12:13], 1, v[124:125]
	s_waitcnt lgkmcnt(0)
	v_lshlrev_b32_e32 v170, 1, v174
	v_lshl_add_u64 v[124:125], v[124:125], 0, v[170:171]
	s_nop 7
	s_nop 4
	global_store_dwordx4 v[124:125], v[120:123], off offset:-3328 nt

.LBB0_303:
	s_andn2_b64 vcc, exec, s[10:11]
	s_cbranch_vccnz .LBB0_305
	s_nop 0
	v_readlane_b32 s40, v252, 11
	v_readlane_b32 s41, v252, 12
	s_waitcnt lgkmcnt(0)
	v_lshlrev_b32_e32 v170, 1, v174
	v_cvt_pk_bf16_f32 v120, v116, v117
	v_lshl_add_u64 v[124:125], s[40:41], 0, v[128:129]
	v_lshl_add_u64 v[124:125], s[12:13], 1, v[124:125]
	v_cvt_pk_bf16_f32 v121, v118, v119
	v_cvt_pk_bf16_f32 v122, v112, v113
	v_cvt_pk_bf16_f32 v123, v114, v115
	v_lshl_add_u64 v[124:125], v[124:125], 0, v[170:171]
	s_nop 7
	s_nop 4
	global_store_dwordx4 v[124:125], v[120:123], off offset:-2304

.LBB0_322:
	s_andn2_b64 vcc, exec, s[10:11]
	s_cbranch_vccnz .LBB0_324
	v_mul_f32_e32 v117, 0xbfb8aa3b, v104
	v_exp_f32_e32 v117, v117
	v_mul_f32_e32 v118, 0xbfb8aa3b, v109
	v_mul_f32_e32 v119, 0xbfb8aa3b, v105
	v_exp_f32_e32 v118, v118
	v_exp_f32_e32 v119, v119
	v_add_f32_e32 v117, 1.0, v117
	v_mul_f32_e32 v116, 0xbfb8aa3b, v108
	v_rcp_f32_e32 v120, v117
	v_add_f32_e32 v117, 1.0, v118
	v_add_f32_e32 v118, 1.0, v119
	v_mul_f32_e32 v119, 0xbfb8aa3b, v110
	v_mul_f32_e32 v121, 0xbfb8aa3b, v106
	v_mul_f32_e32 v122, 0xbfb8aa3b, v111
	v_mul_f32_e32 v123, 0xbfb8aa3b, v107
	v_exp_f32_e32 v116, v116
	v_exp_f32_e32 v119, v119
	v_exp_f32_e32 v121, v121
	v_exp_f32_e32 v122, v122
	v_exp_f32_e32 v123, v123
	v_add_f32_e32 v116, 1.0, v116
	v_add_f32_e32 v119, 1.0, v119
	v_add_f32_e32 v121, 1.0, v121
	v_add_f32_e32 v122, 1.0, v122
	v_add_f32_e32 v123, 1.0, v123
	v_rcp_f32_e32 v116, v116
	v_rcp_f32_e32 v117, v117
	v_rcp_f32_e32 v118, v118
	v_rcp_f32_e32 v119, v119
	v_rcp_f32_e32 v121, v121
	v_rcp_f32_e32 v122, v122
	v_rcp_f32_e32 v123, v123
	s_nop 0
	v_readlane_b32 s42, v252, 13
	v_readlane_b32 s43, v252, 14
	v_cvt_pk_bf16_f32 v116, v116, v117
	v_cvt_pk_bf16_f32 v117, v119, v122
	v_cvt_pk_bf16_f32 v118, v120, v118
	v_cvt_pk_bf16_f32 v119, v121, v123
	v_lshl_add_u64 v[120:121], s[42:43], 0, v[114:115]
	v_lshl_add_u64 v[120:121], s[12:13], 1, v[120:121]
	v_lshlrev_b32_e32 v170, 1, v174
	v_lshl_add_u64 v[120:121], v[120:121], 0, v[170:171]
	s_nop 7
	s_nop 4
	global_store_dwordx4 v[120:121], v[116:119], off offset:-3584 nt

.LBB0_325:
	s_andn2_b64 vcc, exec, s[10:11]
	s_cbranch_vccnz .LBB0_327
	s_nop 0
	v_readlane_b32 s40, v252, 11
	v_readlane_b32 s41, v252, 12
	v_lshlrev_b32_e32 v170, 1, v174
	v_cvt_pk_bf16_f32 v116, v108, v109
	v_lshl_add_u64 v[120:121], s[40:41], 0, v[112:113]
	v_lshl_add_u64 v[120:121], s[12:13], 1, v[120:121]
	v_cvt_pk_bf16_f32 v117, v110, v111
	v_cvt_pk_bf16_f32 v118, v104, v105
	v_cvt_pk_bf16_f32 v119, v106, v107
	v_lshl_add_u64 v[120:121], v[120:121], 0, v[170:171]
	s_nop 7
	s_nop 4
	global_store_dwordx4 v[120:121], v[116:119], off offset:-2560

.LBB0_342:
	v_mov_b32_e32 v195, v194
	s_nop 0
	v_mov_b32_e32 v104, v194
	v_mov_b32_e32 v105, v194
	v_pk_mul_f32 v[102:103], v[102:103], v[104:105]
	v_pk_mul_f32 v[100:101], v[100:101], v[194:195]
	v_pk_mul_f32 v[98:99], v[98:99], v[104:105]
	v_pk_mul_f32 v[96:97], v[96:97], v[194:195]
	s_and_b64 vcc, exec, s[8:9]
	s_mov_b64 s[10:11], -1
	s_cbranch_vccnz .LBB0_354
	s_and_b64 vcc, exec, s[6:7]
	s_cbranch_vccnz .LBB0_351
	s_andn2_b64 vcc, exec, s[58:59]
	s_cbranch_vccnz .LBB0_348
	s_andn2_b64 vcc, exec, s[56:57]
	s_cbranch_vccnz .LBB0_347
	v_mul_f32_e32 v105, 0xbfb8aa3b, v96
	v_exp_f32_e32 v105, v105
	v_mul_f32_e32 v106, 0xbfb8aa3b, v101
	v_mul_f32_e32 v107, 0xbfb8aa3b, v97
	v_exp_f32_e32 v106, v106
	v_exp_f32_e32 v107, v107
	v_add_f32_e32 v105, 1.0, v105
	v_mul_f32_e32 v104, 0xbfb8aa3b, v100
	v_rcp_f32_e32 v108, v105
	v_add_f32_e32 v105, 1.0, v106
	v_add_f32_e32 v106, 1.0, v107
	v_mul_f32_e32 v107, 0xbfb8aa3b, v102
	v_mul_f32_e32 v109, 0xbfb8aa3b, v98
	v_mul_f32_e32 v110, 0xbfb8aa3b, v103
	v_mul_f32_e32 v111, 0xbfb8aa3b, v99
	v_exp_f32_e32 v104, v104
	v_exp_f32_e32 v107, v107
	v_exp_f32_e32 v109, v109
	v_exp_f32_e32 v110, v110
	v_exp_f32_e32 v111, v111
	v_add_f32_e32 v104, 1.0, v104
	v_add_f32_e32 v107, 1.0, v107
	v_add_f32_e32 v109, 1.0, v109
	v_add_f32_e32 v110, 1.0, v110
	v_add_f32_e32 v111, 1.0, v111
	v_rcp_f32_e32 v104, v104
	v_rcp_f32_e32 v105, v105
	v_rcp_f32_e32 v106, v106
	v_rcp_f32_e32 v107, v107
	v_rcp_f32_e32 v109, v109
	v_rcp_f32_e32 v110, v110
	v_rcp_f32_e32 v111, v111
	s_nop 0
	v_readlane_b32 s42, v252, 13
	v_readlane_b32 s43, v252, 14
	v_cvt_pk_bf16_f32 v104, v104, v105
	v_cvt_pk_bf16_f32 v105, v107, v110
	v_cvt_pk_bf16_f32 v106, v108, v106
	v_cvt_pk_bf16_f32 v107, v109, v111
	v_lshl_add_u64 v[108:109], s[42:43], 0, v[114:115]
	v_lshl_add_u64 v[108:109], s[12:13], 1, v[108:109]
	v_lshlrev_b32_e32 v170, 1, v174
	v_lshl_add_u64 v[108:109], v[108:109], 0, v[170:171]
	s_nop 7
	s_nop 4
	global_store_dwordx4 v[108:109], v[104:107], off offset:-3328 nt

.LBB0_348:
	s_andn2_b64 vcc, exec, s[10:11]
	s_cbranch_vccnz .LBB0_350
	s_nop 0
	v_readlane_b32 s40, v252, 11
	v_readlane_b32 s41, v252, 12
	v_lshlrev_b32_e32 v170, 1, v174
	v_cvt_pk_bf16_f32 v104, v100, v101
	v_lshl_add_u64 v[108:109], s[40:41], 0, v[112:113]
	v_lshl_add_u64 v[108:109], s[12:13], 1, v[108:109]
	v_cvt_pk_bf16_f32 v105, v102, v103
	v_cvt_pk_bf16_f32 v106, v96, v97
	v_cvt_pk_bf16_f32 v107, v98, v99
	v_lshl_add_u64 v[108:109], v[108:109], 0, v[170:171]
	s_nop 7
	s_nop 4
	global_store_dwordx4 v[108:109], v[104:107], off offset:-2304

.LBB0_369:
	s_andn2_b64 vcc, exec, s[10:11]
	s_cbranch_vccnz .LBB0_371
	v_mul_f32_e32 v102, 0xbfb8aa3b, v88
	v_exp_f32_e32 v102, v102
	v_mul_f32_e32 v103, 0xbfb8aa3b, v93
	v_mul_f32_e32 v104, 0xbfb8aa3b, v89
	v_exp_f32_e32 v103, v103
	v_exp_f32_e32 v104, v104
	v_add_f32_e32 v102, 1.0, v102
	v_rcp_f32_e32 v105, v102
	v_add_f32_e32 v102, 1.0, v103
	v_add_f32_e32 v103, 1.0, v104
	v_mul_f32_e32 v104, 0xbfb8aa3b, v94
	v_mul_f32_e32 v106, 0xbfb8aa3b, v90
	v_exp_f32_e32 v104, v104
	v_exp_f32_e32 v106, v106
	v_rcp_f32_e32 v107, v103
	s_waitcnt lgkmcnt(2)
	v_mul_f32_e32 v108, 0xbfb8aa3b, v91
	v_add_f32_e32 v103, 1.0, v104
	v_add_f32_e32 v104, 1.0, v106
	v_mul_f32_e32 v106, 0xbfb8aa3b, v95
	v_exp_f32_e32 v106, v106
	v_exp_f32_e32 v108, v108
	v_mul_f32_e32 v97, 0xbfb8aa3b, v92
	v_exp_f32_e32 v97, v97
	s_waitcnt lgkmcnt(0)
	v_rcp_f32_e32 v109, v104
	v_add_f32_e32 v104, 1.0, v106
	v_add_f32_e32 v106, 1.0, v108
	v_rcp_f32_e32 v103, v103
	v_rcp_f32_e32 v104, v104
	v_rcp_f32_e32 v106, v106
	v_add_f32_e32 v97, 1.0, v97
	v_rcp_f32_e32 v97, v97
	v_rcp_f32_e32 v102, v102
	s_nop 0
	v_readlane_b32 s42, v252, 13
	v_readlane_b32 s43, v252, 14
	v_cvt_pk_bf16_f32 v103, v103, v104
	v_cvt_pk_bf16_f32 v104, v105, v107
	v_cvt_pk_bf16_f32 v105, v109, v106
	v_lshl_add_u64 v[106:107], s[42:43], 0, v[100:101]
	v_lshl_add_u64 v[106:107], s[12:13], 1, v[106:107]
	v_lshlrev_b32_e32 v170, 1, v174
	v_cvt_pk_bf16_f32 v102, v97, v102
	v_lshl_add_u64 v[106:107], v[106:107], 0, v[170:171]
	s_nop 7
	s_nop 4
	global_store_dwordx4 v[106:107], v[102:105], off offset:-3584 nt

.LBB0_372:
	s_andn2_b64 vcc, exec, s[10:11]
	s_cbranch_vccnz .LBB0_374
	s_nop 0
	v_readlane_b32 s40, v252, 11
	v_readlane_b32 s41, v252, 12
	v_lshlrev_b32_e32 v170, 1, v174
	v_cvt_pk_bf16_f32 v102, v92, v93
	v_lshl_add_u64 v[106:107], s[40:41], 0, v[98:99]
	v_lshl_add_u64 v[106:107], s[12:13], 1, v[106:107]
	v_cvt_pk_bf16_f32 v103, v94, v95
	v_cvt_pk_bf16_f32 v104, v88, v89
	v_cvt_pk_bf16_f32 v105, v90, v91
	v_lshl_add_u64 v[106:107], v[106:107], 0, v[170:171]
	s_nop 7
	s_nop 4
	global_store_dwordx4 v[106:107], v[102:105], off offset:-2560

.LBB0_389:
	v_mov_b32_e32 v193, v192
	s_nop 0
	v_mov_b32_e32 v88, v192
	v_mov_b32_e32 v89, v192
	v_pk_mul_f32 v[86:87], v[86:87], v[88:89]
	v_pk_mul_f32 v[84:85], v[84:85], v[192:193]
	v_pk_mul_f32 v[82:83], v[82:83], v[88:89]
	v_pk_mul_f32 v[80:81], v[80:81], v[192:193]
	s_and_b64 vcc, exec, s[8:9]
	s_mov_b64 s[10:11], -1
	s_cbranch_vccnz .LBB0_401
	s_and_b64 vcc, exec, s[6:7]
	s_cbranch_vccnz .LBB0_398
	s_andn2_b64 vcc, exec, s[58:59]
	s_cbranch_vccnz .LBB0_395
	s_andn2_b64 vcc, exec, s[56:57]
	s_cbranch_vccnz .LBB0_394
	v_mul_f32_e32 v89, 0xbfb8aa3b, v80
	v_exp_f32_e32 v89, v89
	v_mul_f32_e32 v90, 0xbfb8aa3b, v85
	v_mul_f32_e32 v91, 0xbfb8aa3b, v81
	v_exp_f32_e32 v90, v90
	v_exp_f32_e32 v91, v91
	v_add_f32_e32 v89, 1.0, v89
	v_mul_f32_e32 v88, 0xbfb8aa3b, v84
	v_rcp_f32_e32 v92, v89
	v_add_f32_e32 v89, 1.0, v90
	v_add_f32_e32 v90, 1.0, v91
	v_mul_f32_e32 v91, 0xbfb8aa3b, v86
	v_mul_f32_e32 v93, 0xbfb8aa3b, v82
	v_mul_f32_e32 v94, 0xbfb8aa3b, v87
	v_mul_f32_e32 v95, 0xbfb8aa3b, v83
	v_exp_f32_e32 v88, v88
	v_exp_f32_e32 v91, v91
	v_exp_f32_e32 v93, v93
	v_exp_f32_e32 v94, v94
	v_exp_f32_e32 v95, v95
	v_add_f32_e32 v88, 1.0, v88
	v_add_f32_e32 v91, 1.0, v91
	v_add_f32_e32 v93, 1.0, v93
	v_add_f32_e32 v94, 1.0, v94
	v_add_f32_e32 v95, 1.0, v95
	v_rcp_f32_e32 v88, v88
	v_rcp_f32_e32 v89, v89
	v_rcp_f32_e32 v90, v90
	v_rcp_f32_e32 v91, v91
	v_rcp_f32_e32 v93, v93
	v_rcp_f32_e32 v94, v94
	v_rcp_f32_e32 v95, v95
	s_nop 0
	v_readlane_b32 s42, v252, 13
	v_readlane_b32 s43, v252, 14
	v_cvt_pk_bf16_f32 v88, v88, v89
	v_cvt_pk_bf16_f32 v89, v91, v94
	v_cvt_pk_bf16_f32 v90, v92, v90
	v_cvt_pk_bf16_f32 v91, v93, v95
	v_lshl_add_u64 v[92:93], s[42:43], 0, v[100:101]
	v_lshl_add_u64 v[92:93], s[12:13], 1, v[92:93]
	v_lshlrev_b32_e32 v170, 1, v174
	v_lshl_add_u64 v[92:93], v[92:93], 0, v[170:171]
	s_nop 7
	s_nop 4
	global_store_dwordx4 v[92:93], v[88:91], off offset:-3328 nt

.LBB0_395:
	s_andn2_b64 vcc, exec, s[10:11]
	s_cbranch_vccnz .LBB0_397
	s_nop 0
	v_readlane_b32 s40, v252, 11
	v_readlane_b32 s41, v252, 12
	v_lshlrev_b32_e32 v170, 1, v174
	v_cvt_pk_bf16_f32 v88, v84, v85
	v_lshl_add_u64 v[92:93], s[40:41], 0, v[98:99]
	v_lshl_add_u64 v[92:93], s[12:13], 1, v[92:93]
	v_cvt_pk_bf16_f32 v89, v86, v87
	v_cvt_pk_bf16_f32 v90, v80, v81
	v_cvt_pk_bf16_f32 v91, v82, v83
	v_lshl_add_u64 v[92:93], v[92:93], 0, v[170:171]
	s_nop 7
	s_nop 4
	global_store_dwordx4 v[92:93], v[88:91], off offset:-2304

.LBB0_414:
	s_andn2_b64 vcc, exec, s[10:11]
	s_cbranch_vccnz .LBB0_416
	v_mul_f32_e32 v85, 0xbfb8aa3b, v72
	v_exp_f32_e32 v85, v85
	v_mul_f32_e32 v86, 0xbfb8aa3b, v77
	v_mul_f32_e32 v87, 0xbfb8aa3b, v73
	v_exp_f32_e32 v86, v86
	v_exp_f32_e32 v87, v87
	v_add_f32_e32 v85, 1.0, v85
	v_mul_f32_e32 v84, 0xbfb8aa3b, v76
	v_rcp_f32_e32 v88, v85
	v_add_f32_e32 v85, 1.0, v86
	v_add_f32_e32 v86, 1.0, v87
	v_mul_f32_e32 v87, 0xbfb8aa3b, v78
	v_mul_f32_e32 v89, 0xbfb8aa3b, v74
	v_mul_f32_e32 v90, 0xbfb8aa3b, v79
	v_mul_f32_e32 v91, 0xbfb8aa3b, v75
	v_exp_f32_e32 v84, v84
	v_exp_f32_e32 v87, v87
	v_exp_f32_e32 v89, v89
	v_exp_f32_e32 v90, v90
	v_exp_f32_e32 v91, v91
	v_add_f32_e32 v84, 1.0, v84
	v_add_f32_e32 v87, 1.0, v87
	v_add_f32_e32 v89, 1.0, v89
	v_add_f32_e32 v90, 1.0, v90
	v_add_f32_e32 v91, 1.0, v91
	v_rcp_f32_e32 v84, v84
	v_rcp_f32_e32 v85, v85
	v_rcp_f32_e32 v86, v86
	v_rcp_f32_e32 v87, v87
	v_rcp_f32_e32 v89, v89
	v_rcp_f32_e32 v90, v90
	v_rcp_f32_e32 v91, v91
	s_nop 0
	v_readlane_b32 s42, v252, 13
	v_readlane_b32 s43, v252, 14
	v_cvt_pk_bf16_f32 v84, v84, v85
	v_cvt_pk_bf16_f32 v85, v87, v90
	v_cvt_pk_bf16_f32 v86, v88, v86
	v_cvt_pk_bf16_f32 v87, v89, v91
	v_lshl_add_u64 v[88:89], s[42:43], 0, v[82:83]
	v_lshl_add_u64 v[88:89], s[12:13], 1, v[88:89]
	v_lshlrev_b32_e32 v170, 1, v174
	v_lshl_add_u64 v[88:89], v[88:89], 0, v[170:171]
	s_nop 7
	s_nop 4
	global_store_dwordx4 v[88:89], v[84:87], off offset:-3584 nt

.LBB0_417:
	s_andn2_b64 vcc, exec, s[10:11]
	s_cbranch_vccnz .LBB0_419
	s_nop 0
	v_readlane_b32 s40, v252, 11
	v_readlane_b32 s41, v252, 12
	v_lshlrev_b32_e32 v170, 1, v174
	v_cvt_pk_bf16_f32 v84, v76, v77
	v_lshl_add_u64 v[88:89], s[40:41], 0, v[80:81]
	v_lshl_add_u64 v[88:89], s[12:13], 1, v[88:89]
	v_cvt_pk_bf16_f32 v85, v78, v79
	v_cvt_pk_bf16_f32 v86, v72, v73
	v_cvt_pk_bf16_f32 v87, v74, v75
	v_lshl_add_u64 v[88:89], v[88:89], 0, v[170:171]
	s_nop 7
	s_nop 4
	global_store_dwordx4 v[88:89], v[84:87], off offset:-2560

.LBB0_434:
	v_mov_b32_e32 v191, v190
	s_nop 0
	v_mov_b32_e32 v72, v190
	v_mov_b32_e32 v73, v190
	v_pk_mul_f32 v[70:71], v[70:71], v[72:73]
	v_pk_mul_f32 v[68:69], v[68:69], v[190:191]
	v_pk_mul_f32 v[66:67], v[66:67], v[72:73]
	v_pk_mul_f32 v[64:65], v[64:65], v[190:191]
	s_and_b64 vcc, exec, s[8:9]
	s_mov_b64 s[10:11], -1
	s_cbranch_vccnz .LBB0_466
	s_and_b64 vcc, exec, s[6:7]
	s_cbranch_vccnz .LBB0_443
	s_andn2_b64 vcc, exec, s[58:59]
	s_cbranch_vccnz .LBB0_440
	s_andn2_b64 vcc, exec, s[56:57]
	s_cbranch_vccnz .LBB0_439
	v_mul_f32_e32 v73, 0xbfb8aa3b, v64
	v_exp_f32_e32 v73, v73
	v_mul_f32_e32 v74, 0xbfb8aa3b, v69
	v_mul_f32_e32 v75, 0xbfb8aa3b, v65
	v_exp_f32_e32 v74, v74
	v_exp_f32_e32 v75, v75
	v_add_f32_e32 v73, 1.0, v73
	v_mul_f32_e32 v72, 0xbfb8aa3b, v68
	v_rcp_f32_e32 v76, v73
	v_add_f32_e32 v73, 1.0, v74
	v_add_f32_e32 v74, 1.0, v75
	v_mul_f32_e32 v75, 0xbfb8aa3b, v70
	v_mul_f32_e32 v77, 0xbfb8aa3b, v66
	v_mul_f32_e32 v78, 0xbfb8aa3b, v71
	v_mul_f32_e32 v79, 0xbfb8aa3b, v67
	v_exp_f32_e32 v72, v72
	v_exp_f32_e32 v75, v75
	v_exp_f32_e32 v77, v77
	v_exp_f32_e32 v78, v78
	v_exp_f32_e32 v79, v79
	v_add_f32_e32 v72, 1.0, v72
	v_add_f32_e32 v75, 1.0, v75
	v_add_f32_e32 v77, 1.0, v77
	v_add_f32_e32 v78, 1.0, v78
	v_add_f32_e32 v79, 1.0, v79
	v_rcp_f32_e32 v72, v72
	v_rcp_f32_e32 v73, v73
	v_rcp_f32_e32 v74, v74
	v_rcp_f32_e32 v75, v75
	v_rcp_f32_e32 v77, v77
	v_rcp_f32_e32 v78, v78
	v_rcp_f32_e32 v79, v79
	s_nop 0
	v_readlane_b32 s42, v252, 13
	v_readlane_b32 s43, v252, 14
	v_cvt_pk_bf16_f32 v72, v72, v73
	v_cvt_pk_bf16_f32 v73, v75, v78
	v_cvt_pk_bf16_f32 v74, v76, v74
	v_cvt_pk_bf16_f32 v75, v77, v79
	v_lshl_add_u64 v[76:77], s[42:43], 0, v[82:83]
	v_lshl_add_u64 v[76:77], s[12:13], 1, v[76:77]
	v_lshlrev_b32_e32 v170, 1, v174
	v_lshl_add_u64 v[76:77], v[76:77], 0, v[170:171]
	s_nop 7
	s_nop 4
	global_store_dwordx4 v[76:77], v[72:75], off offset:-3328 nt

.LBB0_440:
	s_andn2_b64 vcc, exec, s[10:11]
	s_cbranch_vccnz .LBB0_442
	s_nop 0
	v_readlane_b32 s40, v252, 11
	v_readlane_b32 s41, v252, 12
	v_lshlrev_b32_e32 v170, 1, v174
	v_cvt_pk_bf16_f32 v72, v68, v69
	v_lshl_add_u64 v[76:77], s[40:41], 0, v[80:81]
	v_lshl_add_u64 v[76:77], s[12:13], 1, v[76:77]
	v_cvt_pk_bf16_f32 v73, v70, v71
	v_cvt_pk_bf16_f32 v74, v64, v65
	v_cvt_pk_bf16_f32 v75, v66, v67
	v_lshl_add_u64 v[76:77], v[76:77], 0, v[170:171]
	s_nop 7
	s_nop 4
	global_store_dwordx4 v[76:77], v[72:75], off offset:-2304

.LBB0_455:
	s_andn2_b64 vcc, exec, s[10:11]
	s_cbranch_vccnz .LBB0_457
	v_mul_f32_e32 v69, 0xbfb8aa3b, v56
	v_exp_f32_e32 v69, v69
	v_mul_f32_e32 v70, 0xbfb8aa3b, v61
	v_mul_f32_e32 v71, 0xbfb8aa3b, v57
	v_exp_f32_e32 v70, v70
	v_exp_f32_e32 v71, v71
	v_add_f32_e32 v69, 1.0, v69
	v_mul_f32_e32 v68, 0xbfb8aa3b, v60
	v_rcp_f32_e32 v72, v69
	v_add_f32_e32 v69, 1.0, v70
	v_add_f32_e32 v70, 1.0, v71
	v_mul_f32_e32 v71, 0xbfb8aa3b, v62
	v_mul_f32_e32 v73, 0xbfb8aa3b, v58
	v_mul_f32_e32 v74, 0xbfb8aa3b, v63
	v_mul_f32_e32 v75, 0xbfb8aa3b, v59
	v_exp_f32_e32 v68, v68
	v_exp_f32_e32 v71, v71
	v_exp_f32_e32 v73, v73
	v_exp_f32_e32 v74, v74
	v_exp_f32_e32 v75, v75
	v_add_f32_e32 v68, 1.0, v68
	v_add_f32_e32 v71, 1.0, v71
	v_add_f32_e32 v73, 1.0, v73
	v_add_f32_e32 v74, 1.0, v74
	v_add_f32_e32 v75, 1.0, v75
	v_rcp_f32_e32 v68, v68
	v_rcp_f32_e32 v69, v69
	v_rcp_f32_e32 v70, v70
	v_rcp_f32_e32 v71, v71
	v_rcp_f32_e32 v73, v73
	v_rcp_f32_e32 v74, v74
	v_rcp_f32_e32 v75, v75
	s_nop 0
	v_readlane_b32 s42, v252, 13
	v_readlane_b32 s43, v252, 14
	v_cvt_pk_bf16_f32 v68, v68, v69
	v_cvt_pk_bf16_f32 v69, v71, v74
	v_cvt_pk_bf16_f32 v70, v72, v70
	v_cvt_pk_bf16_f32 v71, v73, v75
	v_lshl_add_u64 v[72:73], s[42:43], 0, v[66:67]
	v_lshl_add_u64 v[72:73], s[12:13], 1, v[72:73]
	v_lshlrev_b32_e32 v170, 1, v174
	v_lshl_add_u64 v[72:73], v[72:73], 0, v[170:171]
	s_nop 7
	s_nop 4
	global_store_dwordx4 v[72:73], v[68:71], off offset:-3584 nt

.LBB0_458:
	s_andn2_b64 vcc, exec, s[10:11]
	s_cbranch_vccnz .LBB0_460
	s_nop 0
	v_readlane_b32 s40, v252, 11
	v_readlane_b32 s41, v252, 12
	v_lshlrev_b32_e32 v170, 1, v174
	v_cvt_pk_bf16_f32 v68, v60, v61
	v_lshl_add_u64 v[72:73], s[40:41], 0, v[64:65]
	v_lshl_add_u64 v[72:73], s[12:13], 1, v[72:73]
	v_cvt_pk_bf16_f32 v69, v62, v63
	v_cvt_pk_bf16_f32 v70, v56, v57
	v_cvt_pk_bf16_f32 v71, v58, v59
	v_lshl_add_u64 v[72:73], v[72:73], 0, v[170:171]
	s_nop 7
	s_nop 4
	global_store_dwordx4 v[72:73], v[68:71], off offset:-2560

.LBB0_481:
	v_mov_b32_e32 v189, v188
	s_nop 0
	v_mov_b32_e32 v56, v188
	v_mov_b32_e32 v57, v188
	v_pk_mul_f32 v[38:39], v[38:39], v[56:57]
	v_pk_mul_f32 v[36:37], v[36:37], v[188:189]
	v_pk_mul_f32 v[34:35], v[34:35], v[56:57]
	v_pk_mul_f32 v[32:33], v[32:33], v[188:189]
	s_and_b64 vcc, exec, s[8:9]
	s_mov_b64 s[10:11], -1
	s_cbranch_vccnz .LBB0_493
	s_and_b64 vcc, exec, s[6:7]
	s_cbranch_vccnz .LBB0_490
	s_andn2_b64 vcc, exec, s[58:59]
	s_cbranch_vccnz .LBB0_487
	s_andn2_b64 vcc, exec, s[56:57]
	s_cbranch_vccnz .LBB0_486
	v_mul_f32_e32 v57, 0xbfb8aa3b, v32
	v_exp_f32_e32 v57, v57
	v_mul_f32_e32 v58, 0xbfb8aa3b, v37
	v_mul_f32_e32 v59, 0xbfb8aa3b, v33
	v_exp_f32_e32 v58, v58
	v_exp_f32_e32 v59, v59
	v_add_f32_e32 v57, 1.0, v57
	v_mul_f32_e32 v56, 0xbfb8aa3b, v36
	v_rcp_f32_e32 v60, v57
	v_add_f32_e32 v57, 1.0, v58
	v_add_f32_e32 v58, 1.0, v59
	v_mul_f32_e32 v59, 0xbfb8aa3b, v38
	v_mul_f32_e32 v61, 0xbfb8aa3b, v34
	v_mul_f32_e32 v62, 0xbfb8aa3b, v39
	v_mul_f32_e32 v63, 0xbfb8aa3b, v35
	v_exp_f32_e32 v56, v56
	v_exp_f32_e32 v59, v59
	v_exp_f32_e32 v61, v61
	v_exp_f32_e32 v62, v62
	v_exp_f32_e32 v63, v63
	v_add_f32_e32 v56, 1.0, v56
	v_add_f32_e32 v59, 1.0, v59
	v_add_f32_e32 v61, 1.0, v61
	v_add_f32_e32 v62, 1.0, v62
	v_add_f32_e32 v63, 1.0, v63
	v_rcp_f32_e32 v56, v56
	v_rcp_f32_e32 v57, v57
	v_rcp_f32_e32 v58, v58
	v_rcp_f32_e32 v59, v59
	v_rcp_f32_e32 v61, v61
	v_rcp_f32_e32 v62, v62
	v_rcp_f32_e32 v63, v63
	s_nop 0
	v_readlane_b32 s42, v252, 13
	v_readlane_b32 s43, v252, 14
	v_cvt_pk_bf16_f32 v56, v56, v57
	v_cvt_pk_bf16_f32 v57, v59, v62
	v_cvt_pk_bf16_f32 v58, v60, v58
	v_cvt_pk_bf16_f32 v59, v61, v63
	v_lshl_add_u64 v[60:61], s[42:43], 0, v[66:67]
	v_lshl_add_u64 v[60:61], s[12:13], 1, v[60:61]
	v_lshlrev_b32_e32 v170, 1, v174
	v_lshl_add_u64 v[60:61], v[60:61], 0, v[170:171]
	s_nop 7
	s_nop 4
	global_store_dwordx4 v[60:61], v[56:59], off offset:-3328 nt

.LBB0_487:
	s_andn2_b64 vcc, exec, s[10:11]
	s_cbranch_vccnz .LBB0_489
	s_nop 0
	v_readlane_b32 s40, v252, 11
	v_readlane_b32 s41, v252, 12
	v_lshlrev_b32_e32 v170, 1, v174
	v_cvt_pk_bf16_f32 v56, v36, v37
	v_lshl_add_u64 v[60:61], s[40:41], 0, v[64:65]
	v_lshl_add_u64 v[60:61], s[12:13], 1, v[60:61]
	v_cvt_pk_bf16_f32 v57, v38, v39
	v_cvt_pk_bf16_f32 v58, v32, v33
	v_cvt_pk_bf16_f32 v59, v34, v35
	v_lshl_add_u64 v[60:61], v[60:61], 0, v[170:171]
	s_nop 7
	s_nop 4
	global_store_dwordx4 v[60:61], v[56:59], off offset:-2304

.LBB0_506:
	s_andn2_b64 vcc, exec, s[10:11]
	s_cbranch_vccnz .LBB0_508
	v_mul_f32_e32 v37, 0xbfb8aa3b, v8
	v_exp_f32_e32 v37, v37
	v_mul_f32_e32 v38, 0xbfb8aa3b, v13
	v_mul_f32_e32 v39, 0xbfb8aa3b, v9
	v_exp_f32_e32 v38, v38
	v_exp_f32_e32 v39, v39
	v_add_f32_e32 v37, 1.0, v37
	v_mul_f32_e32 v36, 0xbfb8aa3b, v12
	v_rcp_f32_e32 v40, v37
	v_add_f32_e32 v37, 1.0, v38
	v_add_f32_e32 v38, 1.0, v39
	v_mul_f32_e32 v39, 0xbfb8aa3b, v14
	v_mul_f32_e32 v41, 0xbfb8aa3b, v10
	v_mul_f32_e32 v42, 0xbfb8aa3b, v15
	v_mul_f32_e32 v43, 0xbfb8aa3b, v11
	v_exp_f32_e32 v36, v36
	v_exp_f32_e32 v39, v39
	v_exp_f32_e32 v41, v41
	v_exp_f32_e32 v42, v42
	v_exp_f32_e32 v43, v43
	v_add_f32_e32 v36, 1.0, v36
	v_add_f32_e32 v39, 1.0, v39
	v_add_f32_e32 v41, 1.0, v41
	v_add_f32_e32 v42, 1.0, v42
	v_add_f32_e32 v43, 1.0, v43
	v_rcp_f32_e32 v36, v36
	v_rcp_f32_e32 v37, v37
	v_rcp_f32_e32 v38, v38
	v_rcp_f32_e32 v39, v39
	v_rcp_f32_e32 v41, v41
	v_rcp_f32_e32 v42, v42
	v_rcp_f32_e32 v43, v43
	s_nop 0
	v_readlane_b32 s42, v252, 13
	v_readlane_b32 s43, v252, 14
	v_cvt_pk_bf16_f32 v36, v36, v37
	v_cvt_pk_bf16_f32 v37, v39, v42
	v_cvt_pk_bf16_f32 v38, v40, v38
	v_cvt_pk_bf16_f32 v39, v41, v43
	v_lshl_add_u64 v[40:41], s[42:43], 0, v[34:35]
	v_lshl_add_u64 v[40:41], s[12:13], 1, v[40:41]
	v_lshlrev_b32_e32 v170, 1, v174
	v_lshl_add_u64 v[40:41], v[40:41], 0, v[170:171]
	s_nop 7
	s_nop 4
	global_store_dwordx4 v[40:41], v[36:39], off offset:-3584 nt

.LBB0_509:
	s_andn2_b64 vcc, exec, s[10:11]
	s_cbranch_vccnz .LBB0_511
	s_nop 0
	v_readlane_b32 s40, v252, 11
	v_readlane_b32 s41, v252, 12
	v_lshlrev_b32_e32 v170, 1, v174
	v_cvt_pk_bf16_f32 v36, v12, v13
	v_lshl_add_u64 v[40:41], s[40:41], 0, v[32:33]
	v_lshl_add_u64 v[40:41], s[12:13], 1, v[40:41]
	v_cvt_pk_bf16_f32 v37, v14, v15
	v_cvt_pk_bf16_f32 v38, v8, v9
	v_cvt_pk_bf16_f32 v39, v10, v11
	v_lshl_add_u64 v[40:41], v[40:41], 0, v[170:171]
	s_nop 7
	s_nop 4
	global_store_dwordx4 v[40:41], v[36:39], off offset:-2560

.LBB0_526:
	v_mov_b32_e32 v187, v186
	s_nop 0
	v_mov_b32_e32 v8, v186
	v_mov_b32_e32 v9, v186
	v_pk_mul_f32 v[6:7], v[6:7], v[8:9]
	v_pk_mul_f32 v[4:5], v[4:5], v[186:187]
	v_pk_mul_f32 v[2:3], v[2:3], v[8:9]
	v_pk_mul_f32 v[0:1], v[0:1], v[186:187]
	s_and_b64 vcc, exec, s[8:9]
	s_mov_b64 s[8:9], -1
	s_cbranch_vccnz .LBB0_538
	s_and_b64 vcc, exec, s[6:7]
	s_mov_b64 s[6:7], -1
	s_cbranch_vccnz .LBB0_535
	s_andn2_b64 vcc, exec, s[58:59]
	s_cbranch_vccnz .LBB0_532
	s_andn2_b64 vcc, exec, s[56:57]
	s_cbranch_vccnz .LBB0_531
	v_mul_f32_e32 v9, 0xbfb8aa3b, v0
	v_exp_f32_e32 v9, v9
	v_mul_f32_e32 v10, 0xbfb8aa3b, v5
	v_mul_f32_e32 v11, 0xbfb8aa3b, v1
	v_exp_f32_e32 v10, v10
	v_exp_f32_e32 v11, v11
	v_add_f32_e32 v9, 1.0, v9
	v_mul_f32_e32 v8, 0xbfb8aa3b, v4
	v_rcp_f32_e32 v12, v9
	v_add_f32_e32 v9, 1.0, v10
	v_add_f32_e32 v10, 1.0, v11
	v_mul_f32_e32 v11, 0xbfb8aa3b, v6
	v_mul_f32_e32 v13, 0xbfb8aa3b, v2
	v_mul_f32_e32 v14, 0xbfb8aa3b, v7
	v_mul_f32_e32 v15, 0xbfb8aa3b, v3
	v_exp_f32_e32 v8, v8
	v_exp_f32_e32 v11, v11
	v_exp_f32_e32 v13, v13
	v_exp_f32_e32 v14, v14
	v_exp_f32_e32 v15, v15
	v_add_f32_e32 v8, 1.0, v8
	v_add_f32_e32 v11, 1.0, v11
	v_add_f32_e32 v13, 1.0, v13
	v_add_f32_e32 v14, 1.0, v14
	v_add_f32_e32 v15, 1.0, v15
	v_rcp_f32_e32 v8, v8
	v_rcp_f32_e32 v9, v9
	v_rcp_f32_e32 v10, v10
	v_rcp_f32_e32 v11, v11
	v_rcp_f32_e32 v13, v13
	v_rcp_f32_e32 v14, v14
	v_rcp_f32_e32 v15, v15
	s_nop 0
	v_readlane_b32 s42, v252, 13
	v_readlane_b32 s43, v252, 14
	v_cvt_pk_bf16_f32 v8, v8, v9
	v_cvt_pk_bf16_f32 v9, v11, v14
	v_cvt_pk_bf16_f32 v10, v12, v10
	v_cvt_pk_bf16_f32 v11, v13, v15
	v_lshl_add_u64 v[12:13], s[42:43], 0, v[34:35]
	v_lshl_add_u64 v[12:13], s[12:13], 1, v[12:13]
	v_lshlrev_b32_e32 v170, 1, v174
	v_lshl_add_u64 v[12:13], v[12:13], 0, v[170:171]
	s_nop 7
	s_nop 4
	global_store_dwordx4 v[12:13], v[8:11], off offset:-3328 nt

.LBB0_532:
	s_andn2_b64 vcc, exec, s[6:7]
	s_cbranch_vccnz .LBB0_534
	s_nop 0
	v_readlane_b32 s40, v252, 11
	v_readlane_b32 s41, v252, 12
	v_lshlrev_b32_e32 v170, 1, v174
	v_cvt_pk_bf16_f32 v8, v4, v5
	v_lshl_add_u64 v[12:13], s[40:41], 0, v[32:33]
	v_lshl_add_u64 v[12:13], s[12:13], 1, v[12:13]
	v_cvt_pk_bf16_f32 v9, v6, v7
	v_cvt_pk_bf16_f32 v10, v0, v1
	v_cvt_pk_bf16_f32 v11, v2, v3
	v_lshl_add_u64 v[12:13], v[12:13], 0, v[170:171]
	s_nop 7
	s_nop 4
	global_store_dwordx4 v[12:13], v[8:11], off offset:-2304

.LBB0_602:
	s_andn2_b64 vcc, exec, s[0:1]
	s_cbranch_vccnz .LBB0_617
	v_ashrrev_i32_e32 v1, 31, v8
	v_lshrrev_b32_e32 v1, 26, v1
	v_add_u32_e32 v1, v8, v1
	v_ashrrev_i32_e32 v9, 6, v1
	v_bfe_i32 v1, v8, 27, 1
	v_lshlrev_b32_e32 v0, 4, v8
	v_lshrrev_b32_e32 v1, 22, v1
	v_add_u32_e32 v1, v0, v1
	v_and_b32_e32 v1, 0xfffffc00, v1
	v_sub_u32_e32 v1, v0, v1
	v_lshrrev_b32_e32 v2, 4, v1
	v_bitop3_b32 v2, v2, v1, 32 bitop3:0x6c
	v_ashrrev_i32_e32 v1, 31, v1
	v_lshrrev_b32_e32 v1, 26, v1
	v_add_u32_e32 v1, v2, v1
	v_ashrrev_i32_e32 v10, 6, v1
	v_lshlrev_b32_e32 v3, 3, v9
	v_mul_i32_i24_e32 v4, 64, v10
	v_and_b32_e32 v3, -16, v3
	v_sub_u32_e32 v2, v2, v4
	v_mov_b32_e32 v4, 1
	v_add_u32_e32 v1, v10, v3
	v_lshlrev_b32_e32 v3, 5, v9
	v_ashrrev_i16_sdwa v2, v4, sext(v2) dst_sel:DWORD dst_unused:UNUSED_PAD src0_sel:DWORD src1_sel:BYTE_0
	v_and_b32_e32 v3, 32, v3
	v_bfe_i32 v11, v2, 0, 16
	v_and_b32_e32 v6, 3, v10
	s_mov_b32 s1, 0xfffe0
	v_add_lshl_u32 v3, v3, v11, 1
	v_add_u32_e32 v0, 0x2000, v0
	v_lshlrev_b32_e32 v2, 1, v1
	v_lshrrev_b32_e32 v5, 2, v1
	v_and_or_b32 v6, v1, s1, v6
	v_lshl_add_u32 v128, v1, 11, v3
	v_ashrrev_i32_e32 v1, 31, v0
	v_lshrrev_b32_e32 v1, 22, v1
	v_add_u32_e32 v1, v0, v1
	v_ashrrev_i32_e32 v12, 10, v1
	v_mul_i32_i24_e32 v1, 0x400, v12
	v_sub_u32_e32 v0, v0, v1
	v_and_b32_e32 v2, 24, v2
	v_and_b32_e32 v5, 4, v5
	v_lshrrev_b32_e32 v1, 4, v0
	v_or3_b32 v2, v6, v5, v2
	v_bitop3_b32 v0, v1, v0, 32 bitop3:0x6c
	v_lshl_add_u32 v130, v2, 12, v3
	v_ashrrev_i32_e32 v2, 31, v0
	v_lshrrev_b32_e32 v2, 26, v2
	v_add_u32_e32 v2, v0, v2
	v_lshlrev_b32_e32 v1, 3, v12
	v_ashrrev_i32_e32 v13, 6, v2
	v_and_b32_e32 v2, 0xc0, v2
	v_and_b32_e32 v1, -16, v1
	v_sub_u32_e32 v0, v0, v2
	v_add_u32_e32 v1, v13, v1
	v_ashrrev_i16_sdwa v0, v4, sext(v0) dst_sel:DWORD dst_unused:UNUSED_PAD src0_sel:DWORD src1_sel:BYTE_0
	v_and_b32_e32 v4, 3, v13
	s_ashr_i32 s2, s3, 2
	s_ashr_i32 s4, s3, 6
	s_lshl_b32 s3, s3, 3
	v_and_or_b32 v4, v1, s1, v4
	s_ashr_i32 s1, s18, 6
	s_and_b32 s26, s3, 24
	s_ashr_i32 s3, s2, 31
	s_ashr_i32 s5, s4, 31
	s_ashr_i32 s0, s18, 8
	s_lshl_b32 s19, s1, 10
	s_lshl_b64 s[6:7], s[2:3], 19
	s_lshl_b32 s8, s26, 7
	s_lshl_b64 s[4:5], s[4:5], 20
	s_add_u32 s3, s68, s4
	s_addc_u32 s4, s69, s5
	s_add_u32 s24, s3, s8
	s_addc_u32 s25, s4, 0
	s_add_i32 s3, s19, 0
	s_add_i32 m0, s3, 0x10000
	v_lshlrev_b32_e32 v3, 5, v12
	v_bfe_i32 v14, v0, 0, 16
	v_lshlrev_b32_e32 v0, 1, v1
	v_lshrrev_b32_e32 v2, 2, v1
	global_load_lds_dwordx4 v130, s[24:25]
	s_add_i32 m0, s3, 0x12000
	v_readlane_b32 s36, v252, 7
	v_and_b32_e32 v3, 32, v3
	v_and_b32_e32 v0, 24, v0
	v_and_b32_e32 v2, 4, v2
	v_readlane_b32 s37, v252, 8
	s_add_u32 s4, s36, s6
	v_or3_b32 v0, v4, v2, v0
	v_add_lshl_u32 v2, v3, v14, 1
	s_addc_u32 s5, s37, s7
	v_lshl_add_u32 v134, v0, 12, v2
	s_add_u32 s22, s4, s8
	global_load_lds_dwordx4 v134, s[24:25]
	s_addc_u32 s23, s5, 0
	s_mov_b32 m0, s3
	s_add_i32 s20, s3, 0x2000
	v_lshl_add_u32 v132, v1, 11, v2
	global_load_lds_dwordx4 v128, s[22:23]
	s_mov_b32 m0, s20
	s_add_u32 s4, s24, 0x80000
	global_load_lds_dwordx4 v132, s[22:23]
	s_addc_u32 s5, s25, 0
	s_add_i32 m0, s3, 0x14000
	v_mov_b32_e32 v137, 0
	global_load_lds_dwordx4 v130, s[4:5]
	s_add_i32 m0, s3, 0x16000
	v_mov_b32_e32 v131, v137
	global_load_lds_dwordx4 v134, s[4:5]
	s_add_u32 s4, s22, 0x40000
	s_addc_u32 s5, s23, 0
	s_add_i32 s21, s3, 0x4000
	s_mov_b32 m0, s21
	s_add_i32 s27, s3, 0x6000
	global_load_lds_dwordx4 v128, s[4:5]
	s_mov_b32 m0, s27
	v_mov_b32_e32 v135, v137
	global_load_lds_dwordx4 v132, s[4:5]
	v_mov_b32_e32 v129, v137
	v_mov_b32_e32 v133, v137
	s_mov_b32 s28, 0
	v_lshl_add_u64 v[6:7], s[24:25], 0, v[130:131]
	v_lshl_add_u64 v[4:5], s[24:25], 0, v[134:135]
	v_lshl_add_u64 v[2:3], s[22:23], 0, v[128:129]
	s_cmp_lg_u32 s0, 1
	v_lshl_add_u64 v[0:1], s[22:23], 0, v[132:133]
	s_nop 7
	s_nop 5
	s_cbranch_scc1 .LBB0_605
	s_barrier

.LBB0_611:
	s_ashr_i32 s9, s8, 31
	s_xor_b64 s[10:11], s[34:35], -1
	s_lshl_b64 s[14:15], s[8:9], 19
	v_readlane_b32 s44, v252, 7
	v_readlane_b32 s45, v252, 8
	s_add_u32 s7, s44, s14
	s_addc_u32 s9, s45, s15
	s_lshl_b32 s42, s40, 7
	s_add_u32 s14, s7, s42
	s_addc_u32 s15, s9, 0
	s_and_b64 s[16:17], s[34:35], exec
	s_cselect_b32 s9, s15, s23
	s_cselect_b32 s41, s14, s22
	s_ashr_i32 s7, s6, 31
	s_lshl_b64 s[16:17], s[6:7], 20
	s_add_u32 s7, s68, s16
	s_addc_u32 s17, s69, s17
	s_add_u32 s16, s7, s42
	s_addc_u32 s17, s17, 0
	s_and_b64 s[34:35], s[34:35], exec
	s_cselect_b32 s7, s17, s25
	s_cselect_b32 s42, s16, s24
	s_add_u32 s22, s22, 0x40080
	s_addc_u32 s23, s23, 0
	s_add_u32 s43, s24, 0x100
	v_mov_b32_e32 v0, 0
	s_addc_u32 s44, s25, 0
	s_mov_b32 s45, -2
	v_mov_b32_e32 v1, v0
	v_mov_b32_e32 v2, v0
	v_mov_b32_e32 v3, v0
	v_mov_b32_e32 v4, v0
	v_mov_b32_e32 v5, v0
	v_mov_b32_e32 v6, v0
	v_mov_b32_e32 v7, v0
	v_mov_b32_e32 v8, v0
	v_mov_b32_e32 v9, v0
	v_mov_b32_e32 v10, v0
	v_mov_b32_e32 v11, v0
	v_mov_b32_e32 v12, v0
	v_mov_b32_e32 v13, v0
	v_mov_b32_e32 v14, v0
	v_mov_b32_e32 v15, v0
	v_mov_b32_e32 v16, v0
	v_mov_b32_e32 v17, v0
	v_mov_b32_e32 v18, v0
	v_mov_b32_e32 v19, v0
	v_mov_b32_e32 v20, v0
	v_mov_b32_e32 v21, v0
	v_mov_b32_e32 v22, v0
	v_mov_b32_e32 v23, v0
	v_mov_b32_e32 v32, v0
	v_mov_b32_e32 v33, v0
	v_mov_b32_e32 v34, v0
	v_mov_b32_e32 v35, v0
	v_mov_b32_e32 v36, v0
	v_mov_b32_e32 v37, v0
	v_mov_b32_e32 v38, v0
	v_mov_b32_e32 v39, v0
	v_mov_b32_e32 v24, v0
	v_mov_b32_e32 v25, v0
	v_mov_b32_e32 v26, v0
	v_mov_b32_e32 v27, v0
	v_mov_b32_e32 v28, v0
	v_mov_b32_e32 v29, v0
	v_mov_b32_e32 v30, v0
	v_mov_b32_e32 v31, v0
	v_mov_b32_e32 v40, v0
	v_mov_b32_e32 v41, v0
	v_mov_b32_e32 v42, v0
	v_mov_b32_e32 v43, v0
	v_mov_b32_e32 v44, v0
	v_mov_b32_e32 v45, v0
	v_mov_b32_e32 v46, v0
	v_mov_b32_e32 v47, v0
	v_mov_b32_e32 v48, v0
	v_mov_b32_e32 v49, v0
	v_mov_b32_e32 v50, v0
	v_mov_b32_e32 v51, v0
	v_mov_b32_e32 v52, v0
	v_mov_b32_e32 v53, v0
	v_mov_b32_e32 v54, v0
	v_mov_b32_e32 v55, v0
	v_mov_b32_e32 v56, v0
	v_mov_b32_e32 v57, v0
	v_mov_b32_e32 v58, v0
	v_mov_b32_e32 v59, v0
	v_mov_b32_e32 v60, v0
	v_mov_b32_e32 v61, v0
	v_mov_b32_e32 v62, v0
	v_mov_b32_e32 v63, v0
	v_mov_b32_e32 v64, v0
	v_mov_b32_e32 v65, v0
	v_mov_b32_e32 v66, v0
	v_mov_b32_e32 v67, v0
	v_mov_b32_e32 v68, v0
	v_mov_b32_e32 v69, v0
	v_mov_b32_e32 v70, v0
	v_mov_b32_e32 v71, v0
	v_mov_b32_e32 v72, v0
	v_mov_b32_e32 v73, v0
	v_mov_b32_e32 v74, v0
	v_mov_b32_e32 v75, v0
	v_mov_b32_e32 v76, v0
	v_mov_b32_e32 v77, v0
	v_mov_b32_e32 v78, v0
	v_mov_b32_e32 v79, v0
	v_mov_b32_e32 v80, v0
	v_mov_b32_e32 v81, v0
	v_mov_b32_e32 v82, v0
	v_mov_b32_e32 v83, v0
	v_mov_b32_e32 v88, v0
	v_mov_b32_e32 v89, v0
	v_mov_b32_e32 v90, v0
	v_mov_b32_e32 v91, v0
	v_mov_b32_e32 v96, v0
	v_mov_b32_e32 v97, v0
	v_mov_b32_e32 v98, v0
	v_mov_b32_e32 v99, v0
	v_mov_b32_e32 v104, v0
	v_mov_b32_e32 v105, v0
	v_mov_b32_e32 v106, v0
	v_mov_b32_e32 v107, v0
	v_mov_b32_e32 v84, v0
	v_mov_b32_e32 v85, v0
	v_mov_b32_e32 v86, v0
	v_mov_b32_e32 v87, v0
	v_mov_b32_e32 v92, v0
	v_mov_b32_e32 v93, v0
	v_mov_b32_e32 v94, v0
	v_mov_b32_e32 v95, v0
	v_mov_b32_e32 v100, v0
	v_mov_b32_e32 v101, v0
	v_mov_b32_e32 v102, v0
	v_mov_b32_e32 v103, v0
	v_mov_b32_e32 v108, v0
	v_mov_b32_e32 v109, v0
	v_mov_b32_e32 v110, v0
	v_mov_b32_e32 v111, v0
	v_mov_b32_e32 v112, v0
	v_mov_b32_e32 v113, v0
	v_mov_b32_e32 v114, v0
	v_mov_b32_e32 v115, v0
	v_mov_b32_e32 v116, v0
	v_mov_b32_e32 v117, v0
	v_mov_b32_e32 v118, v0
	v_mov_b32_e32 v119, v0
	v_mov_b32_e32 v120, v0
	v_mov_b32_e32 v121, v0
	v_mov_b32_e32 v122, v0
	v_mov_b32_e32 v123, v0
	v_mov_b32_e32 v124, v0
	v_mov_b32_e32 v125, v0
	v_mov_b32_e32 v126, v0
	v_mov_b32_e32 v127, v0
	s_nop 7
	s_nop 5

.LBB0_618:
	v_and_b32_e32 v0, 0x1f8, v152
	v_bfe_u32 v1, v152, 7, 2
	v_readlane_b32 s16, v252, 7
	v_lshlrev_b32_e64 v72, v1, 2
	v_lshlrev_b32_e32 v0, 1, v0
	v_mov_b32_e32 v1, 0
	v_readlane_b32 s20, v252, 11
	v_readlane_b32 s21, v252, 12
	v_readlane_b32 s30, v252, 21
	v_readlane_b32 s31, v252, 22
	v_lshl_add_u64 v[64:65], s[20:21], 0, v[0:1]
	v_lshl_add_u32 v73, s62, 9, v178
	v_lshl_add_u64 v[66:67], s[30:31], 0, v[0:1]
	s_lshl_b32 s2, s92, 9
	s_mov_b32 s3, s62
	v_readlane_b32 s17, v252, 8
	s_nop 1
	v_readlane_b32 s22, v252, 13
	v_readlane_b32 s23, v252, 14
	s_nop 5
	s_branch .LBB0_620

.LBB0_702:
	s_or_b64 exec, exec, s[0:1]
	s_waitcnt lgkmcnt(0)
	v_and_b32_e32 v0, 0xf8, v152
	v_lshlrev_b32_e32 v128, 2, v0
	v_add_u32_e32 v0, 0x600, v178
	s_ashr_i32 s1, s62, 3
	v_lshrrev_b32_e32 v153, 5, v0
	v_or_b32_e32 v0, 0x400, v178
	v_writelane_b32 v252, s1, 49
	s_nop 0
	v_lshrrev_b32_e32 v154, 5, v0
	v_add_u32_e32 v0, 0x200, v178
	v_mov_b32_e32 v129, 0
	s_nop 7
	s_nop 0
	v_readlane_b32 s26, v252, 1
	v_readlane_b32 s27, v252, 2
	s_nop 3
	v_lshrrev_b32_e32 v155, 5, v0
	v_lshlrev_b32_e32 v0, 4, v178
	v_lshl_add_u64 v[130:131], s[26:27], 0, v[128:129]
	v_add_u32_e32 v1, 0x2000, v0
	s_nop 0
	s_xor_b32 s0, s1, s62
	s_movk_i32 s2, 0x7e00
	v_and_b32_e32 v128, 0x7e00, v1
	v_readlane_b32 s24, v252, 15
	v_readlane_b32 s25, v252, 16
	v_mov_b32_e32 v1, 0x4000
	s_and_b32 s15, s0, 7
	v_lshl_add_u64 v[134:135], s[24:25], 0, v[128:129]
	v_bitop3_b32 v128, v0, s2, v1 bitop3:0xc8
	v_add_u32_e32 v1, 0x6000, v0
	s_cmp_gt_i32 s1, 31
	v_lshl_add_u64 v[136:137], s[24:25], 0, v[128:129]
	v_and_b32_e32 v128, 0xfe00, v1
	s_cselect_b64 s[0:1], -1, 0
	s_nop 0
	v_lshl_add_u64 v[138:139], s[24:25], 0, v[128:129]
	v_and_b32_e32 v128, 0x3e00, v0
	v_or_b32_e32 v156, 0xfffff800, v178
	v_lshlrev_b32_e32 v132, 4, v231
	v_mov_b32_e32 v133, v129
	v_lshl_add_u64 v[140:141], s[24:25], 0, v[128:129]
	s_mov_b32 s8, 0
	s_xor_b64 s[16:17], s[0:1], -1
	s_mov_b64 s[0:1], 0x8000
	s_barrier
	v_readlane_b32 s18, v252, 9
	v_readlane_b32 s19, v252, 10
	v_readlane_b32 s20, v252, 11
	s_nop 0
	v_readlane_b32 s22, v252, 13
	v_readlane_b32 s23, v252, 14
	s_nop 0
	v_readlane_b32 s27, v252, 18
	v_readlane_b32 s28, v252, 19
	v_readlane_b32 s29, v252, 20
	s_nop 1
	s_branch .LBB0_704

.LBB0_723:
	v_bfe_i32 v2, v8, 27, 1
	v_lshlrev_b32_e32 v0, 4, v8
	v_lshrrev_b32_e32 v2, 22, v2
	v_add_u32_e32 v2, v0, v2
	v_and_b32_e32 v2, 0xfffffc00, v2
	v_sub_u32_e32 v2, v0, v2
	v_ashrrev_i32_e32 v1, 31, v8
	v_lshrrev_b32_e32 v3, 4, v2
	v_lshrrev_b32_e32 v1, 26, v1
	v_bitop3_b32 v3, v3, v2, 32 bitop3:0x6c
	v_ashrrev_i32_e32 v2, 31, v2
	v_add_u32_e32 v1, v8, v1
	v_lshrrev_b32_e32 v2, 26, v2
	v_ashrrev_i32_e32 v1, 6, v1
	v_add_u32_e32 v2, v3, v2
	v_lshlrev_b32_e32 v4, 3, v1
	v_ashrrev_i32_e32 v2, 6, v2
	v_and_b32_e32 v4, -16, v4
	v_mul_i32_i24_e32 v5, 64, v2
	v_add_u32_e32 v4, v2, v4
	v_sub_u32_e32 v3, v3, v5
	v_mov_b32_e32 v5, 1
	v_lshlrev_b32_e32 v1, 5, v1
	v_ashrrev_i16_sdwa v3, v5, sext(v3) dst_sel:DWORD dst_unused:UNUSED_PAD src0_sel:DWORD src1_sel:BYTE_0
	v_lshlrev_b32_e32 v6, 1, v4
	v_lshrrev_b32_e32 v7, 2, v4
	v_and_b32_e32 v2, 3, v2
	s_mov_b32 s3, 0x7fffe0
	v_and_b32_e32 v1, 32, v1
	v_bfe_i32 v3, v3, 0, 16
	v_and_b32_e32 v6, 24, v6
	v_and_b32_e32 v7, 4, v7
	v_and_or_b32 v2, v4, s3, v2
	v_or3_b32 v2, v2, v7, v6
	v_add_lshl_u32 v1, v1, v3, 1
	v_add_u32_e32 v0, 0x2000, v0
	v_lshl_add_u32 v112, v4, 9, v1
	v_lshl_add_u32 v114, v2, 9, v1
	v_ashrrev_i32_e32 v1, 31, v0
	v_lshrrev_b32_e32 v1, 22, v1
	v_add_u32_e32 v1, v0, v1
	v_ashrrev_i32_e32 v1, 10, v1
	v_mul_i32_i24_e32 v2, 0x400, v1
	v_sub_u32_e32 v0, v0, v2
	v_lshrrev_b32_e32 v2, 4, v0
	v_bitop3_b32 v0, v2, v0, 32 bitop3:0x6c
	v_ashrrev_i32_e32 v3, 31, v0
	v_lshrrev_b32_e32 v3, 26, v3
	v_writelane_b32 v252, s16, 45
	v_lshlrev_b32_e32 v2, 3, v1
	v_add_u32_e32 v3, v0, v3
	v_writelane_b32 v252, s17, 46
	v_and_b32_e32 v2, -16, v2
	v_ashrrev_i32_e32 v4, 6, v3
	s_ashr_i32 s2, s4, 6
	v_add_u32_e32 v2, v4, v2
	v_and_b32_e32 v4, 3, v4
	s_ashr_i32 s9, s8, 31
	s_nop 0
	v_readlane_b32 s64, v253, 55
	v_and_or_b32 v4, v2, s3, v4
	s_mov_b32 s60, s4
	s_ashr_i32 s3, s4, 8
	s_lshl_b32 s18, s2, 10
	s_lshl_b64 s[4:5], s[8:9], 17
	v_readlane_b32 s44, v252, 15
	v_readlane_b32 s65, v253, 56
	v_and_b32_e32 v3, 0xc0, v3
	v_readlane_b32 s45, v252, 16
	s_add_u32 s6, s44, s4
	v_readlane_b32 s66, v253, 57
	v_readlane_b32 s67, v253, 58
	v_readlane_b32 s68, v253, 59
	v_readlane_b32 s69, v253, 60
	v_readlane_b32 s70, v253, 61
	v_readlane_b32 s71, v253, 62
	s_mov_b64 s[52:53], s[64:65]
	v_sub_u32_e32 v0, v0, v3
	s_addc_u32 s7, s45, s5
	s_mov_b64 s[58:59], s[70:71]
	v_lshlrev_b32_e32 v1, 5, v1
	v_ashrrev_i16_sdwa v0, v5, sext(v0) dst_sel:DWORD dst_unused:UNUSED_PAD src0_sel:DWORD src1_sel:BYTE_0
	v_lshlrev_b32_e32 v3, 1, v2
	v_lshrrev_b32_e32 v5, 2, v2
	s_add_u32 s10, s58, s0
	v_and_b32_e32 v1, 32, v1
	v_bfe_i32 v0, v0, 0, 16
	v_and_b32_e32 v3, 24, v3
	v_and_b32_e32 v5, 4, v5
	s_addc_u32 s11, s59, s1
	s_add_i32 s19, s18, 0
	v_or3_b32 v3, v4, v5, v3
	v_add_lshl_u32 v0, v1, v0, 1
	s_add_i32 m0, s19, 0x10000
	v_lshl_add_u32 v118, v3, 9, v0
	global_load_lds_dwordx4 v114, s[10:11]
	s_add_i32 m0, s19, 0x12000
	s_add_i32 s20, s19, 0x2000
	global_load_lds_dwordx4 v118, s[10:11]
	s_mov_b32 m0, s19
	s_add_u32 s0, s10, 0x10000
	v_lshl_add_u32 v116, v2, 9, v0
	global_load_lds_dwordx4 v112, s[6:7]
	s_mov_b32 m0, s20
	s_addc_u32 s1, s11, 0
	s_add_i32 s21, s19, 0x14000
	global_load_lds_dwordx4 v116, s[6:7]
	s_mov_b32 m0, s21
	s_add_i32 s26, s19, 0x16000
	global_load_lds_dwordx4 v114, s[0:1]
	s_mov_b32 m0, s26
	v_mov_b32_e32 v121, 0
	global_load_lds_dwordx4 v118, s[0:1]
	s_add_u32 s0, s6, 0x10000
	s_addc_u32 s1, s7, 0
	s_add_i32 s27, s19, 0x4000
	s_mov_b32 m0, s27
	s_add_i32 s28, s19, 0x6000
	global_load_lds_dwordx4 v112, s[0:1]
	s_mov_b32 m0, s28
	v_mov_b32_e32 v115, v121
	global_load_lds_dwordx4 v116, s[0:1]
	v_mov_b32_e32 v119, v121
	v_mov_b32_e32 v113, v121
	v_mov_b32_e32 v117, v121
	v_lshl_add_u64 v[6:7], s[10:11], 0, v[114:115]
	v_lshl_add_u64 v[4:5], s[10:11], 0, v[118:119]
	v_lshl_add_u64 v[2:3], s[6:7], 0, v[112:113]
	s_cmp_lg_u32 s3, 1
	v_lshl_add_u64 v[0:1], s[6:7], 0, v[116:117]
	s_nop 4
	v_readlane_b32 s42, v252, 13
	s_nop 7
	s_nop 6
	s_mov_b64 s[54:55], s[66:67]
	s_mov_b64 s[56:57], s[68:69]
	s_cbranch_scc1 .LBB0_725
	s_barrier
.LBB0_725:
	v_and_b32_e32 v9, 15, v8
	v_bfe_u32 v11, v8, 4, 2
	v_lshl_or_b32 v18, s3, 6, v9
	v_lshlrev_b32_e32 v122, 6, v18
	v_lshlrev_b32_e32 v12, 4, v11
	s_movk_i32 s0, 0x3c0
	v_lshlrev_b32_e32 v8, 2, v8
	s_mov_b64 s[16:17], 0x80
	s_and_b32 s2, s2, 3
	v_and_or_b32 v13, v122, s0, v12
	s_lshl_b32 s0, s3, 13
	v_and_b32_e32 v8, 32, v8
	s_add_i32 m0, s19, 0x18000
	v_lshl_add_u64 v[6:7], v[6:7], 0, s[16:17]
	v_bitop3_b32 v19, v13, s0, v8 bitop3:0xde
	s_lshl_b32 s9, s2, 5
	v_lshl_or_b32 v12, v9, 6, v12
	s_lshl_b32 s0, s2, 12
	s_waitcnt vmcnt(4)
	s_barrier
	global_load_lds_dwordx4 v[6:7], off
	v_lshl_add_u64 v[4:5], v[4:5], 0, s[16:17]
	s_add_i32 m0, s19, 0x1a000
	s_add_i32 s29, s19, 0x8000
	s_add_i32 s30, s19, 0xa000
	v_bitop3_b32 v154, v12, s0, v8 bitop3:0xde
	global_load_lds_dwordx4 v[4:5], off
	v_lshl_add_u64 v[2:3], v[2:3], 0, s[16:17]
	s_mov_b32 m0, s29
	s_add_u32 s0, s10, 0x10080
	global_load_lds_dwordx4 v[2:3], off
	v_lshl_add_u64 v[0:1], v[0:1], 0, s[16:17]
	s_mov_b32 m0, s30
	s_addc_u32 s1, s11, 0
	s_add_i32 s31, s19, 0x1c000
	global_load_lds_dwordx4 v[0:1], off
	v_lshl_add_u64 v[0:1], s[0:1], 0, v[114:115]
	s_mov_b32 m0, s31
	s_add_i32 s33, s19, 0x1e000
	global_load_lds_dwordx4 v[0:1], off
	v_lshl_add_u64 v[0:1], s[0:1], 0, v[118:119]
	s_mov_b32 m0, s33
	v_lshlrev_b32_e32 v10, 3, v11
	global_load_lds_dwordx4 v[0:1], off
	v_lshlrev_b32_e32 v0, 4, v9
	v_cmp_gt_u32_e64 s[0:1], 2, v11
	v_cmp_eq_u32_e32 vcc, 0, v11
	v_lshl_or_b32 v11, s3, 10, v0
	v_min_i32_e32 v0, 0xfe0, v11
	v_or_b32_e32 v2, 0x100, v11
	s_nop 0
	v_ashrrev_i32_e32 v1, 31, v0
	v_min_i32_e32 v2, 0xfe0, v2
	v_or_b32_e32 v4, 0x200, v11
	s_nop 2
	v_readlane_b32 s76, v252, 3
	v_readlane_b32 s77, v252, 4
	v_lshlrev_b64 v[0:1], 6, v[0:1]
	v_ashrrev_i32_e32 v3, 31, v2
	v_min_i32_e32 v4, 0xfe0, v4
	v_or_b32_e32 v6, 0x300, v11
	v_readlane_b32 s78, v252, 5
	v_readlane_b32 s79, v252, 6
	s_mov_b64 s[64:65], s[76:77]
	v_lshlrev_b64 v[2:3], 6, v[2:3]
	v_ashrrev_i32_e32 v5, 31, v4
	v_min_i32_e32 v6, 0xfe0, v6
	v_add_u32_e32 v8, 0x800, v11
	v_lshl_add_u64 v[0:1], s[64:65], 0, v[0:1]
	s_mov_b64 s[34:35], 0x7c0
	v_lshlrev_b64 v[4:5], 6, v[4:5]
	v_ashrrev_i32_e32 v7, 31, v6
	v_min_i32_e32 v8, 0xfe0, v8
	v_add_u32_e32 v12, 0x900, v11
	v_lshl_add_u64 v[134:135], v[0:1], 0, s[34:35]
	v_lshl_add_u64 v[0:1], s[64:65], 0, v[2:3]
	v_lshlrev_b64 v[6:7], 6, v[6:7]
	v_ashrrev_i32_e32 v9, 31, v8
	v_min_i32_e32 v12, 0xfe0, v12
	v_add_u32_e32 v14, 0xa00, v11
	v_lshl_add_u64 v[136:137], v[0:1], 0, s[34:35]
	v_lshl_add_u64 v[0:1], s[64:65], 0, v[4:5]
	v_lshlrev_b64 v[8:9], 6, v[8:9]
	v_ashrrev_i32_e32 v13, 31, v12
	v_min_i32_e32 v14, 0xfe0, v14
	v_add_u32_e32 v11, 0xb00, v11
	v_lshl_add_u64 v[138:139], v[0:1], 0, s[34:35]
	v_lshl_add_u64 v[0:1], s[64:65], 0, v[6:7]
	s_cmp_eq_u32 s2, 0
	v_lshlrev_b64 v[12:13], 6, v[12:13]
	v_ashrrev_i32_e32 v15, 31, v14
	v_min_i32_e32 v16, 0xfe0, v11
	v_lshl_add_u64 v[140:141], v[0:1], 0, s[34:35]
	v_lshl_add_u64 v[0:1], s[64:65], 0, v[8:9]
	s_cselect_b64 s[22:23], -1, 0
	s_cmp_lt_u32 s2, 2
	v_lshlrev_b64 v[14:15], 6, v[14:15]
	v_ashrrev_i32_e32 v17, 31, v16
	v_lshl_add_u64 v[142:143], v[0:1], 0, s[34:35]
	v_lshl_add_u64 v[0:1], s[64:65], 0, v[12:13]
	s_waitcnt vmcnt(6)
	s_cselect_b64 s[24:25], -1, 0
	v_lshlrev_b64 v[16:17], 6, v[16:17]
	v_add_u32_e32 v11, 0xb0, v18
	v_lshl_add_u64 v[144:145], v[0:1], 0, s[34:35]
	v_lshl_add_u64 v[0:1], s[64:65], 0, v[14:15]
	s_add_i32 s53, 0, 0x10000
	s_add_i32 s96, 0, 0x18000
	v_cndmask_b32_e64 v124, 1.0, -1.0, vcc
	s_movk_i32 s2, 0xcf
	v_add_u32_e32 v126, 0x2000, v122
	v_add_u32_e32 v128, 0x2400, v122
	v_add_u32_e32 v130, 0x2800, v122
	s_movk_i32 s4, 0xff
	v_lshlrev_b32_e32 v132, 6, v11
	v_lshl_add_u64 v[146:147], v[0:1], 0, s[34:35]
	v_lshl_add_u64 v[0:1], s[64:65], 0, v[16:17]
	s_add_i32 s93, s53, s18
	s_add_i32 s97, s96, s18
	v_ashrrev_i32_e32 v123, 31, v122
	v_cmp_eq_u32_e64 s[2:3], s2, v18
	v_ashrrev_i32_e32 v127, 31, v126
	v_ashrrev_i32_e32 v129, 31, v128
	v_ashrrev_i32_e32 v131, 31, v130
	v_cmp_eq_u32_e64 s[4:5], s4, v11
	v_ashrrev_i32_e32 v133, 31, v132
	v_lshl_add_u64 v[148:149], v[0:1], 0, s[34:35]
	v_mov_b32_e32 v125, v124
	s_add_i32 s52, s92, s62
	v_add_u32_e32 v155, 0, v19
	s_add_i32 s14, s19, 0xc000
	s_add_i32 s92, s19, 0xe000
	s_mov_b64 s[34:35], 0x100
	s_add_i32 s94, s93, 0x2000
	s_mov_b64 s[40:41], 0x180
	s_lshl_b32 s95, s9, 1
	v_lshlrev_b32_e32 v120, 1, v10
	s_add_i32 s18, s97, 0x2000
	v_mbcnt_hi_u32_b32 v156, -1, v220
	s_mov_b32 s36, s60
	s_barrier
	s_nop 7
	s_mov_b64 s[66:67], s[78:79]
	s_branch .LBB0_727
.LBB0_726:
	v_readlane_b32 s6, v252, 38
	s_nop 0
	s_add_i32 s52, s52, s6
	s_xor_b64 s[6:7], s[54:55], -1
	s_andn2_b64 vcc, exec, s[6:7]
	s_mov_b32 s8, s44
	s_mov_b64 s[10:11], s[58:59]
	s_mov_b64 s[6:7], s[56:57]
	s_cbranch_vccz .LBB0_778

.LBB0_730:
	s_ashr_i32 s45, s44, 31
	s_nop 0
	s_lshl_b64 s[56:57], s[44:45], 17
	v_readlane_b32 s68, v252, 15
	v_readlane_b32 s69, v252, 16
	s_add_u32 s56, s68, s56
	v_add_u32_e32 v157, s53, v154
	s_addc_u32 s57, s69, s57
	ds_read_b128 v[0:3], v157
	ds_read_b128 v[4:7], v157 offset:1024
	s_waitcnt lgkmcnt(0)
	ds_read_b128 v[8:11], v157 offset:2048
	ds_read_b128 v[12:15], v157 offset:3072
	s_nop 7
	s_nop 3
	s_and_b64 s[58:59], s[54:55], exec
	s_cselect_b32 s63, s57, s7
	s_cselect_b32 s62, s56, s6
	s_ashr_i32 s43, s42, 31
	s_nop 0
	s_lshl_b64 s[58:59], s[42:43], 17
	v_readlane_b32 s70, v253, 61
	v_readlane_b32 s71, v253, 62
	s_add_u32 s58, s70, s58
	s_nop 0
	s_addc_u32 s59, s71, s59
	s_and_b64 s[60:61], s[54:55], exec
	s_nop 7
	s_nop 4
	s_cselect_b32 s61, s59, s11
	s_cselect_b32 s60, s58, s10
	s_add_u32 vcc_lo, s6, 0x10080
	s_addc_u32 vcc_hi, s7, 0
	s_mov_b32 m0, s14
	s_waitcnt vmcnt(0)
	v_lshl_add_u64 v[48:49], vcc, 0, v[112:113]
	ds_read_b128 v[16:19], v155
	ds_read_b128 v[20:23], v155 offset:1024
	ds_read_b128 v[24:27], v155 offset:2048
	ds_read_b128 v[28:31], v155 offset:3072
	ds_read_b128 v[32:35], v155 offset:4096
	ds_read_b128 v[36:39], v155 offset:5120
	ds_read_b128 v[40:43], v155 offset:6144
	ds_read_b128 v[44:47], v155 offset:7168
	global_load_lds_dwordx4 v[48:49], off
	v_lshl_add_u64 v[48:49], vcc, 0, v[116:117]
	s_mov_b32 m0, s92
	s_nop 0
	global_load_lds_dwordx4 v[48:49], off
	s_waitcnt lgkmcnt(8)
	s_barrier
	s_waitcnt lgkmcnt(0)
	s_setprio 1
	s_waitcnt lgkmcnt(0)
	v_mfma_f32_16x16x32_bf16 v[48:51], v[0:3], v[16:19], 0
	v_mfma_f32_16x16x32_bf16 v[16:19], v[8:11], v[16:19], 0
	v_mfma_f32_16x16x32_bf16 v[48:51], v[4:7], v[20:23], v[48:51]
	v_mfma_f32_16x16x32_bf16 v[16:19], v[12:15], v[20:23], v[16:19]
	v_mfma_f32_16x16x32_bf16 v[20:23], v[0:3], v[24:27], 0
	v_mfma_f32_16x16x32_bf16 v[24:27], v[8:11], v[24:27], 0
	v_mfma_f32_16x16x32_bf16 v[20:23], v[4:7], v[28:31], v[20:23]
	v_mfma_f32_16x16x32_bf16 v[24:27], v[12:15], v[28:31], v[24:27]
	v_mfma_f32_16x16x32_bf16 v[28:31], v[0:3], v[32:35], 0
	v_mfma_f32_16x16x32_bf16 v[32:35], v[8:11], v[32:35], 0
	v_mfma_f32_16x16x32_bf16 v[28:31], v[4:7], v[36:39], v[28:31]
	v_mfma_f32_16x16x32_bf16 v[32:35], v[12:15], v[36:39], v[32:35]
	v_mfma_f32_16x16x32_bf16 v[36:39], v[0:3], v[40:43], 0
	v_mfma_f32_16x16x32_bf16 v[40:43], v[8:11], v[40:43], 0
	v_mfma_f32_16x16x32_bf16 v[36:39], v[4:7], v[44:47], v[36:39]
	v_mfma_f32_16x16x32_bf16 v[40:43], v[12:15], v[44:47], v[40:43]
	s_setprio 0
	s_barrier
	v_lshl_add_u64 v[150:151], s[10:11], 0, v[114:115]
	s_mov_b32 m0, s93
	v_lshl_add_u64 v[44:45], v[150:151], 0, s[34:35]
	v_lshl_add_u64 v[152:153], s[10:11], 0, v[118:119]
	global_load_lds_dwordx4 v[44:45], off
	v_lshl_add_u64 v[44:45], v[152:153], 0, s[34:35]
	s_mov_b32 m0, s94
	s_nop 0
	global_load_lds_dwordx4 v[44:45], off
	s_barrier
	s_waitcnt lgkmcnt(0)
	s_setprio 1
	s_setprio 0
	v_lshl_add_u64 v[158:159], s[6:7], 0, v[112:113]
	s_mov_b32 m0, s19
	v_lshl_add_u64 v[80:81], v[158:159], 0, s[34:35]
	v_lshl_add_u64 v[162:163], s[6:7], 0, v[116:117]
	s_barrier
	ds_read_b128 v[44:47], v155 offset:16384
	ds_read_b128 v[52:55], v155 offset:17408
	ds_read_b128 v[56:59], v155 offset:18432
	ds_read_b128 v[60:63], v155 offset:19456
	ds_read_b128 v[64:67], v155 offset:20480
	ds_read_b128 v[68:71], v155 offset:21504
	ds_read_b128 v[72:75], v155 offset:22528
	ds_read_b128 v[76:79], v155 offset:23552
	global_load_lds_dwordx4 v[80:81], off
	v_lshl_add_u64 v[80:81], v[162:163], 0, s[34:35]
	s_mov_b32 m0, s20
	s_nop 0
	global_load_lds_dwordx4 v[80:81], off
	s_barrier
	s_waitcnt lgkmcnt(0)
	s_setprio 1
	s_waitcnt lgkmcnt(0)
	v_mfma_f32_16x16x32_bf16 v[80:83], v[0:3], v[44:47], 0
	v_mfma_f32_16x16x32_bf16 v[44:47], v[8:11], v[44:47], 0
	v_mfma_f32_16x16x32_bf16 v[80:83], v[4:7], v[52:55], v[80:83]
	v_mfma_f32_16x16x32_bf16 v[44:47], v[12:15], v[52:55], v[44:47]
	v_mfma_f32_16x16x32_bf16 v[52:55], v[0:3], v[56:59], 0
	v_mfma_f32_16x16x32_bf16 v[56:59], v[8:11], v[56:59], 0
	v_mfma_f32_16x16x32_bf16 v[52:55], v[4:7], v[60:63], v[52:55]
	v_mfma_f32_16x16x32_bf16 v[56:59], v[12:15], v[60:63], v[56:59]
	v_mfma_f32_16x16x32_bf16 v[60:63], v[0:3], v[64:67], 0
	v_mfma_f32_16x16x32_bf16 v[0:3], v[0:3], v[72:75], 0
	v_mfma_f32_16x16x32_bf16 v[60:63], v[4:7], v[68:71], v[60:63]
	v_mfma_f32_16x16x32_bf16 v[64:67], v[8:11], v[64:67], 0
	v_mfma_f32_16x16x32_bf16 v[0:3], v[4:7], v[76:79], v[0:3]
	v_mfma_f32_16x16x32_bf16 v[4:7], v[8:11], v[72:75], 0
	v_mfma_f32_16x16x32_bf16 v[64:67], v[12:15], v[68:71], v[64:67]
	v_mfma_f32_16x16x32_bf16 v[4:7], v[12:15], v[76:79], v[4:7]
	s_setprio 0
	s_barrier
	s_add_u32 vcc_lo, s10, 0x10100
	s_addc_u32 vcc_hi, s11, 0
	s_mov_b32 m0, s21
	v_lshl_add_u64 v[8:9], vcc, 0, v[114:115]
	global_load_lds_dwordx4 v[8:9], off
	v_lshl_add_u64 v[8:9], vcc, 0, v[118:119]
	s_mov_b32 m0, s26
	s_nop 0
	global_load_lds_dwordx4 v[8:9], off
	s_waitcnt vmcnt(6)
	s_barrier
	s_setprio 1
	s_setprio 0
	v_add_u32_e32 v161, s96, v154
	s_barrier
	ds_read_b128 v[8:11], v161
	ds_read_b128 v[12:15], v161 offset:1024
	ds_read_b128 v[68:71], v161 offset:2048
	ds_read_b128 v[72:75], v161 offset:3072
	s_add_u32 vcc_lo, s6, 0x10100
	s_addc_u32 vcc_hi, s7, 0
	s_mov_b32 m0, s27
	v_lshl_add_u64 v[164:165], vcc, 0, v[112:113]
	ds_read_b128 v[76:79], v155 offset:32768
	ds_read_b128 v[84:87], v155 offset:33792
	ds_read_b128 v[88:91], v155 offset:34816
	ds_read_b128 v[92:95], v155 offset:35840
	ds_read_b128 v[96:99], v155 offset:36864
	ds_read_b128 v[100:103], v155 offset:37888
	ds_read_b128 v[104:107], v155 offset:38912
	ds_read_b128 v[108:111], v155 offset:39936
	global_load_lds_dwordx4 v[164:165], off
	v_lshl_add_u64 v[164:165], vcc, 0, v[116:117]
	s_mov_b32 m0, s28
	s_nop 0
	global_load_lds_dwordx4 v[164:165], off
	s_waitcnt lgkmcnt(8)
	s_barrier
	s_waitcnt lgkmcnt(0)
	s_setprio 1
	s_waitcnt lgkmcnt(0)
	v_mfma_f32_16x16x32_bf16 v[48:51], v[8:11], v[76:79], v[48:51]
	v_mfma_f32_16x16x32_bf16 v[16:19], v[68:71], v[76:79], v[16:19]
	v_mfma_f32_16x16x32_bf16 v[20:23], v[8:11], v[88:91], v[20:23]
	v_mfma_f32_16x16x32_bf16 v[24:27], v[68:71], v[88:91], v[24:27]
	v_mfma_f32_16x16x32_bf16 v[28:31], v[8:11], v[96:99], v[28:31]
	v_mfma_f32_16x16x32_bf16 v[32:35], v[68:71], v[96:99], v[32:35]
	v_mfma_f32_16x16x32_bf16 v[36:39], v[8:11], v[104:107], v[36:39]
	v_mfma_f32_16x16x32_bf16 v[40:43], v[68:71], v[104:107], v[40:43]
	v_mfma_f32_16x16x32_bf16 v[48:51], v[12:15], v[84:87], v[48:51]
	v_mfma_f32_16x16x32_bf16 v[16:19], v[72:75], v[84:87], v[16:19]
	v_mfma_f32_16x16x32_bf16 v[20:23], v[12:15], v[92:95], v[20:23]
	v_mfma_f32_16x16x32_bf16 v[24:27], v[72:75], v[92:95], v[24:27]
	v_mfma_f32_16x16x32_bf16 v[28:31], v[12:15], v[100:103], v[28:31]
	v_mfma_f32_16x16x32_bf16 v[32:35], v[72:75], v[100:103], v[32:35]
	v_mfma_f32_16x16x32_bf16 v[36:39], v[12:15], v[108:111], v[36:39]
	v_mfma_f32_16x16x32_bf16 v[40:43], v[72:75], v[108:111], v[40:43]
	s_setprio 0
	s_barrier
	s_mov_b32 m0, s97
	v_lshl_add_u64 v[76:77], v[150:151], 0, s[40:41]
	global_load_lds_dwordx4 v[76:77], off
	v_lshl_add_u64 v[76:77], v[152:153], 0, s[40:41]
	s_mov_b32 m0, s18
	s_nop 0
	global_load_lds_dwordx4 v[76:77], off
	s_barrier
	s_waitcnt lgkmcnt(0)
	s_setprio 1
	s_setprio 0
	s_mov_b32 m0, s29
	v_lshl_add_u64 v[150:151], v[158:159], 0, s[40:41]
	s_barrier
	ds_read_b128 v[76:79], v155 offset:49152
	ds_read_b128 v[84:87], v155 offset:50176
	ds_read_b128 v[88:91], v155 offset:51200
	ds_read_b128 v[92:95], v155 offset:52224
	ds_read_b128 v[96:99], v155 offset:53248
	ds_read_b128 v[100:103], v155 offset:54272
	ds_read_b128 v[104:107], v155 offset:55296
	ds_read_b128 v[108:111], v155 offset:56320
	global_load_lds_dwordx4 v[150:151], off
	v_lshl_add_u64 v[150:151], v[162:163], 0, s[40:41]
	s_mov_b32 m0, s30
	s_nop 0
	global_load_lds_dwordx4 v[150:151], off
	s_barrier
	s_waitcnt lgkmcnt(0)
	s_setprio 1
	s_waitcnt lgkmcnt(0)
	v_mfma_f32_16x16x32_bf16 v[80:83], v[8:11], v[76:79], v[80:83]
	v_mfma_f32_16x16x32_bf16 v[44:47], v[68:71], v[76:79], v[44:47]
	v_mfma_f32_16x16x32_bf16 v[52:55], v[8:11], v[88:91], v[52:55]
	v_mfma_f32_16x16x32_bf16 v[56:59], v[68:71], v[88:91], v[56:59]
	v_mfma_f32_16x16x32_bf16 v[60:63], v[8:11], v[96:99], v[60:63]
	v_mfma_f32_16x16x32_bf16 v[64:67], v[68:71], v[96:99], v[64:67]
	v_mfma_f32_16x16x32_bf16 v[0:3], v[8:11], v[104:107], v[0:3]
	v_mfma_f32_16x16x32_bf16 v[4:7], v[68:71], v[104:107], v[4:7]
	v_mfma_f32_16x16x32_bf16 v[80:83], v[12:15], v[84:87], v[80:83]
	v_mfma_f32_16x16x32_bf16 v[44:47], v[72:75], v[84:87], v[44:47]
	v_mfma_f32_16x16x32_bf16 v[52:55], v[12:15], v[92:95], v[52:55]
	v_mfma_f32_16x16x32_bf16 v[56:59], v[72:75], v[92:95], v[56:59]
	v_mfma_f32_16x16x32_bf16 v[60:63], v[12:15], v[100:103], v[60:63]
	v_mfma_f32_16x16x32_bf16 v[64:67], v[72:75], v[100:103], v[64:67]
	v_mfma_f32_16x16x32_bf16 v[0:3], v[12:15], v[108:111], v[0:3]
	v_mfma_f32_16x16x32_bf16 v[4:7], v[72:75], v[108:111], v[4:7]
	s_setprio 0
	s_barrier
	s_add_u32 s10, s10, 0x10180
	s_addc_u32 s11, s11, 0
	s_mov_b32 m0, s31
	v_lshl_add_u64 v[8:9], s[10:11], 0, v[114:115]
	global_load_lds_dwordx4 v[8:9], off
	v_lshl_add_u64 v[8:9], s[10:11], 0, v[118:119]
	s_mov_b32 m0, s33
	s_nop 0
	global_load_lds_dwordx4 v[8:9], off
	s_waitcnt vmcnt(6)
	s_barrier
	s_setprio 1
	s_setprio 0
	s_barrier
	ds_read_b128 v[8:11], v157
	ds_read_b128 v[12:15], v157 offset:1024
	ds_read_b128 v[68:71], v157 offset:2048
	ds_read_b128 v[72:75], v157 offset:3072
	s_add_u32 s6, s6, 0x10180
	s_addc_u32 s7, s7, 0
	s_mov_b32 m0, s14
	v_lshl_add_u64 v[150:151], s[6:7], 0, v[112:113]
	ds_read_b128 v[76:79], v155
	ds_read_b128 v[84:87], v155 offset:1024
	ds_read_b128 v[88:91], v155 offset:2048
	ds_read_b128 v[92:95], v155 offset:3072
	ds_read_b128 v[96:99], v155 offset:4096
	ds_read_b128 v[100:103], v155 offset:5120
	ds_read_b128 v[104:107], v155 offset:6144
	ds_read_b128 v[108:111], v155 offset:7168
	global_load_lds_dwordx4 v[150:151], off
	v_lshl_add_u64 v[150:151], s[6:7], 0, v[116:117]
	s_mov_b32 m0, s92
	s_nop 0
	global_load_lds_dwordx4 v[150:151], off
	s_waitcnt lgkmcnt(8)
	s_barrier
	s_waitcnt lgkmcnt(0)
	s_setprio 1
	s_waitcnt lgkmcnt(0)
	v_mfma_f32_16x16x32_bf16 v[48:51], v[8:11], v[76:79], v[48:51]
	v_mfma_f32_16x16x32_bf16 v[16:19], v[68:71], v[76:79], v[16:19]
	v_mfma_f32_16x16x32_bf16 v[20:23], v[8:11], v[88:91], v[20:23]
	v_mfma_f32_16x16x32_bf16 v[24:27], v[68:71], v[88:91], v[24:27]
	v_mfma_f32_16x16x32_bf16 v[28:31], v[8:11], v[96:99], v[28:31]
	v_mfma_f32_16x16x32_bf16 v[32:35], v[68:71], v[96:99], v[32:35]
	v_mfma_f32_16x16x32_bf16 v[36:39], v[8:11], v[104:107], v[36:39]
	v_mfma_f32_16x16x32_bf16 v[40:43], v[68:71], v[104:107], v[40:43]
	v_mfma_f32_16x16x32_bf16 v[48:51], v[12:15], v[84:87], v[48:51]
	v_mfma_f32_16x16x32_bf16 v[16:19], v[72:75], v[84:87], v[16:19]
	v_mfma_f32_16x16x32_bf16 v[20:23], v[12:15], v[92:95], v[20:23]
	v_mfma_f32_16x16x32_bf16 v[24:27], v[72:75], v[92:95], v[24:27]
	v_mfma_f32_16x16x32_bf16 v[28:31], v[12:15], v[100:103], v[28:31]
	v_mfma_f32_16x16x32_bf16 v[32:35], v[72:75], v[100:103], v[32:35]
	v_mfma_f32_16x16x32_bf16 v[36:39], v[12:15], v[108:111], v[36:39]
	v_mfma_f32_16x16x32_bf16 v[40:43], v[72:75], v[108:111], v[40:43]
	s_setprio 0
	s_barrier
	s_mov_b32 m0, s93
	v_lshl_add_u64 v[158:159], s[60:61], 0, v[114:115]
	global_load_lds_dwordx4 v[158:159], off
	v_lshl_add_u64 v[170:171], s[60:61], 0, v[118:119]
	s_mov_b32 m0, s94
	s_nop 0
	global_load_lds_dwordx4 v[170:171], off
	s_barrier
	s_waitcnt lgkmcnt(0)
	s_setprio 1
	s_setprio 0
	s_mov_b32 m0, s19
	v_lshl_add_u64 v[172:173], s[62:63], 0, v[112:113]
	s_barrier
	ds_read_b128 v[76:79], v155 offset:16384
	ds_read_b128 v[84:87], v155 offset:17408
	ds_read_b128 v[88:91], v155 offset:18432
	ds_read_b128 v[92:95], v155 offset:19456
	ds_read_b128 v[96:99], v155 offset:20480
	ds_read_b128 v[100:103], v155 offset:21504
	ds_read_b128 v[104:107], v155 offset:22528
	ds_read_b128 v[108:111], v155 offset:23552
	global_load_lds_dwordx4 v[172:173], off
	v_lshl_add_u64 v[176:177], s[62:63], 0, v[116:117]
	s_mov_b32 m0, s20
	s_nop 0
	global_load_lds_dwordx4 v[176:177], off
	s_barrier
	s_waitcnt lgkmcnt(0)
	s_setprio 1
	s_waitcnt lgkmcnt(0)
	v_mfma_f32_16x16x32_bf16 v[52:55], v[8:11], v[88:91], v[52:55]
	v_mfma_f32_16x16x32_bf16 v[80:83], v[8:11], v[76:79], v[80:83]
	v_mfma_f32_16x16x32_bf16 v[44:47], v[68:71], v[76:79], v[44:47]
	v_mfma_f32_16x16x32_bf16 v[76:79], v[12:15], v[92:95], v[52:55]
	v_mfma_f32_16x16x32_bf16 v[52:55], v[68:71], v[88:91], v[56:59]
	v_mfma_f32_16x16x32_bf16 v[56:59], v[72:75], v[92:95], v[52:55]
	v_mfma_f32_16x16x32_bf16 v[52:55], v[8:11], v[96:99], v[60:63]
	v_mfma_f32_16x16x32_bf16 v[60:63], v[12:15], v[100:103], v[52:55]
	v_mfma_f32_16x16x32_bf16 v[52:55], v[68:71], v[96:99], v[64:67]
	v_mfma_f32_16x16x32_bf16 v[0:3], v[8:11], v[104:107], v[0:3]
	v_mfma_f32_16x16x32_bf16 v[4:7], v[68:71], v[104:107], v[4:7]
	v_mfma_f32_16x16x32_bf16 v[80:83], v[12:15], v[84:87], v[80:83]
	v_mfma_f32_16x16x32_bf16 v[44:47], v[72:75], v[84:87], v[44:47]
	v_mfma_f32_16x16x32_bf16 v[64:67], v[72:75], v[100:103], v[52:55]
	v_mfma_f32_16x16x32_bf16 v[0:3], v[12:15], v[108:111], v[0:3]
	v_mfma_f32_16x16x32_bf16 v[4:7], v[72:75], v[108:111], v[4:7]
	s_setprio 0
	s_barrier
	s_add_u32 s6, s60, 0x10000
	s_addc_u32 s7, s61, 0
	s_mov_b32 m0, s21
	v_lshl_add_u64 v[8:9], s[6:7], 0, v[114:115]
	global_load_lds_dwordx4 v[8:9], off
	v_lshl_add_u64 v[8:9], s[6:7], 0, v[118:119]
	s_mov_b32 m0, s26
	s_nop 0
	global_load_lds_dwordx4 v[8:9], off
	s_waitcnt vmcnt(6)
	s_barrier
	s_setprio 1
	s_setprio 0
	s_barrier
	ds_read_b128 v[84:87], v161
	ds_read_b128 v[88:91], v161 offset:1024
	ds_read_b128 v[100:103], v161 offset:2048
	ds_read_b128 v[104:107], v161 offset:3072
	s_add_u32 s6, s62, 0x10000
	s_addc_u32 s7, s63, 0
	s_mov_b32 m0, s27
	v_lshl_add_u64 v[68:69], s[6:7], 0, v[112:113]
	ds_read_b128 v[8:11], v155 offset:32768
	ds_read_b128 v[12:15], v155 offset:33792
	ds_read_b128 v[52:55], v155 offset:34816
	ds_read_b128 v[72:75], v155 offset:35840
	ds_read_b128 v[108:111], v155 offset:36864
	ds_read_b128 v[150:153], v155 offset:37888
	ds_read_b128 v[162:165], v155 offset:38912
	ds_read_b128 v[166:169], v155 offset:39936
	global_load_lds_dwordx4 v[68:69], off
	v_lshl_add_u64 v[68:69], s[6:7], 0, v[116:117]
	s_mov_b32 m0, s28
	s_nop 0
	global_load_lds_dwordx4 v[68:69], off
	s_waitcnt lgkmcnt(8)
	s_barrier
	s_waitcnt lgkmcnt(0)
	s_setprio 1
	s_waitcnt lgkmcnt(0)
	v_mfma_f32_16x16x32_bf16 v[48:51], v[84:87], v[8:11], v[48:51]
	v_mfma_f32_16x16x32_bf16 v[8:11], v[100:103], v[8:11], v[16:19]
	v_mfma_f32_16x16x32_bf16 v[96:99], v[104:107], v[12:15], v[8:11]
	v_mfma_f32_16x16x32_bf16 v[8:11], v[84:87], v[52:55], v[20:23]
	v_mfma_f32_16x16x32_bf16 v[68:71], v[88:91], v[72:75], v[8:11]
	v_mfma_f32_16x16x32_bf16 v[8:11], v[100:103], v[52:55], v[24:27]
	v_mfma_f32_16x16x32_bf16 v[72:75], v[104:107], v[72:75], v[8:11]
	v_mfma_f32_16x16x32_bf16 v[8:11], v[84:87], v[108:111], v[28:31]
	v_mfma_f32_16x16x32_bf16 v[92:95], v[88:91], v[12:15], v[48:51]
	v_mfma_f32_16x16x32_bf16 v[48:51], v[88:91], v[150:153], v[8:11]
	v_mfma_f32_16x16x32_bf16 v[8:11], v[100:103], v[108:111], v[32:35]
	v_mfma_f32_16x16x32_bf16 v[52:55], v[104:107], v[150:153], v[8:11]
	v_mfma_f32_16x16x32_bf16 v[8:11], v[84:87], v[162:165], v[36:39]
	v_mfma_f32_16x16x32_bf16 v[32:35], v[88:91], v[166:169], v[8:11]
	v_mfma_f32_16x16x32_bf16 v[8:11], v[100:103], v[162:165], v[40:43]
	v_mfma_f32_16x16x32_bf16 v[36:39], v[104:107], v[166:169], v[8:11]
	s_setprio 0
	s_barrier
	s_mov_b32 m0, s97
	s_nop 3
	v_lshl_add_u64 v[8:9], v[158:159], 0, s[16:17]
	global_load_lds_dwordx4 v[8:9], off
	v_lshl_add_u64 v[8:9], v[170:171], 0, s[16:17]
	s_mov_b32 m0, s18
	s_nop 0
	global_load_lds_dwordx4 v[8:9], off
	s_barrier
	s_waitcnt lgkmcnt(0)
	s_setprio 1
	s_setprio 0
	s_mov_b32 m0, s29
	v_lshl_add_u64 v[16:17], v[172:173], 0, s[16:17]
	s_barrier
	ds_read_b128 v[8:11], v155 offset:49152
	ds_read_b128 v[12:15], v155 offset:50176
	ds_read_b128 v[20:23], v155 offset:51200
	ds_read_b128 v[40:43], v155 offset:52224
	ds_read_b128 v[108:111], v155 offset:53248
	ds_read_b128 v[150:153], v155 offset:54272
	ds_read_b128 v[162:165], v155 offset:55296
	ds_read_b128 v[166:169], v155 offset:56320
	global_load_lds_dwordx4 v[16:17], off
	v_lshl_add_u64 v[16:17], v[176:177], 0, s[16:17]
	s_mov_b32 m0, s30
	s_nop 0
	global_load_lds_dwordx4 v[16:17], off
	s_barrier
	s_waitcnt lgkmcnt(0)
	s_setprio 1
	s_waitcnt lgkmcnt(0)
	v_mfma_f32_16x16x32_bf16 v[16:19], v[84:87], v[8:11], v[80:83]
	v_mfma_f32_16x16x32_bf16 v[8:11], v[100:103], v[8:11], v[44:47]
	v_mfma_f32_16x16x32_bf16 v[28:31], v[104:107], v[12:15], v[8:11]
	v_mfma_f32_16x16x32_bf16 v[8:11], v[84:87], v[20:23], v[76:79]
	v_mfma_f32_16x16x32_bf16 v[24:27], v[88:91], v[12:15], v[16:19]
	v_mfma_f32_16x16x32_bf16 v[16:19], v[88:91], v[40:43], v[8:11]
	v_mfma_f32_16x16x32_bf16 v[8:11], v[100:103], v[20:23], v[56:59]
	v_mfma_f32_16x16x32_bf16 v[20:23], v[104:107], v[40:43], v[8:11]
	v_mfma_f32_16x16x32_bf16 v[8:11], v[84:87], v[108:111], v[60:63]
	v_mfma_f32_16x16x32_bf16 v[12:15], v[100:103], v[108:111], v[64:67]
	v_mfma_f32_16x16x32_bf16 v[0:3], v[84:87], v[162:165], v[0:3]
	v_mfma_f32_16x16x32_bf16 v[4:7], v[100:103], v[162:165], v[4:7]
	v_mfma_f32_16x16x32_bf16 v[8:11], v[88:91], v[150:153], v[8:11]
	v_mfma_f32_16x16x32_bf16 v[12:15], v[104:107], v[150:153], v[12:15]
	v_mfma_f32_16x16x32_bf16 v[0:3], v[88:91], v[166:169], v[0:3]
	v_mfma_f32_16x16x32_bf16 v[4:7], v[104:107], v[166:169], v[4:7]
	s_setprio 0
	s_barrier
	s_add_u32 s6, s60, 0x10080
	s_addc_u32 s7, s61, 0
	s_mov_b32 m0, s31
	v_lshl_add_u64 v[40:41], s[6:7], 0, v[114:115]
	global_load_lds_dwordx4 v[40:41], off
	v_lshl_add_u64 v[40:41], s[6:7], 0, v[118:119]
	s_mov_b32 m0, s33
	s_nop 0
	global_load_lds_dwordx4 v[40:41], off
	s_waitcnt vmcnt(6)
	s_barrier
	s_setprio 1
	s_setprio 0
	s_barrier
	global_load_dwordx4 v[88:91], v[136:137], off offset:48
	global_load_dwordx4 v[100:103], v[136:137], off offset:32
	global_load_dwordx4 v[104:107], v[136:137], off offset:16
	global_load_dwordx4 v[108:111], v[136:137], off
	global_load_dwordx4 v[64:67], v[138:139], off offset:48
	global_load_dwordx4 v[76:79], v[138:139], off offset:32
	global_load_dwordx4 v[80:83], v[138:139], off offset:16
	global_load_dwordx4 v[84:87], v[138:139], off
	global_load_dwordx4 v[40:43], v[140:141], off offset:48
	global_load_dwordx4 v[44:47], v[140:141], off offset:32
	global_load_dwordx4 v[56:59], v[140:141], off offset:16
	global_load_dwordx4 v[60:63], v[140:141], off
	s_cmp_lt_u32 s8, 16
	s_cselect_b64 s[10:11], -1, 0
	s_and_b64 s[60:61], s[22:23], s[10:11]
	v_cndmask_b32_e64 v150, 0, 1, s[60:61]
	v_cmp_ne_u32_e64 s[6:7], 1, v150
	s_andn2_b64 vcc, exec, s[60:61]
	s_cbranch_vccnz .LBB0_734
	v_and_b32_e32 v151, 64, v156
	v_xor_b32_e32 v150, 16, v156
	v_add_u32_e32 v151, 64, v151
	v_cmp_lt_i32_e32 vcc, v150, v151
	s_nop 1
	v_cndmask_b32_e32 v150, v156, v150, vcc
	v_lshlrev_b32_e32 v157, 2, v150
	ds_bpermute_b32 v152, v157, v92
	ds_bpermute_b32 v150, v157, v96
	ds_bpermute_b32 v153, v157, v93
	ds_bpermute_b32 v151, v157, v97
	ds_bpermute_b32 v161, v157, v94
	ds_bpermute_b32 v158, v157, v98
	ds_bpermute_b32 v159, v157, v95
	ds_bpermute_b32 v157, v157, v99
	s_and_saveexec_b64 s[60:61], s[0:1]
	s_cbranch_execz .LBB0_733
	global_load_dwordx4 v[162:165], v[134:135], off offset:48
	global_load_dwordx4 v[166:169], v[134:135], off offset:32
	global_load_dwordx4 v[170:173], v[134:135], off offset:16
	global_load_dwordx4 v[180:183], v[134:135], off
	s_waitcnt lgkmcnt(0)
	v_pk_mul_f32 v[152:153], v[124:125], v[152:153]
	v_mul_f32_e32 v158, v124, v158
	v_mul_f32_e32 v161, v124, v161
	v_pk_mul_f32 v[150:151], v[124:125], v[150:151]
	s_waitcnt vmcnt(0)
	v_mul_f32_e32 v98, v98, v162
	v_mul_f32_e32 v158, v163, v158
	v_mul_f32_e32 v163, v124, v157
	v_mov_b32_e32 v177, v182
	v_mov_b32_e32 v182, v181
	v_mov_b32_e32 v176, v180
	v_pk_mul_f32 v[152:153], v[182:183], v[152:153]
	v_mul_f32_e32 v181, v124, v159
	v_mov_b32_e32 v180, v95
	v_mov_b32_e32 v162, v99
	v_pk_mul_f32 v[172:173], v[172:173], v[180:181]
	v_pk_fma_f32 v[92:93], v[92:93], v[176:177], v[152:153]
	v_mov_b32_e32 v153, v168
	v_mov_b32_e32 v168, v167
	v_pk_mul_f32 v[162:163], v[164:165], v[162:163]
	v_mul_f32_e32 v94, v94, v170
	v_mul_f32_e32 v170, v171, v161
	v_mov_b32_e32 v95, v172
	v_mov_b32_e32 v171, v173
	v_mov_b32_e32 v152, v166
	v_pk_mul_f32 v[150:151], v[168:169], v[150:151]
	v_mov_b32_e32 v99, v162
	v_mov_b32_e32 v159, v163
	v_pk_add_f32 v[94:95], v[94:95], v[170:171]
	v_pk_fma_f32 v[96:97], v[96:97], v[152:153], v[150:151]
	v_pk_add_f32 v[98:99], v[98:99], v[158:159]

.LBB0_734:
	s_nop 0
	s_and_b64 s[10:11], s[10:11], exec
	v_readlane_b32 s70, v252, 17
	v_readlane_b32 s71, v252, 18
	v_readlane_b32 s72, v252, 19
	v_readlane_b32 s73, v252, 20
	s_cselect_b32 s9, s71, s73
	s_cselect_b32 s10, s70, s72
	s_lshl_b32 s8, s8, 15
	s_and_b32 s8, s8, 0x78000
	s_add_u32 s8, s10, s8
	s_addc_u32 s9, s9, 0
	s_add_u32 s8, s8, s95
	s_addc_u32 s9, s9, 0
	s_waitcnt lgkmcnt(0)
	v_lshl_add_u64 v[150:151], s[8:9], 0, v[120:121]
	v_cndmask_b32_e64 v152, 0, 1, s[24:25]
	v_cmp_ne_u32_e64 s[8:9], 1, v152
	s_andn2_b64 vcc, exec, s[24:25]
	v_lshl_add_u64 v[152:153], v[122:123], 1, v[150:151]
	s_nop 7
	s_nop 2
	s_cbranch_vccnz .LBB0_758
	v_cvt_pk_bf16_f32 v92, v92, v93
	v_cvt_pk_bf16_f32 v93, v94, v95
	v_cvt_pk_bf16_f32 v94, v96, v97
	v_cvt_pk_bf16_f32 v95, v98, v99
	global_store_dwordx4 v[152:153], v[92:95], off
	s_and_b64 vcc, exec, s[6:7]
	s_cbranch_vccz .LBB0_759

.LBB0_790:
	s_movk_i32 s0, 0xfee0
	s_nop 1
	v_lshl_add_u32 v1, s19, 1, v175
	v_cmp_gt_i32_e32 vcc, s0, v28
	s_movk_i32 s0, 0xfedf
	v_readlane_b32 s38, v253, 4
	v_readlane_b32 s39, v253, 5
	v_readlane_b32 s40, v253, 6
	v_readlane_b32 s41, v253, 7
	v_readlane_b32 s72, v253, 42
	v_readlane_b32 s73, v253, 43
	v_add_u32_e32 v0, 0x520, v1
	v_cmp_lt_i32_e64 s[0:1], s0, v28
	v_mov_b32_e32 v13, 0x400
	v_mov_b32_e32 v20, 0xf18
	v_mov_b64_e32 v[8:9], s[38:39]
	s_nop 6
	v_mov_b64_e32 v[6:7], s[72:73]
	v_mov_b64_e32 v[10:11], s[40:41]
	s_mov_b64 s[6:7], 0
	s_nop 7
	s_nop 7
	s_nop 0
	s_and_saveexec_b64 s[4:5], s[0:1]
	v_readlane_b32 s64, v253, 55
	v_readlane_b32 s65, v253, 56
	v_readlane_b32 s66, v253, 57
	v_readlane_b32 s67, v253, 58
	v_readlane_b32 s68, v253, 59
	v_readlane_b32 s69, v253, 60
	v_readlane_b32 s70, v253, 61
	v_readlane_b32 s71, v253, 62
	s_nop 7
	s_cbranch_execz .LBB0_818
	s_mov_b64 s[8:9], s[64:65]
	s_nop 0
	s_mov_b64 s[12:13], s[68:69]
	v_add_u32_e32 v2, 0x520, v28
	s_movk_i32 s0, 0x47f
	v_readlane_b32 s46, v253, 12
	v_readlane_b32 s47, v253, 13
	s_mov_b64 s[10:11], s[66:67]
	s_mov_b64 s[14:15], s[70:71]
	v_cmp_lt_u32_e64 s[0:1], s0, v2
	v_mov_b64_e32 v[10:11], s[46:47]
	v_mov_b64_e32 v[6:7], s[12:13]
	s_nop 7
	s_nop 4
	s_and_saveexec_b64 s[6:7], s[0:1]
	s_xor_b64 s[6:7], exec, s[6:7]
	s_cbranch_execz .LBB0_815
	s_nop 0
	s_movk_i32 s0, 0x4ff
	v_readlane_b32 s50, v253, 16
	v_readlane_b32 s51, v253, 17
	v_cmp_lt_u32_e64 s[0:1], s0, v2
	s_nop 0
	v_mov_b64_e32 v[10:11], s[50:51]
	s_nop 7
	s_nop 3
	s_and_saveexec_b64 s[8:9], s[0:1]
	s_xor_b64 s[8:9], exec, s[8:9]
	s_cbranch_execz .LBB0_812
	s_nop 0
	s_movk_i32 s0, 0x50f
	v_readlane_b32 s48, v253, 14
	v_readlane_b32 s49, v253, 15
	v_cmp_lt_u32_e64 s[0:1], s0, v2
	v_mov_b64_e32 v[6:7], s[14:15]
	v_mov_b64_e32 v[10:11], s[48:49]
	s_nop 7
	s_nop 4
	s_and_saveexec_b64 s[12:13], s[0:1]
	s_xor_b64 s[12:13], exec, s[12:13]
	s_cbranch_execz .LBB0_809
	v_readlane_b32 s36, v253, 18
	s_movk_i32 s0, 0xfae0
	v_readlane_b32 s37, v253, 19
	v_cmp_gt_u32_e64 s[0:1], s0, v28
	s_nop 0
	v_mov_b64_e32 v[10:11], s[36:37]
	s_nop 7
	s_nop 4
	s_and_saveexec_b64 s[14:15], s[0:1]
	s_xor_b64 s[14:15], exec, s[14:15]
	s_cbranch_execz .LBB0_806
	s_nop 1
	s_movk_i32 s0, 0x59f
	v_readlane_b32 s38, v253, 20
	v_readlane_b32 s39, v253, 21
	v_readlane_b32 s74, v253, 44
	v_readlane_b32 s75, v253, 45
	v_cmp_lt_u32_e64 s[0:1], s0, v2
	s_mov_b64 s[10:11], 0
	v_mov_b32_e32 v20, 0x400
	v_mov_b32_e32 v13, 0x200
	v_mov_b64_e32 v[8:9], 0
	v_mov_b64_e32 v[10:11], s[38:39]
	v_mov_b64_e32 v[6:7], s[74:75]
	v_mov_b32_e32 v0, v28
	s_nop 7
	s_nop 7
	s_nop 7
	s_nop 1
	s_and_saveexec_b64 s[16:17], s[0:1]
	s_cbranch_execz .LBB0_805
	s_nop 1
	s_movk_i32 s0, 0x69f
	v_readlane_b32 s46, v253, 28
	v_readlane_b32 s47, v253, 29
	v_readlane_b32 s78, v253, 48
	v_readlane_b32 s79, v253, 49
	v_cmp_lt_u32_e64 s[0:1], s0, v2
	v_mov_b64_e32 v[10:11], s[46:47]
	s_nop 6
	v_mov_b64_e32 v[6:7], s[78:79]
	s_nop 7
	s_nop 7
	s_nop 2
	s_and_saveexec_b64 s[20:21], s[0:1]
	v_readlane_b32 s64, v253, 55
	s_xor_b64 s[22:23], exec, s[20:21]
	v_readlane_b32 s65, v253, 56
	v_readlane_b32 s66, v253, 57
	v_readlane_b32 s67, v253, 58
	v_readlane_b32 s68, v253, 59
	v_readlane_b32 s69, v253, 60
	v_readlane_b32 s70, v253, 61
	v_readlane_b32 s71, v253, 62
	s_nop 7
	s_cbranch_execz .LBB0_802
	s_nop 0
	s_mov_b64 s[52:53], s[64:65]
	s_movk_i32 s0, 0xa9f
	v_readlane_b32 s48, v253, 30
	v_readlane_b32 s49, v253, 31
	v_readlane_b32 s50, v253, 32
	v_readlane_b32 s51, v253, 33
	v_cmp_lt_u32_e64 s[0:1], s0, v2
	v_mov_b64_e32 v[6:7], s[52:53]
	v_mov_b64_e32 v[10:11], s[50:51]
	v_mov_b64_e32 v[8:9], s[48:49]
	s_mov_b64 s[54:55], s[66:67]
	s_mov_b64 s[56:57], s[68:69]
	s_mov_b64 s[58:59], s[70:71]
	s_nop 7
	s_nop 2
	s_and_saveexec_b64 s[10:11], s[0:1]
	s_xor_b64 s[0:1], exec, s[10:11]
	s_cbranch_execz .LBB0_799
	v_readlane_b32 s64, v253, 34
	v_readlane_b32 s65, v253, 35
	s_nop 7
	s_nop 5
	v_mov_b64_e32 v[10:11], s[64:65]
	v_readlane_b32 s64, v253, 55
	v_readlane_b32 s65, v253, 56
	v_readlane_b32 s66, v253, 57
	v_readlane_b32 s67, v253, 58
	v_readlane_b32 s68, v253, 59
	v_readlane_b32 s69, v253, 60
	v_readlane_b32 s70, v253, 61
	v_readlane_b32 s71, v253, 62
	s_mov_b64 s[52:53], s[64:65]
	s_mov_b64 s[54:55], s[66:67]
	v_add_u32_e32 v0, 0xfffffa80, v1
	v_mov_b64_e32 v[8:9], 0
	s_nop 7
	s_mov_b64 s[56:57], s[68:69]
	s_mov_b64 s[58:59], s[70:71]
	v_mov_b64_e32 v[6:7], s[54:55]

.LBB0_805:
	s_or_b64 exec, exec, s[16:17]
	s_nop 0
	s_nop 7
	s_nop 6

.LBB0_843:
	s_movk_i32 s0, 0xfee0
	s_nop 1
	v_lshl_add_u32 v1, s18, 1, v175
	v_cmp_gt_i32_e32 vcc, s0, v28
	s_movk_i32 s0, 0xfedf
	v_readlane_b32 s38, v253, 4
	v_readlane_b32 s39, v253, 5
	v_readlane_b32 s40, v253, 6
	v_readlane_b32 s41, v253, 7
	v_readlane_b32 s72, v253, 42
	v_readlane_b32 s73, v253, 43
	v_add_u32_e32 v0, 0x520, v1
	v_cmp_lt_i32_e64 s[0:1], s0, v28
	v_mov_b32_e32 v13, 0x400
	v_mov_b32_e32 v20, 0xf18
	v_mov_b64_e32 v[8:9], s[38:39]
	s_nop 6
	v_mov_b64_e32 v[6:7], s[72:73]
	v_mov_b64_e32 v[10:11], s[40:41]
	s_mov_b64 s[4:5], 0
	s_nop 7
	s_nop 7
	s_nop 0
	s_and_saveexec_b64 s[2:3], s[0:1]
	v_readlane_b32 s64, v253, 55
	v_readlane_b32 s65, v253, 56
	v_readlane_b32 s66, v253, 57
	v_readlane_b32 s67, v253, 58
	v_readlane_b32 s68, v253, 59
	v_readlane_b32 s69, v253, 60
	v_readlane_b32 s70, v253, 61
	v_readlane_b32 s71, v253, 62
	s_nop 7
	s_cbranch_execz .LBB0_871
	s_mov_b64 s[8:9], s[64:65]
	s_nop 0
	s_mov_b64 s[12:13], s[68:69]
	v_add_u32_e32 v2, 0x520, v28
	s_movk_i32 s0, 0x47f
	v_readlane_b32 s46, v253, 12
	v_readlane_b32 s47, v253, 13
	s_mov_b64 s[14:15], s[70:71]
	v_cmp_lt_u32_e64 s[0:1], s0, v2
	v_mov_b64_e32 v[10:11], s[46:47]
	v_mov_b64_e32 v[6:7], s[12:13]
	s_mov_b64 s[10:11], s[66:67]
	s_nop 7
	s_nop 4
	s_and_saveexec_b64 s[4:5], s[0:1]
	s_xor_b64 s[4:5], exec, s[4:5]
	s_cbranch_execz .LBB0_868
	s_nop 0
	s_movk_i32 s0, 0x4ff
	v_readlane_b32 s50, v253, 16
	v_readlane_b32 s51, v253, 17
	v_cmp_lt_u32_e64 s[0:1], s0, v2
	s_nop 0
	v_mov_b64_e32 v[10:11], s[50:51]
	s_nop 7
	s_nop 3
	s_and_saveexec_b64 s[6:7], s[0:1]
	s_xor_b64 s[6:7], exec, s[6:7]
	s_cbranch_execz .LBB0_865
	s_nop 0
	s_movk_i32 s0, 0x50f
	v_readlane_b32 s48, v253, 14
	v_readlane_b32 s49, v253, 15
	v_cmp_lt_u32_e64 s[0:1], s0, v2
	v_mov_b64_e32 v[6:7], s[14:15]
	v_mov_b64_e32 v[10:11], s[48:49]
	s_nop 7
	s_nop 4
	s_and_saveexec_b64 s[10:11], s[0:1]
	s_xor_b64 s[10:11], exec, s[10:11]
	s_cbranch_execz .LBB0_862
	v_readlane_b32 s36, v253, 18
	s_movk_i32 s0, 0xfae0
	v_readlane_b32 s37, v253, 19
	v_cmp_gt_u32_e64 s[0:1], s0, v28
	s_nop 0
	v_mov_b64_e32 v[10:11], s[36:37]
	s_nop 7
	s_nop 4
	s_and_saveexec_b64 s[12:13], s[0:1]
	s_xor_b64 s[12:13], exec, s[12:13]
	s_cbranch_execz .LBB0_859
	s_nop 1
	s_movk_i32 s0, 0x59f
	v_readlane_b32 s38, v253, 20
	v_readlane_b32 s39, v253, 21
	v_readlane_b32 s74, v253, 44
	v_readlane_b32 s75, v253, 45
	v_cmp_lt_u32_e64 s[0:1], s0, v2
	s_mov_b64 s[8:9], 0
	v_mov_b32_e32 v20, 0x400
	v_mov_b32_e32 v13, 0x200
	v_mov_b64_e32 v[8:9], 0
	v_mov_b64_e32 v[10:11], s[38:39]
	v_mov_b64_e32 v[6:7], s[74:75]
	v_mov_b32_e32 v0, v28
	s_nop 7
	s_nop 7
	s_nop 7
	s_nop 1
	s_and_saveexec_b64 s[14:15], s[0:1]
	s_cbranch_execz .LBB0_858
	s_nop 1
	s_movk_i32 s0, 0x69f
	v_readlane_b32 s46, v253, 28
	v_readlane_b32 s47, v253, 29
	v_readlane_b32 s78, v253, 48
	v_readlane_b32 s79, v253, 49
	v_cmp_lt_u32_e64 s[0:1], s0, v2
	v_mov_b64_e32 v[10:11], s[46:47]
	s_nop 6
	v_mov_b64_e32 v[6:7], s[78:79]
	s_nop 7
	s_nop 7
	s_nop 2
	s_and_saveexec_b64 s[16:17], s[0:1]
	v_readlane_b32 s64, v253, 55
	s_xor_b64 s[16:17], exec, s[16:17]
	v_readlane_b32 s65, v253, 56
	v_readlane_b32 s66, v253, 57
	v_readlane_b32 s67, v253, 58
	v_readlane_b32 s68, v253, 59
	v_readlane_b32 s69, v253, 60
	v_readlane_b32 s70, v253, 61
	v_readlane_b32 s71, v253, 62
	s_nop 7
	s_cbranch_execz .LBB0_855
	s_nop 0
	s_mov_b64 s[52:53], s[64:65]
	s_movk_i32 s0, 0xa9f
	v_readlane_b32 s48, v253, 30
	v_readlane_b32 s49, v253, 31
	v_readlane_b32 s50, v253, 32
	v_readlane_b32 s51, v253, 33
	v_cmp_lt_u32_e64 s[0:1], s0, v2
	v_mov_b64_e32 v[6:7], s[52:53]
	v_mov_b64_e32 v[10:11], s[50:51]
	v_mov_b64_e32 v[8:9], s[48:49]
	s_mov_b64 s[54:55], s[66:67]
	s_mov_b64 s[56:57], s[68:69]
	s_mov_b64 s[58:59], s[70:71]
	s_nop 7
	s_nop 2
	s_and_saveexec_b64 s[8:9], s[0:1]
	s_xor_b64 s[0:1], exec, s[8:9]
	s_cbranch_execz .LBB0_852
	v_readlane_b32 s64, v253, 34
	v_readlane_b32 s65, v253, 35
	s_nop 7
	s_nop 5
	v_mov_b64_e32 v[10:11], s[64:65]
	v_readlane_b32 s64, v253, 55
	v_readlane_b32 s65, v253, 56
	v_readlane_b32 s66, v253, 57
	v_readlane_b32 s67, v253, 58
	v_readlane_b32 s68, v253, 59
	v_readlane_b32 s69, v253, 60
	v_readlane_b32 s70, v253, 61
	v_readlane_b32 s71, v253, 62
	s_mov_b64 s[52:53], s[64:65]
	s_mov_b64 s[54:55], s[66:67]
	v_add_u32_e32 v0, 0xfffffa80, v1
	v_mov_b64_e32 v[8:9], 0
	s_nop 7
	s_mov_b64 s[56:57], s[68:69]
	s_mov_b64 s[58:59], s[70:71]
	v_mov_b64_e32 v[6:7], s[54:55]

.LBB0_858:
	s_or_b64 exec, exec, s[14:15]
	s_nop 0
	s_nop 7
	s_nop 6

.LBB0_947:
	s_bitcmp0_b32 s33, 0
	s_cselect_b32 s1, s2, s64
	s_add_i32 s0, s1, s0
	s_cmpk_gt_i32 s0, 0x3ff
	s_cbranch_scc1 .LBB0_946
	s_ashr_i32 s75, s0, 4
	v_mov_b32 v213, v178
	s_sub_i32 s97, 63, s75
	v_ashrrev_i32_e32 v210, 6, v213
	v_lshlrev_b32_e32 v194, 3, v210
	v_bfe_u32 v195, v213, 2, 3
	s_lshl_b32 s92, s97, 6
	v_or_b32_e32 v211, v194, v195
	v_add_u32_e32 v148, s92, v211
	s_lshl_b32 s1, s0, 11
	s_and_b32 s68, s1, 0x7000
	v_ashrrev_i32_e32 v149, 31, v148
	s_and_b32 s76, s0, 15
	v_lshl_add_u64 v[2:3], v[148:149], 0, s[68:69]
	s_nop 0
	s_lshl_b32 s0, s0, 2
	v_and_b32_e32 v155, 3, v213
	v_lshlrev_b64 v[4:5], 10, v[2:3]
	v_readlane_b32 s18, v252, 5
	v_readlane_b32 s19, v252, 6
	s_and_b32 s2, s0, 4
	v_bfe_u32 v185, v213, 5, 1
	v_lshl_add_u64 v[6:7], s[18:19], 0, v[4:5]
	v_or_b32_e32 v4, s2, v155
	v_lshlrev_b32_e32 v0, 7, v4
	v_lshl_add_u64 v[6:7], v[6:7], 0, v[0:1]
	v_lshlrev_b32_e32 v0, 4, v185
	v_lshl_add_u64 v[6:7], v[6:7], 0, v[0:1]
	global_load_dwordx4 v[130:133], v[6:7], off
	global_load_dwordx4 v[134:137], v[6:7], off offset:32
	global_load_dwordx4 v[138:141], v[6:7], off offset:64
	global_load_dwordx4 v[142:145], v[6:7], off offset:96
	s_nop 7
	s_nop 5
	v_readlane_b32 s6, v252, 9
	v_readlane_b32 s7, v252, 10
	s_lshl_b32 s68, s2, 2
	v_readlane_b32 s14, v252, 17
	v_mov_b64_e32 v[6:7], s[6:7]
	v_mad_u64_u32 v[6:7], s[0:1], v2, s65, v[6:7]
	v_mad_i32_i24 v7, v3, s65, v7
	v_lshl_add_u64 v[6:7], v[6:7], 0, s[68:69]
	v_lshlrev_b32_e32 v0, 2, v155
	s_lshl_b32 s2, s76, 15
	v_readlane_b32 s15, v252, 18
	v_lshl_add_u64 v[6:7], v[6:7], 0, v[0:1]
	s_add_u32 s0, s14, s2
	v_readlane_b32 s16, v252, 19
	global_load_dword v0, v[6:7], off
	global_load_dword v208, v[6:7], off offset:32
	global_load_dword v149, v[6:7], off offset:64
	s_addc_u32 s1, s15, 0
	v_lshrrev_b32_e32 v5, 5, v213
	v_bfe_u32 v14, v213, 1, 3
	v_lshrrev_b32_e32 v6, 4, v213
	v_readlane_b32 s17, v252, 20
	s_add_u32 s2, s16, s2
	v_bitop3_b32 v5, v5, v14, 1 bitop3:0x6c
	v_lshlrev_b32_e32 v214, 3, v213
	v_xor_b32_e32 v6, v6, v213
	s_addc_u32 s3, s17, 0
	s_sub_i32 s4, s92, 31
	v_lshlrev_b32_e32 v186, 4, v5
	v_and_b32_e32 v5, 0xffffffc0, v214
	v_lshlrev_b32_e32 v6, 3, v6
	s_ashr_i32 s93, s4, 4
	v_and_or_b32 v150, v6, 56, v5
	v_lshlrev_b32_e32 v209, 4, v213
	s_mov_b32 s4, 0x1ffffffc
	v_and_b32_e32 v5, 0xfc0, v209
	v_and_or_b32 v6, v210, s4, v155
	v_ashrrev_i32_e32 v151, 31, v150
	v_add_u32_e32 v187, 0, v209
	s_lshr_b32 s77, s97, 4
	v_lshl_add_u32 v152, v6, 3, v5
	v_lshl_add_u64 v[6:7], v[150:151], 1, s[0:1]
	v_readfirstlane_b32 s0, v187
	v_add_u32_e32 v199, 0x2000, v187
	v_ashrrev_i32_e32 v153, 31, v152
	s_mov_b32 m0, s0
	v_readfirstlane_b32 s0, v199
	s_cmp_gt_u32 s97, 15
	v_add_u32_e32 v200, 0x4000, v187
	v_lshl_add_u64 v[8:9], v[152:153], 1, s[2:3]
	global_load_lds_dwordx4 v[6:7], off
	s_mov_b32 m0, s0
	s_cselect_b32 s68, 0x2000, 0
	v_readfirstlane_b32 s0, v200
	v_add_u32_e32 v202, 0x6000, v187
	global_load_lds_dwordx4 v[8:9], off
	v_lshl_add_u64 v[10:11], v[6:7], 0, s[68:69]
	s_mov_b32 m0, s0
	v_readfirstlane_b32 s0, v202
	global_load_lds_dwordx4 v[10:11], off
	s_mov_b32 m0, s0
	s_min_u32 s0, s77, 2
	v_add_u32_e32 v203, 0x8000, v187
	v_lshl_add_u64 v[10:11], v[8:9], 0, s[68:69]
	s_lshl_b32 s68, s0, 13
	v_readfirstlane_b32 s0, v203
	v_add_u32_e32 v204, 0xa000, v187
	global_load_lds_dwordx4 v[10:11], off
	v_lshl_add_u64 v[10:11], v[6:7], 0, s[68:69]
	s_mov_b32 m0, s0
	v_readfirstlane_b32 s0, v204
	global_load_lds_dwordx4 v[10:11], off
	s_mov_b32 m0, s0
	s_min_u32 s0, s77, 3
	v_add_u32_e32 v205, 0xc000, v187
	v_lshl_add_u64 v[10:11], v[8:9], 0, s[68:69]
	s_lshl_b32 s68, s0, 13
	v_readfirstlane_b32 s0, v205
	v_add_u32_e32 v206, 0xe000, v187
	global_load_lds_dwordx4 v[10:11], off
	v_lshl_add_u64 v[6:7], v[6:7], 0, s[68:69]
	s_mov_b32 m0, s0
	v_readfirstlane_b32 s0, v206
	global_load_lds_dwordx4 v[6:7], off
	v_lshl_add_u64 v[6:7], v[8:9], 0, s[68:69]
	s_mov_b32 m0, s0
	v_lshlrev_b32_e32 v12, 7, v213
	global_load_lds_dwordx4 v[6:7], off
	v_and_b32_e32 v5, 0xf80, v12
	v_add_u32_e32 v188, 0, v5
	v_add_u32_e32 v197, v188, v186
	s_waitcnt vmcnt(0)
	s_waitcnt vmcnt(0) lgkmcnt(0)
	s_barrier
	ds_read_b128 v[6:9], v197
	ds_read_b128 v[10:13], v197 offset:4096
	s_waitcnt lgkmcnt(1)
	v_mfma_f32_32x32x16_bf16 v[98:113], v[6:9], v[130:133], 0
	v_bitop3_b32 v5, v185, v14, 2 bitop3:0x36
	v_lshlrev_b32_e32 v189, 4, v5
	v_add_u32_e32 v198, v188, v189
	v_bitop3_b32 v5, v185, v14, 4 bitop3:0x36
	v_lshlrev_b32_e32 v190, 4, v5
	v_add_u32_e32 v201, v188, v190
	v_bitop3_b32 v5, v185, v14, 6 bitop3:0x36
	s_waitcnt lgkmcnt(0)
	v_mfma_f32_32x32x16_bf16 v[114:129], v[10:13], v[130:133], 0
	ds_read_b128 v[6:9], v198
	ds_read_b128 v[10:13], v198 offset:4096
	v_lshlrev_b32_e32 v191, 4, v5
	v_add_u32_e32 v207, v188, v191
	v_subrev_u32_e32 v5, 31, v148
	v_ashrrev_i32_e32 v156, 4, v5
	v_lshlrev_b32_e32 v196, 2, v185
	s_cmp_gt_i32 s93, 62
	s_waitcnt lgkmcnt(1)
	v_mfma_f32_32x32x16_bf16 v[98:113], v[6:9], v[134:137], v[98:113]
	s_nop 6
	s_waitcnt lgkmcnt(0)
	v_mfma_f32_32x32x16_bf16 v[114:129], v[10:13], v[134:137], v[114:129]
	ds_read_b128 v[6:9], v201
	ds_read_b128 v[10:13], v201 offset:4096
	s_nop 1
	s_waitcnt lgkmcnt(1)
	v_mfma_f32_32x32x16_bf16 v[98:113], v[6:9], v[138:141], v[98:113]
	s_waitcnt lgkmcnt(0)
	v_mfma_f32_32x32x16_bf16 v[114:129], v[10:13], v[138:141], v[114:129]
	ds_read_b128 v[6:9], v207
	ds_read_b128 v[10:13], v207 offset:4096
	s_waitcnt lgkmcnt(1)
	v_mfma_f32_32x32x16_bf16 v[98:113], v[6:9], v[142:145], v[98:113]
	s_waitcnt lgkmcnt(0)
	v_mfma_f32_32x32x16_bf16 v[114:129], v[10:13], v[142:145], v[114:129]
	s_cbranch_scc1 .LBB0_950
	v_sub_u32_e32 v5, v156, v196
	v_cmp_gt_i32_e64 s[60:61], 26, v5
	v_cmp_gt_i32_e64 s[62:63], 27, v5
	v_cmp_gt_i32_e64 s[58:59], 25, v5
	s_and_b64 s[60:61], s[62:63], s[60:61]
	v_cmp_gt_i32_e64 s[56:57], 24, v5
	s_and_b64 s[58:59], s[60:61], s[58:59]
	v_cmp_gt_i32_e64 s[54:55], 19, v5
	s_and_b64 s[56:57], s[58:59], s[56:57]
	v_cmp_gt_i32_e64 s[52:53], 18, v5
	s_and_b64 s[54:55], s[56:57], s[54:55]
	v_cmp_gt_i32_e64 s[50:51], 17, v5
	s_and_b64 s[52:53], s[54:55], s[52:53]
	v_cmp_gt_i32_e64 s[48:49], 16, v5
	s_and_b64 s[50:51], s[52:53], s[50:51]
	v_cmp_gt_i32_e64 s[46:47], 11, v5
	s_and_b64 s[48:49], s[50:51], s[48:49]
	v_cmp_gt_i32_e64 s[44:45], 10, v5
	s_and_b64 s[46:47], s[48:49], s[46:47]
	v_cmp_gt_i32_e64 s[42:43], 9, v5
	s_and_b64 s[44:45], s[46:47], s[44:45]
	v_cmp_gt_i32_e64 s[40:41], 8, v5
	s_and_b64 s[42:43], s[44:45], s[42:43]
	v_cmp_gt_i32_e64 s[38:39], 3, v5
	s_and_b64 s[40:41], s[42:43], s[40:41]
	v_cmp_gt_i32_e64 s[36:37], 2, v5
	s_and_b64 s[38:39], s[40:41], s[38:39]
	v_cmp_gt_i32_e64 s[34:35], 1, v5
	s_and_b64 s[36:37], s[38:39], s[36:37]
	v_cmp_gt_i32_e64 s[30:31], 0, v5
	s_and_b64 s[34:35], s[36:37], s[34:35]
	s_and_b64 s[30:31], s[34:35], s[30:31]
	v_cmp_gt_i32_e64 s[28:29], 58, v5
	v_cndmask_b32_e64 v98, v98, v179, s[30:31]
	v_cmp_gt_i32_e64 s[30:31], 59, v5
	v_cmp_gt_i32_e64 s[26:27], 57, v5
	s_and_b64 s[28:29], s[30:31], s[28:29]
	v_cmp_gt_i32_e64 s[24:25], 56, v5
	s_and_b64 s[26:27], s[28:29], s[26:27]
	v_cmp_gt_i32_e64 s[22:23], 51, v5
	s_and_b64 s[24:25], s[26:27], s[24:25]
	v_cmp_gt_i32_e64 s[20:21], 50, v5
	s_and_b64 s[22:23], s[24:25], s[22:23]
	v_cmp_gt_i32_e64 s[18:19], 49, v5
	s_and_b64 s[20:21], s[22:23], s[20:21]
	v_cmp_gt_i32_e64 s[16:17], 48, v5
	s_and_b64 s[18:19], s[20:21], s[18:19]
	v_cmp_gt_i32_e64 s[14:15], 43, v5
	s_and_b64 s[16:17], s[18:19], s[16:17]
	v_cmp_gt_i32_e64 s[12:13], 42, v5
	s_and_b64 s[14:15], s[16:17], s[14:15]
	v_cmp_gt_i32_e64 s[8:9], 41, v5
	s_and_b64 s[12:13], s[14:15], s[12:13]
	v_cmp_gt_i32_e64 s[6:7], 40, v5
	s_and_b64 s[8:9], s[12:13], s[8:9]
	v_cmp_gt_i32_e64 s[4:5], 35, v5
	s_and_b64 s[6:7], s[8:9], s[6:7]
	v_cmp_gt_i32_e64 s[2:3], 34, v5
	s_and_b64 s[4:5], s[6:7], s[4:5]
	v_cmp_gt_i32_e64 s[0:1], 33, v5
	s_and_b64 s[2:3], s[4:5], s[2:3]
	v_cmp_gt_i32_e32 vcc, 32, v5
	s_and_b64 s[0:1], s[2:3], s[0:1]
	s_and_b64 vcc, s[0:1], vcc
	v_cndmask_b32_e64 v113, v113, v179, s[62:63]
	v_cndmask_b32_e64 v112, v112, v179, s[60:61]
	v_cndmask_b32_e64 v111, v111, v179, s[58:59]
	v_cndmask_b32_e64 v110, v110, v179, s[56:57]
	v_cndmask_b32_e64 v109, v109, v179, s[54:55]
	v_cndmask_b32_e64 v108, v108, v179, s[52:53]
	v_cndmask_b32_e64 v107, v107, v179, s[50:51]
	v_cndmask_b32_e64 v106, v106, v179, s[48:49]
	v_cndmask_b32_e64 v105, v105, v179, s[46:47]
	v_cndmask_b32_e64 v104, v104, v179, s[44:45]
	v_cndmask_b32_e64 v103, v103, v179, s[42:43]
	v_cndmask_b32_e64 v102, v102, v179, s[40:41]
	v_cndmask_b32_e64 v101, v101, v179, s[38:39]
	v_cndmask_b32_e64 v100, v100, v179, s[36:37]
	v_cndmask_b32_e64 v99, v99, v179, s[34:35]
	v_cndmask_b32_e64 v129, v129, v179, s[30:31]
	v_cndmask_b32_e64 v128, v128, v179, s[28:29]
	v_cndmask_b32_e64 v127, v127, v179, s[26:27]
	v_cndmask_b32_e64 v126, v126, v179, s[24:25]
	v_cndmask_b32_e64 v125, v125, v179, s[22:23]
	v_cndmask_b32_e64 v124, v124, v179, s[20:21]
	v_cndmask_b32_e64 v123, v123, v179, s[18:19]
	v_cndmask_b32_e64 v122, v122, v179, s[16:17]
	v_cndmask_b32_e64 v121, v121, v179, s[14:15]
	v_cndmask_b32_e64 v120, v120, v179, s[12:13]
	v_cndmask_b32_e64 v119, v119, v179, s[8:9]
	v_cndmask_b32_e64 v118, v118, v179, s[6:7]
	v_cndmask_b32_e64 v117, v117, v179, s[4:5]
	v_cndmask_b32_e64 v116, v116, v179, s[2:3]
	v_cndmask_b32_e64 v115, v115, v179, s[0:1]
	v_cndmask_b32_e32 v114, v114, v179, vcc

.LBB0_1016:
	v_lshlrev_b32_e32 v2, 12, v210
	v_add3_u32 v156, s70, v2, v6
	v_lshl_add_u32 v2, v211, 3, 0
	v_add_u32_e32 v2, 0x20000, v2
	s_waitcnt lgkmcnt(0)
	s_barrier
	ds_read_b64 v[154:155], v2
	v_pk_mul_f32 v[2:3], v[0:1], v[98:99] op_sel_hi:[0,1]
	v_cvt_pk_bf16_f32 v4, v2, v3
	v_pk_mul_f32 v[2:3], v[0:1], v[114:115] op_sel_hi:[0,1]
	v_cvt_pk_bf16_f32 v5, v2, v3
	v_pk_mul_f32 v[2:3], v[0:1], v[100:101] op_sel_hi:[0,1]
	v_cvt_pk_bf16_f32 v2, v2, v3
	ds_write2st64_b32 v156, v4, v2 offset1:1
	v_pk_mul_f32 v[2:3], v[0:1], v[116:117] op_sel_hi:[0,1]
	v_cvt_pk_bf16_f32 v2, v2, v3
	ds_write2st64_b32 v156, v5, v2 offset0:8 offset1:9
	v_pk_mul_f32 v[2:3], v[0:1], v[102:103] op_sel_hi:[0,1]
	v_cvt_pk_bf16_f32 v4, v2, v3
	v_pk_mul_f32 v[2:3], v[0:1], v[118:119] op_sel_hi:[0,1]
	v_cvt_pk_bf16_f32 v5, v2, v3
	v_pk_mul_f32 v[2:3], v[0:1], v[104:105] op_sel_hi:[0,1]
	v_cvt_pk_bf16_f32 v2, v2, v3
	ds_write2st64_b32 v156, v4, v2 offset0:2 offset1:3
	v_pk_mul_f32 v[2:3], v[0:1], v[120:121] op_sel_hi:[0,1]
	v_cvt_pk_bf16_f32 v2, v2, v3
	ds_write2st64_b32 v156, v5, v2 offset0:10 offset1:11
	v_pk_mul_f32 v[2:3], v[0:1], v[106:107] op_sel_hi:[0,1]
	v_cvt_pk_bf16_f32 v4, v2, v3
	v_pk_mul_f32 v[2:3], v[0:1], v[122:123] op_sel_hi:[0,1]
	v_cvt_pk_bf16_f32 v5, v2, v3
	v_pk_mul_f32 v[2:3], v[0:1], v[108:109] op_sel_hi:[0,1]
	v_cvt_pk_bf16_f32 v2, v2, v3
	ds_write2st64_b32 v156, v4, v2 offset0:4 offset1:5
	v_pk_mul_f32 v[2:3], v[0:1], v[124:125] op_sel_hi:[0,1]
	v_cvt_pk_bf16_f32 v2, v2, v3
	ds_write2st64_b32 v156, v5, v2 offset0:12 offset1:13
	v_pk_mul_f32 v[2:3], v[0:1], v[110:111] op_sel_hi:[0,1]
	s_lshl_b32 s0, s76, 19
	v_readlane_b32 s4, v252, 7
	v_cvt_pk_bf16_f32 v4, v2, v3
	v_pk_mul_f32 v[2:3], v[0:1], v[126:127] op_sel_hi:[0,1]
	v_readlane_b32 s5, v252, 8
	s_add_u32 s0, s4, s0
	v_cvt_pk_bf16_f32 v5, v2, v3
	v_pk_mul_f32 v[2:3], v[0:1], v[112:113] op_sel_hi:[0,1]
	s_addc_u32 s1, s5, 0
	v_cvt_pk_bf16_f32 v2, v2, v3
	v_lshl_add_u64 v[98:99], v[150:151], 1, s[0:1]
	v_lshl_add_u64 v[100:101], v[152:153], 1, s[0:1]
	s_mov_b64 s[0:1], 0x1800000
	ds_write2st64_b32 v156, v4, v2 offset0:6 offset1:7
	v_pk_mul_f32 v[2:3], v[0:1], v[128:129] op_sel_hi:[0,1]
	s_mov_b64 s[2:3], 0x1000000
	v_lshl_add_u64 v[104:105], v[100:101], 0, s[0:1]
	v_readfirstlane_b32 s0, v187
	v_cvt_pk_bf16_f32 v0, v2, v3
	v_lshl_add_u64 v[102:103], v[98:99], 0, s[2:3]
	s_mov_b32 m0, s0
	v_readfirstlane_b32 s0, v199
	s_min_i32 s68, s97, 1
	ds_write2st64_b32 v156, v5, v0 offset0:14 offset1:15
	global_load_lds_dwordx4 v[102:103], off
	s_mov_b32 m0, s0
	s_lshl_b64 s[0:1], s[68:69], 13
	v_readfirstlane_b32 s2, v200
	global_load_lds_dwordx4 v[104:105], off
	v_lshl_add_u64 v[2:3], v[102:103], 0, s[0:1]
	s_mov_b32 m0, s2
	s_min_i32 s68, s97, 2
	global_load_lds_dwordx4 v[2:3], off
	v_lshl_add_u64 v[2:3], v[104:105], 0, s[0:1]
	v_readfirstlane_b32 s0, v202
	s_mov_b32 m0, s0
	s_lshl_b64 s[0:1], s[68:69], 13
	v_readfirstlane_b32 s2, v203
	global_load_lds_dwordx4 v[2:3], off
	v_lshl_add_u64 v[2:3], v[102:103], 0, s[0:1]
	s_mov_b32 m0, s2
	s_min_i32 s68, s97, 3
	global_load_lds_dwordx4 v[2:3], off
	v_lshl_add_u64 v[2:3], v[104:105], 0, s[0:1]
	v_readfirstlane_b32 s0, v204
	s_mov_b32 m0, s0
	s_lshl_b64 s[0:1], s[68:69], 13
	v_readfirstlane_b32 s2, v205
	global_load_lds_dwordx4 v[2:3], off
	v_lshl_add_u64 v[2:3], v[102:103], 0, s[0:1]
	s_mov_b32 m0, s2
	s_min_i32 s68, s97, 4
	global_load_lds_dwordx4 v[2:3], off
	v_lshl_add_u64 v[2:3], v[104:105], 0, s[0:1]
	v_readfirstlane_b32 s0, v206
	v_add_u32_e32 v110, s67, v209
	s_mov_b32 m0, s0
	s_lshl_b64 s[0:1], s[68:69], 13
	v_readfirstlane_b32 s2, v110
	global_load_lds_dwordx4 v[2:3], off
	v_lshl_add_u64 v[2:3], v[102:103], 0, s[0:1]
	s_mov_b32 m0, s2
	v_add_u32_e32 v111, s71, v209
	global_load_lds_dwordx4 v[2:3], off
	v_lshl_add_u64 v[2:3], v[104:105], 0, s[0:1]
	v_readfirstlane_b32 s0, v111
	s_mov_b32 m0, s0
	v_lshlrev_b32_e32 v0, 8, v185
	global_load_lds_dwordx4 v[2:3], off
	s_waitcnt vmcnt(8)
	s_barrier
	ds_read_b128 v[2:5], v197
	ds_read_b128 v[6:9], v197 offset:4096
	s_waitcnt lgkmcnt(0)
	v_mfma_f32_32x32x16_bf16 v[34:49], v[2:5], v[130:133], 0
	v_mov_b32_e32 v10, v1
	v_mov_b32_e32 v11, v1
	v_mov_b32_e32 v12, v1
	v_mov_b32_e32 v13, v1
	v_mov_b32_e32 v14, v1
	v_mov_b32_e32 v15, v1
	v_mov_b32_e32 v16, v1
	v_mfma_f32_32x32x16_bf16 v[50:65], v[6:9], v[130:133], 0
	ds_read_b128 v[2:5], v198
	ds_read_b128 v[6:9], v198 offset:4096
	v_mov_b32_e32 v17, v1
	v_mov_b32_e32 v18, v1
	v_mov_b32_e32 v19, v1
	v_mov_b32_e32 v20, v1
	v_mov_b32_e32 v21, v1
	v_mov_b32_e32 v22, v1
	s_waitcnt lgkmcnt(0)
	v_mfma_f32_32x32x16_bf16 v[34:49], v[2:5], v[134:137], v[34:49]
	v_mov_b32_e32 v23, v1
	v_mov_b32_e32 v24, v1
	v_mov_b32_e32 v25, v1
	v_mov_b32_e32 v26, v1
	v_mov_b32_e32 v27, v1
	v_mov_b32_e32 v28, v1
	v_mov_b32_e32 v29, v1
	v_mfma_f32_32x32x16_bf16 v[50:65], v[6:9], v[134:137], v[50:65]
	ds_read_b128 v[2:5], v201
	ds_read_b128 v[6:9], v201 offset:4096
	v_mov_b32_e32 v30, v1
	v_mov_b32_e32 v31, v1
	s_mov_b32 s42, 0
	v_cmp_gt_i32_e64 s[0:1], 0, v148
	s_mov_b32 s43, 5
	s_mov_b64 s[38:39], -1
	s_waitcnt lgkmcnt(0)
	v_mfma_f32_32x32x16_bf16 v[34:49], v[2:5], v[138:141], v[34:49]
	v_mov_b32_e32 v112, 0
	v_mov_b32_e32 v113, 0xf149f2ca
	s_movk_i32 s44, 0x7f
	s_mov_b32 s45, 0
	s_nop 2
	v_mfma_f32_32x32x16_bf16 v[50:65], v[6:9], v[138:141], v[50:65]
	ds_read_b128 v[2:5], v207
	ds_read_b128 v[6:9], v207 offset:4096
	s_nop 2
	v_readlane_b32 s12, v252, 15
	v_readlane_b32 s13, v252, 16
	s_nop 0
	s_waitcnt lgkmcnt(0)
	v_mfma_f32_32x32x16_bf16 v[34:49], v[2:5], v[142:145], v[34:49]
	v_and_b32_e32 v2, 0xc0, v209
	v_add3_u32 v0, 0, v0, v2
	v_mov_b32_e32 v2, v1
	v_mov_b32_e32 v3, v1
	v_mov_b32_e32 v4, v1
	v_mov_b32_e32 v5, v1
	v_add3_u32 v107, v0, v213, v214
	v_mfma_f32_32x32x16_bf16 v[50:65], v[6:9], v[142:145], v[50:65]
	v_mov_b32_e32 v6, v1
	v_mov_b32_e32 v7, v1
	v_mov_b32_e32 v8, v1
	v_mov_b32_e32 v9, v1
	v_mov_b32_e32 v0, v1
	v_mov_b64_e32 v[32:33], v[30:31]
	v_mov_b64_e32 v[30:31], v[28:29]
	v_mov_b64_e32 v[28:29], v[26:27]
	v_mov_b64_e32 v[26:27], v[24:25]
	v_mov_b64_e32 v[24:25], v[22:23]
	v_mov_b64_e32 v[22:23], v[20:21]
	v_mov_b64_e32 v[20:21], v[18:19]
	v_mov_b64_e32 v[18:19], v[16:17]
	v_mov_b64_e32 v[16:17], v[14:15]
	v_mov_b64_e32 v[14:15], v[12:13]
	v_mov_b64_e32 v[12:13], v[10:11]
	v_mov_b64_e32 v[10:11], v[8:9]
	v_mov_b64_e32 v[8:9], v[6:7]
	v_mov_b64_e32 v[6:7], v[4:5]
	v_mov_b64_e32 v[4:5], v[2:3]
	v_mov_b64_e32 v[2:3], v[0:1]
	s_nop 0
	v_readlane_b32 s16, v252, 19
	v_readlane_b32 s17, v252, 20
	v_readlane_b32 s18, v252, 21
	v_readlane_b32 s19, v252, 22
	s_branch .LBB0_1018

.LBB0_1070:
	s_and_b64 vcc, exec, s[0:1]
	s_cbranch_vccz .LBB0_1203
	v_readlane_b32 s0, v252, 49
	s_sub_i32 s0, 31, s0
	s_mov_b32 s73, 0
	v_writelane_b32 v253, s0, 2
	s_lshl_b32 s0, s62, 1
	s_and_b32 s65, s0, 14
	s_nop 0
	v_readlane_b32 s2, v252, 9
	v_readlane_b32 s3, v252, 10
	s_lshl_b32 s70, s65, 11
	s_mov_b32 s71, s73
	v_mov_b32_e32 v1, 0
	v_mov_b64_e32 v[180:181], s[2:3]
	s_mov_b32 s75, 0xf149f2ca
	v_mbcnt_hi_u32_b32 v179, -1, v220
	s_add_i32 s76, 0, 0x10000
	s_add_i32 s77, 0, 0x18000
	s_add_i32 s78, 0, 0x12000
	s_movk_i32 s69, 0xfdff
	s_movk_i32 s79, 0xfe00
	v_mov_b32_e32 v196, 0xf149f2ca
	v_mov_b32_e32 v197, 0x20000
	v_mov_b32_e32 v198, 0x7149f2ca
	s_mov_b32 s93, 0
	s_nop 7
	s_nop 4
	s_branch .LBB0_1073

.LBB0_1073:
	s_lshl_b32 s0, s93, 5
	s_bitcmp0_b32 s93, 0
	v_readlane_b32 s1, v252, 49
	v_readlane_b32 s2, v253, 2
	s_cselect_b32 s1, s1, s2
	s_add_i32 s0, s1, s0
	s_ashr_i32 s0, s0, 1
	v_mov_b32 v37, v178
	s_sub_i32 s68, 63, s0
	v_ashrrev_i32_e32 v225, 6, v37
	v_lshlrev_b32_e32 v207, 3, v225
	v_bfe_u32 v208, v37, 2, 3
	s_lshl_b32 s33, s68, 6
	v_or_b32_e32 v226, v207, v208
	v_add_u32_e32 v184, s33, v226
	v_ashrrev_i32_e32 v185, 31, v184
	s_and_b32 s2, s1, 1
	v_and_b32_e32 v36, 3, v37
	v_lshl_add_u64 v[34:35], v[184:185], 0, s[70:71]
	s_nop 0
	v_lshlrev_b64 v[2:3], 10, v[34:35]
	v_readlane_b32 s18, v252, 5
	v_readlane_b32 s19, v252, 6
	v_lshl_or_b32 v42, s2, 2, v36
	v_bfe_u32 v199, v37, 5, 1
	v_lshl_add_u64 v[2:3], s[18:19], 0, v[2:3]
	v_lshlrev_b32_e32 v0, 7, v42
	v_lshl_add_u64 v[2:3], v[2:3], 0, v[0:1]
	v_lshlrev_b32_e32 v0, 4, v199
	v_lshl_add_u64 v[2:3], v[2:3], 0, v[0:1]
	s_movk_i32 s3, 0x60
	s_mov_b32 s74, s0
	global_load_dwordx4 v[162:165], v[2:3], off
	global_load_dwordx4 v[166:169], v[2:3], off offset:32
	global_load_dwordx4 v[170:173], v[2:3], off offset:64
	global_load_dwordx4 v[174:177], v[2:3], off offset:96
	v_mad_u64_u32 v[2:3], s[0:1], v34, s3, v[180:181]
	s_nop 7
	s_nop 4
	v_mad_i32_i24 v3, v35, s3, v3
	s_lshl_b32 s72, s2, 4
	v_lshl_add_u64 v[2:3], v[2:3], 0, s[72:73]
	v_lshlrev_b32_e32 v0, 2, v36
	s_nop 0
	s_or_b32 s20, s2, s65
	v_lshl_add_u64 v[2:3], v[2:3], 0, v[0:1]
	s_nop 1
	v_readlane_b32 s14, v252, 17
	v_readlane_b32 s15, v252, 18
	global_load_dword v0, v[2:3], off
	global_load_dword v223, v[2:3], off offset:32
	global_load_dword v185, v[2:3], off offset:64
	s_lshl_b32 s2, s20, 15
	s_mov_b64 s[10:11], s[14:15]
	v_lshrrev_b32_e32 v3, 4, v37
	s_nop 1
	v_readlane_b32 s16, v252, 19
	v_readlane_b32 s17, v252, 20
	s_add_u32 s0, s10, s2
	v_lshlrev_b32_e32 v38, 3, v37
	v_xor_b32_e32 v3, v3, v37
	v_readlane_b32 s18, v252, 21
	v_readlane_b32 s19, v252, 22
	s_mov_b64 s[12:13], s[16:17]
	s_addc_u32 s1, s11, 0
	v_and_b32_e32 v2, 0xffffffc0, v38
	v_lshlrev_b32_e32 v3, 3, v3
	s_add_u32 s2, s12, s2
	v_and_or_b32 v186, v3, 56, v2
	v_lshlrev_b32_e32 v224, 4, v37
	s_mov_b32 s4, 0x1ffffffc
	s_addc_u32 s3, s13, 0
	s_ashr_i32 s72, s68, 4
	v_and_b32_e32 v2, 0xfc0, v224
	v_and_or_b32 v3, v225, s4, v36
	v_ashrrev_i32_e32 v187, 31, v186
	v_lshl_add_u32 v188, v3, 3, v2
	v_lshl_add_u64 v[2:3], v[186:187], 1, s[0:1]
	s_min_i32 s0, s72, 0
	v_ashrrev_i32_e32 v189, 31, v188
	s_ashr_i32 s1, s0, 31
	v_add_u32_e32 v200, 0, v224
	v_lshl_add_u64 v[4:5], v[188:189], 1, s[2:3]
	s_lshl_b64 s[0:1], s[0:1], 13
	v_readfirstlane_b32 s2, v200
	v_lshl_add_u64 v[6:7], v[2:3], 0, s[0:1]
	s_mov_b32 m0, s2
	v_add_u32_e32 v213, 0x2000, v200
	global_load_lds_dwordx4 v[6:7], off
	v_lshl_add_u64 v[6:7], v[4:5], 0, s[0:1]
	v_readfirstlane_b32 s0, v213
	s_mov_b32 m0, s0
	s_min_i32 s0, s72, 1
	s_ashr_i32 s1, s0, 31
	v_add_u32_e32 v214, 0x4000, v200
	s_lshl_b64 s[0:1], s[0:1], 13
	v_readfirstlane_b32 s2, v214
	global_load_lds_dwordx4 v[6:7], off
	v_lshl_add_u64 v[6:7], v[2:3], 0, s[0:1]
	s_mov_b32 m0, s2
	v_add_u32_e32 v215, 0x6000, v200
	global_load_lds_dwordx4 v[6:7], off
	v_lshl_add_u64 v[6:7], v[4:5], 0, s[0:1]
	v_readfirstlane_b32 s0, v215
	s_mov_b32 m0, s0
	s_min_i32 s0, s72, 2
	s_ashr_i32 s1, s0, 31
	v_add_u32_e32 v216, 0x8000, v200
	s_lshl_b64 s[0:1], s[0:1], 13
	v_readfirstlane_b32 s2, v216
	global_load_lds_dwordx4 v[6:7], off
	v_lshl_add_u64 v[6:7], v[2:3], 0, s[0:1]
	s_mov_b32 m0, s2
	v_add_u32_e32 v217, 0xa000, v200
	global_load_lds_dwordx4 v[6:7], off
	v_lshl_add_u64 v[6:7], v[4:5], 0, s[0:1]
	v_readfirstlane_b32 s0, v217
	s_mov_b32 m0, s0
	s_min_i32 s0, s72, 3
	s_ashr_i32 s1, s0, 31
	v_add_u32_e32 v218, 0xc000, v200
	s_lshl_b64 s[0:1], s[0:1], 13
	v_readfirstlane_b32 s2, v218
	global_load_lds_dwordx4 v[6:7], off
	v_lshl_add_u64 v[2:3], v[2:3], 0, s[0:1]
	s_mov_b32 m0, s2
	v_add_u32_e32 v221, 0xe000, v200
	global_load_lds_dwordx4 v[2:3], off
	v_lshl_add_u64 v[2:3], v[4:5], 0, s[0:1]
	v_readfirstlane_b32 s0, v221
	s_mov_b32 m0, s0
	s_sub_i32 s0, s33, 31
	global_load_lds_dwordx4 v[2:3], off
	v_subrev_u32_e32 v2, 31, v184
	v_ashrrev_i32_e32 v40, 4, v2
	v_lshrrev_b32_e32 v2, 5, v37
	v_bfe_u32 v3, v37, 1, 3
	v_bitop3_b32 v2, v2, v3, 1 bitop3:0x6c
	v_lshlrev_b32_e32 v201, 4, v2
	v_bitop3_b32 v2, v199, v3, 2 bitop3:0x36
	v_lshlrev_b32_e32 v202, 4, v2
	v_bitop3_b32 v2, v199, v3, 4 bitop3:0x36
	v_lshlrev_b32_e32 v4, 7, v37
	v_lshlrev_b32_e32 v203, 4, v2
	v_bitop3_b32 v2, v199, v3, 6 bitop3:0x36
	s_ashr_i32 s92, s0, 4
	v_lshlrev_b32_e32 v204, 4, v2
	v_and_b32_e32 v2, 0xf80, v4
	s_waitcnt vmcnt(0)
	v_add_u32_e32 v205, 0, v2
	s_cmp_gt_i32 s72, -1
	s_mov_b32 s64, s20
	v_lshlrev_b32_e32 v210, 2, v199
	s_cselect_b64 s[66:67], -1, 0
	s_cmp_lt_i32 s72, 0
	v_add_u32_e32 v222, v205, v201
	v_add_u32_e32 v219, v205, v202
	v_add_u32_e32 v212, v205, v203
	v_add_u32_e32 v211, v205, v204
	s_nop 2
	v_readlane_b32 s8, v252, 11
	v_readlane_b32 s9, v252, 12
	s_mov_b64 s[14:15], s[18:19]
	s_waitcnt vmcnt(0) lgkmcnt(0)
	s_barrier
	s_cbranch_scc1 .LBB0_1077
	ds_read_b128 v[2:5], v222
	ds_read_b128 v[6:9], v222 offset:4096
	ds_read_b128 v[44:47], v219
	ds_read_b128 v[48:51], v219 offset:4096
	s_cmp_gt_i32 s92, 62
	s_waitcnt lgkmcnt(3)
	v_mfma_f32_32x32x16_bf16 v[18:33], v[2:5], v[162:165], 0
	s_waitcnt lgkmcnt(2)
	v_mfma_f32_32x32x16_bf16 v[2:17], v[6:9], v[162:165], 0
	s_waitcnt lgkmcnt(1)
	v_mfma_f32_32x32x16_bf16 v[18:33], v[44:47], v[166:169], v[18:33]
	s_waitcnt lgkmcnt(0)
	v_mfma_f32_32x32x16_bf16 v[2:17], v[48:51], v[166:169], v[2:17]
	ds_read_b128 v[44:47], v212
	ds_read_b128 v[48:51], v212 offset:4096
	s_waitcnt lgkmcnt(1)
	v_mfma_f32_32x32x16_bf16 v[18:33], v[44:47], v[170:173], v[18:33]
	s_waitcnt lgkmcnt(0)
	v_mfma_f32_32x32x16_bf16 v[2:17], v[48:51], v[170:173], v[2:17]
	ds_read_b128 v[44:47], v211
	ds_read_b128 v[48:51], v211 offset:4096
	s_waitcnt lgkmcnt(1)
	v_mfma_f32_32x32x16_bf16 v[18:33], v[44:47], v[174:177], v[18:33]
	s_waitcnt lgkmcnt(0)
	v_mfma_f32_32x32x16_bf16 v[2:17], v[48:51], v[174:177], v[2:17]
	s_cbranch_scc1 .LBB0_1076
	v_sub_u32_e32 v39, v40, v210
	v_cmp_gt_i32_e64 s[58:59], 26, v39
	v_cmp_gt_i32_e64 s[62:63], 27, v39
	v_cmp_gt_i32_e64 s[56:57], 25, v39
	s_and_b64 s[58:59], s[62:63], s[58:59]
	v_cmp_gt_i32_e64 s[54:55], 24, v39
	s_and_b64 s[56:57], s[58:59], s[56:57]
	v_cmp_gt_i32_e64 s[52:53], 19, v39
	s_and_b64 s[54:55], s[56:57], s[54:55]
	v_cmp_gt_i32_e64 s[50:51], 18, v39
	s_and_b64 s[52:53], s[54:55], s[52:53]
	v_cmp_gt_i32_e64 s[48:49], 17, v39
	s_and_b64 s[50:51], s[52:53], s[50:51]
	v_cmp_gt_i32_e64 s[46:47], 16, v39
	s_and_b64 s[48:49], s[50:51], s[48:49]
	v_cmp_gt_i32_e64 s[44:45], 11, v39
	s_and_b64 s[46:47], s[48:49], s[46:47]
	v_cmp_gt_i32_e64 s[42:43], 10, v39
	s_and_b64 s[44:45], s[46:47], s[44:45]
	v_cmp_gt_i32_e64 s[40:41], 9, v39
	s_and_b64 s[42:43], s[44:45], s[42:43]
	v_cmp_gt_i32_e64 s[38:39], 8, v39
	s_and_b64 s[40:41], s[42:43], s[40:41]
	v_cmp_gt_i32_e64 s[36:37], 3, v39
	s_and_b64 s[38:39], s[40:41], s[38:39]
	v_cmp_gt_i32_e64 s[34:35], 2, v39
	s_and_b64 s[36:37], s[38:39], s[36:37]
	v_cmp_gt_i32_e64 s[30:31], 1, v39
	s_and_b64 s[34:35], s[36:37], s[34:35]
	v_cmp_gt_i32_e64 s[28:29], 0, v39
	s_and_b64 s[30:31], s[34:35], s[30:31]
	s_and_b64 s[28:29], s[30:31], s[28:29]
	v_cmp_gt_i32_e64 s[60:61], 58, v39
	v_cndmask_b32_e64 v18, v18, v196, s[28:29]
	v_cmp_gt_i32_e64 s[28:29], 59, v39
	v_cmp_gt_i32_e64 s[26:27], 57, v39
	v_cmp_gt_i32_e64 s[24:25], 56, v39
	v_cndmask_b32_e64 v17, v17, v196, s[28:29]
	s_and_b64 s[28:29], s[28:29], s[60:61]
	s_and_b64 s[26:27], s[28:29], s[26:27]
	v_cmp_gt_i32_e64 s[22:23], 51, v39
	s_and_b64 s[24:25], s[26:27], s[24:25]
	v_cmp_gt_i32_e64 s[20:21], 50, v39
	s_and_b64 s[22:23], s[24:25], s[22:23]
	v_cmp_gt_i32_e64 s[18:19], 49, v39
	s_and_b64 s[20:21], s[22:23], s[20:21]
	v_cmp_gt_i32_e64 s[16:17], 48, v39
	s_and_b64 s[18:19], s[20:21], s[18:19]
	v_cmp_gt_i32_e64 s[14:15], 43, v39
	s_and_b64 s[16:17], s[18:19], s[16:17]
	v_cmp_gt_i32_e64 s[12:13], 42, v39
	s_and_b64 s[14:15], s[16:17], s[14:15]
	v_cmp_gt_i32_e64 s[8:9], 41, v39
	s_and_b64 s[12:13], s[14:15], s[12:13]
	v_cmp_gt_i32_e64 s[6:7], 40, v39
	s_and_b64 s[8:9], s[12:13], s[8:9]
	v_cmp_gt_i32_e64 s[4:5], 35, v39
	s_and_b64 s[6:7], s[8:9], s[6:7]
	v_cmp_gt_i32_e64 s[2:3], 34, v39
	s_and_b64 s[4:5], s[6:7], s[4:5]
	v_cmp_gt_i32_e64 s[0:1], 33, v39
	s_and_b64 s[2:3], s[4:5], s[2:3]
	v_cmp_gt_i32_e32 vcc, 32, v39
	s_and_b64 s[0:1], s[2:3], s[0:1]
	s_and_b64 vcc, s[0:1], vcc
	v_cndmask_b32_e64 v33, v33, v196, s[62:63]
	v_cndmask_b32_e64 v32, v32, v196, s[58:59]
	v_cndmask_b32_e64 v31, v31, v196, s[56:57]
	v_cndmask_b32_e64 v30, v30, v196, s[54:55]
	v_cndmask_b32_e64 v29, v29, v196, s[52:53]
	v_cndmask_b32_e64 v28, v28, v196, s[50:51]
	v_cndmask_b32_e64 v27, v27, v196, s[48:49]
	v_cndmask_b32_e64 v26, v26, v196, s[46:47]
	v_cndmask_b32_e64 v25, v25, v196, s[44:45]
	v_cndmask_b32_e64 v24, v24, v196, s[42:43]
	v_cndmask_b32_e64 v23, v23, v196, s[40:41]
	v_cndmask_b32_e64 v22, v22, v196, s[38:39]
	v_cndmask_b32_e64 v21, v21, v196, s[36:37]
	v_cndmask_b32_e64 v20, v20, v196, s[34:35]
	v_cndmask_b32_e64 v19, v19, v196, s[30:31]
	v_cndmask_b32_e64 v16, v16, v196, s[28:29]
	v_cndmask_b32_e64 v15, v15, v196, s[26:27]
	v_cndmask_b32_e64 v14, v14, v196, s[24:25]
	v_cndmask_b32_e64 v13, v13, v196, s[22:23]
	v_cndmask_b32_e64 v12, v12, v196, s[20:21]
	v_cndmask_b32_e64 v11, v11, v196, s[18:19]
	v_cndmask_b32_e64 v10, v10, v196, s[16:17]
	v_cndmask_b32_e64 v9, v9, v196, s[14:15]
	v_cndmask_b32_e64 v8, v8, v196, s[12:13]
	v_cndmask_b32_e64 v7, v7, v196, s[8:9]
	v_cndmask_b32_e64 v6, v6, v196, s[6:7]
	v_cndmask_b32_e64 v5, v5, v196, s[4:5]
	v_cndmask_b32_e64 v4, v4, v196, s[2:3]
	v_cndmask_b32_e64 v3, v3, v196, s[0:1]
	v_cndmask_b32_e32 v2, v2, v196, vcc

.LBB0_1147:
	v_lshlrev_b32_e32 v34, 12, v225
	v_add3_u32 v109, s77, v34, v38
	v_lshl_add_u32 v34, v226, 3, 0
	v_add_u32_e32 v34, 0x20000, v34
	v_pk_mul_f32 v[2:3], v[0:1], v[2:3] op_sel_hi:[0,1]
	s_waitcnt lgkmcnt(0)
	s_barrier
	ds_read_b64 v[102:103], v34
	v_cvt_pk_bf16_f32 v34, v2, v3
	v_pk_mul_f32 v[2:3], v[0:1], v[18:19] op_sel_hi:[0,1]
	v_cvt_pk_bf16_f32 v18, v2, v3
	v_pk_mul_f32 v[2:3], v[0:1], v[4:5] op_sel_hi:[0,1]
	v_cvt_pk_bf16_f32 v2, v2, v3
	ds_write2st64_b32 v109, v34, v2 offset1:1
	v_pk_mul_f32 v[2:3], v[0:1], v[20:21] op_sel_hi:[0,1]
	v_cvt_pk_bf16_f32 v2, v2, v3
	ds_write2st64_b32 v109, v18, v2 offset0:8 offset1:9
	v_pk_mul_f32 v[2:3], v[0:1], v[6:7] op_sel_hi:[0,1]
	v_cvt_pk_bf16_f32 v4, v2, v3
	v_pk_mul_f32 v[2:3], v[0:1], v[22:23] op_sel_hi:[0,1]
	v_cvt_pk_bf16_f32 v5, v2, v3
	v_pk_mul_f32 v[2:3], v[0:1], v[8:9] op_sel_hi:[0,1]
	v_cvt_pk_bf16_f32 v2, v2, v3
	ds_write2st64_b32 v109, v4, v2 offset0:2 offset1:3
	v_pk_mul_f32 v[2:3], v[0:1], v[24:25] op_sel_hi:[0,1]
	v_cvt_pk_bf16_f32 v2, v2, v3
	ds_write2st64_b32 v109, v5, v2 offset0:10 offset1:11
	v_pk_mul_f32 v[2:3], v[0:1], v[10:11] op_sel_hi:[0,1]
	v_cvt_pk_bf16_f32 v4, v2, v3
	v_pk_mul_f32 v[2:3], v[0:1], v[26:27] op_sel_hi:[0,1]
	v_cvt_pk_bf16_f32 v5, v2, v3
	v_pk_mul_f32 v[2:3], v[0:1], v[12:13] op_sel_hi:[0,1]
	v_cvt_pk_bf16_f32 v2, v2, v3
	ds_write2st64_b32 v109, v4, v2 offset0:4 offset1:5
	v_pk_mul_f32 v[2:3], v[0:1], v[28:29] op_sel_hi:[0,1]
	s_lshl_b32 s0, s64, 19
	v_readlane_b32 s4, v252, 7
	v_cvt_pk_bf16_f32 v2, v2, v3
	v_readlane_b32 s5, v252, 8
	s_add_u32 s0, s4, s0
	ds_write2st64_b32 v109, v5, v2 offset0:12 offset1:13
	v_pk_mul_f32 v[2:3], v[0:1], v[14:15] op_sel_hi:[0,1]
	s_addc_u32 s1, s5, 0
	v_cvt_pk_bf16_f32 v4, v2, v3
	v_pk_mul_f32 v[2:3], v[0:1], v[30:31] op_sel_hi:[0,1]
	v_lshl_add_u64 v[98:99], v[186:187], 1, s[0:1]
	v_lshl_add_u64 v[100:101], v[188:189], 1, s[0:1]
	s_mov_b64 s[0:1], 0x1800000
	v_cvt_pk_bf16_f32 v5, v2, v3
	v_pk_mul_f32 v[2:3], v[0:1], v[16:17] op_sel_hi:[0,1]
	v_lshl_add_u64 v[106:107], v[100:101], 0, s[0:1]
	s_min_i32 s0, s68, 0
	v_cvt_pk_bf16_f32 v2, v2, v3
	s_mov_b64 s[2:3], 0x1000000
	s_ashr_i32 s1, s0, 31
	ds_write2st64_b32 v109, v4, v2 offset0:6 offset1:7
	v_pk_mul_f32 v[2:3], v[0:1], v[32:33] op_sel_hi:[0,1]
	v_lshl_add_u64 v[104:105], v[98:99], 0, s[2:3]
	s_lshl_b64 s[0:1], s[0:1], 13
	v_readfirstlane_b32 s2, v200
	v_cvt_pk_bf16_f32 v0, v2, v3
	v_lshl_add_u64 v[2:3], v[104:105], 0, s[0:1]
	s_mov_b32 m0, s2
	ds_write2st64_b32 v109, v5, v0 offset0:14 offset1:15
	global_load_lds_dwordx4 v[2:3], off
	v_lshl_add_u64 v[2:3], v[106:107], 0, s[0:1]
	v_readfirstlane_b32 s0, v213
	s_mov_b32 m0, s0
	s_min_i32 s0, s68, 1
	s_ashr_i32 s1, s0, 31
	s_lshl_b64 s[0:1], s[0:1], 13
	v_readfirstlane_b32 s2, v214
	global_load_lds_dwordx4 v[2:3], off
	v_lshl_add_u64 v[2:3], v[104:105], 0, s[0:1]
	s_mov_b32 m0, s2
	v_readfirstlane_b32 s2, v216
	global_load_lds_dwordx4 v[2:3], off
	v_lshl_add_u64 v[2:3], v[106:107], 0, s[0:1]
	v_readfirstlane_b32 s0, v215
	s_mov_b32 m0, s0
	s_min_i32 s0, s68, 2
	s_ashr_i32 s1, s0, 31
	s_lshl_b64 s[0:1], s[0:1], 13
	global_load_lds_dwordx4 v[2:3], off
	v_lshl_add_u64 v[2:3], v[104:105], 0, s[0:1]
	s_mov_b32 m0, s2
	v_readfirstlane_b32 s2, v218
	global_load_lds_dwordx4 v[2:3], off
	v_lshl_add_u64 v[2:3], v[106:107], 0, s[0:1]
	v_readfirstlane_b32 s0, v217
	s_mov_b32 m0, s0
	s_min_i32 s0, s68, 3
	s_ashr_i32 s1, s0, 31
	s_lshl_b64 s[0:1], s[0:1], 13
	global_load_lds_dwordx4 v[2:3], off
	v_lshl_add_u64 v[2:3], v[104:105], 0, s[0:1]
	s_mov_b32 m0, s2
	v_add_u32_e32 v113, s76, v224
	global_load_lds_dwordx4 v[2:3], off
	v_lshl_add_u64 v[2:3], v[106:107], 0, s[0:1]
	v_readfirstlane_b32 s0, v221
	s_mov_b32 m0, s0
	s_min_i32 s0, s68, 4
	s_ashr_i32 s1, s0, 31
	s_lshl_b64 s[0:1], s[0:1], 13
	v_readfirstlane_b32 s2, v113
	global_load_lds_dwordx4 v[2:3], off
	v_lshl_add_u64 v[2:3], v[104:105], 0, s[0:1]
	s_mov_b32 m0, s2
	v_add_u32_e32 v114, s78, v224
	global_load_lds_dwordx4 v[2:3], off
	v_lshl_add_u64 v[2:3], v[106:107], 0, s[0:1]
	v_readfirstlane_b32 s0, v114
	s_mov_b32 m0, s0
	v_lshlrev_b32_e32 v0, 8, v199
	global_load_lds_dwordx4 v[2:3], off
	s_waitcnt vmcnt(8)
	s_barrier
	ds_read_b128 v[2:5], v222
	ds_read_b128 v[6:9], v222 offset:4096
	s_waitcnt lgkmcnt(0)
	v_mfma_f32_32x32x16_bf16 v[34:49], v[2:5], v[162:165], 0
	s_mov_b32 s42, 0
	s_cmp_lt_i32 s74, 64
	s_nop 4
	v_mfma_f32_32x32x16_bf16 v[50:65], v[6:9], v[162:165], 0
	ds_read_b128 v[2:5], v219
	ds_read_b128 v[6:9], v219 offset:4096
	s_nop 0
	v_readlane_b32 s12, v252, 15
	v_readlane_b32 s13, v252, 16
	s_nop 1
	v_readlane_b32 s16, v252, 19
	s_waitcnt lgkmcnt(0)
	v_mfma_f32_32x32x16_bf16 v[34:49], v[2:5], v[166:169], v[34:49]
	v_readlane_b32 s17, v252, 20
	v_readlane_b32 s18, v252, 21
	v_readlane_b32 s19, v252, 22
	v_mfma_f32_32x32x16_bf16 v[50:65], v[6:9], v[166:169], v[50:65]
	ds_read_b128 v[2:5], v212
	ds_read_b128 v[6:9], v212 offset:4096
	s_waitcnt lgkmcnt(0)
	v_mfma_f32_32x32x16_bf16 v[34:49], v[2:5], v[170:173], v[34:49]
	v_mfma_f32_32x32x16_bf16 v[50:65], v[6:9], v[170:173], v[50:65]
	ds_read_b128 v[2:5], v211
	ds_read_b128 v[6:9], v211 offset:4096
	s_waitcnt lgkmcnt(0)
	v_mfma_f32_32x32x16_bf16 v[34:49], v[2:5], v[174:177], v[34:49]
	v_and_b32_e32 v2, 0xc0, v224
	v_add3_u32 v0, 0, v0, v2
	v_add3_u32 v112, v0, v229, v228
	v_mfma_f32_32x32x16_bf16 v[50:65], v[6:9], v[174:177], v[50:65]
	s_cbranch_scc0 .LBB0_1176
	v_mov_b32_e32 v2, v1
	v_mov_b32_e32 v3, v1
	v_mov_b32_e32 v4, v1
	v_mov_b32_e32 v5, v1
	v_mov_b32_e32 v6, v1
	v_mov_b32_e32 v7, v1
	v_mov_b32_e32 v8, v1
	v_mov_b32_e32 v9, v1
	v_mov_b32_e32 v10, v1
	v_mov_b32_e32 v11, v1
	v_mov_b32_e32 v12, v1
	v_mov_b32_e32 v13, v1
	v_mov_b32_e32 v14, v1
	v_mov_b32_e32 v15, v1
	v_mov_b32_e32 v16, v1
	v_mov_b32_e32 v17, v1
	v_mov_b32_e32 v18, v1
	v_mov_b32_e32 v19, v1
	v_mov_b32_e32 v20, v1
	v_mov_b32_e32 v21, v1
	v_mov_b32_e32 v22, v1
	v_mov_b32_e32 v23, v1
	v_mov_b32_e32 v24, v1
	v_mov_b32_e32 v25, v1
	v_mov_b32_e32 v26, v1
	v_mov_b32_e32 v27, v1
	v_mov_b32_e32 v28, v1
	v_mov_b32_e32 v29, v1
	v_mov_b32_e32 v30, v1
	v_mov_b32_e32 v31, v1
	v_mov_b32_e32 v0, v1
	v_mov_b64_e32 v[32:33], v[30:31]
	v_cmp_gt_i32_e64 s[0:1], 0, v184
	s_mov_b32 s43, 5
	s_mov_b64 s[38:39], -1
	v_mov_b32_e32 v115, 0
	v_mov_b32_e32 v116, 0xf149f2ca
	s_movk_i32 s44, 0x7f
	v_mov_b64_e32 v[30:31], v[28:29]
	v_mov_b64_e32 v[28:29], v[26:27]
	v_mov_b64_e32 v[26:27], v[24:25]
	v_mov_b64_e32 v[24:25], v[22:23]
	v_mov_b64_e32 v[22:23], v[20:21]
	v_mov_b64_e32 v[20:21], v[18:19]
	v_mov_b64_e32 v[18:19], v[16:17]
	v_mov_b64_e32 v[16:17], v[14:15]
	v_mov_b64_e32 v[14:15], v[12:13]
	v_mov_b64_e32 v[12:13], v[10:11]
	v_mov_b64_e32 v[10:11], v[8:9]
	v_mov_b64_e32 v[8:9], v[6:7]
	v_mov_b64_e32 v[6:7], v[4:5]
	v_mov_b64_e32 v[4:5], v[2:3]
	v_mov_b64_e32 v[2:3], v[0:1]
	s_mov_b32 s45, 0
	s_branch .LBB0_1150

.LBB0_1203:
	s_waitcnt vmcnt(0)
	s_barrier
	s_mov_b64 s[0:1], exec
	v_readlane_b32 s2, v253, 51
	v_readlane_b32 s64, v253, 55
	v_readlane_b32 s3, v253, 52
	s_nop 1
	s_and_b64 s[2:3], s[0:1], s[2:3]
	v_readlane_b32 s68, v252, 33
	s_xor_b64 s[0:1], s[2:3], s[0:1]
	v_readlane_b32 s65, v253, 56
	v_readlane_b32 s66, v253, 57
	v_readlane_b32 s67, v253, 58
	v_readlane_b32 s69, v252, 34
	s_nop 7
	s_nop 1
	s_mov_b64 exec, s[2:3]
	s_cbranch_execz .LBB0_1256
	s_add_i32 s2, 0, 0x20800
	v_mov_b32_e32 v0, s2
	s_waitcnt vmcnt(0) expcnt(0) lgkmcnt(0)
	ds_read_b32 v2, v0
	s_add_i32 s2, 0, 0x20804
	v_mov_b32_e32 v0, s2
	ds_read_b32 v0, v0
	s_waitcnt lgkmcnt(1)
	v_cmp_ne_u32_e32 vcc, 0, v2
	s_cbranch_vccnz .LBB0_1219
	v_readlane_b32 s2, v253, 1
	s_mul_i32 s16, s93, s2
	s_add_u32 s2, s90, 0x1000
	s_addc_u32 s3, s91, 0
	s_add_u32 s4, s90, 0x1100
	s_addc_u32 s5, s91, 0
	s_add_u32 s6, s90, 0x1200
	s_addc_u32 s7, s91, 0
	s_add_u32 s8, s90, 0x1300
	s_mul_i32 s16, s16, s92
	s_addc_u32 s9, s91, 0
	s_mov_b32 s17, 1
	v_mov_b32_e32 v16, 0
	s_branch .LBB0_1207

.LBB0_1256:
	s_or_b64 exec, exec, s[0:1]
	s_cmpk_lt_i32 s62, 0x200
	v_readlane_b32 s0, v252, 23
	s_cselect_b64 s[8:9], -1, 0
	s_lshr_b32 s0, s0, 30
	s_add_i32 s0, s62, s0
	s_ashr_i32 s2, s0, 2
	s_and_b32 s0, s0, -4
	s_sub_i32 s30, s62, s0
	v_readlane_b32 s0, v252, 25
	s_and_b32 s0, s0, 0x70
	v_readlane_b32 s1, v252, 26
	s_add_i32 s3, s0, s1
	s_add_i32 s34, s3, 8
	s_or_b64 s[4:5], s[68:69], s[8:9]
	s_and_b64 s[0:1], s[68:69], exec
	v_readlane_b32 s0, v252, 24
	s_waitcnt lgkmcnt(0)
	s_barrier
	v_mov_b32 v8, v178
	s_cselect_b32 s0, s0, s30
	v_readfirstlane_b32 s26, v8
	s_cselect_b32 s6, s3, s2
	s_and_b64 vcc, exec, s[4:5]
	s_cbranch_vccz .LBB0_1273
	v_lshlrev_b32_e32 v0, 4, v8
	v_add_u32_e32 v1, 0x2000, v0
	v_ashrrev_i32_e32 v2, 31, v1
	v_lshrrev_b32_e32 v2, 22, v2
	v_add_u32_e32 v2, v1, v2
	v_ashrrev_i32_e32 v9, 10, v2
	v_mul_i32_i24_e32 v2, 0x400, v9
	v_sub_u32_e32 v1, v1, v2
	v_lshrrev_b32_e32 v2, 4, v1
	v_bitop3_b32 v1, v2, v1, 32 bitop3:0x6c
	v_ashrrev_i32_e32 v2, 31, v1
	v_lshrrev_b32_e32 v2, 26, v2
	v_add_u32_e32 v2, v1, v2
	v_lshlrev_b32_e32 v3, 3, v9
	v_ashrrev_i32_e32 v10, 6, v2
	v_and_b32_e32 v3, -16, v3
	v_add_u32_e32 v3, v10, v3
	v_and_b32_e32 v4, 3, v10
	s_mov_b32 s1, 0x3fffe0
	v_lshrrev_b32_e32 v5, 2, v3
	v_lshlrev_b32_e32 v6, 1, v3
	v_and_b32_e32 v2, 0xc0, v2
	v_and_or_b32 v4, v3, s1, v4
	v_and_b32_e32 v5, 4, v5
	v_and_b32_e32 v6, 24, v6
	v_sub_u32_e32 v1, v1, v2
	v_mov_b32_e32 v2, 1
	v_or3_b32 v4, v4, v5, v6
	v_lshlrev_b32_e32 v5, 5, v9
	v_ashrrev_i16_sdwa v1, v2, sext(v1) dst_sel:DWORD dst_unused:UNUSED_PAD src0_sel:DWORD src1_sel:BYTE_0
	v_and_b32_e32 v5, 32, v5
	v_bfe_i32 v11, v1, 0, 16
	v_add_lshl_u32 v1, v5, v11, 1
	v_lshl_add_u32 v128, v4, 10, v1
	v_lshl_add_u32 v130, v3, 10, v1
	v_bfe_i32 v1, v8, 27, 1
	v_lshrrev_b32_e32 v1, 22, v1
	v_add_u32_e32 v1, v0, v1
	v_and_b32_e32 v1, 0xfffffc00, v1
	v_sub_u32_e32 v0, v0, v1
	v_lshrrev_b32_e32 v1, 4, v0
	v_bitop3_b32 v1, v1, v0, 32 bitop3:0x6c
	v_ashrrev_i32_e32 v0, 31, v0
	v_lshrrev_b32_e32 v0, 26, v0
	v_add_u32_e32 v0, v1, v0
	v_ashrrev_i32_e32 v12, 6, v0
	v_ashrrev_i32_e32 v0, 31, v8
	v_lshrrev_b32_e32 v0, 26, v0
	v_add_u32_e32 v0, v8, v0
	v_ashrrev_i32_e32 v13, 6, v0
	v_lshlrev_b32_e32 v0, 3, v13
	v_and_b32_e32 v0, -16, v0
	v_add_u32_e32 v0, v12, v0
	s_ashr_i32 s2, s26, 6
	v_and_b32_e32 v3, 3, v12
	v_lshrrev_b32_e32 v4, 2, v0
	v_lshlrev_b32_e32 v5, 1, v0
	s_ashr_i32 s7, s6, 31
	s_ashr_i32 s12, s26, 8
	s_lshl_b32 s27, s2, 10
	v_and_or_b32 v3, v0, s1, v3
	v_and_b32_e32 v4, 4, v4
	v_and_b32_e32 v5, 24, v5
	s_lshl_b64 s[10:11], s[6:7], 18
	v_or3_b32 v3, v3, v4, v5
	v_mul_i32_i24_e32 v5, 64, v12
	s_add_u32 s10, s80, s10
	v_sub_u32_e32 v1, v1, v5
	s_addc_u32 s11, s81, s11
	s_ashr_i32 s1, s0, 31
	s_nop 0
	v_lshlrev_b32_e32 v4, 5, v13
	v_ashrrev_i16_sdwa v1, v2, sext(v1) dst_sel:DWORD dst_unused:UNUSED_PAD src0_sel:DWORD src1_sel:BYTE_0
	s_lshl_b64 s[14:15], s[0:1], 18
	v_readlane_b32 s46, v253, 44
	v_and_b32_e32 v4, 32, v4
	v_bfe_i32 v14, v1, 0, 16
	v_readlane_b32 s47, v253, 45
	s_add_u32 s22, s46, s14
	v_add_lshl_u32 v1, v4, v14, 1
	s_addc_u32 s23, s47, s15
	s_add_i32 s1, s27, 0
	v_lshl_add_u32 v132, v3, 10, v1
	s_add_i32 m0, s1, 0x10000
	v_lshl_add_u32 v134, v0, 10, v1
	global_load_lds_dwordx4 v132, s[22:23]
	s_add_i32 m0, s1, 0x12000
	s_add_i32 s7, s1, 0x2000
	global_load_lds_dwordx4 v128, s[22:23]
	s_mov_b32 m0, s1
	s_add_u32 s14, s22, 0x20000
	global_load_lds_dwordx4 v134, s[10:11]
	s_mov_b32 m0, s7
	s_addc_u32 s15, s23, 0
	global_load_lds_dwordx4 v130, s[10:11]
	s_add_i32 m0, s1, 0x14000
	v_mov_b32_e32 v133, 0
	global_load_lds_dwordx4 v132, s[14:15]
	s_add_i32 m0, s1, 0x16000
	v_mov_b32_e32 v129, v133
	global_load_lds_dwordx4 v128, s[14:15]
	s_add_u32 s14, s10, 0x20000
	s_addc_u32 s15, s11, 0
	s_add_i32 s28, s1, 0x4000
	s_mov_b32 m0, s28
	s_add_i32 s29, s1, 0x6000
	global_load_lds_dwordx4 v134, s[14:15]
	s_mov_b32 m0, s29
	v_mov_b32_e32 v135, v133
	global_load_lds_dwordx4 v130, s[14:15]
	v_mov_b32_e32 v131, v133
	s_mov_b32 s13, 0
	v_lshl_add_u64 v[6:7], s[22:23], 0, v[132:133]
	v_lshl_add_u64 v[4:5], s[22:23], 0, v[128:129]
	v_lshl_add_u64 v[2:3], s[10:11], 0, v[134:135]
	s_cmp_lg_u32 s12, 1
	v_lshl_add_u64 v[0:1], s[10:11], 0, v[130:131]
	s_nop 7
	s_nop 4
	s_cbranch_scc1 .LBB0_1259
	s_barrier

.LBB0_1267:
	s_ashr_i32 s13, s12, 31
	s_xor_b64 s[18:19], s[24:25], -1
	s_lshl_b64 s[16:17], s[12:13], 18
	s_add_u32 s16, s80, s16
	s_addc_u32 s17, s81, s17
	s_and_b64 s[20:21], s[24:25], exec
	s_nop 0
	s_cselect_b32 s13, s17, s11
	s_cselect_b32 s40, s16, s10
	s_ashr_i32 s15, s14, 31
	s_nop 1
	v_readlane_b32 s54, v253, 44
	v_readlane_b32 s55, v253, 45
	s_lshl_b64 s[20:21], s[14:15], 18
	s_mov_b64 s[50:51], s[54:55]
	s_add_u32 s20, s50, s20
	s_addc_u32 s21, s51, s21
	s_and_b64 s[24:25], s[24:25], exec
	s_cselect_b32 s15, s21, s23
	s_cselect_b32 s41, s20, s22
	s_add_u32 s10, s10, 0x20080
	s_addc_u32 s11, s11, 0
	s_add_u32 s42, s22, 0x100
	v_mov_b32_e32 v0, 0
	s_addc_u32 s43, s23, 0
	s_mov_b32 s44, -2
	v_mov_b32_e32 v1, v0
	v_mov_b32_e32 v2, v0
	v_mov_b32_e32 v3, v0
	v_mov_b32_e32 v4, v0
	v_mov_b32_e32 v5, v0
	v_mov_b32_e32 v6, v0
	v_mov_b32_e32 v7, v0
	v_mov_b32_e32 v12, v0
	v_mov_b32_e32 v13, v0
	v_mov_b32_e32 v14, v0
	v_mov_b32_e32 v15, v0
	v_mov_b32_e32 v20, v0
	v_mov_b32_e32 v21, v0
	v_mov_b32_e32 v22, v0
	v_mov_b32_e32 v23, v0
	v_mov_b32_e32 v28, v0
	v_mov_b32_e32 v29, v0
	v_mov_b32_e32 v30, v0
	v_mov_b32_e32 v31, v0
	v_mov_b32_e32 v36, v0
	v_mov_b32_e32 v37, v0
	v_mov_b32_e32 v38, v0
	v_mov_b32_e32 v39, v0
	v_mov_b32_e32 v44, v0
	v_mov_b32_e32 v45, v0
	v_mov_b32_e32 v46, v0
	v_mov_b32_e32 v47, v0
	v_mov_b32_e32 v52, v0
	v_mov_b32_e32 v53, v0
	v_mov_b32_e32 v54, v0
	v_mov_b32_e32 v55, v0
	v_mov_b32_e32 v8, v0
	v_mov_b32_e32 v9, v0
	v_mov_b32_e32 v10, v0
	v_mov_b32_e32 v11, v0
	v_mov_b32_e32 v16, v0
	v_mov_b32_e32 v17, v0
	v_mov_b32_e32 v18, v0
	v_mov_b32_e32 v19, v0
	v_mov_b32_e32 v24, v0
	v_mov_b32_e32 v25, v0
	v_mov_b32_e32 v26, v0
	v_mov_b32_e32 v27, v0
	v_mov_b32_e32 v32, v0
	v_mov_b32_e32 v33, v0
	v_mov_b32_e32 v34, v0
	v_mov_b32_e32 v35, v0
	v_mov_b32_e32 v40, v0
	v_mov_b32_e32 v41, v0
	v_mov_b32_e32 v42, v0
	v_mov_b32_e32 v43, v0
	v_mov_b32_e32 v48, v0
	v_mov_b32_e32 v49, v0
	v_mov_b32_e32 v50, v0
	v_mov_b32_e32 v51, v0
	v_mov_b32_e32 v56, v0
	v_mov_b32_e32 v57, v0
	v_mov_b32_e32 v58, v0
	v_mov_b32_e32 v59, v0
	v_mov_b32_e32 v60, v0
	v_mov_b32_e32 v61, v0
	v_mov_b32_e32 v62, v0
	v_mov_b32_e32 v63, v0
	v_mov_b32_e32 v64, v0
	v_mov_b32_e32 v65, v0
	v_mov_b32_e32 v66, v0
	v_mov_b32_e32 v67, v0
	v_mov_b32_e32 v68, v0
	v_mov_b32_e32 v69, v0
	v_mov_b32_e32 v70, v0
	v_mov_b32_e32 v71, v0
	v_mov_b32_e32 v76, v0
	v_mov_b32_e32 v77, v0
	v_mov_b32_e32 v78, v0
	v_mov_b32_e32 v79, v0
	v_mov_b32_e32 v84, v0
	v_mov_b32_e32 v85, v0
	v_mov_b32_e32 v86, v0
	v_mov_b32_e32 v87, v0
	v_mov_b32_e32 v92, v0
	v_mov_b32_e32 v93, v0
	v_mov_b32_e32 v94, v0
	v_mov_b32_e32 v95, v0
	v_mov_b32_e32 v100, v0
	v_mov_b32_e32 v101, v0
	v_mov_b32_e32 v102, v0
	v_mov_b32_e32 v103, v0
	v_mov_b32_e32 v108, v0
	v_mov_b32_e32 v109, v0
	v_mov_b32_e32 v110, v0
	v_mov_b32_e32 v111, v0
	v_mov_b32_e32 v116, v0
	v_mov_b32_e32 v117, v0
	v_mov_b32_e32 v118, v0
	v_mov_b32_e32 v119, v0
	v_mov_b32_e32 v72, v0
	v_mov_b32_e32 v73, v0
	v_mov_b32_e32 v74, v0
	v_mov_b32_e32 v75, v0
	v_mov_b32_e32 v80, v0
	v_mov_b32_e32 v81, v0
	v_mov_b32_e32 v82, v0
	v_mov_b32_e32 v83, v0
	v_mov_b32_e32 v88, v0
	v_mov_b32_e32 v89, v0
	v_mov_b32_e32 v90, v0
	v_mov_b32_e32 v91, v0
	v_mov_b32_e32 v96, v0
	v_mov_b32_e32 v97, v0
	v_mov_b32_e32 v98, v0
	v_mov_b32_e32 v99, v0
	v_mov_b32_e32 v104, v0
	v_mov_b32_e32 v105, v0
	v_mov_b32_e32 v106, v0
	v_mov_b32_e32 v107, v0
	v_mov_b32_e32 v112, v0
	v_mov_b32_e32 v113, v0
	v_mov_b32_e32 v114, v0
	v_mov_b32_e32 v115, v0
	v_mov_b32_e32 v120, v0
	v_mov_b32_e32 v121, v0
	v_mov_b32_e32 v122, v0
	v_mov_b32_e32 v123, v0
	v_mov_b32_e32 v124, v0
	v_mov_b32_e32 v125, v0
	v_mov_b32_e32 v126, v0
	v_mov_b32_e32 v127, v0
	s_nop 7
	s_nop 2
.LBB0_1268:
	ds_read_b128 v[140:143], v149
	ds_read_b128 v[152:155], v149 offset:1024
	ds_read_b128 v[156:159], v149 offset:2048
	ds_read_b128 v[160:163], v149 offset:3072
	s_add_u32 s22, s10, 0xfffe0080
	s_addc_u32 s23, s11, -1
	s_cmp_eq_u32 s44, 4
	s_cselect_b32 s25, s13, s23
	s_cselect_b32 s24, s40, s22
	s_cselect_b32 s23, s15, s43
	s_cselect_b32 s22, s41, s42
	v_lshl_add_u64 v[144:145], s[10:11], 0, v[136:137]
	s_add_i32 m0, s1, 0xc000
	ds_read_b128 v[164:167], v150
	ds_read_b128 v[168:171], v150 offset:1024
	ds_read_b128 v[172:175], v150 offset:2048
	ds_read_b128 v[180:183], v150 offset:3072
	ds_read_b128 v[184:187], v150 offset:4096
	ds_read_b128 v[188:191], v150 offset:5120
	ds_read_b128 v[192:195], v150 offset:6144
	ds_read_b128 v[196:199], v150 offset:7168
	global_load_lds_dwordx4 v[144:145], off
	v_lshl_add_u64 v[144:145], s[10:11], 0, v[138:139]
	s_add_i32 m0, s1, 0xe000
	s_nop 0
	global_load_lds_dwordx4 v[144:145], off
	s_waitcnt lgkmcnt(8)
	s_barrier
	s_waitcnt lgkmcnt(0)
	s_setprio 1
	s_waitcnt lgkmcnt(0)
	v_mfma_f32_16x16x32_bf16 v[124:127], v[140:143], v[164:167], v[124:127]
	v_mfma_f32_16x16x32_bf16 v[120:123], v[156:159], v[164:167], v[120:123]
	v_mfma_f32_16x16x32_bf16 v[112:115], v[140:143], v[172:175], v[112:115]
	v_mfma_f32_16x16x32_bf16 v[104:107], v[156:159], v[172:175], v[104:107]
	v_mfma_f32_16x16x32_bf16 v[96:99], v[140:143], v[184:187], v[96:99]
	v_mfma_f32_16x16x32_bf16 v[88:91], v[156:159], v[184:187], v[88:91]
	v_mfma_f32_16x16x32_bf16 v[80:83], v[140:143], v[192:195], v[80:83]
	v_mfma_f32_16x16x32_bf16 v[72:75], v[156:159], v[192:195], v[72:75]
	v_mfma_f32_16x16x32_bf16 v[124:127], v[152:155], v[168:171], v[124:127]
	v_mfma_f32_16x16x32_bf16 v[120:123], v[160:163], v[168:171], v[120:123]
	v_mfma_f32_16x16x32_bf16 v[112:115], v[152:155], v[180:183], v[112:115]
	v_mfma_f32_16x16x32_bf16 v[104:107], v[160:163], v[180:183], v[104:107]
	v_mfma_f32_16x16x32_bf16 v[96:99], v[152:155], v[188:191], v[96:99]
	v_mfma_f32_16x16x32_bf16 v[88:91], v[160:163], v[188:191], v[88:91]
	v_mfma_f32_16x16x32_bf16 v[80:83], v[152:155], v[196:199], v[80:83]
	v_mfma_f32_16x16x32_bf16 v[72:75], v[160:163], v[196:199], v[72:75]
	s_setprio 0
	s_barrier
	s_add_i32 s45, s35, s27
	v_lshl_add_u64 v[144:145], s[22:23], 0, v[132:133]
	s_mov_b32 m0, s45
	ds_read_b128 v[200:203], v151
	ds_read_b128 v[204:207], v151 offset:1024
	ds_read_b128 v[208:211], v151 offset:2048
	ds_read_b128 v[212:215], v151 offset:3072
	global_load_lds_dwordx4 v[144:145], off
	v_lshl_add_u64 v[176:177], s[22:23], 0, v[128:129]
	s_add_i32 m0, s45, 0x2000
	s_nop 0
	global_load_lds_dwordx4 v[176:177], off
	s_barrier
	s_waitcnt lgkmcnt(0)
	s_setprio 1
	s_waitcnt lgkmcnt(0)
	v_mfma_f32_16x16x32_bf16 v[116:119], v[200:203], v[164:167], v[116:119]
	v_mfma_f32_16x16x32_bf16 v[108:111], v[208:211], v[164:167], v[108:111]
	v_mfma_f32_16x16x32_bf16 v[100:103], v[200:203], v[172:175], v[100:103]
	v_mfma_f32_16x16x32_bf16 v[92:95], v[208:211], v[172:175], v[92:95]
	v_mfma_f32_16x16x32_bf16 v[84:87], v[200:203], v[184:187], v[84:87]
	v_mfma_f32_16x16x32_bf16 v[76:79], v[208:211], v[184:187], v[76:79]
	v_mfma_f32_16x16x32_bf16 v[68:71], v[200:203], v[192:195], v[68:71]
	v_mfma_f32_16x16x32_bf16 v[64:67], v[208:211], v[192:195], v[64:67]
	v_mfma_f32_16x16x32_bf16 v[116:119], v[204:207], v[168:171], v[116:119]
	v_mfma_f32_16x16x32_bf16 v[108:111], v[212:215], v[168:171], v[108:111]
	v_mfma_f32_16x16x32_bf16 v[100:103], v[204:207], v[180:183], v[100:103]
	v_mfma_f32_16x16x32_bf16 v[92:95], v[212:215], v[180:183], v[92:95]
	v_mfma_f32_16x16x32_bf16 v[84:87], v[204:207], v[188:191], v[84:87]
	v_mfma_f32_16x16x32_bf16 v[76:79], v[212:215], v[188:191], v[76:79]
	v_mfma_f32_16x16x32_bf16 v[68:71], v[204:207], v[196:199], v[68:71]
	v_mfma_f32_16x16x32_bf16 v[64:67], v[212:215], v[196:199], v[64:67]
	s_setprio 0
	s_mov_b32 m0, s1
	v_lshl_add_u64 v[216:217], s[24:25], 0, v[134:135]
	s_barrier
	ds_read_b128 v[164:167], v150 offset:16384
	ds_read_b128 v[168:171], v150 offset:17408
	ds_read_b128 v[172:175], v150 offset:18432
	ds_read_b128 v[180:183], v150 offset:19456
	ds_read_b128 v[184:187], v150 offset:20480
	ds_read_b128 v[188:191], v150 offset:21504
	ds_read_b128 v[192:195], v150 offset:22528
	ds_read_b128 v[196:199], v150 offset:23552
	global_load_lds_dwordx4 v[216:217], off
	v_lshl_add_u64 v[218:219], s[24:25], 0, v[130:131]
	s_mov_b32 m0, s7
	s_nop 0
	global_load_lds_dwordx4 v[218:219], off
	s_barrier
	s_waitcnt lgkmcnt(0)
	s_setprio 1
	s_waitcnt lgkmcnt(0)
	v_mfma_f32_16x16x32_bf16 v[60:63], v[140:143], v[164:167], v[60:63]
	v_mfma_f32_16x16x32_bf16 v[56:59], v[156:159], v[164:167], v[56:59]
	v_mfma_f32_16x16x32_bf16 v[48:51], v[140:143], v[172:175], v[48:51]
	v_mfma_f32_16x16x32_bf16 v[40:43], v[156:159], v[172:175], v[40:43]
	v_mfma_f32_16x16x32_bf16 v[32:35], v[140:143], v[184:187], v[32:35]
	v_mfma_f32_16x16x32_bf16 v[24:27], v[156:159], v[184:187], v[24:27]
	v_mfma_f32_16x16x32_bf16 v[16:19], v[140:143], v[192:195], v[16:19]
	v_mfma_f32_16x16x32_bf16 v[8:11], v[156:159], v[192:195], v[8:11]
	v_mfma_f32_16x16x32_bf16 v[60:63], v[152:155], v[168:171], v[60:63]
	v_mfma_f32_16x16x32_bf16 v[56:59], v[160:163], v[168:171], v[56:59]
	v_mfma_f32_16x16x32_bf16 v[48:51], v[152:155], v[180:183], v[48:51]
	v_mfma_f32_16x16x32_bf16 v[40:43], v[160:163], v[180:183], v[40:43]
	v_mfma_f32_16x16x32_bf16 v[32:35], v[152:155], v[188:191], v[32:35]
	v_mfma_f32_16x16x32_bf16 v[24:27], v[160:163], v[188:191], v[24:27]
	v_mfma_f32_16x16x32_bf16 v[16:19], v[152:155], v[196:199], v[16:19]
	v_mfma_f32_16x16x32_bf16 v[8:11], v[160:163], v[196:199], v[8:11]
	s_setprio 0
	s_barrier
	s_add_u32 s46, s22, 0x20000
	s_addc_u32 s47, s23, 0
	s_add_i32 s45, s36, s27
	v_lshl_add_u64 v[140:141], s[46:47], 0, v[132:133]
	s_mov_b32 m0, s45
	s_nop 0
	global_load_lds_dwordx4 v[140:141], off
	v_lshl_add_u64 v[140:141], s[46:47], 0, v[128:129]
	s_add_i32 m0, s45, 0x2000
	s_nop 0
	global_load_lds_dwordx4 v[140:141], off
	s_waitcnt vmcnt(6)
	s_barrier
	s_setprio 1
	v_mfma_f32_16x16x32_bf16 v[52:55], v[200:203], v[164:167], v[52:55]
	v_mfma_f32_16x16x32_bf16 v[44:47], v[208:211], v[164:167], v[44:47]
	v_mfma_f32_16x16x32_bf16 v[36:39], v[200:203], v[172:175], v[36:39]
	v_mfma_f32_16x16x32_bf16 v[28:31], v[208:211], v[172:175], v[28:31]
	v_mfma_f32_16x16x32_bf16 v[20:23], v[200:203], v[184:187], v[20:23]
	v_mfma_f32_16x16x32_bf16 v[12:15], v[208:211], v[184:187], v[12:15]
	v_mfma_f32_16x16x32_bf16 v[4:7], v[200:203], v[192:195], v[4:7]
	v_mfma_f32_16x16x32_bf16 v[0:3], v[208:211], v[192:195], v[0:3]
	v_mfma_f32_16x16x32_bf16 v[52:55], v[204:207], v[168:171], v[52:55]
	v_mfma_f32_16x16x32_bf16 v[44:47], v[212:215], v[168:171], v[44:47]
	v_mfma_f32_16x16x32_bf16 v[36:39], v[204:207], v[180:183], v[36:39]
	v_mfma_f32_16x16x32_bf16 v[28:31], v[212:215], v[180:183], v[28:31]
	v_mfma_f32_16x16x32_bf16 v[20:23], v[204:207], v[188:191], v[20:23]
	v_mfma_f32_16x16x32_bf16 v[12:15], v[212:215], v[188:191], v[12:15]
	v_mfma_f32_16x16x32_bf16 v[4:7], v[204:207], v[196:199], v[4:7]
	v_mfma_f32_16x16x32_bf16 v[0:3], v[212:215], v[196:199], v[0:3]
	s_setprio 0
	s_add_i32 s45, 0, 0x18000
	v_add_u32_e32 v160, s45, v147
	s_barrier
	ds_read_b128 v[140:143], v160
	ds_read_b128 v[152:155], v160 offset:1024
	ds_read_b128 v[156:159], v160 offset:2048
	ds_read_b128 v[160:163], v160 offset:3072
	s_add_u32 s24, s24, 0x20000
	s_addc_u32 s25, s25, 0
	s_mov_b32 m0, s28
	v_lshl_add_u64 v[200:201], s[24:25], 0, v[134:135]
	ds_read_b128 v[164:167], v150 offset:32768
	ds_read_b128 v[168:171], v150 offset:33792
	ds_read_b128 v[172:175], v150 offset:34816
	ds_read_b128 v[180:183], v150 offset:35840
	ds_read_b128 v[184:187], v150 offset:36864
	ds_read_b128 v[188:191], v150 offset:37888
	ds_read_b128 v[192:195], v150 offset:38912
	ds_read_b128 v[196:199], v150 offset:39936
	global_load_lds_dwordx4 v[200:201], off
	v_lshl_add_u64 v[200:201], s[24:25], 0, v[130:131]
	s_mov_b32 m0, s29
	s_nop 0
	global_load_lds_dwordx4 v[200:201], off
	s_waitcnt lgkmcnt(8)
	s_barrier
	s_waitcnt lgkmcnt(0)
	s_setprio 1
	s_waitcnt lgkmcnt(0)
	v_mfma_f32_16x16x32_bf16 v[124:127], v[140:143], v[164:167], v[124:127]
	v_mfma_f32_16x16x32_bf16 v[120:123], v[156:159], v[164:167], v[120:123]
	v_mfma_f32_16x16x32_bf16 v[112:115], v[140:143], v[172:175], v[112:115]
	v_mfma_f32_16x16x32_bf16 v[104:107], v[156:159], v[172:175], v[104:107]
	v_mfma_f32_16x16x32_bf16 v[96:99], v[140:143], v[184:187], v[96:99]
	v_mfma_f32_16x16x32_bf16 v[88:91], v[156:159], v[184:187], v[88:91]
	v_mfma_f32_16x16x32_bf16 v[80:83], v[140:143], v[192:195], v[80:83]
	v_mfma_f32_16x16x32_bf16 v[72:75], v[156:159], v[192:195], v[72:75]
	v_mfma_f32_16x16x32_bf16 v[124:127], v[152:155], v[168:171], v[124:127]
	v_mfma_f32_16x16x32_bf16 v[120:123], v[160:163], v[168:171], v[120:123]
	v_mfma_f32_16x16x32_bf16 v[112:115], v[152:155], v[180:183], v[112:115]
	v_mfma_f32_16x16x32_bf16 v[104:107], v[160:163], v[180:183], v[104:107]
	v_mfma_f32_16x16x32_bf16 v[96:99], v[152:155], v[188:191], v[96:99]
	v_mfma_f32_16x16x32_bf16 v[88:91], v[160:163], v[188:191], v[88:91]
	v_mfma_f32_16x16x32_bf16 v[80:83], v[152:155], v[196:199], v[80:83]
	v_mfma_f32_16x16x32_bf16 v[72:75], v[160:163], v[196:199], v[72:75]
	s_setprio 0
	s_barrier
	s_add_i32 s24, 0, 0x1c000
	s_add_i32 s25, s45, s27
	v_add_u32_e32 v179, s24, v147
	v_lshl_add_u64 v[144:145], v[144:145], 0, s[2:3]
	s_mov_b32 m0, s25
	ds_read_b128 v[200:203], v179
	ds_read_b128 v[204:207], v179 offset:1024
	ds_read_b128 v[208:211], v179 offset:2048
	ds_read_b128 v[212:215], v179 offset:3072
	global_load_lds_dwordx4 v[144:145], off
	v_lshl_add_u64 v[144:145], v[176:177], 0, s[2:3]
	s_add_i32 m0, s25, 0x2000
	s_nop 0
	global_load_lds_dwordx4 v[144:145], off
	s_barrier
	s_waitcnt lgkmcnt(0)
	s_setprio 1
	s_waitcnt lgkmcnt(0)
	v_mfma_f32_16x16x32_bf16 v[116:119], v[200:203], v[164:167], v[116:119]
	v_mfma_f32_16x16x32_bf16 v[108:111], v[208:211], v[164:167], v[108:111]
	v_mfma_f32_16x16x32_bf16 v[100:103], v[200:203], v[172:175], v[100:103]
	v_mfma_f32_16x16x32_bf16 v[92:95], v[208:211], v[172:175], v[92:95]
	v_mfma_f32_16x16x32_bf16 v[84:87], v[200:203], v[184:187], v[84:87]
	v_mfma_f32_16x16x32_bf16 v[76:79], v[208:211], v[184:187], v[76:79]
	v_mfma_f32_16x16x32_bf16 v[68:71], v[200:203], v[192:195], v[68:71]
	v_mfma_f32_16x16x32_bf16 v[64:67], v[208:211], v[192:195], v[64:67]
	v_mfma_f32_16x16x32_bf16 v[116:119], v[204:207], v[168:171], v[116:119]
	v_mfma_f32_16x16x32_bf16 v[108:111], v[212:215], v[168:171], v[108:111]
	v_mfma_f32_16x16x32_bf16 v[100:103], v[204:207], v[180:183], v[100:103]
	v_mfma_f32_16x16x32_bf16 v[92:95], v[212:215], v[180:183], v[92:95]
	v_mfma_f32_16x16x32_bf16 v[84:87], v[204:207], v[188:191], v[84:87]
	v_mfma_f32_16x16x32_bf16 v[76:79], v[212:215], v[188:191], v[76:79]
	v_mfma_f32_16x16x32_bf16 v[68:71], v[204:207], v[196:199], v[68:71]
	v_mfma_f32_16x16x32_bf16 v[64:67], v[212:215], v[196:199], v[64:67]
	s_setprio 0
	s_mov_b32 m0, s31
	v_lshl_add_u64 v[144:145], v[216:217], 0, s[2:3]
	s_barrier
	ds_read_b128 v[164:167], v150 offset:49152
	ds_read_b128 v[168:171], v150 offset:50176
	ds_read_b128 v[172:175], v150 offset:51200
	ds_read_b128 v[180:183], v150 offset:52224
	ds_read_b128 v[184:187], v150 offset:53248
	ds_read_b128 v[188:191], v150 offset:54272
	ds_read_b128 v[192:195], v150 offset:55296
	ds_read_b128 v[196:199], v150 offset:56320
	global_load_lds_dwordx4 v[144:145], off
	v_lshl_add_u64 v[144:145], v[218:219], 0, s[2:3]
	s_mov_b32 m0, s33
	s_nop 0
	global_load_lds_dwordx4 v[144:145], off
	s_barrier
	s_waitcnt lgkmcnt(0)
	s_setprio 1
	s_waitcnt lgkmcnt(0)
	v_mfma_f32_16x16x32_bf16 v[60:63], v[140:143], v[164:167], v[60:63]
	v_mfma_f32_16x16x32_bf16 v[56:59], v[156:159], v[164:167], v[56:59]
	v_mfma_f32_16x16x32_bf16 v[48:51], v[140:143], v[172:175], v[48:51]
	v_mfma_f32_16x16x32_bf16 v[40:43], v[156:159], v[172:175], v[40:43]
	v_mfma_f32_16x16x32_bf16 v[32:35], v[140:143], v[184:187], v[32:35]
	v_mfma_f32_16x16x32_bf16 v[24:27], v[156:159], v[184:187], v[24:27]
	v_mfma_f32_16x16x32_bf16 v[16:19], v[140:143], v[192:195], v[16:19]
	v_mfma_f32_16x16x32_bf16 v[8:11], v[156:159], v[192:195], v[8:11]
	v_mfma_f32_16x16x32_bf16 v[60:63], v[152:155], v[168:171], v[60:63]
	v_mfma_f32_16x16x32_bf16 v[56:59], v[160:163], v[168:171], v[56:59]
	v_mfma_f32_16x16x32_bf16 v[48:51], v[152:155], v[180:183], v[48:51]
	v_mfma_f32_16x16x32_bf16 v[40:43], v[160:163], v[180:183], v[40:43]
	v_mfma_f32_16x16x32_bf16 v[32:35], v[152:155], v[188:191], v[32:35]
	v_mfma_f32_16x16x32_bf16 v[24:27], v[160:163], v[188:191], v[24:27]
	v_mfma_f32_16x16x32_bf16 v[16:19], v[152:155], v[196:199], v[16:19]
	v_mfma_f32_16x16x32_bf16 v[8:11], v[160:163], v[196:199], v[8:11]
	s_setprio 0
	s_barrier
	s_add_u32 s22, s22, 0x20080
	s_addc_u32 s23, s23, 0
	s_add_i32 s24, s24, s27
	v_lshl_add_u64 v[140:141], s[22:23], 0, v[132:133]
	s_mov_b32 m0, s24
	s_nop 0
	global_load_lds_dwordx4 v[140:141], off
	v_lshl_add_u64 v[140:141], s[22:23], 0, v[128:129]
	s_add_i32 m0, s24, 0x2000
	s_nop 0
	global_load_lds_dwordx4 v[140:141], off
	s_waitcnt vmcnt(6)
	s_barrier
	s_setprio 1
	v_mfma_f32_16x16x32_bf16 v[52:55], v[200:203], v[164:167], v[52:55]
	v_mfma_f32_16x16x32_bf16 v[44:47], v[208:211], v[164:167], v[44:47]
	v_mfma_f32_16x16x32_bf16 v[36:39], v[200:203], v[172:175], v[36:39]
	v_mfma_f32_16x16x32_bf16 v[28:31], v[208:211], v[172:175], v[28:31]
	v_mfma_f32_16x16x32_bf16 v[20:23], v[200:203], v[184:187], v[20:23]
	v_mfma_f32_16x16x32_bf16 v[12:15], v[208:211], v[184:187], v[12:15]
	v_mfma_f32_16x16x32_bf16 v[4:7], v[200:203], v[192:195], v[4:7]
	v_mfma_f32_16x16x32_bf16 v[0:3], v[208:211], v[192:195], v[0:3]
	v_mfma_f32_16x16x32_bf16 v[52:55], v[204:207], v[168:171], v[52:55]
	v_mfma_f32_16x16x32_bf16 v[44:47], v[212:215], v[168:171], v[44:47]
	v_mfma_f32_16x16x32_bf16 v[36:39], v[204:207], v[180:183], v[36:39]
	v_mfma_f32_16x16x32_bf16 v[28:31], v[212:215], v[180:183], v[28:31]
	v_mfma_f32_16x16x32_bf16 v[20:23], v[204:207], v[188:191], v[20:23]
	v_mfma_f32_16x16x32_bf16 v[12:15], v[212:215], v[188:191], v[12:15]
	v_mfma_f32_16x16x32_bf16 v[4:7], v[204:207], v[196:199], v[4:7]
	v_mfma_f32_16x16x32_bf16 v[0:3], v[212:215], v[196:199], v[0:3]
	s_setprio 0
	s_add_i32 s44, s44, 2
	s_add_u32 s10, s10, 0x100
	s_addc_u32 s11, s11, 0
	s_add_u32 s42, s42, 0x100
	s_addc_u32 s43, s43, 0
	s_cmp_gt_u32 s44, 5
	s_barrier
	s_cbranch_scc0 .LBB0_1268
	v_lshl_add_u32 v142, s39, 8, v146
	s_nop 0
	v_lshl_or_b32 v140, s38, 8, v148
	v_ashrrev_i32_e32 v143, 31, v142
	s_nop 1
	v_readlane_b32 s46, v252, 13
	v_readlane_b32 s47, v252, 14
	v_ashrrev_i32_e32 v141, 31, v140
	v_lshlrev_b64 v[144:145], 12, v[142:143]
	s_mov_b64 s[42:43], s[46:47]
	v_lshl_add_u64 v[144:145], s[42:43], 0, v[144:145]
	v_lshlrev_b64 v[140:141], 1, v[140:141]
	v_or_b32_e32 v172, 16, v142
	v_lshl_add_u64 v[144:145], v[144:145], 0, v[140:141]
	v_ashrrev_i32_e32 v173, 31, v172
	global_load_dwordx4 v[152:155], v[144:145], off
	global_load_dwordx4 v[156:159], v[144:145], off offset:256
	v_lshlrev_b64 v[144:145], 12, v[172:173]
	v_lshl_add_u64 v[144:145], s[42:43], 0, v[144:145]
	v_lshl_add_u64 v[144:145], v[144:145], 0, v[140:141]
	global_load_dwordx4 v[160:163], v[144:145], off
	global_load_dwordx4 v[164:167], v[144:145], off offset:256
	v_or_b32_e32 v176, 32, v142
	v_ashrrev_i32_e32 v177, 31, v176
	v_lshlrev_b64 v[168:169], 12, v[176:177]
	v_lshl_add_u64 v[168:169], s[42:43], 0, v[168:169]
	v_lshl_add_u64 v[182:183], v[168:169], 0, v[140:141]
	global_load_dwordx4 v[168:171], v[182:183], off
	v_or_b32_e32 v144, 48, v142
	v_ashrrev_i32_e32 v145, 31, v144
	v_lshlrev_b64 v[180:181], 12, v[144:145]
	v_lshlrev_b64 v[174:175], 11, v[142:143]
	v_lshlrev_b64 v[172:173], 11, v[172:173]
	v_lshl_add_u64 v[180:181], s[42:43], 0, v[180:181]
	v_lshl_add_u64 v[174:175], s[82:83], 0, v[174:175]
	v_lshl_add_u64 v[172:173], s[82:83], 0, v[172:173]
	v_lshl_add_u64 v[184:185], v[180:181], 0, v[140:141]
	v_lshl_add_u64 v[188:189], v[174:175], 0, v[140:141]
	v_lshl_add_u64 v[190:191], v[172:173], 0, v[140:141]
	global_load_dwordx4 v[172:175], v[182:183], off offset:256
	s_nop 0
	global_load_dwordx4 v[180:183], v[184:185], off
	s_nop 0
	global_load_dwordx4 v[184:187], v[184:185], off offset:256
	s_and_b64 vcc, exec, s[18:19]
	s_mov_b32 s38, s14
	s_mov_b32 s39, s12
	s_mov_b32 s15, s14
	s_mov_b32 s18, s12
	s_mov_b64 s[22:23], s[20:21]
	s_mov_b64 s[10:11], s[16:17]
	s_mov_b32 s13, s37
	s_nop 7
	s_nop 2
	s_waitcnt vmcnt(0)
	v_lshlrev_b32_e32 v194, 16, v154
	v_and_b32_e32 v195, 0xffff0000, v154
	v_lshlrev_b32_e32 v154, 16, v155
	v_and_b32_e32 v155, 0xffff0000, v155
	v_lshlrev_b32_e32 v196, 16, v156
	v_and_b32_e32 v197, 0xffff0000, v156
	v_lshlrev_b32_e32 v156, 16, v157
	v_and_b32_e32 v157, 0xffff0000, v157
	v_lshlrev_b32_e32 v198, 16, v158
	v_and_b32_e32 v199, 0xffff0000, v158
	v_lshlrev_b32_e32 v158, 16, v159
	v_and_b32_e32 v159, 0xffff0000, v159
	v_lshlrev_b32_e32 v192, 16, v152
	v_and_b32_e32 v193, 0xffff0000, v152
	v_lshlrev_b32_e32 v152, 16, v153
	v_and_b32_e32 v153, 0xffff0000, v153
	v_pk_mul_f32 v[120:121], v[120:121], v[194:195]
	v_pk_mul_f32 v[122:123], v[122:123], v[154:155]
	v_pk_mul_f32 v[118:119], v[118:119], v[156:157]
	v_pk_mul_f32 v[154:155], v[110:111], v[158:159]
	v_lshlrev_b32_e32 v156, 16, v160
	v_and_b32_e32 v157, 0xffff0000, v160
	v_lshlrev_b32_e32 v158, 16, v161
	v_and_b32_e32 v159, 0xffff0000, v161
	v_lshlrev_b32_e32 v160, 16, v162
	v_and_b32_e32 v161, 0xffff0000, v162
	v_lshlrev_b32_e32 v162, 16, v163
	v_and_b32_e32 v163, 0xffff0000, v163
	v_pk_mul_f32 v[124:125], v[124:125], v[192:193]
	v_pk_mul_f32 v[126:127], v[126:127], v[152:153]
	v_cvt_pk_bf16_f32 v110, v120, v121
	v_cvt_pk_bf16_f32 v111, v122, v123
	v_pk_mul_f32 v[112:113], v[112:113], v[156:157]
	v_pk_mul_f32 v[114:115], v[114:115], v[158:159]
	v_pk_mul_f32 v[120:121], v[104:105], v[160:161]
	v_pk_mul_f32 v[122:123], v[106:107], v[162:163]
	v_pk_mul_f32 v[116:117], v[116:117], v[196:197]
	v_pk_mul_f32 v[152:153], v[108:109], v[198:199]
	v_cvt_pk_bf16_f32 v108, v124, v125
	v_cvt_pk_bf16_f32 v109, v126, v127
	v_cvt_pk_bf16_f32 v104, v112, v113
	v_cvt_pk_bf16_f32 v105, v114, v115
	v_cvt_pk_bf16_f32 v106, v120, v121
	v_cvt_pk_bf16_f32 v107, v122, v123
	v_cvt_pk_bf16_f32 v116, v116, v117
	v_cvt_pk_bf16_f32 v117, v118, v119
	v_cvt_pk_bf16_f32 v118, v152, v153
	v_cvt_pk_bf16_f32 v119, v154, v155
	global_store_dwordx4 v[188:189], v[108:111], off
	global_store_dwordx4 v[188:189], v[116:119], off offset:256
	global_store_dwordx4 v[190:191], v[104:107], off
	v_lshlrev_b32_e32 v192, 16, v164
	v_and_b32_e32 v193, 0xffff0000, v164
	v_lshlrev_b32_e32 v104, 16, v165
	v_and_b32_e32 v105, 0xffff0000, v165
	v_pk_mul_f32 v[102:103], v[102:103], v[104:105]
	v_lshlrev_b32_e32 v104, 16, v166
	v_and_b32_e32 v105, 0xffff0000, v166
	v_pk_mul_f32 v[104:105], v[92:93], v[104:105]
	v_lshlrev_b32_e32 v92, 16, v167
	v_and_b32_e32 v93, 0xffff0000, v167
	v_pk_mul_f32 v[100:101], v[100:101], v[192:193]
	v_pk_mul_f32 v[106:107], v[94:95], v[92:93]
	v_cvt_pk_bf16_f32 v92, v100, v101
	v_cvt_pk_bf16_f32 v93, v102, v103
	v_cvt_pk_bf16_f32 v94, v104, v105
	v_cvt_pk_bf16_f32 v95, v106, v107
	global_store_dwordx4 v[190:191], v[92:95], off offset:256
	v_add_u32_e32 v102, 0xb0, v142
	v_ashrrev_i32_e32 v103, 31, v102
	v_lshlrev_b32_e32 v94, 16, v168
	v_and_b32_e32 v95, 0xffff0000, v168
	v_pk_mul_f32 v[94:95], v[96:97], v[94:95]
	v_lshlrev_b32_e32 v96, 16, v169
	v_and_b32_e32 v97, 0xffff0000, v169
	v_pk_mul_f32 v[96:97], v[98:99], v[96:97]
	v_lshlrev_b32_e32 v98, 16, v170
	v_and_b32_e32 v99, 0xffff0000, v170
	v_lshlrev_b64 v[92:93], 11, v[176:177]
	v_pk_mul_f32 v[98:99], v[88:89], v[98:99]
	v_lshlrev_b32_e32 v88, 16, v171
	v_and_b32_e32 v89, 0xffff0000, v171
	v_pk_mul_f32 v[100:101], v[90:91], v[88:89]
	v_lshl_add_u64 v[92:93], s[82:83], 0, v[92:93]
	v_cvt_pk_bf16_f32 v88, v94, v95
	v_cvt_pk_bf16_f32 v89, v96, v97
	v_cvt_pk_bf16_f32 v90, v98, v99
	v_cvt_pk_bf16_f32 v91, v100, v101
	v_lshl_add_u64 v[92:93], v[92:93], 0, v[140:141]
	global_store_dwordx4 v[92:93], v[88:91], off
	v_add_u32_e32 v96, 0x80, v142
	v_ashrrev_i32_e32 v97, 31, v96
	v_lshlrev_b32_e32 v88, 16, v172
	v_and_b32_e32 v89, 0xffff0000, v172
	v_pk_mul_f32 v[84:85], v[84:85], v[88:89]
	v_lshlrev_b32_e32 v88, 16, v173
	v_and_b32_e32 v89, 0xffff0000, v173
	v_pk_mul_f32 v[86:87], v[86:87], v[88:89]
	v_lshlrev_b32_e32 v88, 16, v174
	v_and_b32_e32 v89, 0xffff0000, v174
	v_pk_mul_f32 v[88:89], v[76:77], v[88:89]
	v_lshlrev_b32_e32 v76, 16, v175
	v_and_b32_e32 v77, 0xffff0000, v175
	v_pk_mul_f32 v[90:91], v[78:79], v[76:77]
	v_cvt_pk_bf16_f32 v76, v84, v85
	v_cvt_pk_bf16_f32 v77, v86, v87
	v_cvt_pk_bf16_f32 v78, v88, v89
	v_cvt_pk_bf16_f32 v79, v90, v91
	global_store_dwordx4 v[92:93], v[76:79], off offset:256
	v_add_u32_e32 v98, 0x90, v142
	v_ashrrev_i32_e32 v99, 31, v98
	v_lshlrev_b32_e32 v78, 16, v180
	v_and_b32_e32 v79, 0xffff0000, v180
	v_pk_mul_f32 v[78:79], v[80:81], v[78:79]
	v_lshlrev_b32_e32 v80, 16, v181
	v_and_b32_e32 v81, 0xffff0000, v181
	v_pk_mul_f32 v[80:81], v[82:83], v[80:81]
	v_lshlrev_b32_e32 v82, 16, v182
	v_and_b32_e32 v83, 0xffff0000, v182
	v_lshlrev_b64 v[76:77], 11, v[144:145]
	v_pk_mul_f32 v[82:83], v[72:73], v[82:83]
	v_lshlrev_b32_e32 v72, 16, v183
	v_and_b32_e32 v73, 0xffff0000, v183
	v_pk_mul_f32 v[84:85], v[74:75], v[72:73]
	v_lshl_add_u64 v[76:77], s[82:83], 0, v[76:77]
	v_cvt_pk_bf16_f32 v72, v78, v79
	v_cvt_pk_bf16_f32 v73, v80, v81
	v_cvt_pk_bf16_f32 v74, v82, v83
	v_cvt_pk_bf16_f32 v75, v84, v85
	v_lshl_add_u64 v[76:77], v[76:77], 0, v[140:141]
	global_store_dwordx4 v[76:77], v[72:75], off
	v_add_u32_e32 v100, 0xa0, v142
	v_ashrrev_i32_e32 v101, 31, v100
	v_lshlrev_b32_e32 v72, 16, v184
	v_and_b32_e32 v73, 0xffff0000, v184
	v_pk_mul_f32 v[68:69], v[68:69], v[72:73]
	v_lshlrev_b32_e32 v72, 16, v185
	v_and_b32_e32 v73, 0xffff0000, v185
	v_pk_mul_f32 v[70:71], v[70:71], v[72:73]
	v_lshlrev_b32_e32 v72, 16, v186
	v_and_b32_e32 v73, 0xffff0000, v186
	v_pk_mul_f32 v[72:73], v[64:65], v[72:73]
	v_lshlrev_b32_e32 v64, 16, v187
	v_and_b32_e32 v65, 0xffff0000, v187
	v_pk_mul_f32 v[74:75], v[66:67], v[64:65]
	v_cvt_pk_bf16_f32 v64, v68, v69
	v_cvt_pk_bf16_f32 v65, v70, v71
	v_cvt_pk_bf16_f32 v66, v72, v73
	v_cvt_pk_bf16_f32 v67, v74, v75
	global_store_dwordx4 v[76:77], v[64:67], off offset:256
	s_nop 1
	v_lshlrev_b64 v[64:65], 12, v[96:97]
	v_lshl_add_u64 v[64:65], s[42:43], 0, v[64:65]
	v_lshl_add_u64 v[64:65], v[64:65], 0, v[140:141]
	global_load_dwordx4 v[68:71], v[64:65], off
	global_load_dwordx4 v[72:75], v[64:65], off offset:256
	v_lshlrev_b64 v[64:65], 12, v[98:99]
	v_lshl_add_u64 v[64:65], s[42:43], 0, v[64:65]
	v_lshl_add_u64 v[64:65], v[64:65], 0, v[140:141]
	global_load_dwordx4 v[76:79], v[64:65], off
	global_load_dwordx4 v[80:83], v[64:65], off offset:256
	v_lshlrev_b64 v[64:65], 12, v[100:101]
	v_lshl_add_u64 v[64:65], s[42:43], 0, v[64:65]
	v_lshl_add_u64 v[64:65], v[64:65], 0, v[140:141]
	global_load_dwordx4 v[84:87], v[64:65], off
	global_load_dwordx4 v[88:91], v[64:65], off offset:256
	v_lshlrev_b64 v[64:65], 12, v[102:103]
	v_lshl_add_u64 v[64:65], s[42:43], 0, v[64:65]
	v_lshl_add_u64 v[64:65], v[64:65], 0, v[140:141]
	global_load_dwordx4 v[92:95], v[64:65], off
	s_nop 0
	global_load_dwordx4 v[64:67], v[64:65], off offset:256
	v_lshlrev_b64 v[96:97], 11, v[96:97]
	s_waitcnt vmcnt(0)
	v_lshlrev_b32_e32 v104, 16, v68
	v_and_b32_e32 v105, 0xffff0000, v68
	v_lshlrev_b32_e32 v68, 16, v69
	v_and_b32_e32 v69, 0xffff0000, v69
	v_pk_mul_f32 v[62:63], v[62:63], v[68:69]
	v_lshlrev_b32_e32 v68, 16, v70
	v_and_b32_e32 v69, 0xffff0000, v70
	v_pk_mul_f32 v[60:61], v[60:61], v[104:105]
	v_pk_mul_f32 v[68:69], v[56:57], v[68:69]
	v_lshlrev_b32_e32 v56, 16, v71
	v_and_b32_e32 v57, 0xffff0000, v71
	v_pk_mul_f32 v[70:71], v[58:59], v[56:57]
	v_cvt_pk_bf16_f32 v56, v60, v61
	v_lshl_add_u64 v[60:61], s[82:83], 0, v[96:97]
	v_cvt_pk_bf16_f32 v57, v62, v63
	v_cvt_pk_bf16_f32 v58, v68, v69
	v_cvt_pk_bf16_f32 v59, v70, v71
	v_lshl_add_u64 v[60:61], v[60:61], 0, v[140:141]
	global_store_dwordx4 v[60:61], v[56:59], off
	s_nop 1
	v_lshlrev_b32_e32 v56, 16, v72
	v_and_b32_e32 v57, 0xffff0000, v72
	v_pk_mul_f32 v[52:53], v[52:53], v[56:57]
	v_lshlrev_b32_e32 v56, 16, v73
	v_and_b32_e32 v57, 0xffff0000, v73
	v_pk_mul_f32 v[54:55], v[54:55], v[56:57]
	v_lshlrev_b32_e32 v56, 16, v74
	v_and_b32_e32 v57, 0xffff0000, v74
	v_pk_mul_f32 v[56:57], v[44:45], v[56:57]
	v_lshlrev_b32_e32 v44, 16, v75
	v_and_b32_e32 v45, 0xffff0000, v75
	v_pk_mul_f32 v[58:59], v[46:47], v[44:45]
	v_cvt_pk_bf16_f32 v44, v52, v53
	v_cvt_pk_bf16_f32 v45, v54, v55
	v_cvt_pk_bf16_f32 v46, v56, v57
	v_cvt_pk_bf16_f32 v47, v58, v59
	global_store_dwordx4 v[60:61], v[44:47], off offset:256
	s_nop 1
	v_lshlrev_b32_e32 v46, 16, v76
	v_and_b32_e32 v47, 0xffff0000, v76
	v_pk_mul_f32 v[46:47], v[48:49], v[46:47]
	v_lshlrev_b32_e32 v48, 16, v77
	v_and_b32_e32 v49, 0xffff0000, v77
	v_pk_mul_f32 v[48:49], v[50:51], v[48:49]
	v_lshlrev_b32_e32 v50, 16, v78
	v_and_b32_e32 v51, 0xffff0000, v78
	v_lshlrev_b64 v[44:45], 11, v[98:99]
	v_pk_mul_f32 v[50:51], v[40:41], v[50:51]
	v_lshlrev_b32_e32 v40, 16, v79
	v_and_b32_e32 v41, 0xffff0000, v79
	v_pk_mul_f32 v[52:53], v[42:43], v[40:41]
	v_lshl_add_u64 v[44:45], s[82:83], 0, v[44:45]
	v_cvt_pk_bf16_f32 v40, v46, v47
	v_cvt_pk_bf16_f32 v41, v48, v49
	v_cvt_pk_bf16_f32 v42, v50, v51
	v_cvt_pk_bf16_f32 v43, v52, v53
	v_lshl_add_u64 v[44:45], v[44:45], 0, v[140:141]
	global_store_dwordx4 v[44:45], v[40:43], off
	s_nop 1
	v_lshlrev_b32_e32 v40, 16, v80
	v_and_b32_e32 v41, 0xffff0000, v80
	v_pk_mul_f32 v[36:37], v[36:37], v[40:41]
	v_lshlrev_b32_e32 v40, 16, v81
	v_and_b32_e32 v41, 0xffff0000, v81
	v_pk_mul_f32 v[38:39], v[38:39], v[40:41]
	v_lshlrev_b32_e32 v40, 16, v82
	v_and_b32_e32 v41, 0xffff0000, v82
	v_pk_mul_f32 v[40:41], v[28:29], v[40:41]
	v_lshlrev_b32_e32 v28, 16, v83
	v_and_b32_e32 v29, 0xffff0000, v83
	v_pk_mul_f32 v[42:43], v[30:31], v[28:29]
	v_cvt_pk_bf16_f32 v28, v36, v37
	v_cvt_pk_bf16_f32 v29, v38, v39
	v_cvt_pk_bf16_f32 v30, v40, v41
	v_cvt_pk_bf16_f32 v31, v42, v43
	global_store_dwordx4 v[44:45], v[28:31], off offset:256
	s_nop 1
	v_lshlrev_b32_e32 v30, 16, v84
	v_and_b32_e32 v31, 0xffff0000, v84
	v_pk_mul_f32 v[30:31], v[32:33], v[30:31]
	v_lshlrev_b32_e32 v32, 16, v85
	v_and_b32_e32 v33, 0xffff0000, v85
	v_pk_mul_f32 v[32:33], v[34:35], v[32:33]
	v_lshlrev_b32_e32 v34, 16, v86
	v_and_b32_e32 v35, 0xffff0000, v86
	v_lshlrev_b64 v[28:29], 11, v[100:101]
	v_pk_mul_f32 v[34:35], v[24:25], v[34:35]
	v_lshlrev_b32_e32 v24, 16, v87
	v_and_b32_e32 v25, 0xffff0000, v87
	v_pk_mul_f32 v[36:37], v[26:27], v[24:25]
	v_lshl_add_u64 v[28:29], s[82:83], 0, v[28:29]
	v_cvt_pk_bf16_f32 v24, v30, v31
	v_cvt_pk_bf16_f32 v25, v32, v33
	v_cvt_pk_bf16_f32 v26, v34, v35
	v_cvt_pk_bf16_f32 v27, v36, v37
	v_lshl_add_u64 v[28:29], v[28:29], 0, v[140:141]
	global_store_dwordx4 v[28:29], v[24:27], off
	s_nop 1
	v_lshlrev_b32_e32 v24, 16, v88
	v_and_b32_e32 v25, 0xffff0000, v88
	v_pk_mul_f32 v[20:21], v[20:21], v[24:25]
	v_lshlrev_b32_e32 v24, 16, v89
	v_and_b32_e32 v25, 0xffff0000, v89
	v_pk_mul_f32 v[22:23], v[22:23], v[24:25]
	v_lshlrev_b32_e32 v24, 16, v90
	v_and_b32_e32 v25, 0xffff0000, v90
	v_pk_mul_f32 v[24:25], v[12:13], v[24:25]
	v_lshlrev_b32_e32 v12, 16, v91
	v_and_b32_e32 v13, 0xffff0000, v91
	v_pk_mul_f32 v[26:27], v[14:15], v[12:13]
	v_cvt_pk_bf16_f32 v12, v20, v21
	v_cvt_pk_bf16_f32 v13, v22, v23
	v_cvt_pk_bf16_f32 v14, v24, v25
	v_cvt_pk_bf16_f32 v15, v26, v27
	global_store_dwordx4 v[28:29], v[12:15], off offset:256
	s_nop 1
	v_lshlrev_b32_e32 v14, 16, v92
	v_and_b32_e32 v15, 0xffff0000, v92
	v_pk_mul_f32 v[14:15], v[16:17], v[14:15]
	v_lshlrev_b32_e32 v16, 16, v93
	v_and_b32_e32 v17, 0xffff0000, v93
	v_pk_mul_f32 v[16:17], v[18:19], v[16:17]
	v_lshlrev_b32_e32 v18, 16, v94
	v_and_b32_e32 v19, 0xffff0000, v94
	v_lshlrev_b64 v[12:13], 11, v[102:103]
	v_pk_mul_f32 v[18:19], v[8:9], v[18:19]
	v_lshlrev_b32_e32 v8, 16, v95
	v_and_b32_e32 v9, 0xffff0000, v95
	v_pk_mul_f32 v[20:21], v[10:11], v[8:9]
	v_lshl_add_u64 v[12:13], s[82:83], 0, v[12:13]
	v_cvt_pk_bf16_f32 v8, v14, v15
	v_cvt_pk_bf16_f32 v9, v16, v17
	v_cvt_pk_bf16_f32 v10, v18, v19
	v_cvt_pk_bf16_f32 v11, v20, v21
	v_lshl_add_u64 v[12:13], v[12:13], 0, v[140:141]
	global_store_dwordx4 v[12:13], v[8:11], off
	s_nop 1
	v_lshlrev_b32_e32 v8, 16, v64
	v_and_b32_e32 v9, 0xffff0000, v64
	v_pk_mul_f32 v[4:5], v[4:5], v[8:9]
	v_lshlrev_b32_e32 v8, 16, v65
	v_and_b32_e32 v9, 0xffff0000, v65
	v_pk_mul_f32 v[6:7], v[6:7], v[8:9]
	v_lshlrev_b32_e32 v8, 16, v66
	v_and_b32_e32 v9, 0xffff0000, v66
	v_pk_mul_f32 v[8:9], v[0:1], v[8:9]
	v_lshlrev_b32_e32 v0, 16, v67
	v_and_b32_e32 v1, 0xffff0000, v67
	v_pk_mul_f32 v[10:11], v[2:3], v[0:1]
	v_cvt_pk_bf16_f32 v0, v4, v5
	v_cvt_pk_bf16_f32 v1, v6, v7
	v_cvt_pk_bf16_f32 v2, v8, v9
	v_cvt_pk_bf16_f32 v3, v10, v11
	global_store_dwordx4 v[12:13], v[0:3], off offset:256
	s_cbranch_vccz .LBB0_1260
	s_waitcnt vmcnt(0)
	s_cmpk_gt_u32 s26, 0xff
	s_cbranch_scc1 .LBB0_1272
	s_barrier

.LBB0_1273:
	v_cndmask_b32_e64 v0, 0, 1, s[4:5]
	v_mov_b32 v8, v178
	v_cmp_ne_u32_e64 s[2:3], 1, v0
	s_andn2_b64 vcc, exec, s[4:5]
	v_readfirstlane_b32 s26, v8
	v_readlane_b32 s63, v252, 24
	v_readlane_b32 s70, v252, 28
	v_readlane_b32 s72, v252, 31
	s_nop 1
	s_cbranch_vccnz .LBB0_1290
	v_lshlrev_b32_e32 v0, 4, v8
	v_add_u32_e32 v1, 0x2000, v0
	v_ashrrev_i32_e32 v2, 31, v1
	v_lshrrev_b32_e32 v2, 22, v2
	v_add_u32_e32 v2, v1, v2
	v_ashrrev_i32_e32 v9, 10, v2
	v_mul_i32_i24_e32 v2, 0x400, v9
	v_sub_u32_e32 v1, v1, v2
	v_lshrrev_b32_e32 v2, 4, v1
	v_bitop3_b32 v1, v2, v1, 32 bitop3:0x6c
	v_ashrrev_i32_e32 v2, 31, v1
	v_lshrrev_b32_e32 v2, 26, v2
	v_add_u32_e32 v2, v1, v2
	v_lshlrev_b32_e32 v3, 3, v9
	v_ashrrev_i32_e32 v10, 6, v2
	v_and_b32_e32 v3, -16, v3
	v_add_u32_e32 v3, v10, v3
	v_and_b32_e32 v4, 3, v10
	s_mov_b32 s1, 0x3fffe0
	v_lshrrev_b32_e32 v5, 2, v3
	v_lshlrev_b32_e32 v6, 1, v3
	v_and_b32_e32 v2, 0xc0, v2
	v_and_or_b32 v4, v3, s1, v4
	v_and_b32_e32 v5, 4, v5
	v_and_b32_e32 v6, 24, v6
	v_sub_u32_e32 v1, v1, v2
	v_mov_b32_e32 v2, 1
	v_or3_b32 v4, v4, v5, v6
	v_lshlrev_b32_e32 v5, 5, v9
	v_ashrrev_i16_sdwa v1, v2, sext(v1) dst_sel:DWORD dst_unused:UNUSED_PAD src0_sel:DWORD src1_sel:BYTE_0
	v_and_b32_e32 v5, 32, v5
	v_bfe_i32 v11, v1, 0, 16
	v_add_lshl_u32 v1, v5, v11, 1
	v_lshl_add_u32 v152, v4, 10, v1
	v_lshl_add_u32 v154, v3, 10, v1
	v_bfe_i32 v1, v8, 27, 1
	v_lshrrev_b32_e32 v1, 22, v1
	v_add_u32_e32 v1, v0, v1
	v_and_b32_e32 v1, 0xfffffc00, v1
	v_sub_u32_e32 v0, v0, v1
	v_lshrrev_b32_e32 v1, 4, v0
	v_bitop3_b32 v1, v1, v0, 32 bitop3:0x6c
	v_ashrrev_i32_e32 v0, 31, v0
	v_lshrrev_b32_e32 v0, 26, v0
	v_add_u32_e32 v0, v1, v0
	v_ashrrev_i32_e32 v12, 6, v0
	v_ashrrev_i32_e32 v0, 31, v8
	v_lshrrev_b32_e32 v0, 26, v0
	v_add_u32_e32 v0, v8, v0
	v_ashrrev_i32_e32 v13, 6, v0
	v_lshlrev_b32_e32 v0, 3, v13
	v_and_b32_e32 v0, -16, v0
	v_add_u32_e32 v0, v12, v0
	s_nop 0
	s_ashr_i32 s4, s26, 6
	v_and_b32_e32 v3, 3, v12
	v_lshrrev_b32_e32 v4, 2, v0
	v_lshlrev_b32_e32 v5, 1, v0
	s_ashr_i32 s7, s6, 31
	v_readlane_b32 s50, v252, 21
	v_readlane_b32 s51, v252, 22
	s_ashr_i32 s12, s26, 8
	s_lshl_b32 s27, s4, 10
	v_and_or_b32 v3, v0, s1, v3
	v_and_b32_e32 v4, 4, v4
	v_and_b32_e32 v5, 24, v5
	s_lshl_b64 s[10:11], s[6:7], 18
	s_mov_b64 s[22:23], s[50:51]
	v_or3_b32 v3, v3, v4, v5
	v_mul_i32_i24_e32 v5, 64, v12
	s_nop 7
	s_nop 4
	s_add_u32 s10, s22, s10
	v_sub_u32_e32 v1, v1, v5
	s_addc_u32 s11, s23, s11
	s_ashr_i32 s1, s0, 31
	s_nop 0
	v_lshlrev_b32_e32 v4, 5, v13
	v_ashrrev_i16_sdwa v1, v2, sext(v1) dst_sel:DWORD dst_unused:UNUSED_PAD src0_sel:DWORD src1_sel:BYTE_0
	s_lshl_b64 s[14:15], s[0:1], 18
	v_readlane_b32 s48, v253, 46
	v_and_b32_e32 v4, 32, v4
	v_bfe_i32 v14, v1, 0, 16
	v_readlane_b32 s49, v253, 47
	s_add_u32 s22, s48, s14
	v_add_lshl_u32 v1, v4, v14, 1
	s_addc_u32 s23, s49, s15
	s_add_i32 s1, s27, 0
	v_lshl_add_u32 v156, v3, 10, v1
	s_add_i32 m0, s1, 0x10000
	v_lshl_add_u32 v158, v0, 10, v1
	global_load_lds_dwordx4 v156, s[22:23]
	s_add_i32 m0, s1, 0x12000
	s_add_i32 s7, s1, 0x2000
	global_load_lds_dwordx4 v152, s[22:23]
	s_mov_b32 m0, s1
	s_add_u32 s14, s22, 0x20000
	global_load_lds_dwordx4 v158, s[10:11]
	s_mov_b32 m0, s7
	s_addc_u32 s15, s23, 0
	global_load_lds_dwordx4 v154, s[10:11]
	s_add_i32 m0, s1, 0x14000
	v_mov_b32_e32 v157, 0
	global_load_lds_dwordx4 v156, s[14:15]
	s_add_i32 m0, s1, 0x16000
	v_mov_b32_e32 v153, v157
	global_load_lds_dwordx4 v152, s[14:15]
	s_add_u32 s14, s10, 0x20000
	s_addc_u32 s15, s11, 0
	s_add_i32 s28, s1, 0x4000
	s_mov_b32 m0, s28
	s_add_i32 s29, s1, 0x6000
	global_load_lds_dwordx4 v158, s[14:15]
	s_mov_b32 m0, s29
	v_mov_b32_e32 v159, v157
	global_load_lds_dwordx4 v154, s[14:15]
	v_mov_b32_e32 v155, v157
	s_mov_b32 s13, 0
	v_lshl_add_u64 v[6:7], s[22:23], 0, v[156:157]
	v_lshl_add_u64 v[4:5], s[22:23], 0, v[152:153]
	v_lshl_add_u64 v[2:3], s[10:11], 0, v[158:159]
	s_cmp_lg_u32 s12, 1
	v_lshl_add_u64 v[0:1], s[10:11], 0, v[154:155]
	s_nop 7
	s_nop 4
	s_cbranch_scc1 .LBB0_1276
	s_barrier

.LBB0_1284:
	s_nop 0
	s_ashr_i32 s13, s12, 31
	s_nop 1
	v_readlane_b32 s54, v252, 21
	v_readlane_b32 s55, v252, 22
	s_xor_b64 s[18:19], s[24:25], -1
	s_lshl_b64 s[16:17], s[12:13], 18
	s_mov_b64 s[50:51], s[54:55]
	s_add_u32 s16, s50, s16
	s_addc_u32 s17, s51, s17
	s_nop 7
	s_nop 2
	s_and_b64 s[20:21], s[24:25], exec
	s_cselect_b32 s13, s17, s11
	s_cselect_b32 s39, s16, s10
	s_ashr_i32 s15, s14, 31
	s_nop 0
	s_lshl_b64 s[20:21], s[14:15], 18
	v_readlane_b32 s52, v253, 46
	v_readlane_b32 s53, v253, 47
	s_add_u32 s20, s52, s20
	s_addc_u32 s21, s53, s21
	s_and_b64 s[24:25], s[24:25], exec
	s_cselect_b32 s15, s21, s23
	s_cselect_b32 s40, s20, s22
	s_add_u32 s10, s10, 0x20080
	s_nop 0
	s_addc_u32 s11, s11, 0
	s_nop 1
	s_add_u32 s41, s22, 0x100
	v_mov_b32_e32 v0, 0
	s_addc_u32 s42, s23, 0
	s_mov_b32 s43, -2
	v_mov_b32_e32 v1, v0
	v_mov_b32_e32 v2, v0
	v_mov_b32_e32 v3, v0
	v_mov_b32_e32 v4, v0
	v_mov_b32_e32 v5, v0
	v_mov_b32_e32 v6, v0
	v_mov_b32_e32 v7, v0
	v_mov_b32_e32 v16, v0
	v_mov_b32_e32 v17, v0
	v_mov_b32_e32 v18, v0
	v_mov_b32_e32 v19, v0
	v_mov_b32_e32 v20, v0
	v_mov_b32_e32 v21, v0
	v_mov_b32_e32 v22, v0
	v_mov_b32_e32 v23, v0
	v_mov_b32_e32 v32, v0
	v_mov_b32_e32 v33, v0
	v_mov_b32_e32 v34, v0
	v_mov_b32_e32 v35, v0
	v_mov_b32_e32 v36, v0
	v_mov_b32_e32 v37, v0
	v_mov_b32_e32 v38, v0
	v_mov_b32_e32 v39, v0
	v_mov_b32_e32 v48, v0
	v_mov_b32_e32 v49, v0
	v_mov_b32_e32 v50, v0
	v_mov_b32_e32 v51, v0
	v_mov_b32_e32 v52, v0
	v_mov_b32_e32 v53, v0
	v_mov_b32_e32 v54, v0
	v_mov_b32_e32 v55, v0
	v_mov_b32_e32 v8, v0
	v_mov_b32_e32 v9, v0
	v_mov_b32_e32 v10, v0
	v_mov_b32_e32 v11, v0
	v_mov_b32_e32 v12, v0
	v_mov_b32_e32 v13, v0
	v_mov_b32_e32 v14, v0
	v_mov_b32_e32 v15, v0
	v_mov_b32_e32 v24, v0
	v_mov_b32_e32 v25, v0
	v_mov_b32_e32 v26, v0
	v_mov_b32_e32 v27, v0
	v_mov_b32_e32 v28, v0
	v_mov_b32_e32 v29, v0
	v_mov_b32_e32 v30, v0
	v_mov_b32_e32 v31, v0
	v_mov_b32_e32 v40, v0
	v_mov_b32_e32 v41, v0
	v_mov_b32_e32 v42, v0
	v_mov_b32_e32 v43, v0
	v_mov_b32_e32 v44, v0
	v_mov_b32_e32 v45, v0
	v_mov_b32_e32 v46, v0
	v_mov_b32_e32 v47, v0
	v_mov_b32_e32 v56, v0
	v_mov_b32_e32 v57, v0
	v_mov_b32_e32 v58, v0
	v_mov_b32_e32 v59, v0
	v_mov_b32_e32 v60, v0
	v_mov_b32_e32 v61, v0
	v_mov_b32_e32 v62, v0
	v_mov_b32_e32 v63, v0
	v_mov_b32_e32 v64, v0
	v_mov_b32_e32 v65, v0
	v_mov_b32_e32 v66, v0
	v_mov_b32_e32 v67, v0
	v_mov_b32_e32 v68, v0
	v_mov_b32_e32 v69, v0
	v_mov_b32_e32 v70, v0
	v_mov_b32_e32 v71, v0
	v_mov_b32_e32 v80, v0
	v_mov_b32_e32 v81, v0
	v_mov_b32_e32 v82, v0
	v_mov_b32_e32 v83, v0
	v_mov_b32_e32 v84, v0
	v_mov_b32_e32 v85, v0
	v_mov_b32_e32 v86, v0
	v_mov_b32_e32 v87, v0
	v_mov_b32_e32 v96, v0
	v_mov_b32_e32 v97, v0
	v_mov_b32_e32 v98, v0
	v_mov_b32_e32 v99, v0
	v_mov_b32_e32 v100, v0
	v_mov_b32_e32 v101, v0
	v_mov_b32_e32 v102, v0
	v_mov_b32_e32 v103, v0
	v_mov_b32_e32 v112, v0
	v_mov_b32_e32 v113, v0
	v_mov_b32_e32 v114, v0
	v_mov_b32_e32 v115, v0
	v_mov_b32_e32 v116, v0
	v_mov_b32_e32 v117, v0
	v_mov_b32_e32 v118, v0
	v_mov_b32_e32 v119, v0
	v_mov_b32_e32 v72, v0
	v_mov_b32_e32 v73, v0
	v_mov_b32_e32 v74, v0
	v_mov_b32_e32 v75, v0
	v_mov_b32_e32 v76, v0
	v_mov_b32_e32 v77, v0
	v_mov_b32_e32 v78, v0
	v_mov_b32_e32 v79, v0
	v_mov_b32_e32 v88, v0
	v_mov_b32_e32 v89, v0
	v_mov_b32_e32 v90, v0
	v_mov_b32_e32 v91, v0
	v_mov_b32_e32 v92, v0
	v_mov_b32_e32 v93, v0
	v_mov_b32_e32 v94, v0
	v_mov_b32_e32 v95, v0
	v_mov_b32_e32 v104, v0
	v_mov_b32_e32 v105, v0
	v_mov_b32_e32 v106, v0
	v_mov_b32_e32 v107, v0
	v_mov_b32_e32 v108, v0
	v_mov_b32_e32 v109, v0
	v_mov_b32_e32 v110, v0
	v_mov_b32_e32 v111, v0
	v_mov_b32_e32 v120, v0
	v_mov_b32_e32 v121, v0
	v_mov_b32_e32 v122, v0
	v_mov_b32_e32 v123, v0
	v_mov_b32_e32 v124, v0
	v_mov_b32_e32 v125, v0
	v_mov_b32_e32 v126, v0
	v_mov_b32_e32 v127, v0
	s_nop 7
	s_nop 1
.LBB0_1285:
	ds_read_b128 v[128:131], v175
	ds_read_b128 v[132:135], v175 offset:1024
	ds_read_b128 v[136:139], v175 offset:2048
	ds_read_b128 v[140:143], v175 offset:3072
	s_add_u32 s22, s10, 0xfffe0080
	s_addc_u32 s23, s11, -1
	s_cmp_eq_u32 s43, 4
	s_cselect_b32 s25, s13, s23
	s_cselect_b32 s24, s39, s22
	s_cselect_b32 s23, s15, s42
	s_cselect_b32 s22, s40, s41
	v_lshl_add_u64 v[196:197], s[10:11], 0, v[160:161]
	s_add_i32 m0, s1, 0xc000
	ds_read_b128 v[144:147], v176
	ds_read_b128 v[148:151], v176 offset:1024
	ds_read_b128 v[164:167], v176 offset:2048
	ds_read_b128 v[168:171], v176 offset:3072
	ds_read_b128 v[180:183], v176 offset:4096
	ds_read_b128 v[184:187], v176 offset:5120
	ds_read_b128 v[188:191], v176 offset:6144
	ds_read_b128 v[192:195], v176 offset:7168
	global_load_lds_dwordx4 v[196:197], off
	v_lshl_add_u64 v[196:197], s[10:11], 0, v[162:163]
	s_add_i32 m0, s1, 0xe000
	s_nop 0
	global_load_lds_dwordx4 v[196:197], off
	s_waitcnt lgkmcnt(8)
	s_barrier
	s_waitcnt lgkmcnt(0)
	s_setprio 1
	s_waitcnt lgkmcnt(0)
	v_mfma_f32_16x16x32_bf16 v[124:127], v[128:131], v[144:147], v[124:127]
	v_mfma_f32_16x16x32_bf16 v[120:123], v[136:139], v[144:147], v[120:123]
	v_mfma_f32_16x16x32_bf16 v[108:111], v[128:131], v[164:167], v[108:111]
	v_mfma_f32_16x16x32_bf16 v[104:107], v[136:139], v[164:167], v[104:107]
	v_mfma_f32_16x16x32_bf16 v[92:95], v[128:131], v[180:183], v[92:95]
	v_mfma_f32_16x16x32_bf16 v[88:91], v[136:139], v[180:183], v[88:91]
	v_mfma_f32_16x16x32_bf16 v[76:79], v[128:131], v[188:191], v[76:79]
	v_mfma_f32_16x16x32_bf16 v[72:75], v[136:139], v[188:191], v[72:75]
	v_mfma_f32_16x16x32_bf16 v[124:127], v[132:135], v[148:151], v[124:127]
	v_mfma_f32_16x16x32_bf16 v[120:123], v[140:143], v[148:151], v[120:123]
	v_mfma_f32_16x16x32_bf16 v[108:111], v[132:135], v[168:171], v[108:111]
	v_mfma_f32_16x16x32_bf16 v[104:107], v[140:143], v[168:171], v[104:107]
	v_mfma_f32_16x16x32_bf16 v[92:95], v[132:135], v[184:187], v[92:95]
	v_mfma_f32_16x16x32_bf16 v[88:91], v[140:143], v[184:187], v[88:91]
	v_mfma_f32_16x16x32_bf16 v[76:79], v[132:135], v[192:195], v[76:79]
	v_mfma_f32_16x16x32_bf16 v[72:75], v[140:143], v[192:195], v[72:75]
	s_setprio 0
	s_barrier
	s_add_i32 s44, s35, s27
	v_lshl_add_u64 v[212:213], s[22:23], 0, v[156:157]
	s_mov_b32 m0, s44
	ds_read_b128 v[196:199], v177
	ds_read_b128 v[200:203], v177 offset:1024
	ds_read_b128 v[204:207], v177 offset:2048
	ds_read_b128 v[208:211], v177 offset:3072
	global_load_lds_dwordx4 v[212:213], off
	v_lshl_add_u64 v[214:215], s[22:23], 0, v[152:153]
	s_add_i32 m0, s44, 0x2000
	s_nop 0
	global_load_lds_dwordx4 v[214:215], off
	s_barrier
	s_waitcnt lgkmcnt(0)
	s_setprio 1
	s_waitcnt lgkmcnt(0)
	v_mfma_f32_16x16x32_bf16 v[116:119], v[196:199], v[144:147], v[116:119]
	v_mfma_f32_16x16x32_bf16 v[112:115], v[204:207], v[144:147], v[112:115]
	v_mfma_f32_16x16x32_bf16 v[100:103], v[196:199], v[164:167], v[100:103]
	v_mfma_f32_16x16x32_bf16 v[96:99], v[204:207], v[164:167], v[96:99]
	v_mfma_f32_16x16x32_bf16 v[84:87], v[196:199], v[180:183], v[84:87]
	v_mfma_f32_16x16x32_bf16 v[80:83], v[204:207], v[180:183], v[80:83]
	v_mfma_f32_16x16x32_bf16 v[68:71], v[196:199], v[188:191], v[68:71]
	v_mfma_f32_16x16x32_bf16 v[64:67], v[204:207], v[188:191], v[64:67]
	v_mfma_f32_16x16x32_bf16 v[116:119], v[200:203], v[148:151], v[116:119]
	v_mfma_f32_16x16x32_bf16 v[112:115], v[208:211], v[148:151], v[112:115]
	v_mfma_f32_16x16x32_bf16 v[100:103], v[200:203], v[168:171], v[100:103]
	v_mfma_f32_16x16x32_bf16 v[96:99], v[208:211], v[168:171], v[96:99]
	v_mfma_f32_16x16x32_bf16 v[84:87], v[200:203], v[184:187], v[84:87]
	v_mfma_f32_16x16x32_bf16 v[80:83], v[208:211], v[184:187], v[80:83]
	v_mfma_f32_16x16x32_bf16 v[68:71], v[200:203], v[192:195], v[68:71]
	v_mfma_f32_16x16x32_bf16 v[64:67], v[208:211], v[192:195], v[64:67]
	s_setprio 0
	s_mov_b32 m0, s1
	v_lshl_add_u64 v[216:217], s[24:25], 0, v[158:159]
	s_barrier
	ds_read_b128 v[144:147], v176 offset:16384
	ds_read_b128 v[148:151], v176 offset:17408
	ds_read_b128 v[164:167], v176 offset:18432
	ds_read_b128 v[168:171], v176 offset:19456
	ds_read_b128 v[180:183], v176 offset:20480
	ds_read_b128 v[184:187], v176 offset:21504
	ds_read_b128 v[188:191], v176 offset:22528
	ds_read_b128 v[192:195], v176 offset:23552
	global_load_lds_dwordx4 v[216:217], off
	v_lshl_add_u64 v[218:219], s[24:25], 0, v[154:155]
	s_mov_b32 m0, s7
	s_nop 0
	global_load_lds_dwordx4 v[218:219], off
	s_barrier
	s_waitcnt lgkmcnt(0)
	s_setprio 1
	s_waitcnt lgkmcnt(0)
	v_mfma_f32_16x16x32_bf16 v[60:63], v[128:131], v[144:147], v[60:63]
	v_mfma_f32_16x16x32_bf16 v[56:59], v[136:139], v[144:147], v[56:59]
	v_mfma_f32_16x16x32_bf16 v[44:47], v[128:131], v[164:167], v[44:47]
	v_mfma_f32_16x16x32_bf16 v[40:43], v[136:139], v[164:167], v[40:43]
	v_mfma_f32_16x16x32_bf16 v[28:31], v[128:131], v[180:183], v[28:31]
	v_mfma_f32_16x16x32_bf16 v[24:27], v[136:139], v[180:183], v[24:27]
	v_mfma_f32_16x16x32_bf16 v[12:15], v[128:131], v[188:191], v[12:15]
	v_mfma_f32_16x16x32_bf16 v[8:11], v[136:139], v[188:191], v[8:11]
	v_mfma_f32_16x16x32_bf16 v[60:63], v[132:135], v[148:151], v[60:63]
	v_mfma_f32_16x16x32_bf16 v[56:59], v[140:143], v[148:151], v[56:59]
	v_mfma_f32_16x16x32_bf16 v[44:47], v[132:135], v[168:171], v[44:47]
	v_mfma_f32_16x16x32_bf16 v[40:43], v[140:143], v[168:171], v[40:43]
	v_mfma_f32_16x16x32_bf16 v[28:31], v[132:135], v[184:187], v[28:31]
	v_mfma_f32_16x16x32_bf16 v[24:27], v[140:143], v[184:187], v[24:27]
	v_mfma_f32_16x16x32_bf16 v[12:15], v[132:135], v[192:195], v[12:15]
	v_mfma_f32_16x16x32_bf16 v[8:11], v[140:143], v[192:195], v[8:11]
	s_setprio 0
	s_barrier
	s_add_u32 s44, s22, 0x20000
	s_addc_u32 s45, s23, 0
	s_add_i32 s46, s36, s27
	v_lshl_add_u64 v[128:129], s[44:45], 0, v[156:157]
	s_mov_b32 m0, s46
	s_nop 0
	global_load_lds_dwordx4 v[128:129], off
	v_lshl_add_u64 v[128:129], s[44:45], 0, v[152:153]
	s_add_i32 m0, s46, 0x2000
	s_nop 0
	global_load_lds_dwordx4 v[128:129], off
	s_waitcnt vmcnt(6)
	s_barrier
	s_setprio 1
	v_mfma_f32_16x16x32_bf16 v[52:55], v[196:199], v[144:147], v[52:55]
	v_mfma_f32_16x16x32_bf16 v[48:51], v[204:207], v[144:147], v[48:51]
	v_mfma_f32_16x16x32_bf16 v[36:39], v[196:199], v[164:167], v[36:39]
	v_mfma_f32_16x16x32_bf16 v[32:35], v[204:207], v[164:167], v[32:35]
	v_mfma_f32_16x16x32_bf16 v[20:23], v[196:199], v[180:183], v[20:23]
	v_mfma_f32_16x16x32_bf16 v[16:19], v[204:207], v[180:183], v[16:19]
	v_mfma_f32_16x16x32_bf16 v[4:7], v[196:199], v[188:191], v[4:7]
	v_mfma_f32_16x16x32_bf16 v[0:3], v[204:207], v[188:191], v[0:3]
	v_mfma_f32_16x16x32_bf16 v[52:55], v[200:203], v[148:151], v[52:55]
	v_mfma_f32_16x16x32_bf16 v[48:51], v[208:211], v[148:151], v[48:51]
	v_mfma_f32_16x16x32_bf16 v[36:39], v[200:203], v[168:171], v[36:39]
	v_mfma_f32_16x16x32_bf16 v[32:35], v[208:211], v[168:171], v[32:35]
	v_mfma_f32_16x16x32_bf16 v[20:23], v[200:203], v[184:187], v[20:23]
	v_mfma_f32_16x16x32_bf16 v[16:19], v[208:211], v[184:187], v[16:19]
	v_mfma_f32_16x16x32_bf16 v[4:7], v[200:203], v[192:195], v[4:7]
	v_mfma_f32_16x16x32_bf16 v[0:3], v[208:211], v[192:195], v[0:3]
	s_setprio 0
	s_add_i32 s44, 0, 0x18000
	v_add_u32_e32 v140, s44, v173
	s_barrier
	ds_read_b128 v[128:131], v140
	ds_read_b128 v[132:135], v140 offset:1024
	ds_read_b128 v[136:139], v140 offset:2048
	ds_read_b128 v[140:143], v140 offset:3072
	s_add_u32 s24, s24, 0x20000
	s_addc_u32 s25, s25, 0
	s_mov_b32 m0, s28
	v_lshl_add_u64 v[196:197], s[24:25], 0, v[158:159]
	ds_read_b128 v[144:147], v176 offset:32768
	ds_read_b128 v[148:151], v176 offset:33792
	ds_read_b128 v[164:167], v176 offset:34816
	ds_read_b128 v[168:171], v176 offset:35840
	ds_read_b128 v[180:183], v176 offset:36864
	ds_read_b128 v[184:187], v176 offset:37888
	ds_read_b128 v[188:191], v176 offset:38912
	ds_read_b128 v[192:195], v176 offset:39936
	global_load_lds_dwordx4 v[196:197], off
	v_lshl_add_u64 v[196:197], s[24:25], 0, v[154:155]
	s_mov_b32 m0, s29
	s_nop 0
	global_load_lds_dwordx4 v[196:197], off
	s_waitcnt lgkmcnt(8)
	s_barrier
	s_waitcnt lgkmcnt(0)
	s_setprio 1
	s_waitcnt lgkmcnt(0)
	v_mfma_f32_16x16x32_bf16 v[124:127], v[128:131], v[144:147], v[124:127]
	v_mfma_f32_16x16x32_bf16 v[120:123], v[136:139], v[144:147], v[120:123]
	v_mfma_f32_16x16x32_bf16 v[108:111], v[128:131], v[164:167], v[108:111]
	v_mfma_f32_16x16x32_bf16 v[104:107], v[136:139], v[164:167], v[104:107]
	v_mfma_f32_16x16x32_bf16 v[92:95], v[128:131], v[180:183], v[92:95]
	v_mfma_f32_16x16x32_bf16 v[88:91], v[136:139], v[180:183], v[88:91]
	v_mfma_f32_16x16x32_bf16 v[76:79], v[128:131], v[188:191], v[76:79]
	v_mfma_f32_16x16x32_bf16 v[72:75], v[136:139], v[188:191], v[72:75]
	v_mfma_f32_16x16x32_bf16 v[124:127], v[132:135], v[148:151], v[124:127]
	v_mfma_f32_16x16x32_bf16 v[120:123], v[140:143], v[148:151], v[120:123]
	v_mfma_f32_16x16x32_bf16 v[108:111], v[132:135], v[168:171], v[108:111]
	v_mfma_f32_16x16x32_bf16 v[104:107], v[140:143], v[168:171], v[104:107]
	v_mfma_f32_16x16x32_bf16 v[92:95], v[132:135], v[184:187], v[92:95]
	v_mfma_f32_16x16x32_bf16 v[88:91], v[140:143], v[184:187], v[88:91]
	v_mfma_f32_16x16x32_bf16 v[76:79], v[132:135], v[192:195], v[76:79]
	v_mfma_f32_16x16x32_bf16 v[72:75], v[140:143], v[192:195], v[72:75]
	s_setprio 0
	s_barrier
	s_add_i32 s24, 0, 0x1c000
	s_add_i32 s25, s44, s27
	v_add_u32_e32 v179, s24, v173
	v_lshl_add_u64 v[212:213], v[212:213], 0, s[4:5]
	s_mov_b32 m0, s25
	ds_read_b128 v[196:199], v179
	ds_read_b128 v[200:203], v179 offset:1024
	ds_read_b128 v[204:207], v179 offset:2048
	ds_read_b128 v[208:211], v179 offset:3072
	global_load_lds_dwordx4 v[212:213], off
	v_lshl_add_u64 v[212:213], v[214:215], 0, s[4:5]
	s_add_i32 m0, s25, 0x2000
	s_nop 0
	global_load_lds_dwordx4 v[212:213], off
	s_barrier
	s_waitcnt lgkmcnt(0)
	s_setprio 1
	s_waitcnt lgkmcnt(0)
	v_mfma_f32_16x16x32_bf16 v[116:119], v[196:199], v[144:147], v[116:119]
	v_mfma_f32_16x16x32_bf16 v[112:115], v[204:207], v[144:147], v[112:115]
	v_mfma_f32_16x16x32_bf16 v[100:103], v[196:199], v[164:167], v[100:103]
	v_mfma_f32_16x16x32_bf16 v[96:99], v[204:207], v[164:167], v[96:99]
	v_mfma_f32_16x16x32_bf16 v[84:87], v[196:199], v[180:183], v[84:87]
	v_mfma_f32_16x16x32_bf16 v[80:83], v[204:207], v[180:183], v[80:83]
	v_mfma_f32_16x16x32_bf16 v[68:71], v[196:199], v[188:191], v[68:71]
	v_mfma_f32_16x16x32_bf16 v[64:67], v[204:207], v[188:191], v[64:67]
	v_mfma_f32_16x16x32_bf16 v[116:119], v[200:203], v[148:151], v[116:119]
	v_mfma_f32_16x16x32_bf16 v[112:115], v[208:211], v[148:151], v[112:115]
	v_mfma_f32_16x16x32_bf16 v[100:103], v[200:203], v[168:171], v[100:103]
	v_mfma_f32_16x16x32_bf16 v[96:99], v[208:211], v[168:171], v[96:99]
	v_mfma_f32_16x16x32_bf16 v[84:87], v[200:203], v[184:187], v[84:87]
	v_mfma_f32_16x16x32_bf16 v[80:83], v[208:211], v[184:187], v[80:83]
	v_mfma_f32_16x16x32_bf16 v[68:71], v[200:203], v[192:195], v[68:71]
	v_mfma_f32_16x16x32_bf16 v[64:67], v[208:211], v[192:195], v[64:67]
	s_setprio 0
	s_mov_b32 m0, s31
	v_lshl_add_u64 v[212:213], v[216:217], 0, s[4:5]
	s_barrier
	ds_read_b128 v[144:147], v176 offset:49152
	ds_read_b128 v[148:151], v176 offset:50176
	ds_read_b128 v[164:167], v176 offset:51200
	ds_read_b128 v[168:171], v176 offset:52224
	ds_read_b128 v[180:183], v176 offset:53248
	ds_read_b128 v[184:187], v176 offset:54272
	ds_read_b128 v[188:191], v176 offset:55296
	ds_read_b128 v[192:195], v176 offset:56320
	global_load_lds_dwordx4 v[212:213], off
	v_lshl_add_u64 v[212:213], v[218:219], 0, s[4:5]
	s_mov_b32 m0, s33
	s_nop 0
	global_load_lds_dwordx4 v[212:213], off
	s_barrier
	s_waitcnt lgkmcnt(0)
	s_setprio 1
	s_waitcnt lgkmcnt(0)
	v_mfma_f32_16x16x32_bf16 v[60:63], v[128:131], v[144:147], v[60:63]
	v_mfma_f32_16x16x32_bf16 v[56:59], v[136:139], v[144:147], v[56:59]
	v_mfma_f32_16x16x32_bf16 v[44:47], v[128:131], v[164:167], v[44:47]
	v_mfma_f32_16x16x32_bf16 v[40:43], v[136:139], v[164:167], v[40:43]
	v_mfma_f32_16x16x32_bf16 v[28:31], v[128:131], v[180:183], v[28:31]
	v_mfma_f32_16x16x32_bf16 v[24:27], v[136:139], v[180:183], v[24:27]
	v_mfma_f32_16x16x32_bf16 v[12:15], v[128:131], v[188:191], v[12:15]
	v_mfma_f32_16x16x32_bf16 v[8:11], v[136:139], v[188:191], v[8:11]
	v_mfma_f32_16x16x32_bf16 v[60:63], v[132:135], v[148:151], v[60:63]
	v_mfma_f32_16x16x32_bf16 v[56:59], v[140:143], v[148:151], v[56:59]
	v_mfma_f32_16x16x32_bf16 v[44:47], v[132:135], v[168:171], v[44:47]
	v_mfma_f32_16x16x32_bf16 v[40:43], v[140:143], v[168:171], v[40:43]
	v_mfma_f32_16x16x32_bf16 v[28:31], v[132:135], v[184:187], v[28:31]
	v_mfma_f32_16x16x32_bf16 v[24:27], v[140:143], v[184:187], v[24:27]
	v_mfma_f32_16x16x32_bf16 v[12:15], v[132:135], v[192:195], v[12:15]
	v_mfma_f32_16x16x32_bf16 v[8:11], v[140:143], v[192:195], v[8:11]
	s_setprio 0
	s_barrier
	s_add_u32 s22, s22, 0x20080
	s_addc_u32 s23, s23, 0
	s_add_i32 s24, s24, s27
	v_lshl_add_u64 v[128:129], s[22:23], 0, v[156:157]
	s_mov_b32 m0, s24
	s_nop 0
	global_load_lds_dwordx4 v[128:129], off
	v_lshl_add_u64 v[128:129], s[22:23], 0, v[152:153]
	s_add_i32 m0, s24, 0x2000
	s_nop 0
	global_load_lds_dwordx4 v[128:129], off
	s_waitcnt vmcnt(6)
	s_barrier
	s_setprio 1
	v_mfma_f32_16x16x32_bf16 v[52:55], v[196:199], v[144:147], v[52:55]
	v_mfma_f32_16x16x32_bf16 v[48:51], v[204:207], v[144:147], v[48:51]
	v_mfma_f32_16x16x32_bf16 v[36:39], v[196:199], v[164:167], v[36:39]
	v_mfma_f32_16x16x32_bf16 v[32:35], v[204:207], v[164:167], v[32:35]
	v_mfma_f32_16x16x32_bf16 v[20:23], v[196:199], v[180:183], v[20:23]
	v_mfma_f32_16x16x32_bf16 v[16:19], v[204:207], v[180:183], v[16:19]
	v_mfma_f32_16x16x32_bf16 v[4:7], v[196:199], v[188:191], v[4:7]
	v_mfma_f32_16x16x32_bf16 v[0:3], v[204:207], v[188:191], v[0:3]
	v_mfma_f32_16x16x32_bf16 v[52:55], v[200:203], v[148:151], v[52:55]
	v_mfma_f32_16x16x32_bf16 v[48:51], v[208:211], v[148:151], v[48:51]
	v_mfma_f32_16x16x32_bf16 v[36:39], v[200:203], v[168:171], v[36:39]
	v_mfma_f32_16x16x32_bf16 v[32:35], v[208:211], v[168:171], v[32:35]
	v_mfma_f32_16x16x32_bf16 v[20:23], v[200:203], v[184:187], v[20:23]
	v_mfma_f32_16x16x32_bf16 v[16:19], v[208:211], v[184:187], v[16:19]
	v_mfma_f32_16x16x32_bf16 v[4:7], v[200:203], v[192:195], v[4:7]
	v_mfma_f32_16x16x32_bf16 v[0:3], v[208:211], v[192:195], v[0:3]
	s_setprio 0
	s_add_i32 s43, s43, 2
	s_add_u32 s10, s10, 0x100
	s_addc_u32 s11, s11, 0
	s_add_u32 s41, s41, 0x100
	s_addc_u32 s42, s42, 0
	s_cmp_gt_u32 s43, 5
	s_barrier
	s_cbranch_scc0 .LBB0_1285
	v_lshl_add_u32 v164, s38, 8, v172
	s_nop 0
	v_lshl_or_b32 v128, s0, 8, v174
	v_ashrrev_i32_e32 v165, 31, v164
	s_nop 1
	v_readlane_b32 s46, v252, 13
	v_readlane_b32 s47, v252, 14
	v_ashrrev_i32_e32 v129, 31, v128
	v_lshlrev_b64 v[130:131], 12, v[164:165]
	s_mov_b64 s[42:43], s[46:47]
	v_lshl_add_u64 v[130:131], s[42:43], 0, v[130:131]
	v_lshlrev_b64 v[132:133], 11, v[164:165]
	v_lshlrev_b64 v[166:167], 1, v[128:129]
	v_lshl_add_u64 v[132:133], s[82:83], 0, v[132:133]
	v_lshl_add_u64 v[128:129], v[130:131], 0, v[166:167]
	global_load_dwordx4 v[180:183], v[128:129], off offset:2048
	v_lshl_add_u64 v[222:223], v[132:133], 0, v[166:167]
	global_load_dwordx4 v[184:187], v[222:223], off
	global_load_dwordx4 v[188:191], v[128:129], off offset:2304
	global_load_dwordx4 v[192:195], v[222:223], off offset:256
	v_or_b32_e32 v128, 16, v164
	v_ashrrev_i32_e32 v129, 31, v128
	v_lshlrev_b64 v[130:131], 12, v[128:129]
	v_lshlrev_b64 v[128:129], 11, v[128:129]
	v_lshl_add_u64 v[130:131], s[42:43], 0, v[130:131]
	v_lshl_add_u64 v[128:129], s[82:83], 0, v[128:129]
	v_lshl_add_u64 v[130:131], v[130:131], 0, v[166:167]
	v_lshl_add_u64 v[224:225], v[128:129], 0, v[166:167]
	global_load_dwordx4 v[196:199], v[130:131], off offset:2048
	global_load_dwordx4 v[200:203], v[224:225], off
	v_or_b32_e32 v128, 32, v164
	v_or_b32_e32 v132, 48, v164
	v_ashrrev_i32_e32 v129, 31, v128
	v_ashrrev_i32_e32 v133, 31, v132
	v_lshlrev_b64 v[134:135], 12, v[128:129]
	v_lshlrev_b64 v[128:129], 11, v[128:129]
	v_lshlrev_b64 v[136:137], 12, v[132:133]
	v_lshlrev_b64 v[132:133], 11, v[132:133]
	v_lshl_add_u64 v[134:135], s[42:43], 0, v[134:135]
	v_lshl_add_u64 v[128:129], s[82:83], 0, v[128:129]
	v_lshl_add_u64 v[136:137], s[42:43], 0, v[136:137]
	v_lshl_add_u64 v[132:133], s[82:83], 0, v[132:133]
	v_lshl_add_u64 v[134:135], v[134:135], 0, v[166:167]
	v_lshl_add_u64 v[170:171], v[128:129], 0, v[166:167]
	v_lshl_add_u64 v[128:129], v[136:137], 0, v[166:167]
	v_lshl_add_u64 v[168:169], v[132:133], 0, v[166:167]
	global_load_dwordx4 v[204:207], v[130:131], off offset:2304
	global_load_dwordx4 v[208:211], v[224:225], off offset:256
	global_load_dwordx4 v[212:215], v[134:135], off offset:2048
	global_load_dwordx4 v[148:151], v[134:135], off offset:2304
	global_load_dwordx4 v[216:219], v[170:171], off
	global_load_dwordx4 v[144:147], v[170:171], off offset:256
	global_load_dwordx4 v[140:143], v[128:129], off offset:2048
	s_nop 0
	global_load_dwordx4 v[132:135], v[128:129], off offset:2304
	global_load_dwordx4 v[136:139], v[168:169], off
	s_nop 0
	global_load_dwordx4 v[128:131], v[168:169], off offset:256
	s_and_b64 vcc, exec, s[18:19]
	s_mov_b32 s0, s14
	s_mov_b32 s38, s12
	s_mov_b32 s15, s14
	s_mov_b32 s18, s12
	s_mov_b64 s[22:23], s[20:21]
	s_mov_b64 s[10:11], s[16:17]
	s_mov_b32 s13, s37
	s_nop 7
	s_nop 2
	s_waitcnt vmcnt(0)
	v_lshlrev_b32_e32 v228, 16, v184
	v_lshlrev_b32_e32 v226, 16, v180
	v_and_b32_e32 v227, 0xffff0000, v180
	v_and_b32_e32 v229, 0xffff0000, v184
	v_lshlrev_b32_e32 v180, 16, v181
	v_and_b32_e32 v181, 0xffff0000, v181
	v_lshlrev_b32_e32 v184, 16, v185
	v_and_b32_e32 v185, 0xffff0000, v185
	v_lshlrev_b32_e32 v230, 16, v182
	v_and_b32_e32 v231, 0xffff0000, v182
	v_lshlrev_b32_e32 v232, 16, v186
	v_and_b32_e32 v233, 0xffff0000, v186
	v_lshlrev_b32_e32 v182, 16, v183
	v_and_b32_e32 v183, 0xffff0000, v183
	v_lshlrev_b32_e32 v186, 16, v187
	v_and_b32_e32 v187, 0xffff0000, v187
	v_lshlrev_b32_e32 v234, 16, v188
	v_and_b32_e32 v235, 0xffff0000, v188
	v_lshlrev_b32_e32 v236, 16, v192
	v_and_b32_e32 v237, 0xffff0000, v192
	v_lshlrev_b32_e32 v188, 16, v189
	v_and_b32_e32 v189, 0xffff0000, v189
	v_lshlrev_b32_e32 v192, 16, v193
	v_and_b32_e32 v193, 0xffff0000, v193
	v_pk_fma_f32 v[124:125], v[124:125], v[226:227], v[228:229]
	v_pk_fma_f32 v[126:127], v[126:127], v[180:181], v[184:185]
	v_pk_fma_f32 v[120:121], v[120:121], v[230:231], v[232:233]
	v_pk_fma_f32 v[122:123], v[122:123], v[182:183], v[186:187]
	v_lshlrev_b32_e32 v238, 16, v190
	v_and_b32_e32 v239, 0xffff0000, v190
	v_lshlrev_b32_e32 v240, 16, v194
	v_pk_fma_f32 v[180:181], v[116:117], v[234:235], v[236:237]
	v_pk_fma_f32 v[182:183], v[118:119], v[188:189], v[192:193]
	v_cvt_pk_bf16_f32 v116, v124, v125
	v_cvt_pk_bf16_f32 v117, v126, v127
	v_cvt_pk_bf16_f32 v118, v120, v121
	v_cvt_pk_bf16_f32 v119, v122, v123
	v_and_b32_e32 v241, 0xffff0000, v194
	global_store_dwordx4 v[222:223], v[116:119], off
	s_nop 1
	v_pk_fma_f32 v[116:117], v[112:113], v[238:239], v[240:241]
	v_lshlrev_b32_e32 v112, 16, v191
	v_and_b32_e32 v113, 0xffff0000, v191
	v_lshlrev_b32_e32 v118, 16, v195
	v_and_b32_e32 v119, 0xffff0000, v195
	v_pk_fma_f32 v[118:119], v[114:115], v[112:113], v[118:119]
	v_cvt_pk_bf16_f32 v112, v180, v181
	v_cvt_pk_bf16_f32 v113, v182, v183
	v_cvt_pk_bf16_f32 v114, v116, v117
	v_cvt_pk_bf16_f32 v115, v118, v119
	global_store_dwordx4 v[222:223], v[112:115], off offset:256
	s_nop 1
	v_lshlrev_b32_e32 v112, 16, v196
	v_and_b32_e32 v113, 0xffff0000, v196
	v_lshlrev_b32_e32 v114, 16, v200
	v_and_b32_e32 v115, 0xffff0000, v200
	v_pk_fma_f32 v[108:109], v[108:109], v[112:113], v[114:115]
	v_lshlrev_b32_e32 v112, 16, v197
	v_and_b32_e32 v113, 0xffff0000, v197
	v_lshlrev_b32_e32 v114, 16, v201
	v_and_b32_e32 v115, 0xffff0000, v201
	v_pk_fma_f32 v[110:111], v[110:111], v[112:113], v[114:115]
	v_lshlrev_b32_e32 v112, 16, v198
	v_and_b32_e32 v113, 0xffff0000, v198
	v_lshlrev_b32_e32 v114, 16, v202
	v_and_b32_e32 v115, 0xffff0000, v202
	v_pk_fma_f32 v[112:113], v[104:105], v[112:113], v[114:115]
	v_lshlrev_b32_e32 v104, 16, v199
	v_and_b32_e32 v105, 0xffff0000, v199
	v_lshlrev_b32_e32 v114, 16, v203
	v_and_b32_e32 v115, 0xffff0000, v203
	v_pk_fma_f32 v[114:115], v[106:107], v[104:105], v[114:115]
	v_cvt_pk_bf16_f32 v104, v108, v109
	v_cvt_pk_bf16_f32 v105, v110, v111
	v_cvt_pk_bf16_f32 v106, v112, v113
	v_cvt_pk_bf16_f32 v107, v114, v115
	global_store_dwordx4 v[224:225], v[104:107], off
	s_nop 1
	v_lshlrev_b32_e32 v104, 16, v204
	v_and_b32_e32 v105, 0xffff0000, v204
	v_lshlrev_b32_e32 v106, 16, v208
	v_and_b32_e32 v107, 0xffff0000, v208
	v_pk_fma_f32 v[100:101], v[100:101], v[104:105], v[106:107]
	v_lshlrev_b32_e32 v104, 16, v205
	v_and_b32_e32 v105, 0xffff0000, v205
	v_lshlrev_b32_e32 v106, 16, v209
	v_and_b32_e32 v107, 0xffff0000, v209
	v_pk_fma_f32 v[102:103], v[102:103], v[104:105], v[106:107]
	v_lshlrev_b32_e32 v104, 16, v206
	v_and_b32_e32 v105, 0xffff0000, v206
	v_lshlrev_b32_e32 v106, 16, v210
	v_and_b32_e32 v107, 0xffff0000, v210
	v_pk_fma_f32 v[104:105], v[96:97], v[104:105], v[106:107]
	v_lshlrev_b32_e32 v96, 16, v207
	v_and_b32_e32 v97, 0xffff0000, v207
	v_lshlrev_b32_e32 v106, 16, v211
	v_and_b32_e32 v107, 0xffff0000, v211
	v_pk_fma_f32 v[106:107], v[98:99], v[96:97], v[106:107]
	v_cvt_pk_bf16_f32 v96, v100, v101
	v_cvt_pk_bf16_f32 v97, v102, v103
	v_cvt_pk_bf16_f32 v98, v104, v105
	v_cvt_pk_bf16_f32 v99, v106, v107
	global_store_dwordx4 v[224:225], v[96:99], off offset:256
	s_nop 1
	v_lshlrev_b32_e32 v96, 16, v212
	v_and_b32_e32 v97, 0xffff0000, v212
	v_lshlrev_b32_e32 v98, 16, v216
	v_and_b32_e32 v99, 0xffff0000, v216
	v_pk_fma_f32 v[92:93], v[92:93], v[96:97], v[98:99]
	v_lshlrev_b32_e32 v96, 16, v213
	v_and_b32_e32 v97, 0xffff0000, v213
	v_lshlrev_b32_e32 v98, 16, v217
	v_and_b32_e32 v99, 0xffff0000, v217
	v_pk_fma_f32 v[94:95], v[94:95], v[96:97], v[98:99]
	v_lshlrev_b32_e32 v96, 16, v214
	v_and_b32_e32 v97, 0xffff0000, v214
	v_lshlrev_b32_e32 v98, 16, v218
	v_and_b32_e32 v99, 0xffff0000, v218
	v_pk_fma_f32 v[96:97], v[88:89], v[96:97], v[98:99]
	v_lshlrev_b32_e32 v88, 16, v215
	v_and_b32_e32 v89, 0xffff0000, v215
	v_lshlrev_b32_e32 v98, 16, v219
	v_and_b32_e32 v99, 0xffff0000, v219
	v_pk_fma_f32 v[98:99], v[90:91], v[88:89], v[98:99]
	v_cvt_pk_bf16_f32 v88, v92, v93
	v_cvt_pk_bf16_f32 v89, v94, v95
	v_cvt_pk_bf16_f32 v90, v96, v97
	v_cvt_pk_bf16_f32 v91, v98, v99
	global_store_dwordx4 v[170:171], v[88:91], off
	s_nop 1
	v_lshlrev_b32_e32 v88, 16, v148
	v_and_b32_e32 v89, 0xffff0000, v148
	v_lshlrev_b32_e32 v90, 16, v144
	v_and_b32_e32 v91, 0xffff0000, v144
	v_pk_fma_f32 v[84:85], v[84:85], v[88:89], v[90:91]
	v_lshlrev_b32_e32 v88, 16, v149
	v_and_b32_e32 v89, 0xffff0000, v149
	v_lshlrev_b32_e32 v90, 16, v145
	v_and_b32_e32 v91, 0xffff0000, v145
	v_pk_fma_f32 v[86:87], v[86:87], v[88:89], v[90:91]
	v_lshlrev_b32_e32 v88, 16, v150
	v_and_b32_e32 v89, 0xffff0000, v150
	v_lshlrev_b32_e32 v90, 16, v146
	v_and_b32_e32 v91, 0xffff0000, v146
	v_pk_fma_f32 v[88:89], v[80:81], v[88:89], v[90:91]
	v_lshlrev_b32_e32 v80, 16, v151
	v_and_b32_e32 v81, 0xffff0000, v151
	v_lshlrev_b32_e32 v90, 16, v147
	v_and_b32_e32 v91, 0xffff0000, v147
	v_pk_fma_f32 v[90:91], v[82:83], v[80:81], v[90:91]
	v_cvt_pk_bf16_f32 v80, v84, v85
	v_cvt_pk_bf16_f32 v81, v86, v87
	v_cvt_pk_bf16_f32 v82, v88, v89
	v_cvt_pk_bf16_f32 v83, v90, v91
	global_store_dwordx4 v[170:171], v[80:83], off offset:256
	s_nop 1
	v_lshlrev_b32_e32 v80, 16, v140
	v_and_b32_e32 v81, 0xffff0000, v140
	v_lshlrev_b32_e32 v82, 16, v136
	v_and_b32_e32 v83, 0xffff0000, v136
	v_pk_fma_f32 v[76:77], v[76:77], v[80:81], v[82:83]
	v_lshlrev_b32_e32 v80, 16, v141
	v_and_b32_e32 v81, 0xffff0000, v141
	v_lshlrev_b32_e32 v82, 16, v137
	v_and_b32_e32 v83, 0xffff0000, v137
	v_pk_fma_f32 v[78:79], v[78:79], v[80:81], v[82:83]
	v_lshlrev_b32_e32 v80, 16, v142
	v_and_b32_e32 v81, 0xffff0000, v142
	v_lshlrev_b32_e32 v82, 16, v138
	v_and_b32_e32 v83, 0xffff0000, v138
	v_pk_fma_f32 v[80:81], v[72:73], v[80:81], v[82:83]
	v_lshlrev_b32_e32 v72, 16, v143
	v_and_b32_e32 v73, 0xffff0000, v143
	v_lshlrev_b32_e32 v82, 16, v139
	v_and_b32_e32 v83, 0xffff0000, v139
	v_pk_fma_f32 v[82:83], v[74:75], v[72:73], v[82:83]
	v_cvt_pk_bf16_f32 v72, v76, v77
	v_cvt_pk_bf16_f32 v73, v78, v79
	v_cvt_pk_bf16_f32 v74, v80, v81
	v_cvt_pk_bf16_f32 v75, v82, v83
	global_store_dwordx4 v[168:169], v[72:75], off
	s_nop 1
	v_lshlrev_b32_e32 v72, 16, v132
	v_and_b32_e32 v73, 0xffff0000, v132
	v_lshlrev_b32_e32 v74, 16, v128
	v_and_b32_e32 v75, 0xffff0000, v128
	v_pk_fma_f32 v[68:69], v[68:69], v[72:73], v[74:75]
	v_lshlrev_b32_e32 v72, 16, v133
	v_and_b32_e32 v73, 0xffff0000, v133
	v_lshlrev_b32_e32 v74, 16, v129
	v_and_b32_e32 v75, 0xffff0000, v129
	v_pk_fma_f32 v[70:71], v[70:71], v[72:73], v[74:75]
	v_lshlrev_b32_e32 v72, 16, v134
	v_and_b32_e32 v73, 0xffff0000, v134
	v_lshlrev_b32_e32 v74, 16, v130
	v_and_b32_e32 v75, 0xffff0000, v130
	v_pk_fma_f32 v[72:73], v[64:65], v[72:73], v[74:75]
	v_lshlrev_b32_e32 v64, 16, v135
	v_and_b32_e32 v65, 0xffff0000, v135
	v_lshlrev_b32_e32 v74, 16, v131
	v_and_b32_e32 v75, 0xffff0000, v131
	v_pk_fma_f32 v[74:75], v[66:67], v[64:65], v[74:75]
	v_cvt_pk_bf16_f32 v64, v68, v69
	v_cvt_pk_bf16_f32 v65, v70, v71
	v_cvt_pk_bf16_f32 v66, v72, v73
	v_cvt_pk_bf16_f32 v67, v74, v75
	global_store_dwordx4 v[168:169], v[64:67], off offset:256
	s_nop 1
	v_add_u32_e32 v64, 0x80, v164
	v_ashrrev_i32_e32 v65, 31, v64
	v_lshlrev_b64 v[66:67], 12, v[64:65]
	v_lshl_add_u64 v[66:67], s[42:43], 0, v[66:67]
	v_lshlrev_b64 v[64:65], 11, v[64:65]
	v_lshl_add_u64 v[66:67], v[66:67], 0, v[166:167]
	v_lshl_add_u64 v[64:65], s[82:83], 0, v[64:65]
	global_load_dwordx4 v[92:95], v[66:67], off offset:2048
	v_lshl_add_u64 v[132:133], v[64:65], 0, v[166:167]
	global_load_dwordx4 v[96:99], v[132:133], off
	global_load_dwordx4 v[100:103], v[66:67], off offset:2304
	global_load_dwordx4 v[104:107], v[132:133], off offset:256
	v_add_u32_e32 v64, 0x90, v164
	v_ashrrev_i32_e32 v65, 31, v64
	v_lshlrev_b64 v[66:67], 12, v[64:65]
	v_lshl_add_u64 v[66:67], s[42:43], 0, v[66:67]
	v_lshlrev_b64 v[64:65], 11, v[64:65]
	v_lshl_add_u64 v[66:67], v[66:67], 0, v[166:167]
	v_lshl_add_u64 v[64:65], s[82:83], 0, v[64:65]
	global_load_dwordx4 v[108:111], v[66:67], off offset:2048
	v_lshl_add_u64 v[134:135], v[64:65], 0, v[166:167]
	global_load_dwordx4 v[112:115], v[134:135], off
	global_load_dwordx4 v[116:119], v[66:67], off offset:2304
	global_load_dwordx4 v[120:123], v[134:135], off offset:256
	v_add_u32_e32 v64, 0xa0, v164
	v_ashrrev_i32_e32 v65, 31, v64
	v_lshlrev_b64 v[66:67], 12, v[64:65]
	v_lshl_add_u64 v[66:67], s[42:43], 0, v[66:67]
	v_lshlrev_b64 v[64:65], 11, v[64:65]
	v_lshl_add_u64 v[64:65], s[82:83], 0, v[64:65]
	v_lshl_add_u64 v[66:67], v[66:67], 0, v[166:167]
	v_lshl_add_u64 v[90:91], v[64:65], 0, v[166:167]
	global_load_dwordx4 v[124:127], v[66:67], off offset:2048
	global_load_dwordx4 v[84:87], v[66:67], off offset:2304
	global_load_dwordx4 v[128:131], v[90:91], off
	global_load_dwordx4 v[80:83], v[90:91], off offset:256
	v_add_u32_e32 v64, 0xb0, v164
	v_ashrrev_i32_e32 v65, 31, v64
	v_lshlrev_b64 v[66:67], 12, v[64:65]
	v_lshl_add_u64 v[66:67], s[42:43], 0, v[66:67]
	v_lshlrev_b64 v[64:65], 11, v[64:65]
	v_lshl_add_u64 v[64:65], s[82:83], 0, v[64:65]
	v_lshl_add_u64 v[66:67], v[66:67], 0, v[166:167]
	v_lshl_add_u64 v[88:89], v[64:65], 0, v[166:167]
	global_load_dwordx4 v[76:79], v[66:67], off offset:2048
	global_load_dwordx4 v[68:71], v[66:67], off offset:2304
	global_load_dwordx4 v[72:75], v[88:89], off
	s_nop 0
	global_load_dwordx4 v[64:67], v[88:89], off offset:256
	s_waitcnt vmcnt(0)
	v_lshlrev_b32_e32 v136, 16, v92
	v_and_b32_e32 v137, 0xffff0000, v92
	v_lshlrev_b32_e32 v138, 16, v96
	v_and_b32_e32 v139, 0xffff0000, v96
	v_lshlrev_b32_e32 v92, 16, v93
	v_and_b32_e32 v93, 0xffff0000, v93
	v_lshlrev_b32_e32 v96, 16, v97
	v_and_b32_e32 v97, 0xffff0000, v97
	v_pk_fma_f32 v[62:63], v[62:63], v[92:93], v[96:97]
	v_lshlrev_b32_e32 v92, 16, v94
	v_and_b32_e32 v93, 0xffff0000, v94
	v_lshlrev_b32_e32 v96, 16, v98
	v_and_b32_e32 v97, 0xffff0000, v98
	v_pk_fma_f32 v[92:93], v[56:57], v[92:93], v[96:97]
	v_lshlrev_b32_e32 v56, 16, v95
	v_and_b32_e32 v57, 0xffff0000, v95
	v_lshlrev_b32_e32 v94, 16, v99
	v_and_b32_e32 v95, 0xffff0000, v99
	v_pk_fma_f32 v[60:61], v[60:61], v[136:137], v[138:139]
	v_pk_fma_f32 v[94:95], v[58:59], v[56:57], v[94:95]
	v_cvt_pk_bf16_f32 v56, v60, v61
	v_cvt_pk_bf16_f32 v57, v62, v63
	v_cvt_pk_bf16_f32 v58, v92, v93
	v_cvt_pk_bf16_f32 v59, v94, v95
	global_store_dwordx4 v[132:133], v[56:59], off
	s_nop 1
	v_lshlrev_b32_e32 v56, 16, v100
	v_and_b32_e32 v57, 0xffff0000, v100
	v_lshlrev_b32_e32 v58, 16, v104
	v_and_b32_e32 v59, 0xffff0000, v104
	v_pk_fma_f32 v[52:53], v[52:53], v[56:57], v[58:59]
	v_lshlrev_b32_e32 v56, 16, v101
	v_and_b32_e32 v57, 0xffff0000, v101
	v_lshlrev_b32_e32 v58, 16, v105
	v_and_b32_e32 v59, 0xffff0000, v105
	v_pk_fma_f32 v[54:55], v[54:55], v[56:57], v[58:59]
	v_lshlrev_b32_e32 v56, 16, v102
	v_and_b32_e32 v57, 0xffff0000, v102
	v_lshlrev_b32_e32 v58, 16, v106
	v_and_b32_e32 v59, 0xffff0000, v106
	v_pk_fma_f32 v[56:57], v[48:49], v[56:57], v[58:59]
	v_lshlrev_b32_e32 v48, 16, v103
	v_and_b32_e32 v49, 0xffff0000, v103
	v_lshlrev_b32_e32 v58, 16, v107
	v_and_b32_e32 v59, 0xffff0000, v107
	v_pk_fma_f32 v[58:59], v[50:51], v[48:49], v[58:59]
	v_cvt_pk_bf16_f32 v48, v52, v53
	v_cvt_pk_bf16_f32 v49, v54, v55
	v_cvt_pk_bf16_f32 v50, v56, v57
	v_cvt_pk_bf16_f32 v51, v58, v59
	global_store_dwordx4 v[132:133], v[48:51], off offset:256
	s_nop 1
	v_lshlrev_b32_e32 v48, 16, v108
	v_and_b32_e32 v49, 0xffff0000, v108
	v_lshlrev_b32_e32 v50, 16, v112
	v_and_b32_e32 v51, 0xffff0000, v112
	v_pk_fma_f32 v[44:45], v[44:45], v[48:49], v[50:51]
	v_lshlrev_b32_e32 v48, 16, v109
	v_and_b32_e32 v49, 0xffff0000, v109
	v_lshlrev_b32_e32 v50, 16, v113
	v_and_b32_e32 v51, 0xffff0000, v113
	v_pk_fma_f32 v[46:47], v[46:47], v[48:49], v[50:51]
	v_lshlrev_b32_e32 v48, 16, v110
	v_and_b32_e32 v49, 0xffff0000, v110
	v_lshlrev_b32_e32 v50, 16, v114
	v_and_b32_e32 v51, 0xffff0000, v114
	v_pk_fma_f32 v[48:49], v[40:41], v[48:49], v[50:51]
	v_lshlrev_b32_e32 v40, 16, v111
	v_and_b32_e32 v41, 0xffff0000, v111
	v_lshlrev_b32_e32 v50, 16, v115
	v_and_b32_e32 v51, 0xffff0000, v115
	v_pk_fma_f32 v[50:51], v[42:43], v[40:41], v[50:51]
	v_cvt_pk_bf16_f32 v40, v44, v45
	v_cvt_pk_bf16_f32 v41, v46, v47
	v_cvt_pk_bf16_f32 v42, v48, v49
	v_cvt_pk_bf16_f32 v43, v50, v51
	global_store_dwordx4 v[134:135], v[40:43], off
	s_nop 1
	v_lshlrev_b32_e32 v40, 16, v116
	v_and_b32_e32 v41, 0xffff0000, v116
	v_lshlrev_b32_e32 v42, 16, v120
	v_and_b32_e32 v43, 0xffff0000, v120
	v_pk_fma_f32 v[36:37], v[36:37], v[40:41], v[42:43]
	v_lshlrev_b32_e32 v40, 16, v117
	v_and_b32_e32 v41, 0xffff0000, v117
	v_lshlrev_b32_e32 v42, 16, v121
	v_and_b32_e32 v43, 0xffff0000, v121
	v_pk_fma_f32 v[38:39], v[38:39], v[40:41], v[42:43]
	v_lshlrev_b32_e32 v40, 16, v118
	v_and_b32_e32 v41, 0xffff0000, v118
	v_lshlrev_b32_e32 v42, 16, v122
	v_and_b32_e32 v43, 0xffff0000, v122
	v_pk_fma_f32 v[40:41], v[32:33], v[40:41], v[42:43]
	v_lshlrev_b32_e32 v32, 16, v119
	v_and_b32_e32 v33, 0xffff0000, v119
	v_lshlrev_b32_e32 v42, 16, v123
	v_and_b32_e32 v43, 0xffff0000, v123
	v_pk_fma_f32 v[42:43], v[34:35], v[32:33], v[42:43]
	v_cvt_pk_bf16_f32 v32, v36, v37
	v_cvt_pk_bf16_f32 v33, v38, v39
	v_cvt_pk_bf16_f32 v34, v40, v41
	v_cvt_pk_bf16_f32 v35, v42, v43
	global_store_dwordx4 v[134:135], v[32:35], off offset:256
	s_nop 1
	v_lshlrev_b32_e32 v32, 16, v124
	v_and_b32_e32 v33, 0xffff0000, v124
	v_lshlrev_b32_e32 v34, 16, v128
	v_and_b32_e32 v35, 0xffff0000, v128
	v_pk_fma_f32 v[28:29], v[28:29], v[32:33], v[34:35]
	v_lshlrev_b32_e32 v32, 16, v125
	v_and_b32_e32 v33, 0xffff0000, v125
	v_lshlrev_b32_e32 v34, 16, v129
	v_and_b32_e32 v35, 0xffff0000, v129
	v_pk_fma_f32 v[30:31], v[30:31], v[32:33], v[34:35]
	v_lshlrev_b32_e32 v32, 16, v126
	v_and_b32_e32 v33, 0xffff0000, v126
	v_lshlrev_b32_e32 v34, 16, v130
	v_and_b32_e32 v35, 0xffff0000, v130
	v_pk_fma_f32 v[32:33], v[24:25], v[32:33], v[34:35]
	v_lshlrev_b32_e32 v24, 16, v127
	v_and_b32_e32 v25, 0xffff0000, v127
	v_lshlrev_b32_e32 v34, 16, v131
	v_and_b32_e32 v35, 0xffff0000, v131
	v_pk_fma_f32 v[34:35], v[26:27], v[24:25], v[34:35]
	v_cvt_pk_bf16_f32 v24, v28, v29
	v_cvt_pk_bf16_f32 v25, v30, v31
	v_cvt_pk_bf16_f32 v26, v32, v33
	v_cvt_pk_bf16_f32 v27, v34, v35
	global_store_dwordx4 v[90:91], v[24:27], off
	s_nop 1
	v_lshlrev_b32_e32 v24, 16, v84
	v_and_b32_e32 v25, 0xffff0000, v84
	v_lshlrev_b32_e32 v26, 16, v80
	v_and_b32_e32 v27, 0xffff0000, v80
	v_pk_fma_f32 v[20:21], v[20:21], v[24:25], v[26:27]
	v_lshlrev_b32_e32 v24, 16, v85
	v_and_b32_e32 v25, 0xffff0000, v85
	v_lshlrev_b32_e32 v26, 16, v81
	v_and_b32_e32 v27, 0xffff0000, v81
	v_pk_fma_f32 v[22:23], v[22:23], v[24:25], v[26:27]
	v_lshlrev_b32_e32 v24, 16, v86
	v_and_b32_e32 v25, 0xffff0000, v86
	v_lshlrev_b32_e32 v26, 16, v82
	v_and_b32_e32 v27, 0xffff0000, v82
	v_pk_fma_f32 v[24:25], v[16:17], v[24:25], v[26:27]
	v_lshlrev_b32_e32 v16, 16, v87
	v_and_b32_e32 v17, 0xffff0000, v87
	v_lshlrev_b32_e32 v26, 16, v83
	v_and_b32_e32 v27, 0xffff0000, v83
	v_pk_fma_f32 v[26:27], v[18:19], v[16:17], v[26:27]
	v_cvt_pk_bf16_f32 v16, v20, v21
	v_cvt_pk_bf16_f32 v17, v22, v23
	v_cvt_pk_bf16_f32 v18, v24, v25
	v_cvt_pk_bf16_f32 v19, v26, v27
	global_store_dwordx4 v[90:91], v[16:19], off offset:256
	s_nop 1
	v_lshlrev_b32_e32 v16, 16, v76
	v_and_b32_e32 v17, 0xffff0000, v76
	v_lshlrev_b32_e32 v18, 16, v72
	v_and_b32_e32 v19, 0xffff0000, v72
	v_pk_fma_f32 v[12:13], v[12:13], v[16:17], v[18:19]
	v_lshlrev_b32_e32 v16, 16, v77
	v_and_b32_e32 v17, 0xffff0000, v77
	v_lshlrev_b32_e32 v18, 16, v73
	v_and_b32_e32 v19, 0xffff0000, v73
	v_pk_fma_f32 v[14:15], v[14:15], v[16:17], v[18:19]
	v_lshlrev_b32_e32 v16, 16, v78
	v_and_b32_e32 v17, 0xffff0000, v78
	v_lshlrev_b32_e32 v18, 16, v74
	v_and_b32_e32 v19, 0xffff0000, v74
	v_pk_fma_f32 v[16:17], v[8:9], v[16:17], v[18:19]
	v_lshlrev_b32_e32 v8, 16, v79
	v_and_b32_e32 v9, 0xffff0000, v79
	v_lshlrev_b32_e32 v18, 16, v75
	v_and_b32_e32 v19, 0xffff0000, v75
	v_pk_fma_f32 v[18:19], v[10:11], v[8:9], v[18:19]
	v_cvt_pk_bf16_f32 v8, v12, v13
	v_cvt_pk_bf16_f32 v9, v14, v15
	v_cvt_pk_bf16_f32 v10, v16, v17
	v_cvt_pk_bf16_f32 v11, v18, v19
	global_store_dwordx4 v[88:89], v[8:11], off
	s_nop 1
	v_lshlrev_b32_e32 v8, 16, v68
	v_and_b32_e32 v9, 0xffff0000, v68
	v_lshlrev_b32_e32 v10, 16, v64
	v_and_b32_e32 v11, 0xffff0000, v64
	v_pk_fma_f32 v[4:5], v[4:5], v[8:9], v[10:11]
	v_lshlrev_b32_e32 v8, 16, v69
	v_and_b32_e32 v9, 0xffff0000, v69
	v_lshlrev_b32_e32 v10, 16, v65
	v_and_b32_e32 v11, 0xffff0000, v65
	v_pk_fma_f32 v[6:7], v[6:7], v[8:9], v[10:11]
	v_lshlrev_b32_e32 v8, 16, v70
	v_and_b32_e32 v9, 0xffff0000, v70
	v_lshlrev_b32_e32 v10, 16, v66
	v_and_b32_e32 v11, 0xffff0000, v66
	v_pk_fma_f32 v[8:9], v[0:1], v[8:9], v[10:11]
	v_lshlrev_b32_e32 v0, 16, v71
	v_and_b32_e32 v1, 0xffff0000, v71
	v_lshlrev_b32_e32 v10, 16, v67
	v_and_b32_e32 v11, 0xffff0000, v67
	v_pk_fma_f32 v[10:11], v[2:3], v[0:1], v[10:11]
	v_cvt_pk_bf16_f32 v0, v4, v5
	v_cvt_pk_bf16_f32 v1, v6, v7
	v_cvt_pk_bf16_f32 v2, v8, v9
	v_cvt_pk_bf16_f32 v3, v10, v11
	global_store_dwordx4 v[88:89], v[0:3], off offset:256
	s_cbranch_vccz .LBB0_1277
	s_waitcnt vmcnt(0)
	s_cmpk_gt_u32 s26, 0xff
	s_cbranch_scc1 .LBB0_1289
	s_barrier

.LBB0_1343:
	s_or_b64 exec, exec, s[0:1]
	s_cmpk_gt_i32 s62, 0x1ff
	s_cselect_b64 s[0:1], -1, 0
	s_cmpk_lt_i32 s62, 0x200
	s_cselect_b64 s[4:5], -1, 0
	s_or_b64 s[4:5], s[68:69], s[4:5]
	s_waitcnt lgkmcnt(0)
	s_barrier
	v_mov_b32 v9, v178
	s_and_b64 vcc, exec, s[4:5]
	v_readfirstlane_b32 s31, v9
	s_cbranch_vccz .LBB0_1376
	v_lshlrev_b32_e32 v0, 4, v9
	v_add_u32_e32 v1, 0x2000, v0
	v_ashrrev_i32_e32 v2, 31, v1
	v_lshrrev_b32_e32 v2, 22, v2
	v_add_u32_e32 v2, v1, v2
	v_ashrrev_i32_e32 v8, 10, v2
	v_mul_i32_i24_e32 v2, 0x400, v8
	v_sub_u32_e32 v1, v1, v2
	v_lshrrev_b32_e32 v2, 4, v1
	v_bitop3_b32 v1, v2, v1, 32 bitop3:0x6c
	v_ashrrev_i32_e32 v2, 31, v1
	v_lshrrev_b32_e32 v2, 26, v2
	s_ashr_i32 s12, s31, 6
	v_add_u32_e32 v2, v1, v2
	v_lshlrev_b32_e32 v3, 3, v8
	s_ashr_i32 s14, s31, 8
	s_lshl_b32 s33, s12, 10
	s_or_b64 s[0:1], s[68:69], s[0:1]
	v_ashrrev_i32_e32 v10, 6, v2
	v_and_b32_e32 v3, -16, v3
	s_and_b64 s[0:1], s[0:1], exec
	v_add_u32_e32 v3, v10, v3
	v_and_b32_e32 v4, 3, v10
	s_mov_b32 s0, 0x1fffe0
	v_lshrrev_b32_e32 v5, 2, v3
	v_lshlrev_b32_e32 v6, 1, v3
	v_and_b32_e32 v2, 0xc0, v2
	v_and_or_b32 v4, v3, s0, v4
	v_and_b32_e32 v5, 4, v5
	v_and_b32_e32 v6, 24, v6
	v_sub_u32_e32 v1, v1, v2
	v_mov_b32_e32 v2, 1
	v_or3_b32 v4, v4, v5, v6
	v_lshlrev_b32_e32 v5, 5, v8
	v_ashrrev_i16_sdwa v1, v2, sext(v1) dst_sel:DWORD dst_unused:UNUSED_PAD src0_sel:DWORD src1_sel:BYTE_0
	v_and_b32_e32 v5, 32, v5
	v_bfe_i32 v11, v1, 0, 16
	v_add_lshl_u32 v1, v5, v11, 1
	v_lshl_add_u32 v152, v4, 11, v1
	v_lshl_add_u32 v154, v3, 11, v1
	v_bfe_i32 v1, v9, 27, 1
	v_lshrrev_b32_e32 v1, 22, v1
	v_add_u32_e32 v1, v0, v1
	v_and_b32_e32 v1, 0xfffffc00, v1
	v_sub_u32_e32 v0, v0, v1
	v_lshrrev_b32_e32 v1, 4, v0
	v_bitop3_b32 v1, v1, v0, 32 bitop3:0x6c
	v_ashrrev_i32_e32 v0, 31, v0
	v_lshrrev_b32_e32 v0, 26, v0
	v_add_u32_e32 v0, v1, v0
	v_ashrrev_i32_e32 v12, 6, v0
	v_ashrrev_i32_e32 v0, 31, v9
	v_lshrrev_b32_e32 v0, 26, v0
	v_add_u32_e32 v0, v9, v0
	v_ashrrev_i32_e32 v13, 6, v0
	v_lshlrev_b32_e32 v0, 3, v13
	v_and_b32_e32 v0, -16, v0
	v_add_u32_e32 v0, v12, v0
	s_cselect_b32 s4, s63, s30
	v_and_b32_e32 v3, 3, v12
	v_lshrrev_b32_e32 v4, 2, v0
	v_lshlrev_b32_e32 v5, 1, v0
	s_ashr_i32 s7, s6, 31
	v_and_or_b32 v3, v0, s0, v3
	v_and_b32_e32 v4, 4, v4
	v_and_b32_e32 v5, 24, v5
	s_lshl_b64 s[0:1], s[6:7], 19
	v_or3_b32 v3, v3, v4, v5
	v_mul_i32_i24_e32 v5, 64, v12
	s_add_u32 s10, s82, s0
	v_sub_u32_e32 v1, v1, v5
	s_addc_u32 s11, s83, s1
	s_ashr_i32 s5, s4, 31
	s_nop 0
	v_lshlrev_b32_e32 v4, 5, v13
	v_ashrrev_i16_sdwa v1, v2, sext(v1) dst_sel:DWORD dst_unused:UNUSED_PAD src0_sel:DWORD src1_sel:BYTE_0
	s_lshl_b64 s[0:1], s[4:5], 19
	v_readlane_b32 s50, v253, 48
	v_and_b32_e32 v4, 32, v4
	v_bfe_i32 v14, v1, 0, 16
	v_readlane_b32 s51, v253, 49
	s_add_u32 s24, s50, s0
	v_add_lshl_u32 v1, v4, v14, 1
	s_addc_u32 s25, s51, s1
	s_add_i32 s7, s33, 0
	v_lshl_add_u32 v156, v3, 11, v1
	s_add_i32 m0, s7, 0x10000
	v_lshl_add_u32 v158, v0, 11, v1
	global_load_lds_dwordx4 v156, s[24:25]
	s_add_i32 m0, s7, 0x12000
	s_add_i32 s35, s7, 0x2000
	global_load_lds_dwordx4 v152, s[24:25]
	s_mov_b32 m0, s7
	s_add_u32 s0, s24, 0x40000
	global_load_lds_dwordx4 v158, s[10:11]
	s_mov_b32 m0, s35
	s_addc_u32 s1, s25, 0
	global_load_lds_dwordx4 v154, s[10:11]
	s_add_i32 m0, s7, 0x14000
	s_nop 0
	global_load_lds_dwordx4 v156, s[0:1]
	s_add_i32 m0, s7, 0x16000
	v_mov_b32_e32 v161, 0
	global_load_lds_dwordx4 v152, s[0:1]
	s_add_u32 s0, s10, 0x40000
	s_addc_u32 s1, s11, 0
	s_add_i32 s36, s7, 0x4000
	s_mov_b32 m0, s36
	s_add_i32 s37, s7, 0x6000
	global_load_lds_dwordx4 v158, s[0:1]
	s_mov_b32 m0, s37
	v_mov_b32_e32 v157, v161
	global_load_lds_dwordx4 v154, s[0:1]
	v_mov_b32_e32 v153, v161
	v_mov_b32_e32 v159, v161
	v_mov_b32_e32 v155, v161
	s_mov_b32 s5, 0
	v_lshl_add_u64 v[6:7], s[24:25], 0, v[156:157]
	v_lshl_add_u64 v[4:5], s[24:25], 0, v[152:153]
	v_lshl_add_u64 v[2:3], s[10:11], 0, v[158:159]
	s_cmp_lg_u32 s14, 1
	v_lshl_add_u64 v[0:1], s[10:11], 0, v[154:155]
	s_nop 7
	s_nop 3
	s_cbranch_scc1 .LBB0_1346
	s_barrier

.LBB0_1355:
	s_mov_b32 s14, s17
	s_ashr_i32 s15, s17, 31
	s_mov_b32 s16, s20
	s_xor_b64 s[20:21], s[26:27], -1
	s_lshl_b64 s[18:19], s[14:15], 19
	s_add_u32 s18, s82, s18
	s_addc_u32 s19, s83, s19
	s_and_b64 s[22:23], s[26:27], exec
	s_cselect_b32 s15, s19, s11
	s_cselect_b32 s29, s18, s10
	s_ashr_i32 s17, s16, 31
	s_nop 0
	s_lshl_b64 s[22:23], s[16:17], 19
	v_readlane_b32 s58, v253, 48
	v_readlane_b32 s59, v253, 49
	s_add_u32 s22, s58, s22
	s_addc_u32 s23, s59, s23
	s_and_b64 s[26:27], s[26:27], exec
	s_cselect_b32 s17, s23, s25
	s_cselect_b32 s44, s22, s24
	s_add_u32 s10, s10, 0x40080
	s_nop 0
	s_addc_u32 s11, s11, 0
	s_nop 1
	s_add_u32 s45, s24, 0x100
	v_mov_b32_e32 v0, 0
	s_addc_u32 s46, s25, 0
	s_mov_b32 s47, -2
	s_waitcnt lgkmcnt(0)
	v_mov_b32_e32 v1, v0
	v_mov_b32_e32 v2, v0
	v_mov_b32_e32 v3, v0
	v_mov_b32_e32 v4, v0
	v_mov_b32_e32 v5, v0
	v_mov_b32_e32 v6, v0
	v_mov_b32_e32 v7, v0
	v_mov_b32_e32 v16, v0
	v_mov_b32_e32 v17, v0
	v_mov_b32_e32 v18, v0
	v_mov_b32_e32 v19, v0
	v_mov_b32_e32 v20, v0
	v_mov_b32_e32 v21, v0
	v_mov_b32_e32 v22, v0
	v_mov_b32_e32 v23, v0
	v_mov_b32_e32 v32, v0
	v_mov_b32_e32 v33, v0
	v_mov_b32_e32 v34, v0
	v_mov_b32_e32 v35, v0
	v_mov_b32_e32 v36, v0
	v_mov_b32_e32 v37, v0
	v_mov_b32_e32 v38, v0
	v_mov_b32_e32 v39, v0
	v_mov_b32_e32 v48, v0
	v_mov_b32_e32 v49, v0
	v_mov_b32_e32 v50, v0
	v_mov_b32_e32 v51, v0
	v_mov_b32_e32 v52, v0
	v_mov_b32_e32 v53, v0
	v_mov_b32_e32 v54, v0
	v_mov_b32_e32 v55, v0
	v_mov_b32_e32 v8, v0
	v_mov_b32_e32 v9, v0
	v_mov_b32_e32 v10, v0
	v_mov_b32_e32 v11, v0
	v_mov_b32_e32 v12, v0
	v_mov_b32_e32 v13, v0
	v_mov_b32_e32 v14, v0
	v_mov_b32_e32 v15, v0
	v_mov_b32_e32 v24, v0
	v_mov_b32_e32 v25, v0
	v_mov_b32_e32 v26, v0
	v_mov_b32_e32 v27, v0
	v_mov_b32_e32 v28, v0
	v_mov_b32_e32 v29, v0
	v_mov_b32_e32 v30, v0
	v_mov_b32_e32 v31, v0
	v_mov_b32_e32 v40, v0
	v_mov_b32_e32 v41, v0
	v_mov_b32_e32 v42, v0
	v_mov_b32_e32 v43, v0
	v_mov_b32_e32 v44, v0
	v_mov_b32_e32 v45, v0
	v_mov_b32_e32 v46, v0
	v_mov_b32_e32 v47, v0
	v_mov_b32_e32 v56, v0
	v_mov_b32_e32 v57, v0
	v_mov_b32_e32 v58, v0
	v_mov_b32_e32 v59, v0
	v_mov_b32_e32 v60, v0
	v_mov_b32_e32 v61, v0
	v_mov_b32_e32 v62, v0
	v_mov_b32_e32 v63, v0
	v_mov_b32_e32 v64, v0
	v_mov_b32_e32 v65, v0
	v_mov_b32_e32 v66, v0
	v_mov_b32_e32 v67, v0
	v_mov_b32_e32 v68, v0
	v_mov_b32_e32 v69, v0
	v_mov_b32_e32 v70, v0
	v_mov_b32_e32 v71, v0
	v_mov_b32_e32 v80, v0
	v_mov_b32_e32 v81, v0
	v_mov_b32_e32 v82, v0
	v_mov_b32_e32 v83, v0
	v_mov_b32_e32 v84, v0
	v_mov_b32_e32 v85, v0
	v_mov_b32_e32 v86, v0
	v_mov_b32_e32 v87, v0
	v_mov_b32_e32 v96, v0
	v_mov_b32_e32 v97, v0
	v_mov_b32_e32 v98, v0
	v_mov_b32_e32 v99, v0
	v_mov_b32_e32 v100, v0
	v_mov_b32_e32 v101, v0
	v_mov_b32_e32 v102, v0
	v_mov_b32_e32 v103, v0
	v_mov_b32_e32 v112, v0
	v_mov_b32_e32 v113, v0
	v_mov_b32_e32 v114, v0
	v_mov_b32_e32 v115, v0
	v_mov_b32_e32 v116, v0
	v_mov_b32_e32 v117, v0
	v_mov_b32_e32 v118, v0
	v_mov_b32_e32 v119, v0
	v_mov_b32_e32 v72, v0
	v_mov_b32_e32 v73, v0
	v_mov_b32_e32 v74, v0
	v_mov_b32_e32 v75, v0
	v_mov_b32_e32 v76, v0
	v_mov_b32_e32 v77, v0
	v_mov_b32_e32 v78, v0
	v_mov_b32_e32 v79, v0
	v_mov_b32_e32 v88, v0
	v_mov_b32_e32 v89, v0
	v_mov_b32_e32 v90, v0
	v_mov_b32_e32 v91, v0
	v_mov_b32_e32 v92, v0
	v_mov_b32_e32 v93, v0
	v_mov_b32_e32 v94, v0
	v_mov_b32_e32 v95, v0
	v_mov_b32_e32 v104, v0
	v_mov_b32_e32 v105, v0
	v_mov_b32_e32 v106, v0
	v_mov_b32_e32 v107, v0
	v_mov_b32_e32 v108, v0
	v_mov_b32_e32 v109, v0
	v_mov_b32_e32 v110, v0
	v_mov_b32_e32 v111, v0
	v_mov_b32_e32 v120, v0
	v_mov_b32_e32 v121, v0
	v_mov_b32_e32 v122, v0
	v_mov_b32_e32 v123, v0
	v_mov_b32_e32 v124, v0
	v_mov_b32_e32 v125, v0
	v_mov_b32_e32 v126, v0
	v_mov_b32_e32 v127, v0
	s_nop 7
	s_nop 1
.LBB0_1356:
	ds_read_b128 v[128:131], v189
	ds_read_b128 v[132:135], v189 offset:1024
	ds_read_b128 v[136:139], v189 offset:2048
	ds_read_b128 v[140:143], v189 offset:3072
	s_add_u32 s24, s10, 0xfffc0080
	s_addc_u32 s25, s11, -1
	s_cmp_eq_u32 s47, 12
	s_cselect_b32 s27, s15, s25
	s_cselect_b32 s26, s29, s24
	s_cselect_b32 s25, s17, s46
	s_cselect_b32 s24, s44, s45
	v_lshl_add_u64 v[198:199], s[10:11], 0, v[162:163]
	s_add_i32 m0, s7, 0xc000
	ds_read_b128 v[144:147], v190
	ds_read_b128 v[148:151], v190 offset:1024
	ds_read_b128 v[166:169], v190 offset:2048
	ds_read_b128 v[170:173], v190 offset:3072
	ds_read_b128 v[174:177], v190 offset:4096
	ds_read_b128 v[180:183], v190 offset:5120
	ds_read_b128 v[184:187], v190 offset:6144
	ds_read_b128 v[194:197], v190 offset:7168
	global_load_lds_dwordx4 v[198:199], off
	v_lshl_add_u64 v[198:199], s[10:11], 0, v[164:165]
	s_add_i32 m0, s7, 0xe000
	s_nop 0
	global_load_lds_dwordx4 v[198:199], off
	s_waitcnt lgkmcnt(8)
	s_barrier
	s_waitcnt lgkmcnt(0)
	s_setprio 1
	s_waitcnt lgkmcnt(0)
	v_mfma_f32_16x16x32_bf16 v[124:127], v[128:131], v[144:147], v[124:127]
	v_mfma_f32_16x16x32_bf16 v[120:123], v[136:139], v[144:147], v[120:123]
	v_mfma_f32_16x16x32_bf16 v[108:111], v[128:131], v[166:169], v[108:111]
	v_mfma_f32_16x16x32_bf16 v[104:107], v[136:139], v[166:169], v[104:107]
	v_mfma_f32_16x16x32_bf16 v[92:95], v[128:131], v[174:177], v[92:95]
	v_mfma_f32_16x16x32_bf16 v[88:91], v[136:139], v[174:177], v[88:91]
	v_mfma_f32_16x16x32_bf16 v[76:79], v[128:131], v[184:187], v[76:79]
	v_mfma_f32_16x16x32_bf16 v[72:75], v[136:139], v[184:187], v[72:75]
	v_mfma_f32_16x16x32_bf16 v[124:127], v[132:135], v[148:151], v[124:127]
	v_mfma_f32_16x16x32_bf16 v[120:123], v[140:143], v[148:151], v[120:123]
	v_mfma_f32_16x16x32_bf16 v[108:111], v[132:135], v[170:173], v[108:111]
	v_mfma_f32_16x16x32_bf16 v[104:107], v[140:143], v[170:173], v[104:107]
	v_mfma_f32_16x16x32_bf16 v[92:95], v[132:135], v[180:183], v[92:95]
	v_mfma_f32_16x16x32_bf16 v[88:91], v[140:143], v[180:183], v[88:91]
	v_mfma_f32_16x16x32_bf16 v[76:79], v[132:135], v[194:197], v[76:79]
	v_mfma_f32_16x16x32_bf16 v[72:75], v[140:143], v[194:197], v[72:75]
	s_setprio 0
	s_barrier
	s_add_i32 s48, s41, s33
	v_lshl_add_u64 v[214:215], s[24:25], 0, v[156:157]
	s_mov_b32 m0, s48
	ds_read_b128 v[198:201], v191
	ds_read_b128 v[202:205], v191 offset:1024
	ds_read_b128 v[206:209], v191 offset:2048
	ds_read_b128 v[210:213], v191 offset:3072
	global_load_lds_dwordx4 v[214:215], off
	v_lshl_add_u64 v[216:217], s[24:25], 0, v[152:153]
	s_add_i32 m0, s48, 0x2000
	s_nop 0
	global_load_lds_dwordx4 v[216:217], off
	s_barrier
	s_waitcnt lgkmcnt(0)
	s_setprio 1
	s_waitcnt lgkmcnt(0)
	v_mfma_f32_16x16x32_bf16 v[116:119], v[198:201], v[144:147], v[116:119]
	v_mfma_f32_16x16x32_bf16 v[112:115], v[206:209], v[144:147], v[112:115]
	v_mfma_f32_16x16x32_bf16 v[100:103], v[198:201], v[166:169], v[100:103]
	v_mfma_f32_16x16x32_bf16 v[96:99], v[206:209], v[166:169], v[96:99]
	v_mfma_f32_16x16x32_bf16 v[84:87], v[198:201], v[174:177], v[84:87]
	v_mfma_f32_16x16x32_bf16 v[80:83], v[206:209], v[174:177], v[80:83]
	v_mfma_f32_16x16x32_bf16 v[68:71], v[198:201], v[184:187], v[68:71]
	v_mfma_f32_16x16x32_bf16 v[64:67], v[206:209], v[184:187], v[64:67]
	v_mfma_f32_16x16x32_bf16 v[116:119], v[202:205], v[148:151], v[116:119]
	v_mfma_f32_16x16x32_bf16 v[112:115], v[210:213], v[148:151], v[112:115]
	v_mfma_f32_16x16x32_bf16 v[100:103], v[202:205], v[170:173], v[100:103]
	v_mfma_f32_16x16x32_bf16 v[96:99], v[210:213], v[170:173], v[96:99]
	v_mfma_f32_16x16x32_bf16 v[84:87], v[202:205], v[180:183], v[84:87]
	v_mfma_f32_16x16x32_bf16 v[80:83], v[210:213], v[180:183], v[80:83]
	v_mfma_f32_16x16x32_bf16 v[68:71], v[202:205], v[194:197], v[68:71]
	v_mfma_f32_16x16x32_bf16 v[64:67], v[210:213], v[194:197], v[64:67]
	s_setprio 0
	s_mov_b32 m0, s7
	v_lshl_add_u64 v[218:219], s[26:27], 0, v[158:159]
	s_barrier
	ds_read_b128 v[144:147], v190 offset:16384
	ds_read_b128 v[148:151], v190 offset:17408
	ds_read_b128 v[166:169], v190 offset:18432
	ds_read_b128 v[170:173], v190 offset:19456
	ds_read_b128 v[174:177], v190 offset:20480
	ds_read_b128 v[180:183], v190 offset:21504
	ds_read_b128 v[184:187], v190 offset:22528
	ds_read_b128 v[194:197], v190 offset:23552
	global_load_lds_dwordx4 v[218:219], off
	v_lshl_add_u64 v[222:223], s[26:27], 0, v[154:155]
	s_mov_b32 m0, s35
	s_nop 0
	global_load_lds_dwordx4 v[222:223], off
	s_barrier
	s_waitcnt lgkmcnt(0)
	s_setprio 1
	s_waitcnt lgkmcnt(0)
	v_mfma_f32_16x16x32_bf16 v[60:63], v[128:131], v[144:147], v[60:63]
	v_mfma_f32_16x16x32_bf16 v[56:59], v[136:139], v[144:147], v[56:59]
	v_mfma_f32_16x16x32_bf16 v[44:47], v[128:131], v[166:169], v[44:47]
	v_mfma_f32_16x16x32_bf16 v[40:43], v[136:139], v[166:169], v[40:43]
	v_mfma_f32_16x16x32_bf16 v[28:31], v[128:131], v[174:177], v[28:31]
	v_mfma_f32_16x16x32_bf16 v[24:27], v[136:139], v[174:177], v[24:27]
	v_mfma_f32_16x16x32_bf16 v[12:15], v[128:131], v[184:187], v[12:15]
	v_mfma_f32_16x16x32_bf16 v[8:11], v[136:139], v[184:187], v[8:11]
	v_mfma_f32_16x16x32_bf16 v[60:63], v[132:135], v[148:151], v[60:63]
	v_mfma_f32_16x16x32_bf16 v[56:59], v[140:143], v[148:151], v[56:59]
	v_mfma_f32_16x16x32_bf16 v[44:47], v[132:135], v[170:173], v[44:47]
	v_mfma_f32_16x16x32_bf16 v[40:43], v[140:143], v[170:173], v[40:43]
	v_mfma_f32_16x16x32_bf16 v[28:31], v[132:135], v[180:183], v[28:31]
	v_mfma_f32_16x16x32_bf16 v[24:27], v[140:143], v[180:183], v[24:27]
	v_mfma_f32_16x16x32_bf16 v[12:15], v[132:135], v[194:197], v[12:15]
	v_mfma_f32_16x16x32_bf16 v[8:11], v[140:143], v[194:197], v[8:11]
	s_setprio 0
	s_barrier
	s_add_u32 s48, s24, 0x40000
	s_addc_u32 s49, s25, 0
	s_add_i32 s50, s42, s33
	v_lshl_add_u64 v[128:129], s[48:49], 0, v[156:157]
	s_mov_b32 m0, s50
	s_nop 0
	global_load_lds_dwordx4 v[128:129], off
	v_lshl_add_u64 v[128:129], s[48:49], 0, v[152:153]
	s_add_i32 m0, s50, 0x2000
	s_nop 0
	global_load_lds_dwordx4 v[128:129], off
	s_waitcnt vmcnt(6)
	s_barrier
	s_setprio 1
	v_mfma_f32_16x16x32_bf16 v[52:55], v[198:201], v[144:147], v[52:55]
	v_mfma_f32_16x16x32_bf16 v[48:51], v[206:209], v[144:147], v[48:51]
	v_mfma_f32_16x16x32_bf16 v[36:39], v[198:201], v[166:169], v[36:39]
	v_mfma_f32_16x16x32_bf16 v[32:35], v[206:209], v[166:169], v[32:35]
	v_mfma_f32_16x16x32_bf16 v[20:23], v[198:201], v[174:177], v[20:23]
	v_mfma_f32_16x16x32_bf16 v[16:19], v[206:209], v[174:177], v[16:19]
	v_mfma_f32_16x16x32_bf16 v[4:7], v[198:201], v[184:187], v[4:7]
	v_mfma_f32_16x16x32_bf16 v[0:3], v[206:209], v[184:187], v[0:3]
	v_mfma_f32_16x16x32_bf16 v[52:55], v[202:205], v[148:151], v[52:55]
	v_mfma_f32_16x16x32_bf16 v[48:51], v[210:213], v[148:151], v[48:51]
	v_mfma_f32_16x16x32_bf16 v[36:39], v[202:205], v[170:173], v[36:39]
	v_mfma_f32_16x16x32_bf16 v[32:35], v[210:213], v[170:173], v[32:35]
	v_mfma_f32_16x16x32_bf16 v[20:23], v[202:205], v[180:183], v[20:23]
	v_mfma_f32_16x16x32_bf16 v[16:19], v[210:213], v[180:183], v[16:19]
	v_mfma_f32_16x16x32_bf16 v[4:7], v[202:205], v[194:197], v[4:7]
	v_mfma_f32_16x16x32_bf16 v[0:3], v[210:213], v[194:197], v[0:3]
	s_setprio 0
	s_add_i32 s48, 0, 0x18000
	v_add_u32_e32 v140, s48, v188
	s_barrier
	ds_read_b128 v[128:131], v140
	ds_read_b128 v[132:135], v140 offset:1024
	ds_read_b128 v[136:139], v140 offset:2048
	ds_read_b128 v[140:143], v140 offset:3072
	s_add_u32 s26, s26, 0x40000
	s_addc_u32 s27, s27, 0
	s_mov_b32 m0, s36
	v_lshl_add_u64 v[198:199], s[26:27], 0, v[158:159]
	ds_read_b128 v[144:147], v190 offset:32768
	ds_read_b128 v[148:151], v190 offset:33792
	ds_read_b128 v[166:169], v190 offset:34816
	ds_read_b128 v[170:173], v190 offset:35840
	ds_read_b128 v[174:177], v190 offset:36864
	ds_read_b128 v[180:183], v190 offset:37888
	ds_read_b128 v[184:187], v190 offset:38912
	ds_read_b128 v[194:197], v190 offset:39936
	global_load_lds_dwordx4 v[198:199], off
	v_lshl_add_u64 v[198:199], s[26:27], 0, v[154:155]
	s_mov_b32 m0, s37
	s_nop 0
	global_load_lds_dwordx4 v[198:199], off
	s_waitcnt lgkmcnt(8)
	s_barrier
	s_waitcnt lgkmcnt(0)
	s_setprio 1
	s_waitcnt lgkmcnt(0)
	v_mfma_f32_16x16x32_bf16 v[124:127], v[128:131], v[144:147], v[124:127]
	v_mfma_f32_16x16x32_bf16 v[120:123], v[136:139], v[144:147], v[120:123]
	v_mfma_f32_16x16x32_bf16 v[108:111], v[128:131], v[166:169], v[108:111]
	v_mfma_f32_16x16x32_bf16 v[104:107], v[136:139], v[166:169], v[104:107]
	v_mfma_f32_16x16x32_bf16 v[92:95], v[128:131], v[174:177], v[92:95]
	v_mfma_f32_16x16x32_bf16 v[88:91], v[136:139], v[174:177], v[88:91]
	v_mfma_f32_16x16x32_bf16 v[76:79], v[128:131], v[184:187], v[76:79]
	v_mfma_f32_16x16x32_bf16 v[72:75], v[136:139], v[184:187], v[72:75]
	v_mfma_f32_16x16x32_bf16 v[124:127], v[132:135], v[148:151], v[124:127]
	v_mfma_f32_16x16x32_bf16 v[120:123], v[140:143], v[148:151], v[120:123]
	v_mfma_f32_16x16x32_bf16 v[108:111], v[132:135], v[170:173], v[108:111]
	v_mfma_f32_16x16x32_bf16 v[104:107], v[140:143], v[170:173], v[104:107]
	v_mfma_f32_16x16x32_bf16 v[92:95], v[132:135], v[180:183], v[92:95]
	v_mfma_f32_16x16x32_bf16 v[88:91], v[140:143], v[180:183], v[88:91]
	v_mfma_f32_16x16x32_bf16 v[76:79], v[132:135], v[194:197], v[76:79]
	v_mfma_f32_16x16x32_bf16 v[72:75], v[140:143], v[194:197], v[72:75]
	s_setprio 0
	s_barrier
	s_add_i32 s26, 0, 0x1c000
	s_add_i32 s27, s48, s33
	v_add_u32_e32 v193, s26, v188
	v_lshl_add_u64 v[214:215], v[214:215], 0, s[12:13]
	s_mov_b32 m0, s27
	ds_read_b128 v[198:201], v193
	ds_read_b128 v[202:205], v193 offset:1024
	ds_read_b128 v[206:209], v193 offset:2048
	ds_read_b128 v[210:213], v193 offset:3072
	global_load_lds_dwordx4 v[214:215], off
	v_lshl_add_u64 v[214:215], v[216:217], 0, s[12:13]
	s_add_i32 m0, s27, 0x2000
	s_nop 0
	global_load_lds_dwordx4 v[214:215], off
	s_barrier
	s_waitcnt lgkmcnt(0)
	s_setprio 1
	s_waitcnt lgkmcnt(0)
	v_mfma_f32_16x16x32_bf16 v[116:119], v[198:201], v[144:147], v[116:119]
	v_mfma_f32_16x16x32_bf16 v[112:115], v[206:209], v[144:147], v[112:115]
	v_mfma_f32_16x16x32_bf16 v[100:103], v[198:201], v[166:169], v[100:103]
	v_mfma_f32_16x16x32_bf16 v[96:99], v[206:209], v[166:169], v[96:99]
	v_mfma_f32_16x16x32_bf16 v[84:87], v[198:201], v[174:177], v[84:87]
	v_mfma_f32_16x16x32_bf16 v[80:83], v[206:209], v[174:177], v[80:83]
	v_mfma_f32_16x16x32_bf16 v[68:71], v[198:201], v[184:187], v[68:71]
	v_mfma_f32_16x16x32_bf16 v[64:67], v[206:209], v[184:187], v[64:67]
	v_mfma_f32_16x16x32_bf16 v[116:119], v[202:205], v[148:151], v[116:119]
	v_mfma_f32_16x16x32_bf16 v[112:115], v[210:213], v[148:151], v[112:115]
	v_mfma_f32_16x16x32_bf16 v[100:103], v[202:205], v[170:173], v[100:103]
	v_mfma_f32_16x16x32_bf16 v[96:99], v[210:213], v[170:173], v[96:99]
	v_mfma_f32_16x16x32_bf16 v[84:87], v[202:205], v[180:183], v[84:87]
	v_mfma_f32_16x16x32_bf16 v[80:83], v[210:213], v[180:183], v[80:83]
	v_mfma_f32_16x16x32_bf16 v[68:71], v[202:205], v[194:197], v[68:71]
	v_mfma_f32_16x16x32_bf16 v[64:67], v[210:213], v[194:197], v[64:67]
	s_setprio 0
	s_mov_b32 m0, s39
	v_lshl_add_u64 v[214:215], v[218:219], 0, s[12:13]
	s_barrier
	ds_read_b128 v[144:147], v190 offset:49152
	ds_read_b128 v[148:151], v190 offset:50176
	ds_read_b128 v[166:169], v190 offset:51200
	ds_read_b128 v[170:173], v190 offset:52224
	ds_read_b128 v[174:177], v190 offset:53248
	ds_read_b128 v[180:183], v190 offset:54272
	ds_read_b128 v[184:187], v190 offset:55296
	ds_read_b128 v[194:197], v190 offset:56320
	global_load_lds_dwordx4 v[214:215], off
	v_lshl_add_u64 v[214:215], v[222:223], 0, s[12:13]
	s_mov_b32 m0, s40
	s_nop 0
	global_load_lds_dwordx4 v[214:215], off
	s_barrier
	s_waitcnt lgkmcnt(0)
	s_setprio 1
	s_waitcnt lgkmcnt(0)
	v_mfma_f32_16x16x32_bf16 v[60:63], v[128:131], v[144:147], v[60:63]
	v_mfma_f32_16x16x32_bf16 v[56:59], v[136:139], v[144:147], v[56:59]
	v_mfma_f32_16x16x32_bf16 v[44:47], v[128:131], v[166:169], v[44:47]
	v_mfma_f32_16x16x32_bf16 v[40:43], v[136:139], v[166:169], v[40:43]
	v_mfma_f32_16x16x32_bf16 v[28:31], v[128:131], v[174:177], v[28:31]
	v_mfma_f32_16x16x32_bf16 v[24:27], v[136:139], v[174:177], v[24:27]
	v_mfma_f32_16x16x32_bf16 v[12:15], v[128:131], v[184:187], v[12:15]
	v_mfma_f32_16x16x32_bf16 v[8:11], v[136:139], v[184:187], v[8:11]
	v_mfma_f32_16x16x32_bf16 v[60:63], v[132:135], v[148:151], v[60:63]
	v_mfma_f32_16x16x32_bf16 v[56:59], v[140:143], v[148:151], v[56:59]
	v_mfma_f32_16x16x32_bf16 v[44:47], v[132:135], v[170:173], v[44:47]
	v_mfma_f32_16x16x32_bf16 v[40:43], v[140:143], v[170:173], v[40:43]
	v_mfma_f32_16x16x32_bf16 v[28:31], v[132:135], v[180:183], v[28:31]
	v_mfma_f32_16x16x32_bf16 v[24:27], v[140:143], v[180:183], v[24:27]
	v_mfma_f32_16x16x32_bf16 v[12:15], v[132:135], v[194:197], v[12:15]
	v_mfma_f32_16x16x32_bf16 v[8:11], v[140:143], v[194:197], v[8:11]
	s_setprio 0
	s_barrier
	s_add_u32 s24, s24, 0x40080
	s_addc_u32 s25, s25, 0
	s_add_i32 s26, s26, s33
	v_lshl_add_u64 v[128:129], s[24:25], 0, v[156:157]
	s_mov_b32 m0, s26
	s_nop 0
	global_load_lds_dwordx4 v[128:129], off
	v_lshl_add_u64 v[128:129], s[24:25], 0, v[152:153]
	s_add_i32 m0, s26, 0x2000
	s_nop 0
	global_load_lds_dwordx4 v[128:129], off
	s_waitcnt vmcnt(6)
	s_barrier
	s_setprio 1
	v_mfma_f32_16x16x32_bf16 v[52:55], v[198:201], v[144:147], v[52:55]
	v_mfma_f32_16x16x32_bf16 v[48:51], v[206:209], v[144:147], v[48:51]
	v_mfma_f32_16x16x32_bf16 v[36:39], v[198:201], v[166:169], v[36:39]
	v_mfma_f32_16x16x32_bf16 v[32:35], v[206:209], v[166:169], v[32:35]
	v_mfma_f32_16x16x32_bf16 v[20:23], v[198:201], v[174:177], v[20:23]
	v_mfma_f32_16x16x32_bf16 v[16:19], v[206:209], v[174:177], v[16:19]
	v_mfma_f32_16x16x32_bf16 v[4:7], v[198:201], v[184:187], v[4:7]
	v_mfma_f32_16x16x32_bf16 v[0:3], v[206:209], v[184:187], v[0:3]
	v_mfma_f32_16x16x32_bf16 v[52:55], v[202:205], v[148:151], v[52:55]
	v_mfma_f32_16x16x32_bf16 v[48:51], v[210:213], v[148:151], v[48:51]
	v_mfma_f32_16x16x32_bf16 v[36:39], v[202:205], v[170:173], v[36:39]
	v_mfma_f32_16x16x32_bf16 v[32:35], v[210:213], v[170:173], v[32:35]
	v_mfma_f32_16x16x32_bf16 v[20:23], v[202:205], v[180:183], v[20:23]
	v_mfma_f32_16x16x32_bf16 v[16:19], v[210:213], v[180:183], v[16:19]
	v_mfma_f32_16x16x32_bf16 v[4:7], v[202:205], v[194:197], v[4:7]
	v_mfma_f32_16x16x32_bf16 v[0:3], v[210:213], v[194:197], v[0:3]
	s_setprio 0
	s_add_i32 s47, s47, 2
	s_add_u32 s10, s10, 0x100
	s_addc_u32 s11, s11, 0
	s_add_u32 s45, s45, 0x100
	s_addc_u32 s46, s46, 0
	s_cmp_gt_u32 s47, 13
	s_barrier
	s_cbranch_scc0 .LBB0_1356
	s_lshl_b32 s24, s4, 8
	s_ashr_i32 s25, s24, 31
	s_lshl_b32 s10, s4, 2
	s_nop 0
	v_lshl_add_u32 v166, s28, 8, v179
	s_ashr_i32 s11, s10, 31
	s_lshl_b64 s[28:29], s[24:25], 1
	v_readlane_b32 s50, v253, 40
	v_readlane_b32 s51, v253, 41
	s_add_u32 s26, s50, s28
	v_ashrrev_i32_e32 v167, 31, v166
	s_addc_u32 s27, s51, s29
	v_lshlrev_b64 v[204:205], 11, v[166:167]
	v_lshl_add_u64 v[128:129], s[26:27], 0, v[204:205]
	v_lshl_add_u64 v[206:207], v[128:129], 0, v[160:161]
	global_load_dwordx4 v[196:199], v[206:207], off
	global_load_dwordx4 v[200:203], v[206:207], off offset:256
	v_or_b32_e32 v182, 16, v166
	v_or_b32_e32 v174, 32, v166
	v_or_b32_e32 v168, 48, v166
	v_ashrrev_i32_e32 v183, 31, v182
	v_ashrrev_i32_e32 v175, 31, v174
	v_ashrrev_i32_e32 v169, 31, v168
	v_lshlrev_b64 v[186:187], 11, v[182:183]
	v_lshlrev_b64 v[180:181], 11, v[174:175]
	v_lshlrev_b64 v[172:173], 11, v[168:169]
	v_lshl_add_u64 v[128:129], s[26:27], 0, v[186:187]
	v_lshl_add_u64 v[130:131], s[26:27], 0, v[180:181]
	v_lshl_add_u64 v[132:133], s[26:27], 0, v[172:173]
	v_lshl_add_u64 v[184:185], v[128:129], 0, v[160:161]
	v_lshl_add_u64 v[176:177], v[130:131], 0, v[160:161]
	v_lshl_add_u64 v[170:171], v[132:133], 0, v[160:161]
	global_load_dwordx4 v[148:151], v[184:185], off
	global_load_dwordx4 v[144:147], v[184:185], off offset:256
	global_load_dwordx4 v[140:143], v[176:177], off
	global_load_dwordx4 v[136:139], v[176:177], off offset:256
	global_load_dwordx4 v[132:135], v[170:171], off
	global_load_dwordx4 v[128:131], v[170:171], off offset:256
	v_and_b32_e32 v194, 64, v192
	v_xor_b32_e32 v193, 16, v192
	v_add_u32_e32 v194, 64, v194
	v_cmp_lt_i32_e32 vcc, v193, v194
	v_xor_b32_e32 v195, 32, v192
	v_lshl_add_u64 v[204:205], s[50:51], 0, v[204:205]
	v_cndmask_b32_e32 v193, v192, v193, vcc
	v_cmp_lt_i32_e32 vcc, v195, v194
	v_lshlrev_b32_e32 v194, 2, v193
	s_nop 0
	v_cndmask_b32_e32 v195, v192, v195, vcc
	v_lshlrev_b32_e32 v193, 2, v195
	s_nop 7
	s_nop 3
	s_waitcnt vmcnt(0)
	v_lshlrev_b32_e32 v210, 16, v198
	v_and_b32_e32 v211, 0xffff0000, v198
	v_lshlrev_b32_e32 v208, 16, v196
	v_and_b32_e32 v209, 0xffff0000, v196
	v_lshlrev_b32_e32 v198, 16, v199
	v_and_b32_e32 v199, 0xffff0000, v199
	v_lshlrev_b32_e32 v214, 16, v202
	v_and_b32_e32 v215, 0xffff0000, v202
	v_lshlrev_b32_e32 v202, 16, v203
	v_and_b32_e32 v203, 0xffff0000, v203
	v_pk_add_f32 v[120:121], v[120:121], v[210:211]
	v_lshlrev_b32_e32 v196, 16, v197
	v_and_b32_e32 v197, 0xffff0000, v197
	v_pk_add_f32 v[124:125], v[124:125], v[208:209]
	v_pk_add_f32 v[122:123], v[122:123], v[198:199]
	v_pk_add_f32 v[198:199], v[114:115], v[202:203]
	v_cvt_pk_bf16_f32 v114, v120, v121
	v_pk_mul_f32 v[120:121], v[120:121], v[120:121]
	v_pk_add_f32 v[126:127], v[126:127], v[196:197]
	v_cvt_pk_bf16_f32 v115, v122, v123
	v_pk_mul_f32 v[122:123], v[122:123], v[122:123]
	v_pk_fma_f32 v[120:121], v[124:125], v[124:125], v[120:121]
	v_lshlrev_b32_e32 v212, 16, v200
	v_and_b32_e32 v213, 0xffff0000, v200
	v_lshlrev_b32_e32 v200, 16, v201
	v_and_b32_e32 v201, 0xffff0000, v201
	v_pk_add_f32 v[196:197], v[112:113], v[214:215]
	v_pk_fma_f32 v[122:123], v[126:127], v[126:127], v[122:123]
	v_add_f32_e32 v120, v120, v121
	v_pk_add_f32 v[116:117], v[116:117], v[212:213]
	v_pk_add_f32 v[118:119], v[118:119], v[200:201]
	v_pk_mul_f32 v[200:201], v[196:197], v[196:197]
	v_add_f32_e32 v120, v122, v120
	v_cvt_pk_bf16_f32 v112, v124, v125
	v_pk_fma_f32 v[124:125], v[116:117], v[116:117], v[200:201]
	v_add_f32_e32 v120, v123, v120
	v_pk_mul_f32 v[202:203], v[198:199], v[198:199]
	v_add_f32_e32 v120, v124, v120
	v_cvt_pk_bf16_f32 v113, v126, v127
	v_pk_fma_f32 v[126:127], v[118:119], v[118:119], v[202:203]
	v_add_f32_e32 v120, v125, v120
	v_add_f32_e32 v120, v126, v120
	v_add_f32_e32 v122, v127, v120
	ds_bpermute_b32 v123, v194, v122
	global_store_dwordx4 v[206:207], v[112:115], off
	v_lshl_add_u64 v[120:121], v[204:205], 0, s[28:29]
	s_nop 0
	v_cvt_pk_bf16_f32 v114, v116, v117
	s_waitcnt lgkmcnt(0)
	v_add_f32_e32 v112, v122, v123
	ds_bpermute_b32 v113, v193, v112
	v_cvt_pk_bf16_f32 v115, v118, v119
	v_cvt_pk_bf16_f32 v116, v196, v197
	v_cvt_pk_bf16_f32 v117, v198, v199
	v_lshl_add_u64 v[118:119], v[120:121], 0, v[160:161]
	global_store_dwordx4 v[118:119], v[114:117], off offset:256
	s_and_saveexec_b64 s[28:29], s[0:1]
	s_cbranch_execz .LBB0_1359
	s_waitcnt lgkmcnt(0)
	v_add_f32_e32 v114, v112, v113
	v_lshlrev_b64 v[112:113], 6, v[166:167]
	v_lshl_add_u64 v[112:113], s[86:87], 0, v[112:113]
	v_lshl_add_u64 v[112:113], s[10:11], 2, v[112:113]
	s_lshl_b32 s4, s38, 2
	v_lshl_add_u64 v[112:113], v[112:113], 0, s[4:5]
	global_store_dword v[112:113], v114, off
.LBB0_1359:
	s_or_b64 exec, exec, s[28:29]
	v_lshlrev_b32_e32 v112, 16, v148
	s_waitcnt lgkmcnt(0)
	v_and_b32_e32 v113, 0xffff0000, v148
	v_pk_add_f32 v[108:109], v[108:109], v[112:113]
	v_lshlrev_b32_e32 v112, 16, v149
	v_and_b32_e32 v113, 0xffff0000, v149
	v_pk_add_f32 v[110:111], v[110:111], v[112:113]
	v_lshlrev_b32_e32 v112, 16, v150
	v_and_b32_e32 v113, 0xffff0000, v150
	v_pk_add_f32 v[112:113], v[104:105], v[112:113]
	v_lshlrev_b32_e32 v104, 16, v151
	v_and_b32_e32 v105, 0xffff0000, v151
	v_pk_add_f32 v[114:115], v[106:107], v[104:105]
	v_cvt_pk_bf16_f32 v106, v112, v113
	v_pk_mul_f32 v[112:113], v[112:113], v[112:113]
	v_cvt_pk_bf16_f32 v104, v108, v109
	v_pk_fma_f32 v[108:109], v[108:109], v[108:109], v[112:113]
	v_pk_mul_f32 v[112:113], v[114:115], v[114:115]
	v_cvt_pk_bf16_f32 v105, v110, v111
	v_pk_fma_f32 v[110:111], v[110:111], v[110:111], v[112:113]
	v_lshlrev_b32_e32 v112, 16, v144
	v_and_b32_e32 v113, 0xffff0000, v144
	v_pk_add_f32 v[100:101], v[100:101], v[112:113]
	v_lshlrev_b32_e32 v112, 16, v145
	v_and_b32_e32 v113, 0xffff0000, v145
	v_pk_add_f32 v[102:103], v[102:103], v[112:113]
	v_lshlrev_b32_e32 v112, 16, v146
	v_and_b32_e32 v113, 0xffff0000, v146
	v_pk_add_f32 v[112:113], v[96:97], v[112:113]
	v_lshlrev_b32_e32 v96, 16, v147
	v_and_b32_e32 v97, 0xffff0000, v147
	v_add_f32_e32 v108, v108, v109
	v_cvt_pk_bf16_f32 v107, v114, v115
	v_pk_add_f32 v[114:115], v[98:99], v[96:97]
	v_pk_mul_f32 v[96:97], v[112:113], v[112:113]
	v_add_f32_e32 v108, v110, v108
	v_pk_fma_f32 v[96:97], v[100:101], v[100:101], v[96:97]
	v_add_f32_e32 v108, v111, v108
	v_pk_mul_f32 v[98:99], v[114:115], v[114:115]
	v_add_f32_e32 v96, v96, v108
	v_pk_fma_f32 v[98:99], v[102:103], v[102:103], v[98:99]
	v_add_f32_e32 v96, v97, v96
	v_add_f32_e32 v96, v98, v96
	v_add_f32_e32 v96, v99, v96
	ds_bpermute_b32 v97, v194, v96
	s_nop 0
	v_readlane_b32 s50, v253, 40
	v_readlane_b32 s51, v253, 41
	v_cvt_pk_bf16_f32 v98, v100, v101
	s_waitcnt lgkmcnt(0)
	v_add_f32_e32 v96, v96, v97
	ds_bpermute_b32 v97, v193, v96
	v_lshl_add_u64 v[116:117], s[50:51], 0, v[186:187]
	v_lshl_add_u64 v[108:109], s[24:25], 1, v[116:117]
	v_cvt_pk_bf16_f32 v99, v102, v103
	v_cvt_pk_bf16_f32 v100, v112, v113
	v_cvt_pk_bf16_f32 v101, v114, v115
	v_lshl_add_u64 v[102:103], v[108:109], 0, v[160:161]
	s_nop 7
	s_nop 4
	global_store_dwordx4 v[184:185], v[104:107], off
	global_store_dwordx4 v[102:103], v[98:101], off offset:256
	s_and_saveexec_b64 s[28:29], s[0:1]
	s_cbranch_execz .LBB0_1361
	s_waitcnt lgkmcnt(0)
	v_add_f32_e32 v98, v96, v97
	v_lshlrev_b64 v[96:97], 6, v[182:183]
	v_lshl_add_u64 v[96:97], s[86:87], 0, v[96:97]
	v_lshl_add_u64 v[96:97], s[10:11], 2, v[96:97]
	s_lshl_b32 s4, s38, 2
	v_lshl_add_u64 v[96:97], v[96:97], 0, s[4:5]
	global_store_dword v[96:97], v98, off
.LBB0_1361:
	s_or_b64 exec, exec, s[28:29]
	v_lshlrev_b32_e32 v96, 16, v140
	s_waitcnt lgkmcnt(0)
	v_and_b32_e32 v97, 0xffff0000, v140
	v_pk_add_f32 v[92:93], v[92:93], v[96:97]
	v_lshlrev_b32_e32 v96, 16, v141
	v_and_b32_e32 v97, 0xffff0000, v141
	v_pk_add_f32 v[94:95], v[94:95], v[96:97]
	v_lshlrev_b32_e32 v96, 16, v142
	v_and_b32_e32 v97, 0xffff0000, v142
	v_pk_add_f32 v[96:97], v[88:89], v[96:97]
	v_lshlrev_b32_e32 v88, 16, v143
	v_and_b32_e32 v89, 0xffff0000, v143
	v_pk_add_f32 v[98:99], v[90:91], v[88:89]
	v_cvt_pk_bf16_f32 v90, v96, v97
	v_pk_mul_f32 v[96:97], v[96:97], v[96:97]
	v_cvt_pk_bf16_f32 v88, v92, v93
	v_pk_fma_f32 v[92:93], v[92:93], v[92:93], v[96:97]
	v_pk_mul_f32 v[96:97], v[98:99], v[98:99]
	v_cvt_pk_bf16_f32 v89, v94, v95
	v_pk_fma_f32 v[94:95], v[94:95], v[94:95], v[96:97]
	v_lshlrev_b32_e32 v96, 16, v136
	v_and_b32_e32 v97, 0xffff0000, v136
	v_pk_add_f32 v[84:85], v[84:85], v[96:97]
	v_lshlrev_b32_e32 v96, 16, v137
	v_and_b32_e32 v97, 0xffff0000, v137
	v_pk_add_f32 v[86:87], v[86:87], v[96:97]
	v_lshlrev_b32_e32 v96, 16, v138
	v_and_b32_e32 v97, 0xffff0000, v138
	v_pk_add_f32 v[96:97], v[80:81], v[96:97]
	v_lshlrev_b32_e32 v80, 16, v139
	v_and_b32_e32 v81, 0xffff0000, v139
	v_add_f32_e32 v92, v92, v93
	v_cvt_pk_bf16_f32 v91, v98, v99
	v_pk_add_f32 v[98:99], v[82:83], v[80:81]
	v_pk_mul_f32 v[80:81], v[96:97], v[96:97]
	v_add_f32_e32 v92, v94, v92
	v_pk_fma_f32 v[80:81], v[84:85], v[84:85], v[80:81]
	v_add_f32_e32 v92, v95, v92
	v_pk_mul_f32 v[82:83], v[98:99], v[98:99]
	v_add_f32_e32 v80, v80, v92
	v_pk_fma_f32 v[82:83], v[86:87], v[86:87], v[82:83]
	v_add_f32_e32 v80, v81, v80
	v_add_f32_e32 v80, v82, v80
	v_add_f32_e32 v80, v83, v80
	ds_bpermute_b32 v81, v194, v80
	s_nop 0
	v_readlane_b32 s50, v253, 40
	v_readlane_b32 s51, v253, 41
	v_cvt_pk_bf16_f32 v82, v84, v85
	s_waitcnt lgkmcnt(0)
	v_add_f32_e32 v80, v80, v81
	ds_bpermute_b32 v81, v193, v80
	v_lshl_add_u64 v[100:101], s[50:51], 0, v[180:181]
	v_lshl_add_u64 v[92:93], s[24:25], 1, v[100:101]
	v_cvt_pk_bf16_f32 v83, v86, v87
	v_cvt_pk_bf16_f32 v84, v96, v97
	v_cvt_pk_bf16_f32 v85, v98, v99
	v_lshl_add_u64 v[86:87], v[92:93], 0, v[160:161]
	s_nop 7
	s_nop 4
	global_store_dwordx4 v[176:177], v[88:91], off
	global_store_dwordx4 v[86:87], v[82:85], off offset:256
	s_and_saveexec_b64 s[28:29], s[0:1]
	s_cbranch_execz .LBB0_1363
	s_waitcnt lgkmcnt(0)
	v_add_f32_e32 v82, v80, v81
	v_lshlrev_b64 v[80:81], 6, v[174:175]
	v_lshl_add_u64 v[80:81], s[86:87], 0, v[80:81]
	v_lshl_add_u64 v[80:81], s[10:11], 2, v[80:81]
	s_lshl_b32 s4, s38, 2
	v_lshl_add_u64 v[80:81], v[80:81], 0, s[4:5]
	global_store_dword v[80:81], v82, off
.LBB0_1363:
	s_or_b64 exec, exec, s[28:29]
	v_lshlrev_b32_e32 v80, 16, v132
	s_waitcnt lgkmcnt(0)
	v_and_b32_e32 v81, 0xffff0000, v132
	v_pk_add_f32 v[76:77], v[76:77], v[80:81]
	v_lshlrev_b32_e32 v80, 16, v133
	v_and_b32_e32 v81, 0xffff0000, v133
	v_pk_add_f32 v[78:79], v[78:79], v[80:81]
	v_lshlrev_b32_e32 v80, 16, v134
	v_and_b32_e32 v81, 0xffff0000, v134
	v_pk_add_f32 v[80:81], v[72:73], v[80:81]
	v_lshlrev_b32_e32 v72, 16, v135
	v_and_b32_e32 v73, 0xffff0000, v135
	v_pk_add_f32 v[82:83], v[74:75], v[72:73]
	v_cvt_pk_bf16_f32 v74, v80, v81
	v_pk_mul_f32 v[80:81], v[80:81], v[80:81]
	v_cvt_pk_bf16_f32 v72, v76, v77
	v_pk_fma_f32 v[76:77], v[76:77], v[76:77], v[80:81]
	v_pk_mul_f32 v[80:81], v[82:83], v[82:83]
	v_cvt_pk_bf16_f32 v73, v78, v79
	v_pk_fma_f32 v[78:79], v[78:79], v[78:79], v[80:81]
	v_lshlrev_b32_e32 v80, 16, v128
	v_and_b32_e32 v81, 0xffff0000, v128
	v_pk_add_f32 v[68:69], v[68:69], v[80:81]
	v_lshlrev_b32_e32 v80, 16, v129
	v_and_b32_e32 v81, 0xffff0000, v129
	v_pk_add_f32 v[70:71], v[70:71], v[80:81]
	v_lshlrev_b32_e32 v80, 16, v130
	v_and_b32_e32 v81, 0xffff0000, v130
	v_pk_add_f32 v[80:81], v[64:65], v[80:81]
	v_lshlrev_b32_e32 v64, 16, v131
	v_and_b32_e32 v65, 0xffff0000, v131
	v_add_f32_e32 v76, v76, v77
	v_cvt_pk_bf16_f32 v75, v82, v83
	v_pk_add_f32 v[82:83], v[66:67], v[64:65]
	v_pk_mul_f32 v[64:65], v[80:81], v[80:81]
	v_add_f32_e32 v76, v78, v76
	v_pk_fma_f32 v[64:65], v[68:69], v[68:69], v[64:65]
	v_add_f32_e32 v76, v79, v76
	v_pk_mul_f32 v[66:67], v[82:83], v[82:83]
	v_add_f32_e32 v64, v64, v76
	v_pk_fma_f32 v[66:67], v[70:71], v[70:71], v[66:67]
	v_add_f32_e32 v64, v65, v64
	v_add_f32_e32 v64, v66, v64
	v_add_f32_e32 v64, v67, v64
	ds_bpermute_b32 v65, v194, v64
	s_nop 0
	v_readlane_b32 s50, v253, 40
	v_readlane_b32 s51, v253, 41
	v_cvt_pk_bf16_f32 v66, v68, v69
	s_waitcnt lgkmcnt(0)
	v_add_f32_e32 v64, v64, v65
	ds_bpermute_b32 v65, v193, v64
	v_lshl_add_u64 v[84:85], s[50:51], 0, v[172:173]
	v_lshl_add_u64 v[76:77], s[24:25], 1, v[84:85]
	v_cvt_pk_bf16_f32 v67, v70, v71
	v_cvt_pk_bf16_f32 v68, v80, v81
	v_cvt_pk_bf16_f32 v69, v82, v83
	v_lshl_add_u64 v[70:71], v[76:77], 0, v[160:161]
	s_nop 7
	s_nop 4
	global_store_dwordx4 v[170:171], v[72:75], off
	global_store_dwordx4 v[70:71], v[66:69], off offset:256
	s_and_saveexec_b64 s[28:29], s[0:1]
	s_cbranch_execz .LBB0_1365
	s_waitcnt lgkmcnt(0)
	v_add_f32_e32 v66, v64, v65
	v_lshlrev_b64 v[64:65], 6, v[168:169]
	v_lshl_add_u64 v[64:65], s[86:87], 0, v[64:65]
	v_lshl_add_u64 v[64:65], s[10:11], 2, v[64:65]
	s_lshl_b32 s4, s38, 2
	v_lshl_add_u64 v[64:65], v[64:65], 0, s[4:5]
	global_store_dword v[64:65], v66, off
.LBB0_1365:
	s_or_b64 exec, exec, s[28:29]
	v_add_u32_e32 v106, 0x80, v166
	v_ashrrev_i32_e32 v107, 31, v106
	v_lshlrev_b64 v[116:117], 11, v[106:107]
	s_waitcnt lgkmcnt(0)
	v_lshl_add_u64 v[64:65], s[26:27], 0, v[116:117]
	v_lshl_add_u64 v[118:119], v[64:65], 0, v[160:161]
	global_load_dwordx4 v[108:111], v[118:119], off
	global_load_dwordx4 v[112:115], v[118:119], off offset:256
	v_add_u32_e32 v100, 0x90, v166
	v_add_u32_e32 v94, 0xa0, v166
	v_add_u32_e32 v88, 0xb0, v166
	v_ashrrev_i32_e32 v101, 31, v100
	v_ashrrev_i32_e32 v95, 31, v94
	v_ashrrev_i32_e32 v89, 31, v88
	v_lshlrev_b64 v[104:105], 11, v[100:101]
	v_lshlrev_b64 v[98:99], 11, v[94:95]
	v_lshlrev_b64 v[92:93], 11, v[88:89]
	v_lshl_add_u64 v[64:65], s[26:27], 0, v[104:105]
	v_lshl_add_u64 v[66:67], s[26:27], 0, v[98:99]
	v_lshl_add_u64 v[68:69], s[26:27], 0, v[92:93]
	v_lshl_add_u64 v[102:103], v[64:65], 0, v[160:161]
	v_lshl_add_u64 v[96:97], v[66:67], 0, v[160:161]
	v_lshl_add_u64 v[90:91], v[68:69], 0, v[160:161]
	global_load_dwordx4 v[84:87], v[102:103], off
	global_load_dwordx4 v[80:83], v[102:103], off offset:256
	global_load_dwordx4 v[76:79], v[96:97], off
	global_load_dwordx4 v[72:75], v[96:97], off offset:256
	global_load_dwordx4 v[68:71], v[90:91], off
	global_load_dwordx4 v[64:67], v[90:91], off offset:256
	s_nop 0
	v_readlane_b32 s50, v253, 40
	v_readlane_b32 s51, v253, 41
	s_nop 1
	v_lshl_add_u64 v[116:117], s[50:51], 0, v[116:117]
	s_nop 7
	s_nop 2
	s_waitcnt vmcnt(7)
	v_lshlrev_b32_e32 v122, 16, v110
	v_and_b32_e32 v123, 0xffff0000, v110
	v_lshlrev_b32_e32 v120, 16, v108
	v_and_b32_e32 v121, 0xffff0000, v108
	v_lshlrev_b32_e32 v110, 16, v111
	v_and_b32_e32 v111, 0xffff0000, v111
	s_waitcnt vmcnt(6)
	v_lshlrev_b32_e32 v126, 16, v114
	v_and_b32_e32 v127, 0xffff0000, v114
	v_lshlrev_b32_e32 v114, 16, v115
	v_and_b32_e32 v115, 0xffff0000, v115
	v_pk_add_f32 v[56:57], v[56:57], v[122:123]
	v_lshlrev_b32_e32 v108, 16, v109
	v_and_b32_e32 v109, 0xffff0000, v109
	v_pk_add_f32 v[60:61], v[60:61], v[120:121]
	v_pk_add_f32 v[58:59], v[58:59], v[110:111]
	v_pk_add_f32 v[110:111], v[50:51], v[114:115]
	v_cvt_pk_bf16_f32 v50, v56, v57
	v_pk_mul_f32 v[56:57], v[56:57], v[56:57]
	v_pk_add_f32 v[62:63], v[62:63], v[108:109]
	v_cvt_pk_bf16_f32 v51, v58, v59
	v_pk_mul_f32 v[58:59], v[58:59], v[58:59]
	v_pk_fma_f32 v[56:57], v[60:61], v[60:61], v[56:57]
	v_lshlrev_b32_e32 v124, 16, v112
	v_and_b32_e32 v125, 0xffff0000, v112
	v_lshlrev_b32_e32 v112, 16, v113
	v_and_b32_e32 v113, 0xffff0000, v113
	v_pk_add_f32 v[108:109], v[48:49], v[126:127]
	v_pk_fma_f32 v[58:59], v[62:63], v[62:63], v[58:59]
	v_add_f32_e32 v56, v56, v57
	v_pk_add_f32 v[52:53], v[52:53], v[124:125]
	v_pk_add_f32 v[54:55], v[54:55], v[112:113]
	v_pk_mul_f32 v[112:113], v[108:109], v[108:109]
	v_add_f32_e32 v56, v58, v56
	v_cvt_pk_bf16_f32 v48, v60, v61
	v_pk_fma_f32 v[60:61], v[52:53], v[52:53], v[112:113]
	v_add_f32_e32 v56, v59, v56
	v_pk_mul_f32 v[114:115], v[110:111], v[110:111]
	v_add_f32_e32 v56, v60, v56
	v_cvt_pk_bf16_f32 v49, v62, v63
	v_pk_fma_f32 v[62:63], v[54:55], v[54:55], v[114:115]
	v_add_f32_e32 v56, v61, v56
	v_add_f32_e32 v56, v62, v56
	v_add_f32_e32 v58, v63, v56
	ds_bpermute_b32 v59, v194, v58
	global_store_dwordx4 v[118:119], v[48:51], off
	v_lshl_add_u64 v[56:57], s[24:25], 1, v[116:117]
	s_nop 0
	v_cvt_pk_bf16_f32 v50, v52, v53
	s_waitcnt lgkmcnt(0)
	v_add_f32_e32 v48, v58, v59
	ds_bpermute_b32 v49, v193, v48
	v_cvt_pk_bf16_f32 v51, v54, v55
	v_cvt_pk_bf16_f32 v52, v108, v109
	v_cvt_pk_bf16_f32 v53, v110, v111
	v_lshl_add_u64 v[54:55], v[56:57], 0, v[160:161]
	global_store_dwordx4 v[54:55], v[50:53], off offset:256
	s_and_saveexec_b64 s[26:27], s[0:1]
	s_cbranch_execz .LBB0_1367
	s_waitcnt lgkmcnt(0)
	v_add_f32_e32 v50, v48, v49
	v_lshlrev_b64 v[48:49], 6, v[106:107]
	v_lshl_add_u64 v[48:49], s[86:87], 0, v[48:49]
	v_lshl_add_u64 v[48:49], s[10:11], 2, v[48:49]
	s_lshl_b32 s4, s38, 2
	v_lshl_add_u64 v[48:49], v[48:49], 0, s[4:5]
	global_store_dword v[48:49], v50, off
.LBB0_1367:
	s_or_b64 exec, exec, s[26:27]
	s_waitcnt vmcnt(7)
	v_lshlrev_b32_e32 v48, 16, v84
	s_waitcnt lgkmcnt(0)
	v_and_b32_e32 v49, 0xffff0000, v84
	v_pk_add_f32 v[44:45], v[44:45], v[48:49]
	v_lshlrev_b32_e32 v48, 16, v85
	v_and_b32_e32 v49, 0xffff0000, v85
	v_pk_add_f32 v[46:47], v[46:47], v[48:49]
	v_lshlrev_b32_e32 v48, 16, v86
	v_and_b32_e32 v49, 0xffff0000, v86
	v_pk_add_f32 v[48:49], v[40:41], v[48:49]
	v_lshlrev_b32_e32 v40, 16, v87
	v_and_b32_e32 v41, 0xffff0000, v87
	v_pk_add_f32 v[50:51], v[42:43], v[40:41]
	v_cvt_pk_bf16_f32 v42, v48, v49
	v_pk_mul_f32 v[48:49], v[48:49], v[48:49]
	v_cvt_pk_bf16_f32 v40, v44, v45
	v_pk_fma_f32 v[44:45], v[44:45], v[44:45], v[48:49]
	v_pk_mul_f32 v[48:49], v[50:51], v[50:51]
	v_cvt_pk_bf16_f32 v41, v46, v47
	v_pk_fma_f32 v[46:47], v[46:47], v[46:47], v[48:49]
	s_waitcnt vmcnt(6)
	v_lshlrev_b32_e32 v48, 16, v80
	v_and_b32_e32 v49, 0xffff0000, v80
	v_pk_add_f32 v[36:37], v[36:37], v[48:49]
	v_lshlrev_b32_e32 v48, 16, v81
	v_and_b32_e32 v49, 0xffff0000, v81
	v_pk_add_f32 v[38:39], v[38:39], v[48:49]
	v_lshlrev_b32_e32 v48, 16, v82
	v_and_b32_e32 v49, 0xffff0000, v82
	v_pk_add_f32 v[48:49], v[32:33], v[48:49]
	v_lshlrev_b32_e32 v32, 16, v83
	v_and_b32_e32 v33, 0xffff0000, v83
	v_add_f32_e32 v44, v44, v45
	v_cvt_pk_bf16_f32 v43, v50, v51
	v_pk_add_f32 v[50:51], v[34:35], v[32:33]
	v_pk_mul_f32 v[32:33], v[48:49], v[48:49]
	v_add_f32_e32 v44, v46, v44
	v_pk_fma_f32 v[32:33], v[36:37], v[36:37], v[32:33]
	v_add_f32_e32 v44, v47, v44
	v_pk_mul_f32 v[34:35], v[50:51], v[50:51]
	v_add_f32_e32 v32, v32, v44
	v_pk_fma_f32 v[34:35], v[38:39], v[38:39], v[34:35]
	v_add_f32_e32 v32, v33, v32
	v_add_f32_e32 v32, v34, v32
	v_add_f32_e32 v32, v35, v32
	ds_bpermute_b32 v33, v194, v32
	s_nop 0
	v_readlane_b32 s50, v253, 40
	v_readlane_b32 s51, v253, 41
	v_cvt_pk_bf16_f32 v34, v36, v37
	s_waitcnt lgkmcnt(0)
	v_add_f32_e32 v32, v32, v33
	ds_bpermute_b32 v33, v193, v32
	v_lshl_add_u64 v[52:53], s[50:51], 0, v[104:105]
	v_lshl_add_u64 v[44:45], s[24:25], 1, v[52:53]
	v_cvt_pk_bf16_f32 v35, v38, v39
	v_cvt_pk_bf16_f32 v36, v48, v49
	v_cvt_pk_bf16_f32 v37, v50, v51
	v_lshl_add_u64 v[38:39], v[44:45], 0, v[160:161]
	s_nop 7
	s_nop 4
	global_store_dwordx4 v[102:103], v[40:43], off
	global_store_dwordx4 v[38:39], v[34:37], off offset:256
	s_and_saveexec_b64 s[26:27], s[0:1]
	s_cbranch_execz .LBB0_1369
	s_waitcnt lgkmcnt(0)
	v_add_f32_e32 v34, v32, v33
	v_lshlrev_b64 v[32:33], 6, v[100:101]
	v_lshl_add_u64 v[32:33], s[86:87], 0, v[32:33]
	v_lshl_add_u64 v[32:33], s[10:11], 2, v[32:33]
	s_lshl_b32 s4, s38, 2
	v_lshl_add_u64 v[32:33], v[32:33], 0, s[4:5]
	global_store_dword v[32:33], v34, off
.LBB0_1369:
	s_or_b64 exec, exec, s[26:27]
	s_waitcnt vmcnt(7)
	v_lshlrev_b32_e32 v32, 16, v76
	s_waitcnt lgkmcnt(0)
	v_and_b32_e32 v33, 0xffff0000, v76
	v_pk_add_f32 v[28:29], v[28:29], v[32:33]
	v_lshlrev_b32_e32 v32, 16, v77
	v_and_b32_e32 v33, 0xffff0000, v77
	v_pk_add_f32 v[30:31], v[30:31], v[32:33]
	v_lshlrev_b32_e32 v32, 16, v78
	v_and_b32_e32 v33, 0xffff0000, v78
	v_pk_add_f32 v[32:33], v[24:25], v[32:33]
	v_lshlrev_b32_e32 v24, 16, v79
	v_and_b32_e32 v25, 0xffff0000, v79
	v_pk_add_f32 v[34:35], v[26:27], v[24:25]
	v_cvt_pk_bf16_f32 v26, v32, v33
	v_pk_mul_f32 v[32:33], v[32:33], v[32:33]
	v_cvt_pk_bf16_f32 v24, v28, v29
	v_pk_fma_f32 v[28:29], v[28:29], v[28:29], v[32:33]
	v_pk_mul_f32 v[32:33], v[34:35], v[34:35]
	v_cvt_pk_bf16_f32 v25, v30, v31
	v_pk_fma_f32 v[30:31], v[30:31], v[30:31], v[32:33]
	s_waitcnt vmcnt(6)
	v_lshlrev_b32_e32 v32, 16, v72
	v_and_b32_e32 v33, 0xffff0000, v72
	v_pk_add_f32 v[20:21], v[20:21], v[32:33]
	v_lshlrev_b32_e32 v32, 16, v73
	v_and_b32_e32 v33, 0xffff0000, v73
	v_pk_add_f32 v[22:23], v[22:23], v[32:33]
	v_lshlrev_b32_e32 v32, 16, v74
	v_and_b32_e32 v33, 0xffff0000, v74
	v_pk_add_f32 v[32:33], v[16:17], v[32:33]
	v_lshlrev_b32_e32 v16, 16, v75
	v_and_b32_e32 v17, 0xffff0000, v75
	v_add_f32_e32 v28, v28, v29
	v_cvt_pk_bf16_f32 v27, v34, v35
	v_pk_add_f32 v[34:35], v[18:19], v[16:17]
	v_pk_mul_f32 v[16:17], v[32:33], v[32:33]
	v_add_f32_e32 v28, v30, v28
	v_pk_fma_f32 v[16:17], v[20:21], v[20:21], v[16:17]
	v_add_f32_e32 v28, v31, v28
	v_pk_mul_f32 v[18:19], v[34:35], v[34:35]
	v_add_f32_e32 v16, v16, v28
	v_pk_fma_f32 v[18:19], v[22:23], v[22:23], v[18:19]
	v_add_f32_e32 v16, v17, v16
	v_add_f32_e32 v16, v18, v16
	v_add_f32_e32 v16, v19, v16
	ds_bpermute_b32 v17, v194, v16
	s_nop 0
	v_readlane_b32 s50, v253, 40
	v_readlane_b32 s51, v253, 41
	v_cvt_pk_bf16_f32 v18, v20, v21
	s_waitcnt lgkmcnt(0)
	v_add_f32_e32 v16, v16, v17
	ds_bpermute_b32 v17, v193, v16
	v_lshl_add_u64 v[36:37], s[50:51], 0, v[98:99]
	v_lshl_add_u64 v[28:29], s[24:25], 1, v[36:37]
	v_cvt_pk_bf16_f32 v19, v22, v23
	v_cvt_pk_bf16_f32 v20, v32, v33
	v_cvt_pk_bf16_f32 v21, v34, v35
	v_lshl_add_u64 v[22:23], v[28:29], 0, v[160:161]
	s_nop 7
	s_nop 4
	global_store_dwordx4 v[96:97], v[24:27], off
	global_store_dwordx4 v[22:23], v[18:21], off offset:256
	s_and_saveexec_b64 s[26:27], s[0:1]
	s_cbranch_execz .LBB0_1371
	s_waitcnt lgkmcnt(0)
	v_add_f32_e32 v18, v16, v17
	v_lshlrev_b64 v[16:17], 6, v[94:95]
	v_lshl_add_u64 v[16:17], s[86:87], 0, v[16:17]
	v_lshl_add_u64 v[16:17], s[10:11], 2, v[16:17]
	s_lshl_b32 s4, s38, 2
	v_lshl_add_u64 v[16:17], v[16:17], 0, s[4:5]
	global_store_dword v[16:17], v18, off
.LBB0_1371:
	s_or_b64 exec, exec, s[26:27]
	s_waitcnt vmcnt(7)
	v_lshlrev_b32_e32 v16, 16, v68
	s_waitcnt lgkmcnt(0)
	v_and_b32_e32 v17, 0xffff0000, v68
	v_pk_add_f32 v[12:13], v[12:13], v[16:17]
	v_lshlrev_b32_e32 v16, 16, v69
	v_and_b32_e32 v17, 0xffff0000, v69
	v_pk_add_f32 v[14:15], v[14:15], v[16:17]
	v_lshlrev_b32_e32 v16, 16, v70
	v_and_b32_e32 v17, 0xffff0000, v70
	v_pk_add_f32 v[16:17], v[8:9], v[16:17]
	v_lshlrev_b32_e32 v8, 16, v71
	v_and_b32_e32 v9, 0xffff0000, v71
	v_pk_add_f32 v[18:19], v[10:11], v[8:9]
	v_cvt_pk_bf16_f32 v10, v16, v17
	v_pk_mul_f32 v[16:17], v[16:17], v[16:17]
	v_cvt_pk_bf16_f32 v8, v12, v13
	v_pk_fma_f32 v[12:13], v[12:13], v[12:13], v[16:17]
	v_pk_mul_f32 v[16:17], v[18:19], v[18:19]
	v_cvt_pk_bf16_f32 v9, v14, v15
	v_pk_fma_f32 v[14:15], v[14:15], v[14:15], v[16:17]
	s_waitcnt vmcnt(6)
	v_lshlrev_b32_e32 v16, 16, v64
	v_and_b32_e32 v17, 0xffff0000, v64
	v_pk_add_f32 v[4:5], v[4:5], v[16:17]
	v_lshlrev_b32_e32 v16, 16, v65
	v_and_b32_e32 v17, 0xffff0000, v65
	v_pk_add_f32 v[6:7], v[6:7], v[16:17]
	v_lshlrev_b32_e32 v16, 16, v66
	v_and_b32_e32 v17, 0xffff0000, v66
	v_pk_add_f32 v[16:17], v[0:1], v[16:17]
	v_lshlrev_b32_e32 v0, 16, v67
	v_and_b32_e32 v1, 0xffff0000, v67
	v_add_f32_e32 v12, v12, v13
	v_cvt_pk_bf16_f32 v11, v18, v19
	v_pk_add_f32 v[18:19], v[2:3], v[0:1]
	v_pk_mul_f32 v[0:1], v[16:17], v[16:17]
	v_add_f32_e32 v12, v14, v12
	v_pk_fma_f32 v[0:1], v[4:5], v[4:5], v[0:1]
	v_add_f32_e32 v12, v15, v12
	v_pk_mul_f32 v[2:3], v[18:19], v[18:19]
	v_add_f32_e32 v0, v0, v12
	v_pk_fma_f32 v[2:3], v[6:7], v[6:7], v[2:3]
	v_add_f32_e32 v0, v1, v0
	v_add_f32_e32 v0, v2, v0
	v_add_f32_e32 v0, v3, v0
	ds_bpermute_b32 v1, v194, v0
	s_nop 0
	v_readlane_b32 s50, v253, 40
	v_readlane_b32 s51, v253, 41
	v_cvt_pk_bf16_f32 v2, v4, v5
	s_waitcnt lgkmcnt(0)
	v_add_f32_e32 v0, v0, v1
	ds_bpermute_b32 v1, v193, v0
	v_lshl_add_u64 v[20:21], s[50:51], 0, v[92:93]
	v_lshl_add_u64 v[12:13], s[24:25], 1, v[20:21]
	v_cvt_pk_bf16_f32 v3, v6, v7
	v_cvt_pk_bf16_f32 v4, v16, v17
	v_cvt_pk_bf16_f32 v5, v18, v19
	v_lshl_add_u64 v[6:7], v[12:13], 0, v[160:161]
	s_nop 7
	s_nop 4
	global_store_dwordx4 v[90:91], v[8:11], off
	global_store_dwordx4 v[6:7], v[2:5], off offset:256
	s_and_saveexec_b64 s[24:25], s[0:1]
	s_cbranch_execz .LBB0_1347
	s_waitcnt lgkmcnt(0)
	v_add_f32_e32 v2, v0, v1
	v_lshlrev_b64 v[0:1], 6, v[88:89]
	v_lshl_add_u64 v[0:1], s[86:87], 0, v[0:1]
	v_lshl_add_u64 v[0:1], s[10:11], 2, v[0:1]
	s_lshl_b32 s4, s38, 2
	v_lshl_add_u64 v[0:1], v[0:1], 0, s[4:5]
	global_store_dword v[0:1], v2, off
	s_branch .LBB0_1347

.LBB0_1429:
	s_or_b64 exec, exec, s[0:1]
	v_readlane_b32 s0, v252, 35
	v_readlane_b32 s1, v252, 36
	s_waitcnt lgkmcnt(0)
	s_barrier
	v_mov_b32 v9, v178
	s_and_b64 vcc, exec, s[0:1]
	v_readfirstlane_b32 s7, v9
	s_cbranch_vccz .LBB0_1446
	v_lshlrev_b32_e32 v0, 4, v9
	v_add_u32_e32 v1, 0x2000, v0
	v_ashrrev_i32_e32 v2, 31, v1
	v_lshrrev_b32_e32 v2, 22, v2
	v_add_u32_e32 v2, v1, v2
	v_ashrrev_i32_e32 v8, 10, v2
	v_mul_i32_i24_e32 v2, 0x400, v8
	v_sub_u32_e32 v1, v1, v2
	v_lshrrev_b32_e32 v2, 4, v1
	v_bitop3_b32 v1, v2, v1, 32 bitop3:0x6c
	v_ashrrev_i32_e32 v2, 31, v1
	v_lshrrev_b32_e32 v2, 26, v2
	v_add_u32_e32 v2, v1, v2
	v_lshlrev_b32_e32 v3, 3, v8
	v_ashrrev_i32_e32 v10, 6, v2
	v_and_b32_e32 v3, -16, v3
	v_add_u32_e32 v3, v10, v3
	v_and_b32_e32 v4, 3, v10
	s_mov_b32 s0, 0x1fffe0
	v_lshrrev_b32_e32 v5, 2, v3
	v_lshlrev_b32_e32 v6, 1, v3
	v_and_b32_e32 v2, 0xc0, v2
	v_and_or_b32 v4, v3, s0, v4
	v_and_b32_e32 v5, 4, v5
	v_and_b32_e32 v6, 24, v6
	v_sub_u32_e32 v1, v1, v2
	v_mov_b32_e32 v2, 1
	v_or3_b32 v4, v4, v5, v6
	v_lshlrev_b32_e32 v5, 5, v8
	v_ashrrev_i16_sdwa v1, v2, sext(v1) dst_sel:DWORD dst_unused:UNUSED_PAD src0_sel:DWORD src1_sel:BYTE_0
	v_and_b32_e32 v5, 32, v5
	v_bfe_i32 v11, v1, 0, 16
	v_add_lshl_u32 v1, v5, v11, 1
	v_lshl_add_u32 v128, v4, 11, v1
	v_lshl_add_u32 v130, v3, 11, v1
	v_bfe_i32 v1, v9, 27, 1
	v_lshrrev_b32_e32 v1, 22, v1
	v_add_u32_e32 v1, v0, v1
	v_and_b32_e32 v1, 0xfffffc00, v1
	v_sub_u32_e32 v0, v0, v1
	v_lshrrev_b32_e32 v1, 4, v0
	v_bitop3_b32 v1, v1, v0, 32 bitop3:0x6c
	v_ashrrev_i32_e32 v0, 31, v0
	v_lshrrev_b32_e32 v0, 26, v0
	v_add_u32_e32 v0, v1, v0
	v_ashrrev_i32_e32 v12, 6, v0
	v_ashrrev_i32_e32 v0, 31, v9
	v_lshrrev_b32_e32 v0, 26, v0
	v_add_u32_e32 v0, v9, v0
	v_ashrrev_i32_e32 v13, 6, v0
	v_lshlrev_b32_e32 v0, 3, v13
	v_and_b32_e32 v0, -16, v0
	s_nop 0
	v_add_u32_e32 v0, v12, v0
	v_readlane_b32 s40, v253, 38
	v_readlane_b32 s41, v253, 39
	s_ashr_i32 s11, s7, 6
	v_and_b32_e32 v3, 3, v12
	v_lshrrev_b32_e32 v4, 2, v0
	v_lshlrev_b32_e32 v5, 1, v0
	s_ashr_i32 s73, s72, 31
	v_readlane_b32 s42, v253, 40
	v_readlane_b32 s43, v253, 41
	s_mov_b64 s[20:21], s[40:41]
	s_ashr_i32 s10, s7, 8
	s_lshl_b32 s15, s11, 10
	v_and_or_b32 v3, v0, s0, v3
	v_and_b32_e32 v4, 4, v4
	v_and_b32_e32 v5, 24, v5
	s_lshl_b64 s[0:1], s[72:73], 19
	s_mov_b64 s[22:23], s[42:43]
	v_or3_b32 v3, v3, v4, v5
	v_mul_i32_i24_e32 v5, 64, v12
	s_add_u32 s0, s22, s0
	v_sub_u32_e32 v1, v1, v5
	s_addc_u32 s1, s23, s1
	s_ashr_i32 s71, s70, 31
	v_lshlrev_b32_e32 v4, 5, v13
	v_ashrrev_i16_sdwa v1, v2, sext(v1) dst_sel:DWORD dst_unused:UNUSED_PAD src0_sel:DWORD src1_sel:BYTE_0
	s_lshl_b64 s[4:5], s[70:71], 19
	v_and_b32_e32 v4, 32, v4
	v_bfe_i32 v14, v1, 0, 16
	s_add_u32 s4, s64, s4
	v_add_lshl_u32 v1, v4, v14, 1
	s_addc_u32 s5, s65, s5
	s_add_i32 s17, s15, 0
	v_lshl_add_u32 v132, v3, 11, v1
	s_add_i32 m0, s17, 0x10000
	v_lshl_add_u32 v134, v0, 11, v1
	global_load_lds_dwordx4 v132, s[4:5]
	s_add_i32 m0, s17, 0x12000
	s_add_i32 s28, s17, 0x2000
	global_load_lds_dwordx4 v128, s[4:5]
	s_mov_b32 m0, s17
	s_add_u32 s12, s4, 0x40000
	global_load_lds_dwordx4 v134, s[0:1]
	s_mov_b32 m0, s28
	s_addc_u32 s13, s5, 0
	global_load_lds_dwordx4 v130, s[0:1]
	s_add_i32 m0, s17, 0x14000
	v_mov_b32_e32 v137, 0
	global_load_lds_dwordx4 v132, s[12:13]
	s_add_i32 m0, s17, 0x16000
	v_mov_b32_e32 v133, v137
	global_load_lds_dwordx4 v128, s[12:13]
	s_add_u32 s12, s0, 0x40000
	s_addc_u32 s13, s1, 0
	s_add_i32 s29, s17, 0x4000
	s_mov_b32 m0, s29
	s_add_i32 s31, s17, 0x6000
	global_load_lds_dwordx4 v134, s[12:13]
	s_mov_b32 m0, s31
	v_mov_b32_e32 v129, v137
	global_load_lds_dwordx4 v130, s[12:13]
	v_mov_b32_e32 v135, v137
	v_mov_b32_e32 v131, v137
	s_mov_b32 s19, 0
	v_lshl_add_u64 v[6:7], s[4:5], 0, v[132:133]
	v_lshl_add_u64 v[4:5], s[4:5], 0, v[128:129]
	v_lshl_add_u64 v[2:3], s[0:1], 0, v[134:135]
	s_cmp_lg_u32 s10, 1
	v_lshl_add_u64 v[0:1], s[0:1], 0, v[130:131]
	s_nop 7
	s_nop 2
	s_cbranch_scc1 .LBB0_1432
	s_barrier

.LBB0_1440:
	s_nop 3
	v_readlane_b32 s48, v253, 38
	v_readlane_b32 s49, v253, 39
	s_ashr_i32 s19, s18, 31
	v_readlane_b32 s50, v253, 40
	v_readlane_b32 s51, v253, 41
	s_mov_b64 s[44:45], s[48:49]
	s_xor_b64 s[24:25], s[10:11], -1
	s_lshl_b64 s[22:23], s[18:19], 19
	s_mov_b64 s[46:47], s[50:51]
	s_add_u32 s22, s46, s22
	s_addc_u32 s23, s47, s23
	s_and_b64 s[26:27], s[10:11], exec
	s_cselect_b32 s19, s23, s1
	s_cselect_b32 s41, s22, s0
	s_ashr_i32 s21, s20, 31
	s_lshl_b64 s[26:27], s[20:21], 19
	s_add_u32 s26, s64, s26
	s_addc_u32 s27, s65, s27
	s_and_b64 s[10:11], s[10:11], exec
	s_cselect_b32 s21, s27, s5
	s_cselect_b32 s42, s26, s4
	s_add_u32 s0, s0, 0x40080
	s_addc_u32 s1, s1, 0
	s_add_u32 s43, s4, 0x100
	v_mov_b32_e32 v0, 0
	s_addc_u32 s44, s5, 0
	s_mov_b32 s45, -2
	v_mov_b32_e32 v1, v0
	v_mov_b32_e32 v2, v0
	v_mov_b32_e32 v3, v0
	v_mov_b32_e32 v4, v0
	v_mov_b32_e32 v5, v0
	v_mov_b32_e32 v6, v0
	v_mov_b32_e32 v7, v0
	v_mov_b32_e32 v16, v0
	v_mov_b32_e32 v17, v0
	v_mov_b32_e32 v18, v0
	v_mov_b32_e32 v19, v0
	v_mov_b32_e32 v20, v0
	v_mov_b32_e32 v21, v0
	v_mov_b32_e32 v22, v0
	v_mov_b32_e32 v23, v0
	v_mov_b32_e32 v32, v0
	v_mov_b32_e32 v33, v0
	v_mov_b32_e32 v34, v0
	v_mov_b32_e32 v35, v0
	v_mov_b32_e32 v36, v0
	v_mov_b32_e32 v37, v0
	v_mov_b32_e32 v38, v0
	v_mov_b32_e32 v39, v0
	v_mov_b32_e32 v48, v0
	v_mov_b32_e32 v49, v0
	v_mov_b32_e32 v50, v0
	v_mov_b32_e32 v51, v0
	v_mov_b32_e32 v52, v0
	v_mov_b32_e32 v53, v0
	v_mov_b32_e32 v54, v0
	v_mov_b32_e32 v55, v0
	v_mov_b32_e32 v8, v0
	v_mov_b32_e32 v9, v0
	v_mov_b32_e32 v10, v0
	v_mov_b32_e32 v11, v0
	v_mov_b32_e32 v12, v0
	v_mov_b32_e32 v13, v0
	v_mov_b32_e32 v14, v0
	v_mov_b32_e32 v15, v0
	v_mov_b32_e32 v24, v0
	v_mov_b32_e32 v25, v0
	v_mov_b32_e32 v26, v0
	v_mov_b32_e32 v27, v0
	v_mov_b32_e32 v28, v0
	v_mov_b32_e32 v29, v0
	v_mov_b32_e32 v30, v0
	v_mov_b32_e32 v31, v0
	v_mov_b32_e32 v40, v0
	v_mov_b32_e32 v41, v0
	v_mov_b32_e32 v42, v0
	v_mov_b32_e32 v43, v0
	v_mov_b32_e32 v44, v0
	v_mov_b32_e32 v45, v0
	v_mov_b32_e32 v46, v0
	v_mov_b32_e32 v47, v0
	v_mov_b32_e32 v56, v0
	v_mov_b32_e32 v57, v0
	v_mov_b32_e32 v58, v0
	v_mov_b32_e32 v59, v0
	v_mov_b32_e32 v60, v0
	v_mov_b32_e32 v61, v0
	v_mov_b32_e32 v62, v0
	v_mov_b32_e32 v63, v0
	v_mov_b32_e32 v64, v0
	v_mov_b32_e32 v65, v0
	v_mov_b32_e32 v66, v0
	v_mov_b32_e32 v67, v0
	v_mov_b32_e32 v68, v0
	v_mov_b32_e32 v69, v0
	v_mov_b32_e32 v70, v0
	v_mov_b32_e32 v71, v0
	v_mov_b32_e32 v80, v0
	v_mov_b32_e32 v81, v0
	v_mov_b32_e32 v82, v0
	v_mov_b32_e32 v83, v0
	v_mov_b32_e32 v84, v0
	v_mov_b32_e32 v85, v0
	v_mov_b32_e32 v86, v0
	v_mov_b32_e32 v87, v0
	v_mov_b32_e32 v96, v0
	v_mov_b32_e32 v97, v0
	v_mov_b32_e32 v98, v0
	v_mov_b32_e32 v99, v0
	v_mov_b32_e32 v100, v0
	v_mov_b32_e32 v101, v0
	v_mov_b32_e32 v102, v0
	v_mov_b32_e32 v103, v0
	v_mov_b32_e32 v112, v0
	v_mov_b32_e32 v113, v0
	v_mov_b32_e32 v114, v0
	v_mov_b32_e32 v115, v0
	v_mov_b32_e32 v116, v0
	v_mov_b32_e32 v117, v0
	v_mov_b32_e32 v118, v0
	v_mov_b32_e32 v119, v0
	v_mov_b32_e32 v72, v0
	v_mov_b32_e32 v73, v0
	v_mov_b32_e32 v74, v0
	v_mov_b32_e32 v75, v0
	v_mov_b32_e32 v76, v0
	v_mov_b32_e32 v77, v0
	v_mov_b32_e32 v78, v0
	v_mov_b32_e32 v79, v0
	v_mov_b32_e32 v88, v0
	v_mov_b32_e32 v89, v0
	v_mov_b32_e32 v90, v0
	v_mov_b32_e32 v91, v0
	v_mov_b32_e32 v92, v0
	v_mov_b32_e32 v93, v0
	v_mov_b32_e32 v94, v0
	v_mov_b32_e32 v95, v0
	v_mov_b32_e32 v104, v0
	v_mov_b32_e32 v105, v0
	v_mov_b32_e32 v106, v0
	v_mov_b32_e32 v107, v0
	v_mov_b32_e32 v108, v0
	v_mov_b32_e32 v109, v0
	v_mov_b32_e32 v110, v0
	v_mov_b32_e32 v111, v0
	v_mov_b32_e32 v120, v0
	v_mov_b32_e32 v121, v0
	v_mov_b32_e32 v122, v0
	v_mov_b32_e32 v123, v0
	v_mov_b32_e32 v124, v0
	v_mov_b32_e32 v125, v0
	v_mov_b32_e32 v126, v0
	v_mov_b32_e32 v127, v0
	s_nop 7

.LBB0_1502:
	s_add_u32 s38, s90, 0x3600
	s_addc_u32 s39, s91, 0
	s_and_b32 s40, s0, 3
	s_lshl_b32 s3, s2, 13
	s_lshl_b32 s5, s40, 12
	s_add_u32 s0, s24, 0x20000
	s_addc_u32 s1, s25, 0
	s_add_i32 m0, s33, 0x18000
	v_lshl_add_u64 v[8:9], s[0:1], 0, v[156:157]
	s_waitcnt vmcnt(4)
	s_barrier
	global_load_lds_dwordx4 v[8:9], off
	s_add_i32 m0, s33, 0x1a000
	v_lshl_add_u64 v[8:9], s[0:1], 0, v[152:153]
	s_add_u32 s0, s26, 0x400000
	s_addc_u32 s1, s27, 0
	s_add_i32 s41, s33, 0x8000
	global_load_lds_dwordx4 v[8:9], off
	v_lshl_add_u64 v[8:9], s[0:1], 0, v[158:159]
	s_mov_b32 m0, s41
	s_add_i32 s42, s33, 0xa000
	global_load_lds_dwordx4 v[8:9], off
	v_lshl_add_u64 v[8:9], s[0:1], 0, v[154:155]
	s_add_u32 s0, s24, 0x24000
	s_mov_b32 m0, s42
	s_addc_u32 s1, s25, 0
	global_load_lds_dwordx4 v[8:9], off
	s_add_i32 m0, s33, 0x1c000
	v_lshl_add_u64 v[8:9], s[0:1], 0, v[156:157]
	global_load_lds_dwordx4 v[8:9], off
	v_lshl_add_u64 v[8:9], s[0:1], 0, v[152:153]
	s_add_i32 m0, s33, 0x1e000
	v_and_b32_e32 v7, 15, v3
	global_load_lds_dwordx4 v[8:9], off
	v_bfe_u32 v8, v3, 4, 2
	v_lshlrev_b32_e32 v160, 4, v8
	v_lshlrev_b32_e32 v3, 2, v3
	v_lshl_or_b32 v10, v7, 6, v160
	v_and_b32_e32 v3, 32, v3
	v_bitop3_b32 v11, v10, s3, v3 bitop3:0xde
	v_bitop3_b32 v202, v10, s5, v3 bitop3:0xde
	v_or_b32_e32 v3, v8, v7
	v_lshl_or_b32 v163, s2, 6, v7
	s_lshl_b32 s43, s2, 4
	v_cmp_eq_u32_e64 s[2:3], 0, v3
	v_lshlrev_b32_e32 v3, 10, v5
	v_and_b32_e32 v3, 0xfffff800, v3
	v_lshl_add_u32 v3, v4, 7, v3
	v_and_b32_e32 v4, 1, v5
	v_lshl_or_b32 v3, v4, 6, v3
	v_lshl_add_u32 v168, v6, 1, v3
	v_lshlrev_b32_e32 v3, 10, v0
	v_lshlrev_b32_e32 v9, 3, v8
	s_nop 0
	v_and_b32_e32 v3, 0xfffff800, v3
	s_waitcnt vmcnt(6)
	v_lshl_or_b32 v162, s40, 5, v9
	s_nop 0
	v_lshl_add_u32 v1, v1, 7, v3
	v_and_b32_e32 v0, 1, v0
	v_lshl_add_u64 v[164:165], s[88:89], 0, v[160:161]
	v_lshlrev_b32_e32 v160, 2, v162
	v_readlane_b32 s46, v253, 36
	v_readlane_b32 s47, v253, 37
	v_lshl_or_b32 v0, v0, 6, v1
	s_add_i32 s44, 0, 0x10000
	s_add_i32 s45, 0, 0x14000
	v_cmp_eq_u32_e64 s[0:1], 0, v8
	v_lshl_add_u64 v[166:167], s[46:47], 0, v[160:161]
	v_mov_b32_e32 v169, v161
	v_lshl_add_u32 v170, v2, 1, v0
	v_mov_b32_e32 v171, v161
	v_add_u32_e32 v203, s44, v202
	v_add_u32_e32 v204, 0, v11
	v_add_u32_e32 v205, s45, v202
	v_mbcnt_hi_u32_b32 v206, -1, v220
	v_lshlrev_b32_e32 v160, 1, v162
	s_mov_b32 s10, 0x3a800000
	s_mov_b32 s12, 0x358637bd
	s_mov_b32 s46, 0x800000
	s_mov_b32 s8, 0
	s_barrier
	s_nop 7
	s_nop 3
	s_branch .LBB0_1504
.LBB0_1503:
	s_waitcnt lgkmcnt(0)
	v_lshl_add_u64 v[2:3], v[164:165], 0, v[188:189]
	global_load_dwordx2 v[210:211], v[2:3], off sc1
	global_load_dwordx2 v[212:213], v[2:3], off offset:8 sc1
	v_lshl_add_u64 v[2:3], v[164:165], 0, v[190:191]
	global_load_dwordx2 v[214:215], v[2:3], off sc1
	global_load_dwordx2 v[216:217], v[2:3], off offset:8 sc1
	v_lshl_add_u64 v[2:3], v[164:165], 0, v[192:193]
	v_lshl_add_u64 v[4:5], v[164:165], 0, v[194:195]
	global_load_dwordx2 v[218:219], v[2:3], off sc1
	global_load_dwordx2 v[198:199], v[2:3], off offset:8 sc1
	global_load_dwordx2 v[220:221], v[4:5], off sc1
	global_load_dwordx2 v[200:201], v[4:5], off offset:8 sc1
	v_lshl_add_u64 v[2:3], v[164:165], 0, v[196:197]
	v_lshl_add_u64 v[0:1], v[164:165], 0, v[0:1]
	s_lshl_b64 s[6:7], s[24:25], 2
	v_lshl_add_u64 v[4:5], v[164:165], 0, v[80:81]
	v_lshl_add_u64 v[6:7], v[164:165], 0, v[82:83]
	global_load_dwordx2 v[194:195], v[2:3], off sc1
	global_load_dwordx2 v[190:191], v[2:3], off offset:8 sc1
	global_load_dwordx2 v[196:197], v[4:5], off sc1
	global_load_dwordx2 v[192:193], v[4:5], off offset:8 sc1
	global_load_dwordx2 v[86:87], v[6:7], off sc1
	global_load_dwordx2 v[82:83], v[6:7], off offset:8 sc1
	global_load_dwordx2 v[188:189], v[0:1], off sc1
	global_load_dwordx2 v[84:85], v[0:1], off offset:8 sc1
	v_lshl_add_u64 v[0:1], v[166:167], 0, s[6:7]
	global_load_dwordx4 v[12:15], v[0:1], off
	global_load_dwordx4 v[8:11], v[0:1], off offset:16
	global_load_dwordx4 v[4:7], v[0:1], off offset:512
	s_nop 0
	global_load_dwordx4 v[0:3], v[0:1], off offset:528
	v_lshlrev_b64 v[222:223], 12, v[178:179]
	v_mov_b64_e32 v[178:179], s[12:13]
	s_nop 0
	v_readlane_b32 s68, v253, 38
	v_readlane_b32 s69, v253, 39
	v_readlane_b32 s70, v253, 40
	v_readlane_b32 s71, v253, 41
	s_mov_b64 s[48:49], s[68:69]
	v_lshlrev_b64 v[176:177], 12, v[176:177]
	v_lshl_add_u64 v[222:223], s[48:49], 0, v[222:223]
	v_lshlrev_b32_e32 v80, 2, v162
	v_mov_b32_e32 v81, v161
	v_lshl_add_u64 v[176:177], s[48:49], 0, v[176:177]
	v_lshl_add_u64 v[176:177], v[176:177], 0, s[6:7]
	v_lshl_add_u64 v[176:177], v[176:177], 0, v[80:81]
	s_nop 7
	s_nop 2
	s_mov_b64 s[50:51], s[70:71]
	s_nop 0
	s_mov_b64 s[24:25], s[22:23]
	s_mov_b64 s[26:27], s[18:19]
	s_mov_b32 s8, s47
	v_readlane_b32 s66, v253, 57
	v_readlane_b32 s67, v253, 58
	s_nop 7
	s_nop 4
	s_waitcnt vmcnt(19)
	v_mov_b32_e32 v225, v210
	s_waitcnt vmcnt(17)
	v_mov_b32_e32 v224, v214
	v_mov_b32_e32 v210, v215
	s_waitcnt vmcnt(16)
	v_mov_b32_e32 v214, v216
	v_mov_b32_e32 v215, v212
	v_mov_b32_e32 v212, v217
	v_pk_add_f32 v[210:211], v[224:225], v[210:211]
	v_pk_add_f32 v[212:213], v[214:215], v[212:213]
	s_waitcnt vmcnt(13)
	v_mov_b32_e32 v216, v220
	v_pk_add_f32 v[210:211], v[210:211], v[212:213]
	ds_bpermute_b32 v213, v207, v211
	ds_bpermute_b32 v212, v207, v210
	s_waitcnt vmcnt(12)
	v_mov_b32_e32 v220, v200
	v_mov_b32_e32 v217, v218
	v_mov_b32_e32 v218, v221
	v_mov_b32_e32 v221, v198
	s_waitcnt lgkmcnt(0)
	v_pk_add_f32 v[210:211], v[210:211], v[212:213]
	ds_bpermute_b32 v213, v208, v211
	ds_bpermute_b32 v212, v208, v210
	v_lshl_add_u64 v[214:215], v[222:223], 0, s[6:7]
	v_lshl_add_u64 v[214:215], v[214:215], 0, v[80:81]
	s_waitcnt lgkmcnt(0)
	v_pk_add_f32 v[210:211], v[210:211], v[212:213]
	s_nop 0
	v_pk_fma_f32 v[210:211], v[210:211], s[10:11], v[178:179] op_sel_hi:[1,0,0]
	s_nop 0
	v_mul_f32_e32 v200, 0x4b800000, v211
	v_cmp_gt_f32_e32 vcc, s46, v211
	v_mul_f32_e32 v209, 0x4b800000, v210
	v_cmp_gt_f32_e64 s[4:5], s46, v210
	v_cndmask_b32_e32 v200, v211, v200, vcc
	v_rsq_f32_e32 v200, v200
	v_cndmask_b32_e64 v209, v210, v209, s[4:5]
	v_rsq_f32_e32 v209, v209
	v_pk_add_f32 v[210:211], v[216:217], v[218:219]
	v_mul_f32_e32 v198, 0x45800000, v200
	v_cndmask_b32_e32 v198, v200, v198, vcc
	v_mul_f32_e32 v212, 0x45800000, v209
	v_cndmask_b32_e64 v200, v209, v212, s[4:5]
	v_pk_mul_f32 v[124:125], v[124:125], v[198:199] op_sel_hi:[1,0]
	v_pk_mul_f32 v[126:127], v[126:127], v[198:199] op_sel_hi:[1,0]
	v_pk_mul_f32 v[120:121], v[120:121], v[198:199] op_sel_hi:[1,0]
	v_pk_mul_f32 v[122:123], v[122:123], v[198:199] op_sel_hi:[1,0]
	v_pk_mul_f32 v[116:117], v[116:117], v[198:199] op_sel_hi:[1,0]
	v_pk_mul_f32 v[118:119], v[118:119], v[198:199] op_sel_hi:[1,0]
	v_pk_mul_f32 v[112:113], v[112:113], v[198:199] op_sel_hi:[1,0]
	v_pk_mul_f32 v[114:115], v[114:115], v[198:199] op_sel_hi:[1,0]
	v_pk_mul_f32 v[212:213], v[108:109], v[200:201] op_sel_hi:[1,0]
	v_pk_mul_f32 v[216:217], v[110:111], v[200:201] op_sel_hi:[1,0]
	v_pk_mul_f32 v[218:219], v[104:105], v[200:201] op_sel_hi:[1,0]
	v_pk_mul_f32 v[222:223], v[106:107], v[200:201] op_sel_hi:[1,0]
	v_pk_mul_f32 v[224:225], v[100:101], v[200:201] op_sel_hi:[1,0]
	v_pk_mul_f32 v[226:227], v[102:103], v[200:201] op_sel_hi:[1,0]
	s_waitcnt vmcnt(3)
	v_pk_mul_f32 v[102:103], v[14:15], v[126:127]
	v_pk_mul_f32 v[100:101], v[12:13], v[124:125]
	v_mov_b32_e32 v198, v201
	s_waitcnt vmcnt(2)
	v_pk_mul_f32 v[106:107], v[10:11], v[122:123]
	v_pk_mul_f32 v[104:105], v[8:9], v[120:121]
	s_waitcnt vmcnt(1)
	v_pk_mul_f32 v[110:111], v[6:7], v[118:119]
	v_pk_mul_f32 v[108:109], v[4:5], v[116:117]
	s_waitcnt vmcnt(0)
	v_pk_mul_f32 v[114:115], v[2:3], v[114:115]
	v_pk_mul_f32 v[112:113], v[0:1], v[112:113]
	v_pk_mul_f32 v[118:119], v[14:15], v[216:217]
	v_pk_mul_f32 v[116:117], v[12:13], v[212:213]
	v_pk_mul_f32 v[122:123], v[10:11], v[222:223]
	v_pk_mul_f32 v[120:121], v[8:9], v[218:219]
	global_store_dwordx4 v[214:215], v[100:103], off nt
	global_store_dwordx4 v[214:215], v[104:107], off offset:16 nt
	global_store_dwordx4 v[214:215], v[108:111], off offset:512 nt
	global_store_dwordx4 v[214:215], v[112:115], off offset:528 nt
	global_store_dwordx4 v[176:177], v[116:119], off nt
	global_store_dwordx4 v[176:177], v[120:123], off offset:16 nt
	v_pk_add_f32 v[100:101], v[220:221], v[198:199]
	v_pk_mul_f32 v[96:97], v[96:97], v[200:201] op_sel_hi:[1,0]
	v_pk_add_f32 v[100:101], v[210:211], v[100:101]
	ds_bpermute_b32 v103, v207, v101
	ds_bpermute_b32 v102, v207, v100
	v_pk_mul_f32 v[98:99], v[98:99], v[200:201] op_sel_hi:[1,0]
	v_pk_mul_f32 v[96:97], v[0:1], v[96:97]
	v_pk_mul_f32 v[98:99], v[2:3], v[98:99]
	global_store_dwordx4 v[176:177], v[96:99], off offset:528 nt
	s_waitcnt lgkmcnt(0)
	v_pk_add_f32 v[100:101], v[100:101], v[102:103]
	ds_bpermute_b32 v103, v208, v101
	ds_bpermute_b32 v102, v208, v100
	v_lshlrev_b64 v[96:97], 12, v[174:175]
	v_lshl_add_u64 v[96:97], s[48:49], 0, v[96:97]
	v_lshl_add_u64 v[96:97], v[96:97], 0, s[6:7]
	v_pk_mul_f32 v[124:125], v[6:7], v[226:227]
	s_waitcnt lgkmcnt(0)
	v_pk_add_f32 v[98:99], v[100:101], v[102:103]
	v_pk_mul_f32 v[122:123], v[4:5], v[224:225]
	v_pk_fma_f32 v[98:99], v[98:99], s[10:11], v[178:179] op_sel_hi:[1,0,0]
	global_store_dwordx4 v[176:177], v[122:125], off offset:512 nt
	v_mul_f32_e32 v100, 0x4b800000, v99
	v_cmp_gt_f32_e32 vcc, s46, v99
	s_mov_b32 s4, s16
	s_mov_b32 s5, s16
	v_cndmask_b32_e32 v99, v99, v100, vcc
	v_rsq_f32_e32 v99, v99
	v_lshl_add_u64 v[100:101], v[96:97], 0, v[80:81]
	v_mul_f32_e32 v96, 0x45800000, v99
	v_cndmask_b32_e32 v102, v99, v96, vcc
	v_pk_mul_f32 v[104:105], v[140:141], v[102:103] op_sel_hi:[1,0]
	v_pk_mul_f32 v[94:95], v[94:95], v[102:103] op_sel_hi:[1,0]
	v_pk_mul_f32 v[92:93], v[92:93], v[102:103] op_sel_hi:[1,0]
	v_pk_mul_f32 v[96:97], v[14:15], v[94:95]
	v_pk_mul_f32 v[94:95], v[12:13], v[104:105]
	global_store_dwordx4 v[100:101], v[94:97], off nt
	v_cmp_gt_f32_e32 vcc, s46, v98
	s_nop 0
	v_pk_mul_f32 v[96:97], v[142:143], v[102:103] op_sel_hi:[1,0]
	v_pk_mul_f32 v[94:95], v[10:11], v[92:93]
	v_pk_mul_f32 v[92:93], v[8:9], v[96:97]
	v_mul_f32_e32 v96, 0x4b800000, v98
	v_cndmask_b32_e32 v96, v98, v96, vcc
	global_store_dwordx4 v[100:101], v[92:95], off offset:16 nt
	v_rsq_f32_e32 v96, v96
	s_nop 0
	v_pk_mul_f32 v[92:93], v[144:145], v[102:103] op_sel_hi:[1,0]
	v_pk_mul_f32 v[94:95], v[136:137], v[102:103] op_sel_hi:[1,0]
	v_pk_mul_f32 v[92:93], v[4:5], v[92:93]
	v_pk_mul_f32 v[94:95], v[6:7], v[94:95]
	global_store_dwordx4 v[100:101], v[92:95], off offset:512 nt
	s_nop 1
	v_pk_mul_f32 v[92:93], v[146:147], v[102:103] op_sel_hi:[1,0]
	v_pk_mul_f32 v[94:95], v[138:139], v[102:103] op_sel_hi:[1,0]
	v_pk_mul_f32 v[92:93], v[0:1], v[92:93]
	v_pk_mul_f32 v[94:95], v[2:3], v[94:95]
	global_store_dwordx4 v[100:101], v[92:95], off offset:528 nt
	v_mov_b32_e32 v100, v196
	v_mov_b32_e32 v101, v194
	v_mul_f32_e32 v92, 0x45800000, v96
	v_cndmask_b32_e32 v96, v96, v92, vcc
	v_lshlrev_b64 v[92:93], 12, v[172:173]
	v_lshl_add_u64 v[92:93], s[48:49], 0, v[92:93]
	v_mov_b32_e32 v194, v197
	v_mov_b32_e32 v102, v192
	v_mov_b32_e32 v103, v190
	v_mov_b32_e32 v190, v193
	v_lshl_add_u64 v[92:93], v[92:93], 0, s[6:7]
	v_pk_add_f32 v[100:101], v[100:101], v[194:195]
	v_pk_add_f32 v[102:103], v[102:103], v[190:191]
	v_lshl_add_u64 v[98:99], v[92:93], 0, v[80:81]
	v_pk_mul_f32 v[92:93], v[150:151], v[96:97] op_sel_hi:[1,0]
	v_pk_mul_f32 v[94:95], v[148:149], v[96:97] op_sel_hi:[1,0]
	v_pk_add_f32 v[100:101], v[100:101], v[102:103]
	v_pk_mul_f32 v[94:95], v[14:15], v[94:95]
	v_pk_mul_f32 v[92:93], v[12:13], v[92:93]
	ds_bpermute_b32 v103, v207, v101
	ds_bpermute_b32 v102, v207, v100
	global_store_dwordx4 v[98:99], v[92:95], off nt
	s_nop 1
	v_pk_mul_f32 v[92:93], v[180:181], v[96:97] op_sel_hi:[1,0]
	v_pk_mul_f32 v[94:95], v[134:135], v[96:97] op_sel_hi:[1,0]
	v_pk_mul_f32 v[92:93], v[8:9], v[92:93]
	v_pk_mul_f32 v[94:95], v[10:11], v[94:95]
	global_store_dwordx4 v[98:99], v[92:95], off offset:16 nt
	s_nop 1
	v_pk_mul_f32 v[92:93], v[186:187], v[96:97] op_sel_hi:[1,0]
	v_pk_mul_f32 v[94:95], v[182:183], v[96:97] op_sel_hi:[1,0]
	v_pk_mul_f32 v[92:93], v[4:5], v[92:93]
	v_pk_mul_f32 v[94:95], v[6:7], v[94:95]
	global_store_dwordx4 v[98:99], v[92:95], off offset:512 nt
	s_nop 1
	v_pk_mul_f32 v[92:93], v[132:133], v[96:97] op_sel_hi:[1,0]
	v_pk_mul_f32 v[94:95], v[130:131], v[96:97] op_sel_hi:[1,0]
	s_waitcnt lgkmcnt(0)
	v_pk_add_f32 v[96:97], v[100:101], v[102:103]
	ds_bpermute_b32 v101, v208, v97
	ds_bpermute_b32 v100, v208, v96
	v_pk_mul_f32 v[94:95], v[2:3], v[94:95]
	v_pk_mul_f32 v[92:93], v[0:1], v[92:93]
	global_store_dwordx4 v[98:99], v[92:95], off offset:528 nt
	s_waitcnt lgkmcnt(0)
	s_nop 0
	v_pk_add_f32 v[94:95], v[96:97], v[100:101]
	v_lshlrev_b64 v[92:93], 12, v[184:185]
	v_pk_fma_f32 v[94:95], v[94:95], s[10:11], v[178:179] op_sel_hi:[1,0,0]
	v_lshl_add_u64 v[92:93], s[48:49], 0, v[92:93]
	v_mul_f32_e32 v96, 0x4b800000, v95
	v_cmp_gt_f32_e32 vcc, s46, v95
	v_lshl_add_u64 v[92:93], v[92:93], 0, s[6:7]
	v_lshl_add_u64 v[92:93], v[92:93], 0, v[80:81]
	v_cndmask_b32_e32 v95, v95, v96, vcc
	v_rsq_f32_e32 v95, v95
	s_nop 0
	v_mul_f32_e32 v96, 0x45800000, v95
	v_cndmask_b32_e32 v96, v95, v96, vcc
	v_pk_mul_f32 v[52:53], v[52:53], v[96:97] op_sel_hi:[1,0]
	v_pk_mul_f32 v[54:55], v[54:55], v[96:97] op_sel_hi:[1,0]
	v_pk_mul_f32 v[52:53], v[4:5], v[52:53]
	v_pk_mul_f32 v[54:55], v[6:7], v[54:55]
	global_store_dwordx4 v[92:93], v[52:55], off offset:512 nt
	v_cmp_gt_f32_e32 vcc, s46, v94
	v_pk_mul_f32 v[48:49], v[48:49], v[96:97] op_sel_hi:[1,0]
	v_mul_f32_e32 v52, 0x4b800000, v94
	v_cndmask_b32_e32 v52, v94, v52, vcc
	v_rsq_f32_e32 v52, v52
	v_pk_mul_f32 v[50:51], v[50:51], v[96:97] op_sel_hi:[1,0]
	v_pk_mul_f32 v[48:49], v[0:1], v[48:49]
	v_pk_mul_f32 v[50:51], v[2:3], v[50:51]
	global_store_dwordx4 v[92:93], v[48:51], off offset:528 nt
	v_pk_mul_f32 v[60:61], v[60:61], v[96:97] op_sel_hi:[1,0]
	v_pk_mul_f32 v[62:63], v[62:63], v[96:97] op_sel_hi:[1,0]
	v_mul_f32_e32 v48, 0x45800000, v52
	v_lshlrev_b64 v[50:51], 12, v[128:129]
	v_cndmask_b32_e32 v48, v52, v48, vcc
	v_lshl_add_u64 v[50:51], s[48:49], 0, v[50:51]
	v_lshl_add_u64 v[50:51], v[50:51], 0, s[6:7]
	v_pk_mul_f32 v[40:41], v[40:41], v[48:49] op_sel_hi:[1,0]
	v_pk_mul_f32 v[42:43], v[42:43], v[48:49] op_sel_hi:[1,0]
	v_lshl_add_u64 v[50:51], v[50:51], 0, v[80:81]
	v_pk_mul_f32 v[42:43], v[10:11], v[42:43]
	v_pk_mul_f32 v[40:41], v[8:9], v[40:41]
	global_store_dwordx4 v[50:51], v[40:43], off offset:16 nt
	v_pk_mul_f32 v[36:37], v[36:37], v[48:49] op_sel_hi:[1,0]
	v_pk_mul_f32 v[38:39], v[38:39], v[48:49] op_sel_hi:[1,0]
	v_mov_b32_e32 v40, v188
	v_mov_b32_e32 v41, v86
	v_mov_b32_e32 v86, v189
	v_mov_b32_e32 v42, v84
	v_mov_b32_e32 v43, v82
	v_mov_b32_e32 v82, v85
	v_pk_add_f32 v[40:41], v[40:41], v[86:87]
	v_pk_add_f32 v[42:43], v[42:43], v[82:83]
	v_pk_mul_f32 v[38:39], v[6:7], v[38:39]
	v_pk_add_f32 v[40:41], v[40:41], v[42:43]
	ds_bpermute_b32 v43, v207, v41
	ds_bpermute_b32 v42, v207, v40
	v_pk_mul_f32 v[36:37], v[4:5], v[36:37]
	global_store_dwordx4 v[50:51], v[36:39], off offset:512 nt
	v_pk_mul_f32 v[32:33], v[32:33], v[48:49] op_sel_hi:[1,0]
	v_pk_mul_f32 v[34:35], v[34:35], v[48:49] op_sel_hi:[1,0]
	s_waitcnt lgkmcnt(0)
	v_pk_add_f32 v[36:37], v[40:41], v[42:43]
	ds_bpermute_b32 v39, v208, v37
	ds_bpermute_b32 v38, v208, v36
	v_pk_mul_f32 v[34:35], v[2:3], v[34:35]
	v_pk_mul_f32 v[32:33], v[0:1], v[32:33]
	global_store_dwordx4 v[50:51], v[32:35], off offset:528 nt
	v_pk_mul_f32 v[44:45], v[44:45], v[48:49] op_sel_hi:[1,0]
	v_pk_mul_f32 v[46:47], v[46:47], v[48:49] op_sel_hi:[1,0]
	s_waitcnt lgkmcnt(0)
	v_pk_add_f32 v[34:35], v[36:37], v[38:39]
	v_lshlrev_b64 v[32:33], 12, v[90:91]
	v_pk_fma_f32 v[34:35], v[34:35], s[10:11], v[178:179] op_sel_hi:[1,0,0]
	v_lshl_add_u64 v[32:33], s[48:49], 0, v[32:33]
	v_mul_f32_e32 v36, 0x4b800000, v35
	v_cmp_gt_f32_e32 vcc, s46, v35
	v_lshl_add_u64 v[32:33], v[32:33], 0, s[6:7]
	v_lshl_add_u64 v[32:33], v[32:33], 0, v[80:81]
	v_cndmask_b32_e32 v35, v35, v36, vcc
	v_rsq_f32_e32 v35, v35
	v_pk_mul_f32 v[62:63], v[14:15], v[62:63]
	v_pk_mul_f32 v[60:61], v[12:13], v[60:61]
	v_pk_mul_f32 v[46:47], v[14:15], v[46:47]
	v_mul_f32_e32 v36, 0x45800000, v35
	v_cndmask_b32_e32 v36, v35, v36, vcc
	v_pk_mul_f32 v[20:21], v[20:21], v[36:37] op_sel_hi:[1,0]
	v_pk_mul_f32 v[22:23], v[22:23], v[36:37] op_sel_hi:[1,0]
	v_pk_mul_f32 v[20:21], v[4:5], v[20:21]
	v_pk_mul_f32 v[22:23], v[6:7], v[22:23]
	global_store_dwordx4 v[32:33], v[20:23], off offset:512 nt
	v_cmp_gt_f32_e32 vcc, s46, v34
	v_pk_mul_f32 v[16:17], v[16:17], v[36:37] op_sel_hi:[1,0]
	v_mul_f32_e32 v20, 0x4b800000, v34
	v_cndmask_b32_e32 v20, v34, v20, vcc
	v_rsq_f32_e32 v20, v20
	v_pk_mul_f32 v[18:19], v[18:19], v[36:37] op_sel_hi:[1,0]
	v_pk_mul_f32 v[16:17], v[0:1], v[16:17]
	v_pk_mul_f32 v[18:19], v[2:3], v[18:19]
	global_store_dwordx4 v[32:33], v[16:19], off offset:528 nt
	v_pk_mul_f32 v[28:29], v[28:29], v[36:37] op_sel_hi:[1,0]
	v_pk_mul_f32 v[30:31], v[30:31], v[36:37] op_sel_hi:[1,0]
	v_mul_f32_e32 v16, 0x45800000, v20
	v_lshlrev_b64 v[18:19], 12, v[88:89]
	v_cndmask_b32_e32 v16, v20, v16, vcc
	v_lshl_add_u64 v[18:19], s[48:49], 0, v[18:19]
	v_lshl_add_u64 v[18:19], v[18:19], 0, s[6:7]
	v_pk_mul_f32 v[20:21], v[72:73], v[16:17] op_sel_hi:[1,0]
	v_pk_mul_f32 v[22:23], v[68:69], v[16:17] op_sel_hi:[1,0]
	v_pk_mul_f32 v[44:45], v[12:13], v[44:45]
	v_pk_mul_f32 v[30:31], v[14:15], v[30:31]
	v_pk_mul_f32 v[28:29], v[12:13], v[28:29]
	v_lshl_add_u64 v[18:19], v[18:19], 0, v[80:81]
	v_pk_mul_f32 v[14:15], v[14:15], v[22:23]
	v_pk_mul_f32 v[12:13], v[12:13], v[20:21]
	v_pk_mul_f32 v[56:57], v[56:57], v[96:97] op_sel_hi:[1,0]
	v_pk_mul_f32 v[58:59], v[58:59], v[96:97] op_sel_hi:[1,0]
	v_pk_mul_f32 v[24:25], v[24:25], v[36:37] op_sel_hi:[1,0]
	v_pk_mul_f32 v[26:27], v[26:27], v[36:37] op_sel_hi:[1,0]
	global_store_dwordx4 v[18:19], v[12:15], off nt
	v_pk_mul_f32 v[58:59], v[10:11], v[58:59]
	v_pk_mul_f32 v[56:57], v[8:9], v[56:57]
	v_pk_mul_f32 v[12:13], v[74:75], v[16:17] op_sel_hi:[1,0]
	v_pk_mul_f32 v[14:15], v[70:71], v[16:17] op_sel_hi:[1,0]
	v_pk_mul_f32 v[26:27], v[10:11], v[26:27]
	v_pk_mul_f32 v[24:25], v[8:9], v[24:25]
	v_pk_mul_f32 v[10:11], v[10:11], v[14:15]
	v_pk_mul_f32 v[8:9], v[8:9], v[12:13]
	global_store_dwordx4 v[18:19], v[8:11], off offset:16 nt
	s_and_b64 vcc, exec, s[20:21]
	s_mov_b32 s6, s14
	v_pk_mul_f32 v[8:9], v[76:77], v[16:17] op_sel_hi:[1,0]
	v_pk_mul_f32 v[10:11], v[64:65], v[16:17] op_sel_hi:[1,0]
	v_pk_mul_f32 v[4:5], v[4:5], v[8:9]
	v_pk_mul_f32 v[6:7], v[6:7], v[10:11]
	global_store_dwordx4 v[18:19], v[4:7], off offset:512 nt
	s_mov_b32 s7, s14
	global_store_dwordx4 v[92:93], v[60:63], off nt
	v_pk_mul_f32 v[4:5], v[78:79], v[16:17] op_sel_hi:[1,0]
	v_pk_mul_f32 v[6:7], v[66:67], v[16:17] op_sel_hi:[1,0]
	v_pk_mul_f32 v[0:1], v[0:1], v[4:5]
	v_pk_mul_f32 v[2:3], v[2:3], v[6:7]
	global_store_dwordx4 v[92:93], v[56:59], off offset:16 nt
	global_store_dwordx4 v[50:51], v[44:47], off nt
	global_store_dwordx4 v[32:33], v[28:31], off nt
	global_store_dwordx4 v[32:33], v[24:27], off offset:16 nt
	global_store_dwordx4 v[18:19], v[0:3], off offset:528 nt
	s_cbranch_vccnz .LBB0_1545

.LBB0_1512:
	ds_read_b128 v[128:131], v203
	ds_read_b128 v[132:135], v203 offset:1024
	ds_read_b128 v[136:139], v203 offset:2048
	ds_read_b128 v[140:143], v203 offset:3072
	s_add_u32 s26, s24, 0x3fc000
	s_addc_u32 s27, s25, 0
	s_cmp_eq_u32 s49, 60
	s_cselect_b32 s30, s7, s26
	s_cselect_b32 s31, s5, s27
	s_cselect_b32 s26, s15, s17
	s_cselect_b32 s27, s8, s48
	s_add_u32 s28, s30, 0x400000
	s_addc_u32 s29, s31, 0
	v_lshl_add_u64 v[196:197], s[24:25], 0, v[168:169]
	s_add_i32 m0, s33, 0xc000
	ds_read_b128 v[144:147], v204
	ds_read_b128 v[148:151], v204 offset:1024
	ds_read_b128 v[172:175], v204 offset:2048
	ds_read_b128 v[176:179], v204 offset:3072
	ds_read_b128 v[180:183], v204 offset:4096
	ds_read_b128 v[184:187], v204 offset:5120
	ds_read_b128 v[188:191], v204 offset:6144
	ds_read_b128 v[192:195], v204 offset:7168
	global_load_lds_dwordx4 v[196:197], off
	v_lshl_add_u64 v[196:197], s[24:25], 0, v[170:171]
	s_add_i32 m0, s33, 0xe000
	s_nop 0
	global_load_lds_dwordx4 v[196:197], off
	s_waitcnt lgkmcnt(8)
	s_barrier
	s_waitcnt lgkmcnt(0)
	s_setprio 1
	s_waitcnt lgkmcnt(0)
	v_mfma_f32_16x16x32_bf16 v[124:127], v[128:131], v[144:147], v[124:127]
	v_mfma_f32_16x16x32_bf16 v[120:123], v[136:139], v[144:147], v[120:123]
	v_mfma_f32_16x16x32_bf16 v[108:111], v[128:131], v[172:175], v[108:111]
	v_mfma_f32_16x16x32_bf16 v[104:107], v[136:139], v[172:175], v[104:107]
	v_mfma_f32_16x16x32_bf16 v[92:95], v[128:131], v[180:183], v[92:95]
	v_mfma_f32_16x16x32_bf16 v[88:91], v[136:139], v[180:183], v[88:91]
	v_mfma_f32_16x16x32_bf16 v[76:79], v[128:131], v[188:191], v[76:79]
	v_mfma_f32_16x16x32_bf16 v[72:75], v[136:139], v[188:191], v[72:75]
	v_mfma_f32_16x16x32_bf16 v[124:127], v[132:135], v[148:151], v[124:127]
	v_mfma_f32_16x16x32_bf16 v[120:123], v[140:143], v[148:151], v[120:123]
	v_mfma_f32_16x16x32_bf16 v[108:111], v[132:135], v[176:179], v[108:111]
	v_mfma_f32_16x16x32_bf16 v[104:107], v[140:143], v[176:179], v[104:107]
	v_mfma_f32_16x16x32_bf16 v[92:95], v[132:135], v[184:187], v[92:95]
	v_mfma_f32_16x16x32_bf16 v[88:91], v[140:143], v[184:187], v[88:91]
	v_mfma_f32_16x16x32_bf16 v[76:79], v[132:135], v[192:195], v[76:79]
	v_mfma_f32_16x16x32_bf16 v[72:75], v[140:143], v[192:195], v[72:75]
	s_setprio 0
	s_barrier
	s_add_i32 s50, s44, s13
	v_lshl_add_u64 v[200:201], s[26:27], 0, v[156:157]
	s_mov_b32 m0, s50
	ds_read_b128 v[196:199], v205
	ds_read_b128 v[208:211], v205 offset:1024
	ds_read_b128 v[212:215], v205 offset:2048
	ds_read_b128 v[216:219], v205 offset:3072
	global_load_lds_dwordx4 v[200:201], off
	v_lshl_add_u64 v[200:201], s[26:27], 0, v[152:153]
	s_add_i32 m0, s50, 0x2000
	s_nop 0
	global_load_lds_dwordx4 v[200:201], off
	s_barrier
	s_waitcnt lgkmcnt(0)
	s_setprio 1
	s_waitcnt lgkmcnt(0)
	v_mfma_f32_16x16x32_bf16 v[116:119], v[196:199], v[144:147], v[116:119]
	v_mfma_f32_16x16x32_bf16 v[112:115], v[212:215], v[144:147], v[112:115]
	v_mfma_f32_16x16x32_bf16 v[100:103], v[196:199], v[172:175], v[100:103]
	v_mfma_f32_16x16x32_bf16 v[96:99], v[212:215], v[172:175], v[96:99]
	v_mfma_f32_16x16x32_bf16 v[84:87], v[196:199], v[180:183], v[84:87]
	v_mfma_f32_16x16x32_bf16 v[80:83], v[212:215], v[180:183], v[80:83]
	v_mfma_f32_16x16x32_bf16 v[68:71], v[196:199], v[188:191], v[68:71]
	v_mfma_f32_16x16x32_bf16 v[64:67], v[212:215], v[188:191], v[64:67]
	v_mfma_f32_16x16x32_bf16 v[116:119], v[208:211], v[148:151], v[116:119]
	v_mfma_f32_16x16x32_bf16 v[112:115], v[216:219], v[148:151], v[112:115]
	v_mfma_f32_16x16x32_bf16 v[100:103], v[208:211], v[176:179], v[100:103]
	v_mfma_f32_16x16x32_bf16 v[96:99], v[216:219], v[176:179], v[96:99]
	v_mfma_f32_16x16x32_bf16 v[84:87], v[208:211], v[184:187], v[84:87]
	v_mfma_f32_16x16x32_bf16 v[80:83], v[216:219], v[184:187], v[80:83]
	v_mfma_f32_16x16x32_bf16 v[68:71], v[208:211], v[192:195], v[68:71]
	v_mfma_f32_16x16x32_bf16 v[64:67], v[216:219], v[192:195], v[64:67]
	s_setprio 0
	s_mov_b32 m0, s33
	v_lshl_add_u64 v[200:201], s[30:31], 0, v[158:159]
	s_barrier
	ds_read_b128 v[144:147], v204 offset:16384
	ds_read_b128 v[148:151], v204 offset:17408
	ds_read_b128 v[172:175], v204 offset:18432
	ds_read_b128 v[176:179], v204 offset:19456
	ds_read_b128 v[180:183], v204 offset:20480
	ds_read_b128 v[184:187], v204 offset:21504
	ds_read_b128 v[188:191], v204 offset:22528
	ds_read_b128 v[192:195], v204 offset:23552
	global_load_lds_dwordx4 v[200:201], off
	v_lshl_add_u64 v[200:201], s[30:31], 0, v[154:155]
	s_mov_b32 m0, s35
	s_nop 0
	global_load_lds_dwordx4 v[200:201], off
	s_barrier
	s_waitcnt lgkmcnt(0)
	s_setprio 1
	s_waitcnt lgkmcnt(0)
	v_mfma_f32_16x16x32_bf16 v[60:63], v[128:131], v[144:147], v[60:63]
	v_mfma_f32_16x16x32_bf16 v[56:59], v[136:139], v[144:147], v[56:59]
	v_mfma_f32_16x16x32_bf16 v[44:47], v[128:131], v[172:175], v[44:47]
	v_mfma_f32_16x16x32_bf16 v[40:43], v[136:139], v[172:175], v[40:43]
	v_mfma_f32_16x16x32_bf16 v[28:31], v[128:131], v[180:183], v[28:31]
	v_mfma_f32_16x16x32_bf16 v[24:27], v[136:139], v[180:183], v[24:27]
	v_mfma_f32_16x16x32_bf16 v[12:15], v[128:131], v[188:191], v[12:15]
	v_mfma_f32_16x16x32_bf16 v[8:11], v[136:139], v[188:191], v[8:11]
	v_mfma_f32_16x16x32_bf16 v[60:63], v[132:135], v[148:151], v[60:63]
	v_mfma_f32_16x16x32_bf16 v[56:59], v[140:143], v[148:151], v[56:59]
	v_mfma_f32_16x16x32_bf16 v[44:47], v[132:135], v[176:179], v[44:47]
	v_mfma_f32_16x16x32_bf16 v[40:43], v[140:143], v[176:179], v[40:43]
	v_mfma_f32_16x16x32_bf16 v[28:31], v[132:135], v[184:187], v[28:31]
	v_mfma_f32_16x16x32_bf16 v[24:27], v[140:143], v[184:187], v[24:27]
	v_mfma_f32_16x16x32_bf16 v[12:15], v[132:135], v[192:195], v[12:15]
	v_mfma_f32_16x16x32_bf16 v[8:11], v[140:143], v[192:195], v[8:11]
	s_setprio 0
	s_barrier
	s_add_u32 s50, s26, 0x4000
	s_addc_u32 s51, s27, 0
	s_add_i32 s52, s45, s13
	v_lshl_add_u64 v[128:129], s[50:51], 0, v[156:157]
	s_mov_b32 m0, s52
	s_nop 0
	global_load_lds_dwordx4 v[128:129], off
	v_lshl_add_u64 v[128:129], s[50:51], 0, v[152:153]
	s_add_i32 m0, s52, 0x2000
	s_nop 0
	global_load_lds_dwordx4 v[128:129], off
	s_waitcnt vmcnt(6)
	s_barrier
	s_setprio 1
	v_mfma_f32_16x16x32_bf16 v[52:55], v[196:199], v[144:147], v[52:55]
	v_mfma_f32_16x16x32_bf16 v[48:51], v[212:215], v[144:147], v[48:51]
	v_mfma_f32_16x16x32_bf16 v[36:39], v[196:199], v[172:175], v[36:39]
	v_mfma_f32_16x16x32_bf16 v[32:35], v[212:215], v[172:175], v[32:35]
	v_mfma_f32_16x16x32_bf16 v[20:23], v[196:199], v[180:183], v[20:23]
	v_mfma_f32_16x16x32_bf16 v[16:19], v[212:215], v[180:183], v[16:19]
	v_mfma_f32_16x16x32_bf16 v[4:7], v[196:199], v[188:191], v[4:7]
	v_mfma_f32_16x16x32_bf16 v[0:3], v[212:215], v[188:191], v[0:3]
	v_mfma_f32_16x16x32_bf16 v[52:55], v[208:211], v[148:151], v[52:55]
	v_mfma_f32_16x16x32_bf16 v[48:51], v[216:219], v[148:151], v[48:51]
	v_mfma_f32_16x16x32_bf16 v[36:39], v[208:211], v[176:179], v[36:39]
	v_mfma_f32_16x16x32_bf16 v[32:35], v[216:219], v[176:179], v[32:35]
	v_mfma_f32_16x16x32_bf16 v[20:23], v[208:211], v[184:187], v[20:23]
	v_mfma_f32_16x16x32_bf16 v[16:19], v[216:219], v[184:187], v[16:19]
	v_mfma_f32_16x16x32_bf16 v[4:7], v[208:211], v[192:195], v[4:7]
	v_mfma_f32_16x16x32_bf16 v[0:3], v[216:219], v[192:195], v[0:3]
	s_setprio 0
	s_add_i32 s50, 0, 0x18000
	v_add_u32_e32 v140, s50, v202
	s_barrier
	ds_read_b128 v[128:131], v140
	ds_read_b128 v[132:135], v140 offset:1024
	ds_read_b128 v[136:139], v140 offset:2048
	ds_read_b128 v[140:143], v140 offset:3072
	s_add_u32 s30, s30, 0x4000
	s_addc_u32 s31, s31, 0
	s_mov_b32 m0, s36
	v_lshl_add_u64 v[196:197], s[30:31], 0, v[158:159]
	ds_read_b128 v[144:147], v204 offset:32768
	ds_read_b128 v[148:151], v204 offset:33792
	ds_read_b128 v[172:175], v204 offset:34816
	ds_read_b128 v[176:179], v204 offset:35840
	ds_read_b128 v[180:183], v204 offset:36864
	ds_read_b128 v[184:187], v204 offset:37888
	ds_read_b128 v[188:191], v204 offset:38912
	ds_read_b128 v[192:195], v204 offset:39936
	global_load_lds_dwordx4 v[196:197], off
	v_lshl_add_u64 v[196:197], s[30:31], 0, v[154:155]
	s_mov_b32 m0, s37
	s_nop 0
	global_load_lds_dwordx4 v[196:197], off
	s_waitcnt lgkmcnt(8)
	s_barrier
	s_waitcnt lgkmcnt(0)
	s_setprio 1
	s_waitcnt lgkmcnt(0)
	v_mfma_f32_16x16x32_bf16 v[124:127], v[128:131], v[144:147], v[124:127]
	v_mfma_f32_16x16x32_bf16 v[120:123], v[136:139], v[144:147], v[120:123]
	v_mfma_f32_16x16x32_bf16 v[108:111], v[128:131], v[172:175], v[108:111]
	v_mfma_f32_16x16x32_bf16 v[104:107], v[136:139], v[172:175], v[104:107]
	v_mfma_f32_16x16x32_bf16 v[92:95], v[128:131], v[180:183], v[92:95]
	v_mfma_f32_16x16x32_bf16 v[88:91], v[136:139], v[180:183], v[88:91]
	v_mfma_f32_16x16x32_bf16 v[76:79], v[128:131], v[188:191], v[76:79]
	v_mfma_f32_16x16x32_bf16 v[72:75], v[136:139], v[188:191], v[72:75]
	v_mfma_f32_16x16x32_bf16 v[124:127], v[132:135], v[148:151], v[124:127]
	v_mfma_f32_16x16x32_bf16 v[120:123], v[140:143], v[148:151], v[120:123]
	v_mfma_f32_16x16x32_bf16 v[108:111], v[132:135], v[176:179], v[108:111]
	v_mfma_f32_16x16x32_bf16 v[104:107], v[140:143], v[176:179], v[104:107]
	v_mfma_f32_16x16x32_bf16 v[92:95], v[132:135], v[184:187], v[92:95]
	v_mfma_f32_16x16x32_bf16 v[88:91], v[140:143], v[184:187], v[88:91]
	v_mfma_f32_16x16x32_bf16 v[76:79], v[132:135], v[192:195], v[76:79]
	v_mfma_f32_16x16x32_bf16 v[72:75], v[140:143], v[192:195], v[72:75]
	s_setprio 0
	s_barrier
	s_add_i32 s51, 0, 0x1c000
	s_add_u32 s30, s26, 0x20000
	v_add_u32_e32 v200, s51, v202
	s_addc_u32 s31, s27, 0
	s_add_i32 s50, s50, s13
	ds_read_b128 v[196:199], v200
	ds_read_b128 v[208:211], v200 offset:1024
	ds_read_b128 v[212:215], v200 offset:2048
	ds_read_b128 v[216:219], v200 offset:3072
	v_lshl_add_u64 v[200:201], s[30:31], 0, v[156:157]
	s_mov_b32 m0, s50
	s_nop 0
	global_load_lds_dwordx4 v[200:201], off
	v_lshl_add_u64 v[200:201], s[30:31], 0, v[152:153]
	s_add_i32 m0, s50, 0x2000
	s_nop 0
	global_load_lds_dwordx4 v[200:201], off
	s_barrier
	s_waitcnt lgkmcnt(0)
	s_setprio 1
	s_waitcnt lgkmcnt(0)
	v_mfma_f32_16x16x32_bf16 v[116:119], v[196:199], v[144:147], v[116:119]
	v_mfma_f32_16x16x32_bf16 v[112:115], v[212:215], v[144:147], v[112:115]
	v_mfma_f32_16x16x32_bf16 v[100:103], v[196:199], v[172:175], v[100:103]
	v_mfma_f32_16x16x32_bf16 v[96:99], v[212:215], v[172:175], v[96:99]
	v_mfma_f32_16x16x32_bf16 v[84:87], v[196:199], v[180:183], v[84:87]
	v_mfma_f32_16x16x32_bf16 v[80:83], v[212:215], v[180:183], v[80:83]
	v_mfma_f32_16x16x32_bf16 v[68:71], v[196:199], v[188:191], v[68:71]
	v_mfma_f32_16x16x32_bf16 v[64:67], v[212:215], v[188:191], v[64:67]
	v_mfma_f32_16x16x32_bf16 v[116:119], v[208:211], v[148:151], v[116:119]
	v_mfma_f32_16x16x32_bf16 v[112:115], v[216:219], v[148:151], v[112:115]
	v_mfma_f32_16x16x32_bf16 v[100:103], v[208:211], v[176:179], v[100:103]
	v_mfma_f32_16x16x32_bf16 v[96:99], v[216:219], v[176:179], v[96:99]
	v_mfma_f32_16x16x32_bf16 v[84:87], v[208:211], v[184:187], v[84:87]
	v_mfma_f32_16x16x32_bf16 v[80:83], v[216:219], v[184:187], v[80:83]
	v_mfma_f32_16x16x32_bf16 v[68:71], v[208:211], v[192:195], v[68:71]
	v_mfma_f32_16x16x32_bf16 v[64:67], v[216:219], v[192:195], v[64:67]
	s_setprio 0
	s_mov_b32 m0, s41
	v_lshl_add_u64 v[200:201], s[28:29], 0, v[158:159]
	s_barrier
	ds_read_b128 v[144:147], v204 offset:49152
	ds_read_b128 v[148:151], v204 offset:50176
	ds_read_b128 v[172:175], v204 offset:51200
	ds_read_b128 v[176:179], v204 offset:52224
	ds_read_b128 v[180:183], v204 offset:53248
	ds_read_b128 v[184:187], v204 offset:54272
	ds_read_b128 v[188:191], v204 offset:55296
	ds_read_b128 v[192:195], v204 offset:56320
	global_load_lds_dwordx4 v[200:201], off
	v_lshl_add_u64 v[200:201], s[28:29], 0, v[154:155]
	s_mov_b32 m0, s42
	s_nop 0
	global_load_lds_dwordx4 v[200:201], off
	s_barrier
	s_waitcnt lgkmcnt(0)
	s_setprio 1
	s_waitcnt lgkmcnt(0)
	v_mfma_f32_16x16x32_bf16 v[60:63], v[128:131], v[144:147], v[60:63]
	v_mfma_f32_16x16x32_bf16 v[56:59], v[136:139], v[144:147], v[56:59]
	v_mfma_f32_16x16x32_bf16 v[44:47], v[128:131], v[172:175], v[44:47]
	v_mfma_f32_16x16x32_bf16 v[40:43], v[136:139], v[172:175], v[40:43]
	v_mfma_f32_16x16x32_bf16 v[28:31], v[128:131], v[180:183], v[28:31]
	v_mfma_f32_16x16x32_bf16 v[24:27], v[136:139], v[180:183], v[24:27]
	v_mfma_f32_16x16x32_bf16 v[12:15], v[128:131], v[188:191], v[12:15]
	v_mfma_f32_16x16x32_bf16 v[8:11], v[136:139], v[188:191], v[8:11]
	v_mfma_f32_16x16x32_bf16 v[60:63], v[132:135], v[148:151], v[60:63]
	v_mfma_f32_16x16x32_bf16 v[56:59], v[140:143], v[148:151], v[56:59]
	v_mfma_f32_16x16x32_bf16 v[44:47], v[132:135], v[176:179], v[44:47]
	v_mfma_f32_16x16x32_bf16 v[40:43], v[140:143], v[176:179], v[40:43]
	v_mfma_f32_16x16x32_bf16 v[28:31], v[132:135], v[184:187], v[28:31]
	v_mfma_f32_16x16x32_bf16 v[24:27], v[140:143], v[184:187], v[24:27]
	v_mfma_f32_16x16x32_bf16 v[12:15], v[132:135], v[192:195], v[12:15]
	v_mfma_f32_16x16x32_bf16 v[8:11], v[140:143], v[192:195], v[8:11]
	s_setprio 0
	s_barrier
	s_add_u32 s26, s26, 0x24000
	s_addc_u32 s27, s27, 0
	s_add_i32 s28, s51, s13
	v_lshl_add_u64 v[128:129], s[26:27], 0, v[156:157]
	s_mov_b32 m0, s28
	s_nop 0
	global_load_lds_dwordx4 v[128:129], off
	v_lshl_add_u64 v[128:129], s[26:27], 0, v[152:153]
	s_add_i32 m0, s28, 0x2000
	s_nop 0
	global_load_lds_dwordx4 v[128:129], off
	s_waitcnt vmcnt(6)
	s_barrier
	s_setprio 1
	v_mfma_f32_16x16x32_bf16 v[52:55], v[196:199], v[144:147], v[52:55]
	v_mfma_f32_16x16x32_bf16 v[48:51], v[212:215], v[144:147], v[48:51]
	v_mfma_f32_16x16x32_bf16 v[36:39], v[196:199], v[172:175], v[36:39]
	v_mfma_f32_16x16x32_bf16 v[32:35], v[212:215], v[172:175], v[32:35]
	v_mfma_f32_16x16x32_bf16 v[20:23], v[196:199], v[180:183], v[20:23]
	v_mfma_f32_16x16x32_bf16 v[16:19], v[212:215], v[180:183], v[16:19]
	v_mfma_f32_16x16x32_bf16 v[4:7], v[196:199], v[188:191], v[4:7]
	v_mfma_f32_16x16x32_bf16 v[0:3], v[212:215], v[188:191], v[0:3]
	v_mfma_f32_16x16x32_bf16 v[52:55], v[208:211], v[148:151], v[52:55]
	v_mfma_f32_16x16x32_bf16 v[48:51], v[216:219], v[148:151], v[48:51]
	v_mfma_f32_16x16x32_bf16 v[36:39], v[208:211], v[176:179], v[36:39]
	v_mfma_f32_16x16x32_bf16 v[32:35], v[216:219], v[176:179], v[32:35]
	v_mfma_f32_16x16x32_bf16 v[20:23], v[208:211], v[184:187], v[20:23]
	v_mfma_f32_16x16x32_bf16 v[16:19], v[216:219], v[184:187], v[16:19]
	v_mfma_f32_16x16x32_bf16 v[4:7], v[208:211], v[192:195], v[4:7]
	v_mfma_f32_16x16x32_bf16 v[0:3], v[216:219], v[192:195], v[0:3]
	s_setprio 0
	s_add_i32 s49, s49, 2
	s_add_u32 s17, s17, 0x40000
	s_addc_u32 s48, s48, 0
	s_add_u32 s24, s24, 0x800000
	s_addc_u32 s25, s25, 0
	s_cmp_gt_u32 s49, 61
	s_barrier
	s_cbranch_scc0 .LBB0_1512
	s_nop 0
	s_lshl_b32 s24, s4, 8
	v_readlane_b32 s68, v253, 38
	v_readlane_b32 s69, v253, 39
	s_ashr_i32 s25, s24, 31
	s_lshl_b32 s4, s4, 2
	v_readlane_b32 s70, v253, 40
	v_readlane_b32 s71, v253, 41
	s_mov_b64 s[48:49], s[68:69]
	v_lshl_add_u32 v178, s6, 8, v163
	s_ashr_i32 s5, s4, 31
	s_lshl_b64 s[26:27], s[24:25], 1
	s_mov_b64 s[50:51], s[70:71]
	s_add_u32 s26, s50, s26
	v_ashrrev_i32_e32 v179, 31, v178
	s_addc_u32 s27, s51, s27
	v_lshlrev_b64 v[128:129], 11, v[178:179]
	v_lshl_add_u64 v[128:129], s[26:27], 0, v[128:129]
	v_lshl_add_u64 v[128:129], v[128:129], 0, v[160:161]
	global_load_dwordx4 v[180:183], v[128:129], off
	global_load_dwordx4 v[184:187], v[128:129], off offset:256
	v_or_b32_e32 v176, 16, v178
	v_or_b32_e32 v174, 32, v178
	v_or_b32_e32 v172, 48, v178
	v_ashrrev_i32_e32 v177, 31, v176
	v_ashrrev_i32_e32 v175, 31, v174
	v_ashrrev_i32_e32 v173, 31, v172
	v_lshlrev_b64 v[128:129], 11, v[176:177]
	v_lshlrev_b64 v[130:131], 11, v[174:175]
	v_lshlrev_b64 v[132:133], 11, v[172:173]
	v_lshl_add_u64 v[128:129], s[26:27], 0, v[128:129]
	v_lshl_add_u64 v[130:131], s[26:27], 0, v[130:131]
	v_lshl_add_u64 v[132:133], s[26:27], 0, v[132:133]
	v_lshl_add_u64 v[128:129], v[128:129], 0, v[160:161]
	v_lshl_add_u64 v[130:131], v[130:131], 0, v[160:161]
	v_lshl_add_u64 v[188:189], v[132:133], 0, v[160:161]
	global_load_dwordx4 v[148:151], v[128:129], off
	global_load_dwordx4 v[144:147], v[128:129], off offset:256
	global_load_dwordx4 v[140:143], v[130:131], off
	global_load_dwordx4 v[136:139], v[130:131], off offset:256
	global_load_dwordx4 v[132:135], v[188:189], off
	s_nop 0
	global_load_dwordx4 v[128:131], v[188:189], off offset:256
	v_and_b32_e32 v189, 64, v206
	v_xor_b32_e32 v188, 16, v206
	v_add_u32_e32 v196, 64, v189
	v_cmp_lt_i32_e32 vcc, v188, v196
	s_nop 1
	v_cndmask_b32_e32 v188, v206, v188, vcc
	v_lshlrev_b32_e32 v207, 2, v188
	s_nop 7
	s_nop 0
	s_waitcnt vmcnt(0)
	v_lshlrev_b32_e32 v190, 16, v182
	v_and_b32_e32 v191, 0xffff0000, v182
	v_lshlrev_b32_e32 v188, 16, v180
	v_and_b32_e32 v189, 0xffff0000, v180
	v_lshlrev_b32_e32 v180, 16, v181
	v_and_b32_e32 v181, 0xffff0000, v181
	v_lshlrev_b32_e32 v182, 16, v183
	v_and_b32_e32 v183, 0xffff0000, v183
	v_pk_add_f32 v[120:121], v[120:121], v[190:191]
	v_pk_add_f32 v[126:127], v[126:127], v[180:181]
	v_pk_add_f32 v[124:125], v[124:125], v[188:189]
	v_pk_add_f32 v[122:123], v[122:123], v[182:183]
	v_mul_f32_e32 v180, v120, v120
	v_mul_f32_e32 v181, v121, v121
	v_lshlrev_b32_e32 v194, 16, v186
	v_and_b32_e32 v195, 0xffff0000, v186
	v_mul_f32_e32 v182, v122, v122
	v_fmac_f32_e32 v180, v124, v124
	v_fmac_f32_e32 v181, v125, v125
	v_lshlrev_b32_e32 v192, 16, v184
	v_and_b32_e32 v193, 0xffff0000, v184
	v_lshlrev_b32_e32 v184, 16, v185
	v_and_b32_e32 v185, 0xffff0000, v185
	v_pk_add_f32 v[112:113], v[112:113], v[194:195]
	v_mul_f32_e32 v183, v123, v123
	v_fmac_f32_e32 v182, v126, v126
	v_add_f32_e32 v180, v180, v181
	v_lshlrev_b32_e32 v186, 16, v187
	v_and_b32_e32 v187, 0xffff0000, v187
	v_pk_add_f32 v[118:119], v[118:119], v[184:185]
	v_pk_add_f32 v[116:117], v[116:117], v[192:193]
	v_mul_f32_e32 v184, v112, v112
	v_fmac_f32_e32 v183, v127, v127
	v_add_f32_e32 v180, v182, v180
	v_pk_add_f32 v[114:115], v[114:115], v[186:187]
	v_mul_f32_e32 v185, v113, v113
	v_fmac_f32_e32 v184, v116, v116
	v_add_f32_e32 v180, v183, v180
	v_mul_f32_e32 v186, v114, v114
	v_fmac_f32_e32 v185, v117, v117
	v_add_f32_e32 v180, v184, v180
	v_mul_f32_e32 v187, v115, v115
	v_fmac_f32_e32 v186, v118, v118
	v_add_f32_e32 v180, v185, v180
	v_add_f32_e32 v180, v186, v180
	v_fmac_f32_e32 v187, v119, v119
	v_add_f32_e32 v180, v187, v180
	ds_bpermute_b32 v181, v207, v180
	v_xor_b32_e32 v182, 32, v206
	v_cmp_lt_i32_e32 vcc, v182, v196
	v_lshlrev_b64 v[188:189], 6, v[178:179]
	s_waitcnt lgkmcnt(0)
	v_add_f32_e32 v180, v180, v181
	v_cndmask_b32_e32 v182, v206, v182, vcc
	v_lshlrev_b32_e32 v208, 2, v182
	ds_bpermute_b32 v181, v208, v180
	s_and_saveexec_b64 s[28:29], s[0:1]
	s_cbranch_execz .LBB0_1515
	s_waitcnt lgkmcnt(0)
	v_add_f32_e32 v182, v180, v181
	v_lshl_add_u64 v[180:181], s[88:89], 0, v[188:189]
	v_lshl_add_u64 v[180:181], s[4:5], 2, v[180:181]
	s_lshl_b32 s8, s40, 2
	v_lshl_add_u64 v[180:181], v[180:181], 0, s[8:9]
	global_store_dword v[180:181], v182, off sc1
